# v077 with a vmcnt(10) wait at the end of every phase instead of vmcnt(8)/vmcnt(10) at four: every LDS-DMA load gets five phases to land
# baseline (speedup 1.0000x reference)
.LBB0_329:
	s_add_u32 s19, s16, 0xfff80080
	s_addc_u32 s26, s17, -1
	s_add_i32 s31, 0, 0x10000
	v_add_u32_e32 v2, s31, v158
	ds_read_b128 v[132:135], v2
	ds_read_b128 v[148:151], v2 offset:1024
	ds_read_b128 v[152:155], v2 offset:2048
	ds_read_b128 v[160:163], v2 offset:3072
	s_cmp_eq_u32 s15, 28
	s_cselect_b32 s39, s37, s26
	s_cselect_b32 s38, s36, s19
	s_cselect_b32 s27, s49, s14
	s_cselect_b32 s26, s48, s10
	s_add_i32 m0, s6, 0xc000
	ds_read_b128 v[164:167], v159
	ds_read_b128 v[168:171], v159 offset:1024
	ds_read_b128 v[172:175], v159 offset:2048
	ds_read_b128 v[176:179], v159 offset:3072
	ds_read_b128 v[180:183], v159 offset:4096
	ds_read_b128 v[184:187], v159 offset:5120
	ds_read_b128 v[188:191], v159 offset:6144
	ds_read_b128 v[192:195], v159 offset:7168
	global_load_lds_dwordx4 v144, s[16:17]
	s_add_i32 m0, s6, 0xe000
	s_nop 0
	global_load_lds_dwordx4 v146, s[16:17]
	s_waitcnt vmcnt(10)
	s_barrier
	s_waitcnt lgkmcnt(0)
	v_mfma_f32_16x16x32_f16 v[128:131], v[132:135], v[164:167], v[128:131]
	v_mfma_f32_16x16x32_f16 v[124:127], v[152:155], v[164:167], v[124:127]
	v_mfma_f32_16x16x32_f16 v[112:115], v[132:135], v[172:175], v[112:115]
	v_mfma_f32_16x16x32_f16 v[108:111], v[152:155], v[172:175], v[108:111]
	v_mfma_f32_16x16x32_f16 v[96:99], v[132:135], v[180:183], v[96:99]
	v_mfma_f32_16x16x32_f16 v[92:95], v[152:155], v[180:183], v[92:95]
	v_mfma_f32_16x16x32_f16 v[80:83], v[132:135], v[188:191], v[80:83]
	v_mfma_f32_16x16x32_f16 v[76:79], v[152:155], v[188:191], v[76:79]
	v_mfma_f32_16x16x32_f16 v[128:131], v[148:151], v[168:171], v[128:131]
	v_mfma_f32_16x16x32_f16 v[124:127], v[160:163], v[168:171], v[124:127]
	v_mfma_f32_16x16x32_f16 v[112:115], v[148:151], v[176:179], v[112:115]
	v_mfma_f32_16x16x32_f16 v[108:111], v[160:163], v[176:179], v[108:111]
	v_mfma_f32_16x16x32_f16 v[96:99], v[148:151], v[184:187], v[96:99]
	v_mfma_f32_16x16x32_f16 v[92:95], v[160:163], v[184:187], v[92:95]
	v_mfma_f32_16x16x32_f16 v[80:83], v[148:151], v[192:195], v[80:83]
	v_mfma_f32_16x16x32_f16 v[76:79], v[160:163], v[192:195], v[76:79]
	s_barrier
	s_add_i32 s19, 0, 0x14000
	s_add_i32 s31, s31, s5
	v_add_u32_e32 v2, s19, v158
	v_lshl_add_u64 v[214:215], s[26:27], 0, v[138:139]
	s_mov_b32 m0, s31
	ds_read_b128 v[196:199], v2
	ds_read_b128 v[200:203], v2 offset:1024
	ds_read_b128 v[206:209], v2 offset:2048
	ds_read_b128 v[210:213], v2 offset:3072
	global_load_lds_dwordx4 v[214:215], off
	v_lshl_add_u64 v[216:217], s[26:27], 0, v[142:143]
	s_add_i32 m0, s31, 0x2000
	s_nop 0
	global_load_lds_dwordx4 v[216:217], off
	s_waitcnt vmcnt(10)
	s_barrier
	s_waitcnt lgkmcnt(0)
	v_mfma_f32_16x16x32_f16 v[120:123], v[196:199], v[164:167], v[120:123]
	v_mfma_f32_16x16x32_f16 v[116:119], v[206:209], v[164:167], v[116:119]
	v_mfma_f32_16x16x32_f16 v[104:107], v[196:199], v[172:175], v[104:107]
	v_mfma_f32_16x16x32_f16 v[100:103], v[206:209], v[172:175], v[100:103]
	v_mfma_f32_16x16x32_f16 v[88:91], v[196:199], v[180:183], v[88:91]
	v_mfma_f32_16x16x32_f16 v[84:87], v[206:209], v[180:183], v[84:87]
	v_mfma_f32_16x16x32_f16 v[72:75], v[196:199], v[188:191], v[72:75]
	v_mfma_f32_16x16x32_f16 v[68:71], v[206:209], v[188:191], v[68:71]
	v_mfma_f32_16x16x32_f16 v[120:123], v[200:203], v[168:171], v[120:123]
	v_mfma_f32_16x16x32_f16 v[116:119], v[210:213], v[168:171], v[116:119]
	v_mfma_f32_16x16x32_f16 v[104:107], v[200:203], v[176:179], v[104:107]
	v_mfma_f32_16x16x32_f16 v[100:103], v[210:213], v[176:179], v[100:103]
	v_mfma_f32_16x16x32_f16 v[88:91], v[200:203], v[184:187], v[88:91]
	v_mfma_f32_16x16x32_f16 v[84:87], v[210:213], v[184:187], v[84:87]
	v_mfma_f32_16x16x32_f16 v[72:75], v[200:203], v[192:195], v[72:75]
	v_mfma_f32_16x16x32_f16 v[68:71], v[210:213], v[192:195], v[68:71]
	s_mov_b32 m0, s6
	v_lshl_add_u64 v[218:219], s[38:39], 0, v[136:137]
	s_barrier
	ds_read_b128 v[164:167], v159 offset:16384
	ds_read_b128 v[168:171], v159 offset:17408
	ds_read_b128 v[172:175], v159 offset:18432
	ds_read_b128 v[176:179], v159 offset:19456
	ds_read_b128 v[180:183], v159 offset:20480
	ds_read_b128 v[184:187], v159 offset:21504
	ds_read_b128 v[188:191], v159 offset:22528
	ds_read_b128 v[192:195], v159 offset:23552
	global_load_lds_dwordx4 v[218:219], off
	v_lshl_add_u64 v[220:221], s[38:39], 0, v[140:141]
	s_mov_b32 m0, s7
	s_nop 0
	global_load_lds_dwordx4 v[220:221], off
	s_waitcnt vmcnt(10)
	s_barrier
	s_waitcnt lgkmcnt(0)
	v_mfma_f32_16x16x32_f16 v[64:67], v[132:135], v[164:167], v[64:67]
	v_mfma_f32_16x16x32_f16 v[60:63], v[152:155], v[164:167], v[60:63]
	v_mfma_f32_16x16x32_f16 v[48:51], v[132:135], v[172:175], v[48:51]
	v_mfma_f32_16x16x32_f16 v[44:47], v[152:155], v[172:175], v[44:47]
	v_mfma_f32_16x16x32_f16 v[32:35], v[132:135], v[180:183], v[32:35]
	v_mfma_f32_16x16x32_f16 v[28:31], v[152:155], v[180:183], v[28:31]
	v_mfma_f32_16x16x32_f16 v[16:19], v[132:135], v[188:191], v[16:19]
	v_mfma_f32_16x16x32_f16 v[12:15], v[152:155], v[188:191], v[12:15]
	v_mfma_f32_16x16x32_f16 v[64:67], v[148:151], v[168:171], v[64:67]
	v_mfma_f32_16x16x32_f16 v[60:63], v[160:163], v[168:171], v[60:63]
	v_mfma_f32_16x16x32_f16 v[48:51], v[148:151], v[176:179], v[48:51]
	v_mfma_f32_16x16x32_f16 v[44:47], v[160:163], v[176:179], v[44:47]
	v_mfma_f32_16x16x32_f16 v[32:35], v[148:151], v[184:187], v[32:35]
	v_mfma_f32_16x16x32_f16 v[28:31], v[160:163], v[184:187], v[28:31]
	v_mfma_f32_16x16x32_f16 v[16:19], v[148:151], v[192:195], v[16:19]
	v_mfma_f32_16x16x32_f16 v[12:15], v[160:163], v[192:195], v[12:15]
	s_barrier
	s_add_u32 s42, s26, 0x80000
	s_addc_u32 s43, s27, 0
	s_add_i32 s19, s19, s5
	s_mov_b32 m0, s19
	s_nop 0
	global_load_lds_dwordx4 v138, s[42:43]
	s_add_i32 m0, s19, 0x2000
	s_nop 0
	global_load_lds_dwordx4 v142, s[42:43]
	s_waitcnt vmcnt(10)
	s_barrier
	v_mfma_f32_16x16x32_f16 v[56:59], v[196:199], v[164:167], v[56:59]
	v_mfma_f32_16x16x32_f16 v[52:55], v[206:209], v[164:167], v[52:55]
	v_mfma_f32_16x16x32_f16 v[40:43], v[196:199], v[172:175], v[40:43]
	v_mfma_f32_16x16x32_f16 v[36:39], v[206:209], v[172:175], v[36:39]
	v_mfma_f32_16x16x32_f16 v[24:27], v[196:199], v[180:183], v[24:27]
	v_mfma_f32_16x16x32_f16 v[20:23], v[206:209], v[180:183], v[20:23]
	v_mfma_f32_16x16x32_f16 v[8:11], v[196:199], v[188:191], v[8:11]
	v_mfma_f32_16x16x32_f16 v[4:7], v[206:209], v[188:191], v[4:7]
	v_mfma_f32_16x16x32_f16 v[56:59], v[200:203], v[168:171], v[56:59]
	v_mfma_f32_16x16x32_f16 v[52:55], v[210:213], v[168:171], v[52:55]
	v_mfma_f32_16x16x32_f16 v[40:43], v[200:203], v[176:179], v[40:43]
	v_mfma_f32_16x16x32_f16 v[36:39], v[210:213], v[176:179], v[36:39]
	v_mfma_f32_16x16x32_f16 v[24:27], v[200:203], v[184:187], v[24:27]
	v_mfma_f32_16x16x32_f16 v[20:23], v[210:213], v[184:187], v[20:23]
	v_mfma_f32_16x16x32_f16 v[8:11], v[200:203], v[192:195], v[8:11]
	v_mfma_f32_16x16x32_f16 v[4:7], v[210:213], v[192:195], v[4:7]
	s_add_i32 s19, 0, 0x18000
	v_add_u32_e32 v2, s19, v158
	s_barrier
	ds_read_b128 v[132:135], v2
	ds_read_b128 v[148:151], v2 offset:1024
	ds_read_b128 v[152:155], v2 offset:2048
	ds_read_b128 v[160:163], v2 offset:3072
	s_add_u32 s38, s38, 0x80000
	s_addc_u32 s39, s39, 0
	s_mov_b32 m0, s8
	ds_read_b128 v[164:167], v159 offset:32768
	ds_read_b128 v[168:171], v159 offset:33792
	ds_read_b128 v[172:175], v159 offset:34816
	ds_read_b128 v[176:179], v159 offset:35840
	ds_read_b128 v[180:183], v159 offset:36864
	ds_read_b128 v[184:187], v159 offset:37888
	ds_read_b128 v[188:191], v159 offset:38912
	ds_read_b128 v[192:195], v159 offset:39936
	global_load_lds_dwordx4 v136, s[38:39]
	s_mov_b32 m0, s9
	s_nop 0
	global_load_lds_dwordx4 v140, s[38:39]
	s_waitcnt vmcnt(10)
	s_barrier
	s_waitcnt lgkmcnt(0)
	v_mfma_f32_16x16x32_f16 v[128:131], v[132:135], v[164:167], v[128:131]
	v_mfma_f32_16x16x32_f16 v[124:127], v[152:155], v[164:167], v[124:127]
	v_mfma_f32_16x16x32_f16 v[112:115], v[132:135], v[172:175], v[112:115]
	v_mfma_f32_16x16x32_f16 v[108:111], v[152:155], v[172:175], v[108:111]
	v_mfma_f32_16x16x32_f16 v[96:99], v[132:135], v[180:183], v[96:99]
	v_mfma_f32_16x16x32_f16 v[92:95], v[152:155], v[180:183], v[92:95]
	v_mfma_f32_16x16x32_f16 v[80:83], v[132:135], v[188:191], v[80:83]
	v_mfma_f32_16x16x32_f16 v[76:79], v[152:155], v[188:191], v[76:79]
	v_mfma_f32_16x16x32_f16 v[128:131], v[148:151], v[168:171], v[128:131]
	v_mfma_f32_16x16x32_f16 v[124:127], v[160:163], v[168:171], v[124:127]
	v_mfma_f32_16x16x32_f16 v[112:115], v[148:151], v[176:179], v[112:115]
	v_mfma_f32_16x16x32_f16 v[108:111], v[160:163], v[176:179], v[108:111]
	v_mfma_f32_16x16x32_f16 v[96:99], v[148:151], v[184:187], v[96:99]
	v_mfma_f32_16x16x32_f16 v[92:95], v[160:163], v[184:187], v[92:95]
	v_mfma_f32_16x16x32_f16 v[80:83], v[148:151], v[192:195], v[80:83]
	v_mfma_f32_16x16x32_f16 v[76:79], v[160:163], v[192:195], v[76:79]
	s_barrier
	s_add_i32 s31, 0, 0x1c000
	s_add_i32 s19, s19, s5
	v_add_u32_e32 v2, s31, v158
	v_lshl_add_u64 v[214:215], v[214:215], 0, s[88:89]
	s_mov_b32 m0, s19
	ds_read_b128 v[196:199], v2
	ds_read_b128 v[200:203], v2 offset:1024
	ds_read_b128 v[206:209], v2 offset:2048
	ds_read_b128 v[210:213], v2 offset:3072
	global_load_lds_dwordx4 v[214:215], off
	v_lshl_add_u64 v[214:215], v[216:217], 0, s[88:89]
	s_add_i32 m0, s19, 0x2000
	s_nop 0
	global_load_lds_dwordx4 v[214:215], off
	s_waitcnt vmcnt(10)
	s_barrier
	s_waitcnt lgkmcnt(0)
	v_mfma_f32_16x16x32_f16 v[120:123], v[196:199], v[164:167], v[120:123]
	v_mfma_f32_16x16x32_f16 v[116:119], v[206:209], v[164:167], v[116:119]
	v_mfma_f32_16x16x32_f16 v[104:107], v[196:199], v[172:175], v[104:107]
	v_mfma_f32_16x16x32_f16 v[100:103], v[206:209], v[172:175], v[100:103]
	v_mfma_f32_16x16x32_f16 v[88:91], v[196:199], v[180:183], v[88:91]
	v_mfma_f32_16x16x32_f16 v[84:87], v[206:209], v[180:183], v[84:87]
	v_mfma_f32_16x16x32_f16 v[72:75], v[196:199], v[188:191], v[72:75]
	v_mfma_f32_16x16x32_f16 v[68:71], v[206:209], v[188:191], v[68:71]
	v_mfma_f32_16x16x32_f16 v[120:123], v[200:203], v[168:171], v[120:123]
	v_mfma_f32_16x16x32_f16 v[116:119], v[210:213], v[168:171], v[116:119]
	v_mfma_f32_16x16x32_f16 v[104:107], v[200:203], v[176:179], v[104:107]
	v_mfma_f32_16x16x32_f16 v[100:103], v[210:213], v[176:179], v[100:103]
	v_mfma_f32_16x16x32_f16 v[88:91], v[200:203], v[184:187], v[88:91]
	v_mfma_f32_16x16x32_f16 v[84:87], v[210:213], v[184:187], v[84:87]
	v_mfma_f32_16x16x32_f16 v[72:75], v[200:203], v[192:195], v[72:75]
	v_mfma_f32_16x16x32_f16 v[68:71], v[210:213], v[192:195], v[68:71]
	s_mov_b32 m0, s30
	v_lshl_add_u64 v[214:215], v[218:219], 0, s[88:89]
	s_barrier
	ds_read_b128 v[164:167], v159 offset:49152
	ds_read_b128 v[168:171], v159 offset:50176
	ds_read_b128 v[172:175], v159 offset:51200
	ds_read_b128 v[176:179], v159 offset:52224
	ds_read_b128 v[180:183], v159 offset:53248
	ds_read_b128 v[184:187], v159 offset:54272
	ds_read_b128 v[188:191], v159 offset:55296
	ds_read_b128 v[192:195], v159 offset:56320
	global_load_lds_dwordx4 v[214:215], off
	v_lshl_add_u64 v[214:215], v[220:221], 0, s[88:89]
	s_mov_b32 m0, s52
	s_nop 0
	global_load_lds_dwordx4 v[214:215], off
	s_waitcnt vmcnt(10)
	s_barrier
	s_waitcnt lgkmcnt(0)
	v_mfma_f32_16x16x32_f16 v[64:67], v[132:135], v[164:167], v[64:67]
	v_mfma_f32_16x16x32_f16 v[60:63], v[152:155], v[164:167], v[60:63]
	v_mfma_f32_16x16x32_f16 v[48:51], v[132:135], v[172:175], v[48:51]
	v_mfma_f32_16x16x32_f16 v[44:47], v[152:155], v[172:175], v[44:47]
	v_mfma_f32_16x16x32_f16 v[32:35], v[132:135], v[180:183], v[32:35]
	v_mfma_f32_16x16x32_f16 v[28:31], v[152:155], v[180:183], v[28:31]
	v_mfma_f32_16x16x32_f16 v[16:19], v[132:135], v[188:191], v[16:19]
	v_mfma_f32_16x16x32_f16 v[12:15], v[152:155], v[188:191], v[12:15]
	v_mfma_f32_16x16x32_f16 v[64:67], v[148:151], v[168:171], v[64:67]
	v_mfma_f32_16x16x32_f16 v[60:63], v[160:163], v[168:171], v[60:63]
	v_mfma_f32_16x16x32_f16 v[48:51], v[148:151], v[176:179], v[48:51]
	v_mfma_f32_16x16x32_f16 v[44:47], v[160:163], v[176:179], v[44:47]
	v_mfma_f32_16x16x32_f16 v[32:35], v[148:151], v[184:187], v[32:35]
	v_mfma_f32_16x16x32_f16 v[28:31], v[160:163], v[184:187], v[28:31]
	v_mfma_f32_16x16x32_f16 v[16:19], v[148:151], v[192:195], v[16:19]
	v_mfma_f32_16x16x32_f16 v[12:15], v[160:163], v[192:195], v[12:15]
	s_barrier
	s_add_u32 s26, s26, 0x80080
	s_addc_u32 s27, s27, 0
	s_add_i32 s19, s31, s5
	s_mov_b32 m0, s19
	s_nop 0
	global_load_lds_dwordx4 v138, s[26:27]
	s_add_i32 m0, s19, 0x2000
	s_nop 0
	global_load_lds_dwordx4 v142, s[26:27]
	s_waitcnt vmcnt(10)
	s_barrier
	v_mfma_f32_16x16x32_f16 v[56:59], v[196:199], v[164:167], v[56:59]
	v_mfma_f32_16x16x32_f16 v[52:55], v[206:209], v[164:167], v[52:55]
	v_mfma_f32_16x16x32_f16 v[40:43], v[196:199], v[172:175], v[40:43]
	v_mfma_f32_16x16x32_f16 v[36:39], v[206:209], v[172:175], v[36:39]
	v_mfma_f32_16x16x32_f16 v[24:27], v[196:199], v[180:183], v[24:27]
	v_mfma_f32_16x16x32_f16 v[20:23], v[206:209], v[180:183], v[20:23]
	v_mfma_f32_16x16x32_f16 v[8:11], v[196:199], v[188:191], v[8:11]
	v_mfma_f32_16x16x32_f16 v[4:7], v[206:209], v[188:191], v[4:7]
	v_mfma_f32_16x16x32_f16 v[56:59], v[200:203], v[168:171], v[56:59]
	v_mfma_f32_16x16x32_f16 v[52:55], v[210:213], v[168:171], v[52:55]
	v_mfma_f32_16x16x32_f16 v[40:43], v[200:203], v[176:179], v[40:43]
	v_mfma_f32_16x16x32_f16 v[36:39], v[210:213], v[176:179], v[36:39]
	v_mfma_f32_16x16x32_f16 v[24:27], v[200:203], v[184:187], v[24:27]
	v_mfma_f32_16x16x32_f16 v[20:23], v[210:213], v[184:187], v[20:23]
	v_mfma_f32_16x16x32_f16 v[8:11], v[200:203], v[192:195], v[8:11]
	v_mfma_f32_16x16x32_f16 v[4:7], v[210:213], v[192:195], v[4:7]
	s_add_i32 s15, s15, 2
	s_add_u32 s16, s16, 0x100
	s_addc_u32 s17, s17, 0
	s_add_u32 s10, s10, 0x100
	s_addc_u32 s14, s14, 0
	s_cmp_gt_u32 s15, 29
	s_barrier
	s_cbranch_scc0 .LBB0_329
	s_lshl_b32 s19, s11, 8
	v_mov_b32_e32 v2, v156
	s_add_i32 s10, s19, s12
	v_mov_b32_e32 v132, v157
	v_add_u32_e32 v161, s10, v2
	s_lshl_b32 s10, s29, 8
	s_or_b32 s14, s10, s13
	s_cmp_gt_i32 s29, 1
	v_lshlrev_b32_e32 v154, 3, v132
	v_add_u32_e32 v160, s14, v154
	s_cselect_b64 s[16:17], -1, 0
	s_add_i32 s14, s29, -14
	s_cmp_gt_u32 s14, 5
	s_cselect_b64 s[38:39], -1, 0
	s_sub_i32 s14, s29, 20
	s_cmp_gt_u32 s14, 23
	s_cselect_b64 s[50:51], -1, 0
	s_cmp_eq_u32 s29, 44
	s_mul_i32 s14, s29, 0x42
	s_cselect_b64 s[42:43], -1, 0
	s_addk_i32 s14, 0xfad8
	s_ashr_i32 s15, s14, 31
	s_ashr_i32 s26, s11, 31
	s_add_u32 s14, s14, s11
	s_addc_u32 s15, s15, s26
	v_lshlrev_b32_e32 v133, 7, v2
	s_lshl_b64 s[26:27], s[14:15], 17
	v_and_b32_e32 v132, 0xffffe000, v161
	v_and_b32_e32 v162, 0x1f80, v133
	v_bfe_u32 v133, v161, 6, 7
	s_movk_i32 s14, 0x4000
	v_or3_b32 v132, v132, v133, v162
	v_cmp_gt_i32_e32 vcc, s14, v161
	s_sub_i32 s29, s10, s19
	s_addk_i32 s29, 0xf200
	v_cndmask_b32_e32 v132, v161, v132, vcc
	v_mad_i64_i32 v[152:153], s[14:15], v132, s33, 0
	v_add_u32_e32 v132, s12, v2
	v_ashrrev_i32_e32 v133, 31, v132
	v_lshlrev_b64 v[150:151], 9, v[132:133]
	v_add_u32_e32 v132, s29, v161
	s_mov_b32 s14, 0x8400
	v_mad_i64_i32 v[148:149], s[14:15], v132, s14, 0
	s_sub_i32 s11, s19, s10
	v_cvt_pk_f16_f32 v135, v126, v127
	v_cvt_pk_f16_f32 v134, v124, v125
	v_cvt_pk_f16_f32 v133, v130, v131
	v_cvt_pk_f16_f32 v132, v128, v129
	s_mov_b64 s[14:15], -1
	s_and_b64 vcc, exec, s[16:17]
	s_cbranch_vccz .LBB0_340
	s_and_b64 vcc, exec, s[38:39]
	s_cbranch_vccz .LBB0_337
	s_and_b64 vcc, exec, s[50:51]
	s_cbranch_vccz .LBB0_334
	v_add_u32_e32 v155, 0xffffe200, v160
	v_cndmask_b32_e64 v166, v160, v155, s[42:43]
	v_lshl_add_u64 v[164:165], s[22:23], 0, v[152:153]
	v_ashrrev_i32_e32 v167, 31, v166
	v_lshl_add_u64 v[164:165], v[166:167], 1, v[164:165]
	global_store_dwordx4 v[164:165], v[132:135], off
	s_mov_b64 s[14:15], 0

.LBB0_1341:
	s_add_u32 s29, s26, 0xffc00080
	s_addc_u32 s31, s27, -1
	s_add_i32 s48, 0, 0x10000
	v_add_u32_e32 v2, s48, v190
	ds_read_b128 v[28:31], v2
	ds_read_b128 v[32:35], v2 offset:1024
	ds_read_b128 v[100:103], v2 offset:2048
	ds_read_b128 v[112:115], v2 offset:3072
	s_cmp_eq_u32 s19, 4
	s_cselect_b32 s43, s35, s31
	s_cselect_b32 s42, s34, s29
	s_cselect_b32 s39, s37, s17
	s_cselect_b32 s38, s36, s11
	s_add_i32 m0, s7, 0xc000
	ds_read_b128 v[124:127], v191
	ds_read_b128 v[136:139], v191 offset:1024
	ds_read_b128 v[148:151], v191 offset:2048
	ds_read_b128 v[156:159], v191 offset:3072
	ds_read_b128 v[164:167], v191 offset:4096
	ds_read_b128 v[168:171], v191 offset:5120
	ds_read_b128 v[184:187], v191 offset:6144
	ds_read_b128 v[192:195], v191 offset:7168
	global_load_lds_dwordx4 v180, s[26:27]
	s_add_i32 m0, s7, 0xe000
	s_nop 0
	global_load_lds_dwordx4 v182, s[26:27]
	s_waitcnt vmcnt(10)
	s_barrier
	s_waitcnt lgkmcnt(0)
	v_mfma_f32_16x16x32_f16 v[160:163], v[28:31], v[124:127], v[160:163]
	v_mfma_f32_16x16x32_f16 v[152:155], v[100:103], v[124:127], v[152:155]
	v_mfma_f32_16x16x32_f16 v[132:135], v[28:31], v[148:151], v[132:135]
	v_mfma_f32_16x16x32_f16 v[128:131], v[100:103], v[148:151], v[128:131]
	v_mfma_f32_16x16x32_f16 v[108:111], v[28:31], v[164:167], v[108:111]
	v_mfma_f32_16x16x32_f16 v[104:107], v[100:103], v[164:167], v[104:107]
	v_mfma_f32_16x16x32_f16 v[88:91], v[28:31], v[184:187], v[88:91]
	v_mfma_f32_16x16x32_f16 v[84:87], v[100:103], v[184:187], v[84:87]
	v_mfma_f32_16x16x32_f16 v[160:163], v[32:35], v[136:139], v[160:163]
	v_mfma_f32_16x16x32_f16 v[152:155], v[112:115], v[136:139], v[152:155]
	v_mfma_f32_16x16x32_f16 v[132:135], v[32:35], v[156:159], v[132:135]
	v_mfma_f32_16x16x32_f16 v[128:131], v[112:115], v[156:159], v[128:131]
	v_mfma_f32_16x16x32_f16 v[108:111], v[32:35], v[168:171], v[108:111]
	v_mfma_f32_16x16x32_f16 v[104:107], v[112:115], v[168:171], v[104:107]
	v_mfma_f32_16x16x32_f16 v[88:91], v[32:35], v[192:195], v[88:91]
	v_mfma_f32_16x16x32_f16 v[84:87], v[112:115], v[192:195], v[84:87]
	s_barrier
	s_add_i32 s29, 0, 0x14000
	s_add_i32 s31, s48, s6
	v_add_u32_e32 v2, s29, v190
	v_lshl_add_u64 v[214:215], s[38:39], 0, v[176:177]
	s_mov_b32 m0, s31
	ds_read_b128 v[196:199], v2
	ds_read_b128 v[200:203], v2 offset:1024
	ds_read_b128 v[206:209], v2 offset:2048
	ds_read_b128 v[210:213], v2 offset:3072
	global_load_lds_dwordx4 v[214:215], off
	v_lshl_add_u64 v[216:217], s[38:39], 0, v[172:173]
	s_add_i32 m0, s31, 0x2000
	s_nop 0
	global_load_lds_dwordx4 v[216:217], off
	s_waitcnt vmcnt(10)
	s_barrier
	s_waitcnt lgkmcnt(0)
	v_mfma_f32_16x16x32_f16 v[144:147], v[196:199], v[124:127], v[144:147]
	v_mfma_f32_16x16x32_f16 v[120:123], v[196:199], v[148:151], v[120:123]
	v_mfma_f32_16x16x32_f16 v[116:119], v[206:209], v[148:151], v[116:119]
	v_mfma_f32_16x16x32_f16 v[96:99], v[196:199], v[164:167], v[96:99]
	v_mfma_f32_16x16x32_f16 v[92:95], v[206:209], v[164:167], v[92:95]
	v_mfma_f32_16x16x32_f16 v[80:83], v[196:199], v[184:187], v[80:83]
	v_mfma_f32_16x16x32_f16 v[76:79], v[206:209], v[184:187], v[76:79]
	v_mfma_f32_16x16x32_f16 v[144:147], v[200:203], v[136:139], v[144:147]
	v_mfma_f32_16x16x32_f16 v[124:127], v[206:209], v[124:127], v[140:143]
	v_mfma_f32_16x16x32_f16 v[120:123], v[200:203], v[156:159], v[120:123]
	v_mfma_f32_16x16x32_f16 v[116:119], v[210:213], v[156:159], v[116:119]
	v_mfma_f32_16x16x32_f16 v[96:99], v[200:203], v[168:171], v[96:99]
	v_mfma_f32_16x16x32_f16 v[92:95], v[210:213], v[168:171], v[92:95]
	v_mfma_f32_16x16x32_f16 v[80:83], v[200:203], v[192:195], v[80:83]
	v_mfma_f32_16x16x32_f16 v[76:79], v[210:213], v[192:195], v[76:79]
	v_mfma_f32_16x16x32_f16 v[124:127], v[210:213], v[136:139], v[124:127]
	s_mov_b32 m0, s7
	v_lshl_add_u64 v[218:219], s[42:43], 0, v[178:179]
	s_barrier
	ds_read_b128 v[136:139], v191 offset:16384
	ds_read_b128 v[140:143], v191 offset:17408
	ds_read_b128 v[148:151], v191 offset:18432
	ds_read_b128 v[156:159], v191 offset:19456
	ds_read_b128 v[164:167], v191 offset:20480
	ds_read_b128 v[168:171], v191 offset:21504
	ds_read_b128 v[184:187], v191 offset:22528
	ds_read_b128 v[192:195], v191 offset:23552
	global_load_lds_dwordx4 v[218:219], off
	v_lshl_add_u64 v[220:221], s[42:43], 0, v[174:175]
	s_mov_b32 m0, s8
	s_nop 0
	global_load_lds_dwordx4 v[220:221], off
	s_waitcnt vmcnt(10)
	s_barrier
	s_waitcnt lgkmcnt(0)
	v_mfma_f32_16x16x32_f16 v[72:75], v[28:31], v[136:139], v[72:75]
	v_mfma_f32_16x16x32_f16 v[68:71], v[100:103], v[136:139], v[68:71]
	v_mfma_f32_16x16x32_f16 v[56:59], v[28:31], v[148:151], v[56:59]
	v_mfma_f32_16x16x32_f16 v[52:55], v[100:103], v[148:151], v[52:55]
	v_mfma_f32_16x16x32_f16 v[40:43], v[28:31], v[164:167], v[40:43]
	v_mfma_f32_16x16x32_f16 v[36:39], v[100:103], v[164:167], v[36:39]
	v_mfma_f32_16x16x32_f16 v[16:19], v[28:31], v[184:187], v[16:19]
	v_mfma_f32_16x16x32_f16 v[12:15], v[100:103], v[184:187], v[12:15]
	v_mfma_f32_16x16x32_f16 v[72:75], v[32:35], v[140:143], v[72:75]
	v_mfma_f32_16x16x32_f16 v[68:71], v[112:115], v[140:143], v[68:71]
	v_mfma_f32_16x16x32_f16 v[56:59], v[32:35], v[156:159], v[56:59]
	v_mfma_f32_16x16x32_f16 v[52:55], v[112:115], v[156:159], v[52:55]
	v_mfma_f32_16x16x32_f16 v[40:43], v[32:35], v[168:171], v[40:43]
	v_mfma_f32_16x16x32_f16 v[36:39], v[112:115], v[168:171], v[36:39]
	v_mfma_f32_16x16x32_f16 v[16:19], v[32:35], v[192:195], v[16:19]
	v_mfma_f32_16x16x32_f16 v[12:15], v[112:115], v[192:195], v[12:15]
	s_barrier
	s_add_u32 s48, s38, 0x20000
	s_addc_u32 s49, s39, 0
	s_add_i32 s29, s29, s6
	s_mov_b32 m0, s29
	s_nop 0
	global_load_lds_dwordx4 v176, s[48:49]
	s_add_i32 m0, s29, 0x2000
	s_nop 0
	global_load_lds_dwordx4 v172, s[48:49]
	s_waitcnt vmcnt(10)
	s_barrier
	v_mfma_f32_16x16x32_f16 v[48:51], v[196:199], v[148:151], v[48:51]
	v_mfma_f32_16x16x32_f16 v[44:47], v[206:209], v[148:151], v[44:47]
	v_mfma_f32_16x16x32_f16 v[24:27], v[196:199], v[164:167], v[24:27]
	v_mfma_f32_16x16x32_f16 v[20:23], v[206:209], v[164:167], v[20:23]
	v_mfma_f32_16x16x32_f16 v[8:11], v[196:199], v[184:187], v[8:11]
	v_mfma_f32_16x16x32_f16 v[4:7], v[206:209], v[184:187], v[4:7]
	v_mfma_f32_16x16x32_f16 v[28:31], v[196:199], v[136:139], v[64:67]
	v_mfma_f32_16x16x32_f16 v[32:35], v[206:209], v[136:139], v[60:63]
	v_mfma_f32_16x16x32_f16 v[48:51], v[200:203], v[156:159], v[48:51]
	v_mfma_f32_16x16x32_f16 v[44:47], v[210:213], v[156:159], v[44:47]
	v_mfma_f32_16x16x32_f16 v[24:27], v[200:203], v[168:171], v[24:27]
	v_mfma_f32_16x16x32_f16 v[20:23], v[210:213], v[168:171], v[20:23]
	v_mfma_f32_16x16x32_f16 v[8:11], v[200:203], v[192:195], v[8:11]
	v_mfma_f32_16x16x32_f16 v[4:7], v[210:213], v[192:195], v[4:7]
	v_mfma_f32_16x16x32_f16 v[28:31], v[200:203], v[140:143], v[28:31]
	v_mfma_f32_16x16x32_f16 v[32:35], v[210:213], v[140:143], v[32:35]
	s_add_i32 s29, 0, 0x18000
	v_add_u32_e32 v2, s29, v190
	s_barrier
	ds_read_b128 v[60:63], v2
	ds_read_b128 v[64:67], v2 offset:1024
	ds_read_b128 v[100:103], v2 offset:2048
	ds_read_b128 v[112:115], v2 offset:3072
	s_add_u32 s42, s42, 0x400000
	s_addc_u32 s43, s43, 0
	s_mov_b32 m0, s9
	ds_read_b128 v[136:139], v191 offset:32768
	ds_read_b128 v[140:143], v191 offset:33792
	ds_read_b128 v[148:151], v191 offset:34816
	ds_read_b128 v[156:159], v191 offset:35840
	ds_read_b128 v[164:167], v191 offset:36864
	ds_read_b128 v[168:171], v191 offset:37888
	ds_read_b128 v[184:187], v191 offset:38912
	ds_read_b128 v[192:195], v191 offset:39936
	global_load_lds_dwordx4 v178, s[42:43]
	s_mov_b32 m0, s12
	s_nop 0
	global_load_lds_dwordx4 v174, s[42:43]
	s_waitcnt vmcnt(10)
	s_barrier
	s_waitcnt lgkmcnt(0)
	v_mfma_f32_16x16x32_f16 v[160:163], v[60:63], v[136:139], v[160:163]
	v_mfma_f32_16x16x32_f16 v[152:155], v[100:103], v[136:139], v[152:155]
	v_mfma_f32_16x16x32_f16 v[132:135], v[60:63], v[148:151], v[132:135]
	v_mfma_f32_16x16x32_f16 v[128:131], v[100:103], v[148:151], v[128:131]
	v_mfma_f32_16x16x32_f16 v[108:111], v[60:63], v[164:167], v[108:111]
	v_mfma_f32_16x16x32_f16 v[104:107], v[100:103], v[164:167], v[104:107]
	v_mfma_f32_16x16x32_f16 v[88:91], v[60:63], v[184:187], v[88:91]
	v_mfma_f32_16x16x32_f16 v[84:87], v[100:103], v[184:187], v[84:87]
	v_mfma_f32_16x16x32_f16 v[160:163], v[64:67], v[140:143], v[160:163]
	v_mfma_f32_16x16x32_f16 v[152:155], v[112:115], v[140:143], v[152:155]
	v_mfma_f32_16x16x32_f16 v[132:135], v[64:67], v[156:159], v[132:135]
	v_mfma_f32_16x16x32_f16 v[128:131], v[112:115], v[156:159], v[128:131]
	v_mfma_f32_16x16x32_f16 v[108:111], v[64:67], v[168:171], v[108:111]
	v_mfma_f32_16x16x32_f16 v[104:107], v[112:115], v[168:171], v[104:107]
	v_mfma_f32_16x16x32_f16 v[88:91], v[64:67], v[192:195], v[88:91]
	v_mfma_f32_16x16x32_f16 v[84:87], v[112:115], v[192:195], v[84:87]
	s_barrier
	s_add_i32 s31, 0, 0x1c000
	s_add_i32 s29, s29, s6
	v_add_u32_e32 v2, s31, v190
	v_lshl_add_u64 v[214:215], v[214:215], 0, s[88:89]
	s_mov_b32 m0, s29
	ds_read_b128 v[196:199], v2
	ds_read_b128 v[200:203], v2 offset:1024
	ds_read_b128 v[206:209], v2 offset:2048
	ds_read_b128 v[210:213], v2 offset:3072
	global_load_lds_dwordx4 v[214:215], off
	v_lshl_add_u64 v[214:215], v[216:217], 0, s[88:89]
	s_add_i32 m0, s29, 0x2000
	s_nop 0
	global_load_lds_dwordx4 v[214:215], off
	s_waitcnt vmcnt(10)
	s_barrier
	s_waitcnt lgkmcnt(0)
	v_mfma_f32_16x16x32_f16 v[144:147], v[196:199], v[136:139], v[144:147]
	v_mfma_f32_16x16x32_f16 v[124:127], v[206:209], v[136:139], v[124:127]
	v_mfma_f32_16x16x32_f16 v[120:123], v[196:199], v[148:151], v[120:123]
	v_mfma_f32_16x16x32_f16 v[116:119], v[206:209], v[148:151], v[116:119]
	v_mfma_f32_16x16x32_f16 v[96:99], v[196:199], v[164:167], v[96:99]
	v_mfma_f32_16x16x32_f16 v[92:95], v[206:209], v[164:167], v[92:95]
	v_mfma_f32_16x16x32_f16 v[80:83], v[196:199], v[184:187], v[80:83]
	v_mfma_f32_16x16x32_f16 v[76:79], v[206:209], v[184:187], v[76:79]
	v_mfma_f32_16x16x32_f16 v[144:147], v[200:203], v[140:143], v[144:147]
	v_mfma_f32_16x16x32_f16 v[140:143], v[210:213], v[140:143], v[124:127]
	v_mfma_f32_16x16x32_f16 v[120:123], v[200:203], v[156:159], v[120:123]
	v_mfma_f32_16x16x32_f16 v[116:119], v[210:213], v[156:159], v[116:119]
	v_mfma_f32_16x16x32_f16 v[96:99], v[200:203], v[168:171], v[96:99]
	v_mfma_f32_16x16x32_f16 v[92:95], v[210:213], v[168:171], v[92:95]
	v_mfma_f32_16x16x32_f16 v[80:83], v[200:203], v[192:195], v[80:83]
	v_mfma_f32_16x16x32_f16 v[76:79], v[210:213], v[192:195], v[76:79]
	s_mov_b32 m0, s15
	v_lshl_add_u64 v[214:215], v[218:219], 0, s[88:89]
	s_barrier
	ds_read_b128 v[124:127], v191 offset:49152
	ds_read_b128 v[136:139], v191 offset:50176
	ds_read_b128 v[148:151], v191 offset:51200
	ds_read_b128 v[156:159], v191 offset:52224
	ds_read_b128 v[164:167], v191 offset:53248
	ds_read_b128 v[168:171], v191 offset:54272
	ds_read_b128 v[184:187], v191 offset:55296
	ds_read_b128 v[192:195], v191 offset:56320
	global_load_lds_dwordx4 v[214:215], off
	v_lshl_add_u64 v[214:215], v[220:221], 0, s[88:89]
	s_mov_b32 m0, s30
	s_nop 0
	global_load_lds_dwordx4 v[214:215], off
	s_waitcnt vmcnt(10)
	s_barrier
	s_waitcnt lgkmcnt(0)
	v_mfma_f32_16x16x32_f16 v[72:75], v[60:63], v[124:127], v[72:75]
	v_mfma_f32_16x16x32_f16 v[68:71], v[100:103], v[124:127], v[68:71]
	v_mfma_f32_16x16x32_f16 v[56:59], v[60:63], v[148:151], v[56:59]
	v_mfma_f32_16x16x32_f16 v[52:55], v[100:103], v[148:151], v[52:55]
	v_mfma_f32_16x16x32_f16 v[40:43], v[60:63], v[164:167], v[40:43]
	v_mfma_f32_16x16x32_f16 v[36:39], v[100:103], v[164:167], v[36:39]
	v_mfma_f32_16x16x32_f16 v[16:19], v[60:63], v[184:187], v[16:19]
	v_mfma_f32_16x16x32_f16 v[12:15], v[100:103], v[184:187], v[12:15]
	v_mfma_f32_16x16x32_f16 v[72:75], v[64:67], v[136:139], v[72:75]
	v_mfma_f32_16x16x32_f16 v[68:71], v[112:115], v[136:139], v[68:71]
	v_mfma_f32_16x16x32_f16 v[56:59], v[64:67], v[156:159], v[56:59]
	v_mfma_f32_16x16x32_f16 v[52:55], v[112:115], v[156:159], v[52:55]
	v_mfma_f32_16x16x32_f16 v[40:43], v[64:67], v[168:171], v[40:43]
	v_mfma_f32_16x16x32_f16 v[36:39], v[112:115], v[168:171], v[36:39]
	v_mfma_f32_16x16x32_f16 v[16:19], v[64:67], v[192:195], v[16:19]
	v_mfma_f32_16x16x32_f16 v[12:15], v[112:115], v[192:195], v[12:15]
	s_barrier
	s_add_u32 s38, s38, 0x20080
	s_addc_u32 s39, s39, 0
	s_add_i32 s29, s31, s6
	s_mov_b32 m0, s29
	s_nop 0
	global_load_lds_dwordx4 v176, s[38:39]
	s_add_i32 m0, s29, 0x2000
	s_nop 0
	global_load_lds_dwordx4 v172, s[38:39]
	s_waitcnt vmcnt(10)
	s_barrier
	v_mfma_f32_16x16x32_f16 v[28:31], v[196:199], v[124:127], v[28:31]
	v_mfma_f32_16x16x32_f16 v[64:67], v[200:203], v[136:139], v[28:31]
	v_mfma_f32_16x16x32_f16 v[28:31], v[206:209], v[124:127], v[32:35]
	v_mfma_f32_16x16x32_f16 v[60:63], v[210:213], v[136:139], v[28:31]
	v_mfma_f32_16x16x32_f16 v[28:31], v[196:199], v[148:151], v[48:51]
	v_mfma_f32_16x16x32_f16 v[48:51], v[200:203], v[156:159], v[28:31]
	v_mfma_f32_16x16x32_f16 v[28:31], v[206:209], v[148:151], v[44:47]
	v_mfma_f32_16x16x32_f16 v[24:27], v[196:199], v[164:167], v[24:27]
	v_mfma_f32_16x16x32_f16 v[20:23], v[206:209], v[164:167], v[20:23]
	v_mfma_f32_16x16x32_f16 v[8:11], v[196:199], v[184:187], v[8:11]
	v_mfma_f32_16x16x32_f16 v[4:7], v[206:209], v[184:187], v[4:7]
	v_mfma_f32_16x16x32_f16 v[44:47], v[210:213], v[156:159], v[28:31]
	v_mfma_f32_16x16x32_f16 v[24:27], v[200:203], v[168:171], v[24:27]
	v_mfma_f32_16x16x32_f16 v[20:23], v[210:213], v[168:171], v[20:23]
	v_mfma_f32_16x16x32_f16 v[8:11], v[200:203], v[192:195], v[8:11]
	v_mfma_f32_16x16x32_f16 v[4:7], v[210:213], v[192:195], v[4:7]
	s_add_i32 s19, s19, 2
	s_add_u32 s26, s26, 0x100
	s_addc_u32 s27, s27, 0
	s_add_u32 s11, s11, 0x100
	s_addc_u32 s17, s17, 0
	s_cmp_gt_u32 s19, 5
	s_barrier
	s_cbranch_scc0 .LBB0_1341
	v_mov_b32_e32 v2, v188
	s_lshl_b32 s10, s10, 8
	s_lshl_b32 s26, s16, 4
	v_mov_b32_e32 v28, v189
	s_add_i32 s10, s10, s44
	s_ashr_i32 s27, s26, 31
	v_add_u32_e32 v100, s10, v2
	v_lshlrev_b32_e32 v2, 3, v28
	s_lshl_b64 s[10:11], s[26:27], 2
	v_and_b32_e32 v193, 8, v2
	s_add_u32 s10, s13, s10
	v_add_u32_e32 v186, s45, v2
	s_addc_u32 s11, s14, s11
	v_lshlrev_b32_e32 v2, 2, v193
	s_ashr_i32 s17, s16, 31
	v_lshl_add_u64 v[28:29], s[10:11], 0, v[2:3]
	s_lshl_b64 s[10:11], s[16:17], 10
	v_readlane_b32 s16, v253, 2
	v_readlane_b32 s17, v253, 3
	s_add_u32 s10, s16, s10
	v_ashrrev_i32_e32 v187, 31, v186
	s_addc_u32 s11, s17, s11
	v_ashrrev_i32_e32 v101, 31, v100
	v_lshlrev_b32_e32 v192, 4, v100
	v_lshl_add_u64 v[102:103], v[186:187], 1, s[10:11]
	v_lshlrev_b64 v[100:101], 15, v[100:101]
	v_lshl_add_u64 v[184:185], v[102:103], 0, v[100:101]
	s_mov_b64 s[10:11], 0x80000
	v_lshl_add_u64 v[148:149], v[184:185], 0, s[10:11]
	s_mov_b64 s[10:11], 0x100000
	v_lshl_add_u64 v[124:125], v[184:185], 0, s[10:11]
	s_mov_b64 s[10:11], 0x180000
	v_lshl_add_u64 v[100:101], v[184:185], 0, s[10:11]
	s_mov_b32 s10, 0x180000
	v_add_co_u32_e32 v102, vcc, s10, v184
	s_mov_b32 s10, 0x100000
	s_nop 0
	v_addc_co_u32_e32 v103, vcc, 0, v185, vcc
	flat_load_dwordx4 v[32:35], v[28:29]
	s_nop 0
	flat_load_dwordx4 v[28:31], v[28:29] offset:16
	s_mov_b32 s38, 0x3a800000
	global_load_dwordx4 v[112:115], v[102:103], off
	v_add_co_u32_e32 v102, vcc, s10, v184
	s_mov_b32 s10, 0x80000
	s_nop 0
	v_addc_co_u32_e32 v103, vcc, 0, v185, vcc
	global_load_dwordx4 v[136:139], v[102:103], off
	v_add_co_u32_e32 v102, vcc, s10, v184
	v_readlane_b32 s16, v253, 25
	s_nop 0
	v_addc_co_u32_e32 v103, vcc, 0, v185, vcc
	global_load_dwordx4 v[156:159], v[102:103], off
	global_load_dwordx4 v[164:167], v[184:185], off offset:256
	global_load_dwordx4 v[168:171], v[184:185], off
	s_nop 0
	global_load_dwordx4 v[100:103], v[100:101], off offset:256
	s_nop 0
	global_load_dwordx4 v[124:127], v[124:125], off offset:256
	s_nop 0
	global_load_dwordx4 v[148:151], v[148:149], off offset:256
	v_readlane_b32 s17, v253, 26
	s_lshl_b64 s[42:43], s[26:27], 1
	s_mov_b64 s[10:11], 0x400000
	s_mov_b64 s[26:27], s[34:35]
	s_waitcnt vmcnt(0)
	s_nop 0
	v_cvt_f32_f16_e32 v194, v168
	v_cvt_f32_f16_sdwa v195, v168 dst_sel:DWORD dst_unused:UNUSED_PAD src0_sel:WORD_1
	s_waitcnt lgkmcnt(0)
	v_pk_mul_f32 v[194:195], v[32:33], v[194:195]
	s_nop 0
	v_pk_fma_f32 v[160:161], v[160:161], s[38:39], v[194:195] op_sel_hi:[1,0,1]
	s_nop 0
	v_mul_f32_e32 v2, 0x3d372713, v160
	v_mul_f32_e32 v2, v160, v2
	v_fma_f32 v2, v160, v2, v160
	v_mul_f32_e32 v2, 0x3f4c422a, v2
	v_mul_f32_e32 v2, -2.0, v2
	v_mul_f32_e32 v2, 0x3fb8aa3b, v2
	v_exp_f32_e32 v2, v2
	s_nop 0
	v_add_f32_e32 v2, 1.0, v2
	v_rcp_f32_e32 v194, v2
	v_mul_f32_e32 v2, 0x3d372713, v161
	v_mul_f32_e32 v2, v161, v2
	v_fma_f32 v2, v161, v2, v161
	v_mul_f32_e32 v2, 0x3f4c422a, v2
	v_mul_f32_e32 v2, -2.0, v2
	v_mul_f32_e32 v2, 0x3fb8aa3b, v2
	v_exp_f32_e32 v2, v2
	s_nop 0
	v_add_f32_e32 v2, 1.0, v2
	v_rcp_f32_e32 v195, v2
	s_nop 0
	v_pk_mul_f32 v[160:161], v[160:161], v[194:195]
	s_nop 0
	v_cvt_pk_f16_f32 v2, v160, v161
	v_cvt_f32_f16_e32 v160, v170
	v_cvt_f32_f16_sdwa v161, v170 dst_sel:DWORD dst_unused:UNUSED_PAD src0_sel:WORD_1
	v_pk_mul_f32 v[160:161], v[28:29], v[160:161]
	s_nop 0
	v_pk_fma_f32 v[152:153], v[152:153], s[38:39], v[160:161] op_sel_hi:[1,0,1]
	s_nop 0
	v_mul_f32_e32 v160, 0x3d372713, v152
	v_mul_f32_e32 v161, 0x3d372713, v153
	v_mul_f32_e32 v160, v152, v160
	v_mul_f32_e32 v161, v153, v161
	v_fma_f32 v160, v152, v160, v152
	v_fma_f32 v161, v153, v161, v153
	v_mul_f32_e32 v160, 0x3f4c422a, v160
	v_mul_f32_e32 v161, 0x3f4c422a, v161
	v_mul_f32_e32 v160, -2.0, v160
	v_mul_f32_e32 v161, -2.0, v161
	v_mul_f32_e32 v160, 0x3fb8aa3b, v160
	v_mul_f32_e32 v161, 0x3fb8aa3b, v161
	v_exp_f32_e32 v160, v160
	v_exp_f32_e32 v161, v161
	v_add_f32_e32 v160, 1.0, v160
	v_add_f32_e32 v161, 1.0, v161
	v_rcp_f32_e32 v160, v160
	v_rcp_f32_e32 v161, v161
	s_nop 0
	v_pk_mul_f32 v[152:153], v[152:153], v[160:161]
	s_nop 0
	v_cvt_pk_f16_f32 v168, v152, v153
	v_cvt_f32_f16_e32 v152, v169
	v_cvt_f32_f16_sdwa v153, v169 dst_sel:DWORD dst_unused:UNUSED_PAD src0_sel:WORD_1
	v_pk_mul_f32 v[152:153], v[34:35], v[152:153]
	s_nop 0
	v_pk_fma_f32 v[152:153], v[162:163], s[38:39], v[152:153] op_sel_hi:[1,0,1]
	s_nop 0
	v_mul_f32_e32 v160, 0x3d372713, v152
	v_mul_f32_e32 v161, 0x3d372713, v153
	v_mul_f32_e32 v160, v152, v160
	v_mul_f32_e32 v161, v153, v161
	v_fma_f32 v160, v152, v160, v152
	v_fma_f32 v161, v153, v161, v153
	v_mul_f32_e32 v160, 0x3f4c422a, v160
	v_mul_f32_e32 v161, 0x3f4c422a, v161
	v_mul_f32_e32 v160, -2.0, v160
	v_mul_f32_e32 v161, -2.0, v161
	v_mul_f32_e32 v160, 0x3fb8aa3b, v160
	v_mul_f32_e32 v161, 0x3fb8aa3b, v161
	v_exp_f32_e32 v160, v160
	v_exp_f32_e32 v161, v161
	v_add_f32_e32 v160, 1.0, v160
	v_add_f32_e32 v161, 1.0, v161
	v_rcp_f32_e32 v160, v160
	v_rcp_f32_e32 v161, v161
	s_nop 0
	v_pk_mul_f32 v[152:153], v[152:153], v[160:161]
	s_nop 0
	v_cvt_pk_f16_f32 v161, v152, v153
	v_cvt_f32_f16_e32 v152, v171
	v_cvt_f32_f16_sdwa v153, v171 dst_sel:DWORD dst_unused:UNUSED_PAD src0_sel:WORD_1
	v_pk_mul_f32 v[152:153], v[30:31], v[152:153]
	s_nop 0
	v_pk_fma_f32 v[152:153], v[154:155], s[38:39], v[152:153] op_sel_hi:[1,0,1]
	s_nop 0
	v_mul_f32_e32 v154, 0x3d372713, v152
	v_mul_f32_e32 v155, 0x3d372713, v153
	v_mul_f32_e32 v154, v152, v154
	v_mul_f32_e32 v155, v153, v155
	v_fma_f32 v154, v152, v154, v152
	v_fma_f32 v155, v153, v155, v153
	v_mul_f32_e32 v154, 0x3f4c422a, v154
	v_mul_f32_e32 v155, 0x3f4c422a, v155
	v_mul_f32_e32 v154, -2.0, v154
	v_mul_f32_e32 v155, -2.0, v155
	v_mul_f32_e32 v154, 0x3fb8aa3b, v154
	v_mul_f32_e32 v155, 0x3fb8aa3b, v155
	v_exp_f32_e32 v154, v154
	v_exp_f32_e32 v155, v155
	v_add_f32_e32 v154, 1.0, v154
	v_add_f32_e32 v155, 1.0, v155
	v_rcp_f32_e32 v154, v154
	v_rcp_f32_e32 v155, v155
	s_nop 0
	v_pk_mul_f32 v[152:153], v[152:153], v[154:155]
	v_lshrrev_b32_e32 v154, 4, v2
	v_and_b32_e32 v154, 0x10001, v154
	v_add3_u32 v2, v2, v154, s21
	v_and_b32_e32 v160, 0xfff0fff0, v2
	v_lshrrev_b32_e32 v2, 4, v161
	v_and_b32_e32 v2, 0x10001, v2
	v_add3_u32 v2, v161, v2, s21
	v_and_b32_e32 v161, 0xfff0fff0, v2
	v_lshrrev_b32_e32 v2, 4, v168
	v_cvt_pk_f16_f32 v153, v152, v153
	v_ashrrev_i32_e32 v152, 4, v186
	v_and_b32_e32 v2, 0x10001, v2
	v_add3_u32 v2, v168, v2, s21
	v_add_u32_e32 v154, v152, v192
	v_and_b32_e32 v162, 0xfff0fff0, v2
	v_lshrrev_b32_e32 v2, 4, v153
	v_ashrrev_i32_e32 v155, 31, v154
	v_and_b32_e32 v2, 0x10001, v2
	v_lshlrev_b64 v[154:155], 10, v[154:155]
	v_add3_u32 v2, v153, v2, s21
	v_lshl_add_u64 v[154:155], s[16:17], 0, v[154:155]
	v_and_b32_e32 v163, 0xfff0fff0, v2
	v_lshl_add_u64 v[154:155], v[154:155], 0, s[42:43]
	v_lshlrev_b32_e32 v2, 1, v193
	v_lshl_add_u64 v[154:155], v[154:155], 0, v[2:3]
	global_store_dwordx4 v[154:155], v[160:163], off
	v_cvt_f32_f16_e32 v154, v164
	v_cvt_f32_f16_sdwa v155, v164 dst_sel:DWORD dst_unused:UNUSED_PAD src0_sel:WORD_1
	v_add_u32_e32 v153, 0x80, v186
	v_pk_mul_f32 v[154:155], v[32:33], v[154:155]
	s_nop 0
	v_pk_fma_f32 v[144:145], v[144:145], s[38:39], v[154:155] op_sel_hi:[1,0,1]
	s_nop 0
	v_mul_f32_e32 v154, 0x3d372713, v144
	v_mul_f32_e32 v155, 0x3d372713, v145
	v_mul_f32_e32 v154, v144, v154
	v_mul_f32_e32 v155, v145, v155
	v_fma_f32 v154, v144, v154, v144
	v_fma_f32 v155, v145, v155, v145
	v_mul_f32_e32 v154, 0x3f4c422a, v154
	v_mul_f32_e32 v155, 0x3f4c422a, v155
	v_mul_f32_e32 v154, -2.0, v154
	v_mul_f32_e32 v155, -2.0, v155
	v_mul_f32_e32 v154, 0x3fb8aa3b, v154
	v_mul_f32_e32 v155, 0x3fb8aa3b, v155
	v_exp_f32_e32 v154, v154
	v_exp_f32_e32 v155, v155
	v_add_f32_e32 v154, 1.0, v154
	v_add_f32_e32 v155, 1.0, v155
	v_rcp_f32_e32 v154, v154
	v_rcp_f32_e32 v155, v155
	s_nop 0
	v_pk_mul_f32 v[144:145], v[144:145], v[154:155]
	s_nop 0
	v_cvt_pk_f16_f32 v154, v144, v145
	v_cvt_f32_f16_e32 v144, v166
	v_cvt_f32_f16_sdwa v145, v166 dst_sel:DWORD dst_unused:UNUSED_PAD src0_sel:WORD_1
	v_pk_mul_f32 v[144:145], v[28:29], v[144:145]
	s_nop 0
	v_pk_fma_f32 v[140:141], v[140:141], s[38:39], v[144:145] op_sel_hi:[1,0,1]
	s_nop 0
	v_mul_f32_e32 v144, 0x3d372713, v140
	v_mul_f32_e32 v145, 0x3d372713, v141
	v_mul_f32_e32 v144, v140, v144
	v_mul_f32_e32 v145, v141, v145
	v_fma_f32 v144, v140, v144, v140
	v_fma_f32 v145, v141, v145, v141
	v_mul_f32_e32 v144, 0x3f4c422a, v144
	v_mul_f32_e32 v145, 0x3f4c422a, v145
	v_mul_f32_e32 v144, -2.0, v144
	v_mul_f32_e32 v145, -2.0, v145
	v_mul_f32_e32 v144, 0x3fb8aa3b, v144
	v_mul_f32_e32 v145, 0x3fb8aa3b, v145
	v_exp_f32_e32 v144, v144
	v_exp_f32_e32 v145, v145
	v_add_f32_e32 v144, 1.0, v144
	v_add_f32_e32 v145, 1.0, v145
	v_rcp_f32_e32 v144, v144
	v_rcp_f32_e32 v145, v145
	s_nop 0
	v_pk_mul_f32 v[140:141], v[140:141], v[144:145]
	s_nop 0
	v_cvt_pk_f16_f32 v155, v140, v141
	v_cvt_f32_f16_e32 v140, v165
	v_cvt_f32_f16_sdwa v141, v165 dst_sel:DWORD dst_unused:UNUSED_PAD src0_sel:WORD_1
	v_pk_mul_f32 v[140:141], v[34:35], v[140:141]
	s_nop 0
	v_pk_fma_f32 v[140:141], v[146:147], s[38:39], v[140:141] op_sel_hi:[1,0,1]
	s_nop 0
	v_mul_f32_e32 v144, 0x3d372713, v140
	v_mul_f32_e32 v145, 0x3d372713, v141
	v_mul_f32_e32 v144, v140, v144
	v_mul_f32_e32 v145, v141, v145
	v_fma_f32 v144, v140, v144, v140
	v_fma_f32 v145, v141, v145, v141
	v_mul_f32_e32 v144, 0x3f4c422a, v144
	v_mul_f32_e32 v145, 0x3f4c422a, v145
	v_mul_f32_e32 v144, -2.0, v144
	v_mul_f32_e32 v145, -2.0, v145
	v_mul_f32_e32 v144, 0x3fb8aa3b, v144
	v_mul_f32_e32 v145, 0x3fb8aa3b, v145
	v_exp_f32_e32 v144, v144
	v_exp_f32_e32 v145, v145
	v_add_f32_e32 v144, 1.0, v144
	v_add_f32_e32 v145, 1.0, v145
	v_rcp_f32_e32 v144, v144
	v_rcp_f32_e32 v145, v145
	s_nop 0
	v_pk_mul_f32 v[140:141], v[140:141], v[144:145]
	s_nop 0
	v_cvt_pk_f16_f32 v144, v140, v141
	v_cvt_f32_f16_e32 v140, v167
	v_cvt_f32_f16_sdwa v141, v167 dst_sel:DWORD dst_unused:UNUSED_PAD src0_sel:WORD_1
	v_pk_mul_f32 v[140:141], v[30:31], v[140:141]
	s_nop 0
	v_pk_fma_f32 v[140:141], v[142:143], s[38:39], v[140:141] op_sel_hi:[1,0,1]
	s_nop 0
	v_mul_f32_e32 v142, 0x3d372713, v140
	v_mul_f32_e32 v143, 0x3d372713, v141
	v_mul_f32_e32 v142, v140, v142
	v_mul_f32_e32 v143, v141, v143
	v_fma_f32 v142, v140, v142, v140
	v_fma_f32 v143, v141, v143, v141
	v_mul_f32_e32 v142, 0x3f4c422a, v142
	v_mul_f32_e32 v143, 0x3f4c422a, v143
	v_mul_f32_e32 v142, -2.0, v142
	v_mul_f32_e32 v143, -2.0, v143
	v_mul_f32_e32 v142, 0x3fb8aa3b, v142
	v_mul_f32_e32 v143, 0x3fb8aa3b, v143
	v_exp_f32_e32 v142, v142
	v_exp_f32_e32 v143, v143
	v_add_f32_e32 v142, 1.0, v142
	v_add_f32_e32 v143, 1.0, v143
	v_rcp_f32_e32 v142, v142
	v_rcp_f32_e32 v143, v143
	s_nop 0
	v_pk_mul_f32 v[140:141], v[140:141], v[142:143]
	s_nop 0
	v_cvt_pk_f16_f32 v141, v140, v141
	v_ashrrev_i32_e32 v140, 4, v153
	v_lshrrev_b32_e32 v143, 4, v144
	v_add_u32_e32 v146, v140, v192
	v_and_b32_e32 v143, 0x10001, v143
	v_ashrrev_i32_e32 v147, 31, v146
	v_lshrrev_b32_e32 v142, 4, v154
	v_add3_u32 v143, v144, v143, s21
	v_lshrrev_b32_e32 v144, 4, v155
	v_lshrrev_b32_e32 v145, 4, v141
	v_lshlrev_b64 v[146:147], 10, v[146:147]
	v_and_b32_e32 v142, 0x10001, v142
	v_and_b32_e32 v144, 0x10001, v144
	v_and_b32_e32 v145, 0x10001, v145
	v_lshl_add_u64 v[146:147], s[16:17], 0, v[146:147]
	v_add3_u32 v142, v154, v142, s21
	v_add3_u32 v144, v155, v144, s21
	v_add3_u32 v141, v141, v145, s21
	v_lshl_add_u64 v[146:147], v[146:147], 0, s[42:43]
	v_and_b32_e32 v142, 0xfff0fff0, v142
	v_and_b32_e32 v143, 0xfff0fff0, v143
	v_and_b32_e32 v144, 0xfff0fff0, v144
	v_and_b32_e32 v145, 0xfff0fff0, v141
	v_lshl_add_u64 v[146:147], v[146:147], 0, v[2:3]
	global_store_dwordx4 v[146:147], v[142:145], off
	v_add_u32_e32 v141, 0x100, v192
	s_nop 0
	v_cvt_f32_f16_e32 v142, v156
	v_cvt_f32_f16_sdwa v143, v156 dst_sel:DWORD dst_unused:UNUSED_PAD src0_sel:WORD_1
	v_pk_mul_f32 v[142:143], v[32:33], v[142:143]
	s_nop 0
	v_pk_fma_f32 v[132:133], v[132:133], s[38:39], v[142:143] op_sel_hi:[1,0,1]
	s_nop 0
	v_mul_f32_e32 v142, 0x3d372713, v132
	v_mul_f32_e32 v143, 0x3d372713, v133
	v_mul_f32_e32 v142, v132, v142
	v_mul_f32_e32 v143, v133, v143
	v_fma_f32 v142, v132, v142, v132
	v_fma_f32 v143, v133, v143, v133
	v_mul_f32_e32 v142, 0x3f4c422a, v142
	v_mul_f32_e32 v143, 0x3f4c422a, v143
	v_mul_f32_e32 v142, -2.0, v142
	v_mul_f32_e32 v143, -2.0, v143
	v_mul_f32_e32 v142, 0x3fb8aa3b, v142
	v_mul_f32_e32 v143, 0x3fb8aa3b, v143
	v_exp_f32_e32 v142, v142
	v_exp_f32_e32 v143, v143
	v_add_f32_e32 v142, 1.0, v142
	v_add_f32_e32 v143, 1.0, v143
	v_rcp_f32_e32 v142, v142
	v_rcp_f32_e32 v143, v143
	s_nop 0
	v_pk_mul_f32 v[132:133], v[132:133], v[142:143]
	s_nop 0
	v_cvt_pk_f16_f32 v142, v132, v133
	v_cvt_f32_f16_e32 v132, v158
	v_cvt_f32_f16_sdwa v133, v158 dst_sel:DWORD dst_unused:UNUSED_PAD src0_sel:WORD_1
	v_pk_mul_f32 v[132:133], v[28:29], v[132:133]
	s_nop 0
	v_pk_fma_f32 v[128:129], v[128:129], s[38:39], v[132:133] op_sel_hi:[1,0,1]
	s_nop 0
	v_mul_f32_e32 v132, 0x3d372713, v128
	v_mul_f32_e32 v133, 0x3d372713, v129
	v_mul_f32_e32 v132, v128, v132
	v_mul_f32_e32 v133, v129, v133
	v_fma_f32 v132, v128, v132, v128
	v_fma_f32 v133, v129, v133, v129
	v_mul_f32_e32 v132, 0x3f4c422a, v132
	v_mul_f32_e32 v133, 0x3f4c422a, v133
	v_mul_f32_e32 v132, -2.0, v132
	v_mul_f32_e32 v133, -2.0, v133
	v_mul_f32_e32 v132, 0x3fb8aa3b, v132
	v_mul_f32_e32 v133, 0x3fb8aa3b, v133
	v_exp_f32_e32 v132, v132
	v_exp_f32_e32 v133, v133
	v_add_f32_e32 v132, 1.0, v132
	v_add_f32_e32 v133, 1.0, v133
	v_rcp_f32_e32 v132, v132
	v_rcp_f32_e32 v133, v133
	s_nop 0
	v_pk_mul_f32 v[128:129], v[128:129], v[132:133]
	s_nop 0
	v_cvt_pk_f16_f32 v143, v128, v129
	v_cvt_f32_f16_e32 v128, v157
	v_cvt_f32_f16_sdwa v129, v157 dst_sel:DWORD dst_unused:UNUSED_PAD src0_sel:WORD_1
	v_pk_mul_f32 v[128:129], v[34:35], v[128:129]
	s_nop 0
	v_pk_fma_f32 v[128:129], v[134:135], s[38:39], v[128:129] op_sel_hi:[1,0,1]
	s_nop 0
	v_mul_f32_e32 v132, 0x3d372713, v128
	v_mul_f32_e32 v133, 0x3d372713, v129
	v_mul_f32_e32 v132, v128, v132
	v_mul_f32_e32 v133, v129, v133
	v_fma_f32 v132, v128, v132, v128
	v_fma_f32 v133, v129, v133, v129
	v_mul_f32_e32 v132, 0x3f4c422a, v132
	v_mul_f32_e32 v133, 0x3f4c422a, v133
	v_mul_f32_e32 v132, -2.0, v132
	v_mul_f32_e32 v133, -2.0, v133
	v_mul_f32_e32 v132, 0x3fb8aa3b, v132
	v_mul_f32_e32 v133, 0x3fb8aa3b, v133
	v_exp_f32_e32 v132, v132
	v_exp_f32_e32 v133, v133
	v_add_f32_e32 v132, 1.0, v132
	v_add_f32_e32 v133, 1.0, v133
	v_rcp_f32_e32 v132, v132
	v_rcp_f32_e32 v133, v133
	s_nop 0
	v_pk_mul_f32 v[128:129], v[128:129], v[132:133]
	s_nop 0
	v_cvt_pk_f16_f32 v132, v128, v129
	v_cvt_f32_f16_e32 v128, v159
	v_cvt_f32_f16_sdwa v129, v159 dst_sel:DWORD dst_unused:UNUSED_PAD src0_sel:WORD_1
	v_pk_mul_f32 v[128:129], v[30:31], v[128:129]
	s_nop 0
	v_pk_fma_f32 v[128:129], v[130:131], s[38:39], v[128:129] op_sel_hi:[1,0,1]
	s_nop 0
	v_mul_f32_e32 v130, 0x3d372713, v128
	v_mul_f32_e32 v131, 0x3d372713, v129
	v_mul_f32_e32 v130, v128, v130
	v_mul_f32_e32 v131, v129, v131
	v_fma_f32 v130, v128, v130, v128
	v_fma_f32 v131, v129, v131, v129
	v_mul_f32_e32 v130, 0x3f4c422a, v130
	v_mul_f32_e32 v131, 0x3f4c422a, v131
	v_mul_f32_e32 v130, -2.0, v130
	v_mul_f32_e32 v131, -2.0, v131
	v_mul_f32_e32 v130, 0x3fb8aa3b, v130
	v_mul_f32_e32 v131, 0x3fb8aa3b, v131
	v_exp_f32_e32 v130, v130
	v_exp_f32_e32 v131, v131
	v_add_f32_e32 v130, 1.0, v130
	v_add_f32_e32 v131, 1.0, v131
	v_rcp_f32_e32 v130, v130
	v_rcp_f32_e32 v131, v131
	s_nop 0
	v_pk_mul_f32 v[128:129], v[128:129], v[130:131]
	s_nop 0
	v_cvt_pk_f16_f32 v131, v128, v129
	v_lshrrev_b32_e32 v129, 4, v132
	v_and_b32_e32 v129, 0x10001, v129
	v_add3_u32 v129, v132, v129, s21
	v_lshrrev_b32_e32 v132, 4, v131
	v_and_b32_e32 v132, 0x10001, v132
	v_add3_u32 v131, v131, v132, s21
	v_add_u32_e32 v132, v152, v141
	v_ashrrev_i32_e32 v133, 31, v132
	v_lshrrev_b32_e32 v128, 4, v142
	v_lshrrev_b32_e32 v130, 4, v143
	v_lshlrev_b64 v[132:133], 10, v[132:133]
	v_and_b32_e32 v128, 0x10001, v128
	v_and_b32_e32 v130, 0x10001, v130
	v_lshl_add_u64 v[132:133], s[16:17], 0, v[132:133]
	v_add3_u32 v128, v142, v128, s21
	v_add3_u32 v130, v143, v130, s21
	v_lshl_add_u64 v[132:133], v[132:133], 0, s[42:43]
	v_and_b32_e32 v128, 0xfff0fff0, v128
	v_and_b32_e32 v129, 0xfff0fff0, v129
	v_and_b32_e32 v130, 0xfff0fff0, v130
	v_and_b32_e32 v131, 0xfff0fff0, v131
	v_lshl_add_u64 v[132:133], v[132:133], 0, v[2:3]
	global_store_dwordx4 v[132:133], v[128:131], off
	s_nop 1
	v_cvt_f32_f16_e32 v128, v148
	v_cvt_f32_f16_sdwa v129, v148 dst_sel:DWORD dst_unused:UNUSED_PAD src0_sel:WORD_1
	v_pk_mul_f32 v[128:129], v[32:33], v[128:129]
	s_nop 0
	v_pk_fma_f32 v[120:121], v[120:121], s[38:39], v[128:129] op_sel_hi:[1,0,1]
	s_nop 0
	v_mul_f32_e32 v128, 0x3d372713, v120
	v_mul_f32_e32 v129, 0x3d372713, v121
	v_mul_f32_e32 v128, v120, v128
	v_mul_f32_e32 v129, v121, v129
	v_fma_f32 v128, v120, v128, v120
	v_fma_f32 v129, v121, v129, v121
	v_mul_f32_e32 v128, 0x3f4c422a, v128
	v_mul_f32_e32 v129, 0x3f4c422a, v129
	v_mul_f32_e32 v128, -2.0, v128
	v_mul_f32_e32 v129, -2.0, v129
	v_mul_f32_e32 v128, 0x3fb8aa3b, v128
	v_mul_f32_e32 v129, 0x3fb8aa3b, v129
	v_exp_f32_e32 v128, v128
	v_exp_f32_e32 v129, v129
	v_add_f32_e32 v128, 1.0, v128
	v_add_f32_e32 v129, 1.0, v129
	v_rcp_f32_e32 v128, v128
	v_rcp_f32_e32 v129, v129
	s_nop 0
	v_pk_mul_f32 v[120:121], v[120:121], v[128:129]
	s_nop 0
	v_cvt_pk_f16_f32 v128, v120, v121
	v_cvt_f32_f16_e32 v120, v150
	v_cvt_f32_f16_sdwa v121, v150 dst_sel:DWORD dst_unused:UNUSED_PAD src0_sel:WORD_1
	v_pk_mul_f32 v[120:121], v[28:29], v[120:121]
	s_nop 0
	v_pk_fma_f32 v[116:117], v[116:117], s[38:39], v[120:121] op_sel_hi:[1,0,1]
	s_nop 0
	v_mul_f32_e32 v120, 0x3d372713, v116
	v_mul_f32_e32 v121, 0x3d372713, v117
	v_mul_f32_e32 v120, v116, v120
	v_mul_f32_e32 v121, v117, v121
	v_fma_f32 v120, v116, v120, v116
	v_fma_f32 v121, v117, v121, v117
	v_mul_f32_e32 v120, 0x3f4c422a, v120
	v_mul_f32_e32 v121, 0x3f4c422a, v121
	v_mul_f32_e32 v120, -2.0, v120
	v_mul_f32_e32 v121, -2.0, v121
	v_mul_f32_e32 v120, 0x3fb8aa3b, v120
	v_mul_f32_e32 v121, 0x3fb8aa3b, v121
	v_exp_f32_e32 v120, v120
	v_exp_f32_e32 v121, v121
	v_add_f32_e32 v120, 1.0, v120
	v_add_f32_e32 v121, 1.0, v121
	v_rcp_f32_e32 v120, v120
	v_rcp_f32_e32 v121, v121
	s_nop 0
	v_pk_mul_f32 v[116:117], v[116:117], v[120:121]
	s_nop 0
	v_cvt_pk_f16_f32 v129, v116, v117
	v_cvt_f32_f16_e32 v116, v149
	v_cvt_f32_f16_sdwa v117, v149 dst_sel:DWORD dst_unused:UNUSED_PAD src0_sel:WORD_1
	v_pk_mul_f32 v[116:117], v[34:35], v[116:117]
	s_nop 0
	v_pk_fma_f32 v[116:117], v[122:123], s[38:39], v[116:117] op_sel_hi:[1,0,1]
	s_nop 0
	v_mul_f32_e32 v120, 0x3d372713, v116
	v_mul_f32_e32 v121, 0x3d372713, v117
	v_mul_f32_e32 v120, v116, v120
	v_mul_f32_e32 v121, v117, v121
	v_fma_f32 v120, v116, v120, v116
	v_fma_f32 v121, v117, v121, v117
	v_mul_f32_e32 v120, 0x3f4c422a, v120
	v_mul_f32_e32 v121, 0x3f4c422a, v121
	v_mul_f32_e32 v120, -2.0, v120
	v_mul_f32_e32 v121, -2.0, v121
	v_mul_f32_e32 v120, 0x3fb8aa3b, v120
	v_mul_f32_e32 v121, 0x3fb8aa3b, v121
	v_exp_f32_e32 v120, v120
	v_exp_f32_e32 v121, v121
	v_add_f32_e32 v120, 1.0, v120
	v_add_f32_e32 v121, 1.0, v121
	v_rcp_f32_e32 v120, v120
	v_rcp_f32_e32 v121, v121
	s_nop 0
	v_pk_mul_f32 v[116:117], v[116:117], v[120:121]
	s_nop 0
	v_cvt_pk_f16_f32 v120, v116, v117
	v_cvt_f32_f16_e32 v116, v151
	v_cvt_f32_f16_sdwa v117, v151 dst_sel:DWORD dst_unused:UNUSED_PAD src0_sel:WORD_1
	v_pk_mul_f32 v[116:117], v[30:31], v[116:117]
	s_nop 0
	v_pk_fma_f32 v[116:117], v[118:119], s[38:39], v[116:117] op_sel_hi:[1,0,1]
	s_nop 0
	v_mul_f32_e32 v118, 0x3d372713, v116
	v_mul_f32_e32 v119, 0x3d372713, v117
	v_mul_f32_e32 v118, v116, v118
	v_mul_f32_e32 v119, v117, v119
	v_fma_f32 v118, v116, v118, v116
	v_fma_f32 v119, v117, v119, v117
	v_mul_f32_e32 v118, 0x3f4c422a, v118
	v_mul_f32_e32 v119, 0x3f4c422a, v119
	v_mul_f32_e32 v118, -2.0, v118
	v_mul_f32_e32 v119, -2.0, v119
	v_mul_f32_e32 v118, 0x3fb8aa3b, v118
	v_mul_f32_e32 v119, 0x3fb8aa3b, v119
	v_exp_f32_e32 v118, v118
	v_exp_f32_e32 v119, v119
	v_add_f32_e32 v118, 1.0, v118
	v_add_f32_e32 v119, 1.0, v119
	v_rcp_f32_e32 v118, v118
	v_rcp_f32_e32 v119, v119
	s_nop 0
	v_pk_mul_f32 v[116:117], v[116:117], v[118:119]
	s_nop 0
	v_cvt_pk_f16_f32 v119, v116, v117
	v_lshrrev_b32_e32 v117, 4, v120
	v_and_b32_e32 v117, 0x10001, v117
	v_add3_u32 v117, v120, v117, s21
	v_lshrrev_b32_e32 v120, 4, v119
	v_and_b32_e32 v120, 0x10001, v120
	v_add3_u32 v119, v119, v120, s21
	v_add_u32_e32 v120, v140, v141
	v_ashrrev_i32_e32 v121, 31, v120
	v_lshrrev_b32_e32 v116, 4, v128
	v_lshrrev_b32_e32 v118, 4, v129
	v_lshlrev_b64 v[120:121], 10, v[120:121]
	v_and_b32_e32 v116, 0x10001, v116
	v_and_b32_e32 v118, 0x10001, v118
	v_lshl_add_u64 v[120:121], s[16:17], 0, v[120:121]
	v_add3_u32 v116, v128, v116, s21
	v_add3_u32 v118, v129, v118, s21
	v_lshl_add_u64 v[120:121], v[120:121], 0, s[42:43]
	v_and_b32_e32 v116, 0xfff0fff0, v116
	v_and_b32_e32 v117, 0xfff0fff0, v117
	v_and_b32_e32 v118, 0xfff0fff0, v118
	v_and_b32_e32 v119, 0xfff0fff0, v119
	v_lshl_add_u64 v[120:121], v[120:121], 0, v[2:3]
	global_store_dwordx4 v[120:121], v[116:119], off
	s_nop 1
	v_cvt_f32_f16_e32 v118, v136
	v_cvt_f32_f16_sdwa v119, v136 dst_sel:DWORD dst_unused:UNUSED_PAD src0_sel:WORD_1
	v_add_u32_e32 v116, 0x200, v192
	v_pk_mul_f32 v[118:119], v[32:33], v[118:119]
	s_nop 0
	v_pk_fma_f32 v[108:109], v[108:109], s[38:39], v[118:119] op_sel_hi:[1,0,1]
	s_nop 0
	v_mul_f32_e32 v117, 0x3d372713, v108
	v_mul_f32_e32 v117, v108, v117
	v_fma_f32 v117, v108, v117, v108
	v_mul_f32_e32 v117, 0x3f4c422a, v117
	v_mul_f32_e32 v117, -2.0, v117
	v_mul_f32_e32 v117, 0x3fb8aa3b, v117
	v_exp_f32_e32 v117, v117
	s_nop 0
	v_add_f32_e32 v117, 1.0, v117
	v_rcp_f32_e32 v118, v117
	v_mul_f32_e32 v117, 0x3d372713, v109
	v_mul_f32_e32 v117, v109, v117
	v_fma_f32 v117, v109, v117, v109
	v_mul_f32_e32 v117, 0x3f4c422a, v117
	v_mul_f32_e32 v117, -2.0, v117
	v_mul_f32_e32 v117, 0x3fb8aa3b, v117
	v_exp_f32_e32 v117, v117
	s_nop 0
	v_add_f32_e32 v117, 1.0, v117
	v_rcp_f32_e32 v119, v117
	s_nop 0
	v_pk_mul_f32 v[108:109], v[108:109], v[118:119]
	s_nop 0
	v_cvt_pk_f16_f32 v117, v108, v109
	v_cvt_f32_f16_e32 v108, v138
	v_cvt_f32_f16_sdwa v109, v138 dst_sel:DWORD dst_unused:UNUSED_PAD src0_sel:WORD_1
	v_pk_mul_f32 v[108:109], v[28:29], v[108:109]
	s_nop 0
	v_pk_fma_f32 v[104:105], v[104:105], s[38:39], v[108:109] op_sel_hi:[1,0,1]
	s_nop 0
	v_mul_f32_e32 v108, 0x3d372713, v104
	v_mul_f32_e32 v109, 0x3d372713, v105
	v_mul_f32_e32 v108, v104, v108
	v_mul_f32_e32 v109, v105, v109
	v_fma_f32 v108, v104, v108, v104
	v_fma_f32 v109, v105, v109, v105
	v_mul_f32_e32 v108, 0x3f4c422a, v108
	v_mul_f32_e32 v109, 0x3f4c422a, v109
	v_mul_f32_e32 v108, -2.0, v108
	v_mul_f32_e32 v109, -2.0, v109
	v_mul_f32_e32 v108, 0x3fb8aa3b, v108
	v_mul_f32_e32 v109, 0x3fb8aa3b, v109
	v_exp_f32_e32 v108, v108
	v_exp_f32_e32 v109, v109
	v_add_f32_e32 v108, 1.0, v108
	v_add_f32_e32 v109, 1.0, v109
	v_rcp_f32_e32 v108, v108
	v_rcp_f32_e32 v109, v109
	s_nop 0
	v_pk_mul_f32 v[104:105], v[104:105], v[108:109]
	s_nop 0
	v_cvt_pk_f16_f32 v118, v104, v105
	v_cvt_f32_f16_e32 v104, v137
	v_cvt_f32_f16_sdwa v105, v137 dst_sel:DWORD dst_unused:UNUSED_PAD src0_sel:WORD_1
	v_pk_mul_f32 v[104:105], v[34:35], v[104:105]
	s_nop 0
	v_pk_fma_f32 v[104:105], v[110:111], s[38:39], v[104:105] op_sel_hi:[1,0,1]
	s_nop 0
	v_mul_f32_e32 v108, 0x3d372713, v104
	v_mul_f32_e32 v109, 0x3d372713, v105
	v_mul_f32_e32 v108, v104, v108
	v_mul_f32_e32 v109, v105, v109
	v_fma_f32 v108, v104, v108, v104
	v_fma_f32 v109, v105, v109, v105
	v_mul_f32_e32 v108, 0x3f4c422a, v108
	v_mul_f32_e32 v109, 0x3f4c422a, v109
	v_mul_f32_e32 v108, -2.0, v108
	v_mul_f32_e32 v109, -2.0, v109
	v_mul_f32_e32 v108, 0x3fb8aa3b, v108
	v_mul_f32_e32 v109, 0x3fb8aa3b, v109
	v_exp_f32_e32 v108, v108
	v_exp_f32_e32 v109, v109
	v_add_f32_e32 v108, 1.0, v108
	v_add_f32_e32 v109, 1.0, v109
	v_rcp_f32_e32 v108, v108
	v_rcp_f32_e32 v109, v109
	s_nop 0
	v_pk_mul_f32 v[104:105], v[104:105], v[108:109]
	s_nop 0
	v_cvt_pk_f16_f32 v108, v104, v105
	v_cvt_f32_f16_e32 v104, v139
	v_cvt_f32_f16_sdwa v105, v139 dst_sel:DWORD dst_unused:UNUSED_PAD src0_sel:WORD_1
	v_pk_mul_f32 v[104:105], v[30:31], v[104:105]
	s_nop 0
	v_pk_fma_f32 v[104:105], v[106:107], s[38:39], v[104:105] op_sel_hi:[1,0,1]
	s_nop 0
	v_mul_f32_e32 v106, 0x3d372713, v104
	v_mul_f32_e32 v107, 0x3d372713, v105
	v_mul_f32_e32 v106, v104, v106
	v_mul_f32_e32 v107, v105, v107
	v_fma_f32 v106, v104, v106, v104
	v_fma_f32 v107, v105, v107, v105
	v_mul_f32_e32 v106, 0x3f4c422a, v106
	v_mul_f32_e32 v107, 0x3f4c422a, v107
	v_mul_f32_e32 v106, -2.0, v106
	v_mul_f32_e32 v107, -2.0, v107
	v_mul_f32_e32 v106, 0x3fb8aa3b, v106
	v_mul_f32_e32 v107, 0x3fb8aa3b, v107
	v_exp_f32_e32 v106, v106
	v_exp_f32_e32 v107, v107
	v_add_f32_e32 v106, 1.0, v106
	v_add_f32_e32 v107, 1.0, v107
	v_rcp_f32_e32 v106, v106
	v_rcp_f32_e32 v107, v107
	s_nop 0
	v_pk_mul_f32 v[104:105], v[104:105], v[106:107]
	s_nop 0
	v_cvt_pk_f16_f32 v107, v104, v105
	v_lshrrev_b32_e32 v105, 4, v108
	v_and_b32_e32 v105, 0x10001, v105
	v_add3_u32 v105, v108, v105, s21
	v_lshrrev_b32_e32 v108, 4, v107
	v_and_b32_e32 v108, 0x10001, v108
	v_add3_u32 v107, v107, v108, s21
	v_add_u32_e32 v108, v152, v116
	v_ashrrev_i32_e32 v109, 31, v108
	v_lshrrev_b32_e32 v104, 4, v117
	v_lshrrev_b32_e32 v106, 4, v118
	v_lshlrev_b64 v[108:109], 10, v[108:109]
	v_and_b32_e32 v104, 0x10001, v104
	v_and_b32_e32 v106, 0x10001, v106
	v_lshl_add_u64 v[108:109], s[16:17], 0, v[108:109]
	v_add3_u32 v104, v117, v104, s21
	v_add3_u32 v106, v118, v106, s21
	v_lshl_add_u64 v[108:109], v[108:109], 0, s[42:43]
	v_and_b32_e32 v104, 0xfff0fff0, v104
	v_and_b32_e32 v105, 0xfff0fff0, v105
	v_and_b32_e32 v106, 0xfff0fff0, v106
	v_and_b32_e32 v107, 0xfff0fff0, v107
	v_lshl_add_u64 v[108:109], v[108:109], 0, v[2:3]
	global_store_dwordx4 v[108:109], v[104:107], off
	s_nop 1
	v_cvt_f32_f16_e32 v104, v124
	v_cvt_f32_f16_sdwa v105, v124 dst_sel:DWORD dst_unused:UNUSED_PAD src0_sel:WORD_1
	v_pk_mul_f32 v[104:105], v[32:33], v[104:105]
	s_nop 0
	v_pk_fma_f32 v[96:97], v[96:97], s[38:39], v[104:105] op_sel_hi:[1,0,1]
	s_nop 0
	v_mul_f32_e32 v104, 0x3d372713, v96
	v_mul_f32_e32 v105, 0x3d372713, v97
	v_mul_f32_e32 v104, v96, v104
	v_mul_f32_e32 v105, v97, v105
	v_fma_f32 v104, v96, v104, v96
	v_fma_f32 v105, v97, v105, v97
	v_mul_f32_e32 v104, 0x3f4c422a, v104
	v_mul_f32_e32 v105, 0x3f4c422a, v105
	v_mul_f32_e32 v104, -2.0, v104
	v_mul_f32_e32 v105, -2.0, v105
	v_mul_f32_e32 v104, 0x3fb8aa3b, v104
	v_mul_f32_e32 v105, 0x3fb8aa3b, v105
	v_exp_f32_e32 v104, v104
	v_exp_f32_e32 v105, v105
	v_add_f32_e32 v104, 1.0, v104
	v_add_f32_e32 v105, 1.0, v105
	v_rcp_f32_e32 v104, v104
	v_rcp_f32_e32 v105, v105
	s_nop 0
	v_pk_mul_f32 v[96:97], v[96:97], v[104:105]
	s_nop 0
	v_cvt_pk_f16_f32 v104, v96, v97
	v_cvt_f32_f16_e32 v96, v126
	v_cvt_f32_f16_sdwa v97, v126 dst_sel:DWORD dst_unused:UNUSED_PAD src0_sel:WORD_1
	v_pk_mul_f32 v[96:97], v[28:29], v[96:97]
	s_nop 0
	v_pk_fma_f32 v[92:93], v[92:93], s[38:39], v[96:97] op_sel_hi:[1,0,1]
	s_nop 0
	v_mul_f32_e32 v96, 0x3d372713, v92
	v_mul_f32_e32 v97, 0x3d372713, v93
	v_mul_f32_e32 v96, v92, v96
	v_mul_f32_e32 v97, v93, v97
	v_fma_f32 v96, v92, v96, v92
	v_fma_f32 v97, v93, v97, v93
	v_mul_f32_e32 v96, 0x3f4c422a, v96
	v_mul_f32_e32 v97, 0x3f4c422a, v97
	v_mul_f32_e32 v96, -2.0, v96
	v_mul_f32_e32 v97, -2.0, v97
	v_mul_f32_e32 v96, 0x3fb8aa3b, v96
	v_mul_f32_e32 v97, 0x3fb8aa3b, v97
	v_exp_f32_e32 v96, v96
	v_exp_f32_e32 v97, v97
	v_add_f32_e32 v96, 1.0, v96
	v_add_f32_e32 v97, 1.0, v97
	v_rcp_f32_e32 v96, v96
	v_rcp_f32_e32 v97, v97
	s_nop 0
	v_pk_mul_f32 v[92:93], v[92:93], v[96:97]
	s_nop 0
	v_cvt_pk_f16_f32 v105, v92, v93
	v_cvt_f32_f16_e32 v92, v125
	v_cvt_f32_f16_sdwa v93, v125 dst_sel:DWORD dst_unused:UNUSED_PAD src0_sel:WORD_1
	v_pk_mul_f32 v[92:93], v[34:35], v[92:93]
	s_nop 0
	v_pk_fma_f32 v[92:93], v[98:99], s[38:39], v[92:93] op_sel_hi:[1,0,1]
	s_nop 0
	v_mul_f32_e32 v96, 0x3d372713, v92
	v_mul_f32_e32 v97, 0x3d372713, v93
	v_mul_f32_e32 v96, v92, v96
	v_mul_f32_e32 v97, v93, v97
	v_fma_f32 v96, v92, v96, v92
	v_fma_f32 v97, v93, v97, v93
	v_mul_f32_e32 v96, 0x3f4c422a, v96
	v_mul_f32_e32 v97, 0x3f4c422a, v97
	v_mul_f32_e32 v96, -2.0, v96
	v_mul_f32_e32 v97, -2.0, v97
	v_mul_f32_e32 v96, 0x3fb8aa3b, v96
	v_mul_f32_e32 v97, 0x3fb8aa3b, v97
	v_exp_f32_e32 v96, v96
	v_exp_f32_e32 v97, v97
	v_add_f32_e32 v96, 1.0, v96
	v_add_f32_e32 v97, 1.0, v97
	v_rcp_f32_e32 v96, v96
	v_rcp_f32_e32 v97, v97
	s_nop 0
	v_pk_mul_f32 v[92:93], v[92:93], v[96:97]
	s_nop 0
	v_cvt_pk_f16_f32 v96, v92, v93
	v_cvt_f32_f16_e32 v92, v127
	v_cvt_f32_f16_sdwa v93, v127 dst_sel:DWORD dst_unused:UNUSED_PAD src0_sel:WORD_1
	v_pk_mul_f32 v[92:93], v[30:31], v[92:93]
	s_nop 0
	v_pk_fma_f32 v[92:93], v[94:95], s[38:39], v[92:93] op_sel_hi:[1,0,1]
	s_nop 0
	v_mul_f32_e32 v94, 0x3d372713, v92
	v_mul_f32_e32 v95, 0x3d372713, v93
	v_mul_f32_e32 v94, v92, v94
	v_mul_f32_e32 v95, v93, v95
	v_fma_f32 v94, v92, v94, v92
	v_fma_f32 v95, v93, v95, v93
	v_mul_f32_e32 v94, 0x3f4c422a, v94
	v_mul_f32_e32 v95, 0x3f4c422a, v95
	v_mul_f32_e32 v94, -2.0, v94
	v_mul_f32_e32 v95, -2.0, v95
	v_mul_f32_e32 v94, 0x3fb8aa3b, v94
	v_mul_f32_e32 v95, 0x3fb8aa3b, v95
	v_exp_f32_e32 v94, v94
	v_exp_f32_e32 v95, v95
	v_add_f32_e32 v94, 1.0, v94
	v_add_f32_e32 v95, 1.0, v95
	v_rcp_f32_e32 v94, v94
	v_rcp_f32_e32 v95, v95
	s_nop 0
	v_pk_mul_f32 v[92:93], v[92:93], v[94:95]
	s_nop 0
	v_cvt_pk_f16_f32 v95, v92, v93
	v_lshrrev_b32_e32 v93, 4, v96
	v_and_b32_e32 v93, 0x10001, v93
	v_add3_u32 v93, v96, v93, s21
	v_lshrrev_b32_e32 v96, 4, v95
	v_and_b32_e32 v96, 0x10001, v96
	v_add3_u32 v95, v95, v96, s21
	v_add_u32_e32 v96, v140, v116
	v_ashrrev_i32_e32 v97, 31, v96
	v_lshrrev_b32_e32 v92, 4, v104
	v_lshrrev_b32_e32 v94, 4, v105
	v_lshlrev_b64 v[96:97], 10, v[96:97]
	v_and_b32_e32 v92, 0x10001, v92
	v_and_b32_e32 v94, 0x10001, v94
	v_lshl_add_u64 v[96:97], s[16:17], 0, v[96:97]
	v_add3_u32 v92, v104, v92, s21
	v_add3_u32 v94, v105, v94, s21
	v_lshl_add_u64 v[96:97], v[96:97], 0, s[42:43]
	v_and_b32_e32 v92, 0xfff0fff0, v92
	v_and_b32_e32 v93, 0xfff0fff0, v93
	v_and_b32_e32 v94, 0xfff0fff0, v94
	v_and_b32_e32 v95, 0xfff0fff0, v95
	v_lshl_add_u64 v[96:97], v[96:97], 0, v[2:3]
	global_store_dwordx4 v[96:97], v[92:95], off
	v_add_u32_e32 v104, 0x800, v192
	s_nop 0
	v_cvt_f32_f16_e32 v94, v112
	v_cvt_f32_f16_sdwa v95, v112 dst_sel:DWORD dst_unused:UNUSED_PAD src0_sel:WORD_1
	v_add_u32_e32 v92, 0x300, v192
	v_pk_mul_f32 v[94:95], v[32:33], v[94:95]
	s_nop 0
	v_pk_fma_f32 v[88:89], v[88:89], s[38:39], v[94:95] op_sel_hi:[1,0,1]
	s_nop 0
	v_mul_f32_e32 v93, 0x3d372713, v88
	v_mul_f32_e32 v93, v88, v93
	v_fma_f32 v93, v88, v93, v88
	v_mul_f32_e32 v93, 0x3f4c422a, v93
	v_mul_f32_e32 v93, -2.0, v93
	v_mul_f32_e32 v93, 0x3fb8aa3b, v93
	v_exp_f32_e32 v93, v93
	s_nop 0
	v_add_f32_e32 v93, 1.0, v93
	v_rcp_f32_e32 v94, v93
	v_mul_f32_e32 v93, 0x3d372713, v89
	v_mul_f32_e32 v93, v89, v93
	v_fma_f32 v93, v89, v93, v89
	v_mul_f32_e32 v93, 0x3f4c422a, v93
	v_mul_f32_e32 v93, -2.0, v93
	v_mul_f32_e32 v93, 0x3fb8aa3b, v93
	v_exp_f32_e32 v93, v93
	s_nop 0
	v_add_f32_e32 v93, 1.0, v93
	v_rcp_f32_e32 v95, v93
	s_nop 0
	v_pk_mul_f32 v[88:89], v[88:89], v[94:95]
	s_nop 0
	v_cvt_pk_f16_f32 v93, v88, v89
	v_cvt_f32_f16_e32 v88, v114
	v_cvt_f32_f16_sdwa v89, v114 dst_sel:DWORD dst_unused:UNUSED_PAD src0_sel:WORD_1
	v_pk_mul_f32 v[88:89], v[28:29], v[88:89]
	s_nop 0
	v_pk_fma_f32 v[84:85], v[84:85], s[38:39], v[88:89] op_sel_hi:[1,0,1]
	s_nop 0
	v_mul_f32_e32 v88, 0x3d372713, v84
	v_mul_f32_e32 v89, 0x3d372713, v85
	v_mul_f32_e32 v88, v84, v88
	v_mul_f32_e32 v89, v85, v89
	v_fma_f32 v88, v84, v88, v84
	v_fma_f32 v89, v85, v89, v85
	v_mul_f32_e32 v88, 0x3f4c422a, v88
	v_mul_f32_e32 v89, 0x3f4c422a, v89
	v_mul_f32_e32 v88, -2.0, v88
	v_mul_f32_e32 v89, -2.0, v89
	v_mul_f32_e32 v88, 0x3fb8aa3b, v88
	v_mul_f32_e32 v89, 0x3fb8aa3b, v89
	v_exp_f32_e32 v88, v88
	v_exp_f32_e32 v89, v89
	v_add_f32_e32 v88, 1.0, v88
	v_add_f32_e32 v89, 1.0, v89
	v_rcp_f32_e32 v88, v88
	v_rcp_f32_e32 v89, v89
	s_nop 0
	v_pk_mul_f32 v[84:85], v[84:85], v[88:89]
	s_nop 0
	v_cvt_pk_f16_f32 v94, v84, v85
	v_cvt_f32_f16_e32 v84, v113
	v_cvt_f32_f16_sdwa v85, v113 dst_sel:DWORD dst_unused:UNUSED_PAD src0_sel:WORD_1
	v_pk_mul_f32 v[84:85], v[34:35], v[84:85]
	s_nop 0
	v_pk_fma_f32 v[84:85], v[90:91], s[38:39], v[84:85] op_sel_hi:[1,0,1]
	s_nop 0
	v_mul_f32_e32 v88, 0x3d372713, v84
	v_mul_f32_e32 v89, 0x3d372713, v85
	v_mul_f32_e32 v88, v84, v88
	v_mul_f32_e32 v89, v85, v89
	v_fma_f32 v88, v84, v88, v84
	v_fma_f32 v89, v85, v89, v85
	v_mul_f32_e32 v88, 0x3f4c422a, v88
	v_mul_f32_e32 v89, 0x3f4c422a, v89
	v_mul_f32_e32 v88, -2.0, v88
	v_mul_f32_e32 v89, -2.0, v89
	v_mul_f32_e32 v88, 0x3fb8aa3b, v88
	v_mul_f32_e32 v89, 0x3fb8aa3b, v89
	v_exp_f32_e32 v88, v88
	v_exp_f32_e32 v89, v89
	v_add_f32_e32 v88, 1.0, v88
	v_add_f32_e32 v89, 1.0, v89
	v_rcp_f32_e32 v88, v88
	v_rcp_f32_e32 v89, v89
	s_nop 0
	v_pk_mul_f32 v[84:85], v[84:85], v[88:89]
	s_nop 0
	v_cvt_pk_f16_f32 v88, v84, v85
	v_cvt_f32_f16_e32 v84, v115
	v_cvt_f32_f16_sdwa v85, v115 dst_sel:DWORD dst_unused:UNUSED_PAD src0_sel:WORD_1
	v_pk_mul_f32 v[84:85], v[30:31], v[84:85]
	s_nop 0
	v_pk_fma_f32 v[84:85], v[86:87], s[38:39], v[84:85] op_sel_hi:[1,0,1]
	s_nop 0
	v_mul_f32_e32 v86, 0x3d372713, v84
	v_mul_f32_e32 v87, 0x3d372713, v85
	v_mul_f32_e32 v86, v84, v86
	v_mul_f32_e32 v87, v85, v87
	v_fma_f32 v86, v84, v86, v84
	v_fma_f32 v87, v85, v87, v85
	v_mul_f32_e32 v86, 0x3f4c422a, v86
	v_mul_f32_e32 v87, 0x3f4c422a, v87
	v_mul_f32_e32 v86, -2.0, v86
	v_mul_f32_e32 v87, -2.0, v87
	v_mul_f32_e32 v86, 0x3fb8aa3b, v86
	v_mul_f32_e32 v87, 0x3fb8aa3b, v87
	v_exp_f32_e32 v86, v86
	v_exp_f32_e32 v87, v87
	v_add_f32_e32 v86, 1.0, v86
	v_add_f32_e32 v87, 1.0, v87
	v_rcp_f32_e32 v86, v86
	v_rcp_f32_e32 v87, v87
	s_nop 0
	v_pk_mul_f32 v[84:85], v[84:85], v[86:87]
	s_nop 0
	v_cvt_pk_f16_f32 v87, v84, v85
	v_lshrrev_b32_e32 v85, 4, v88
	v_and_b32_e32 v85, 0x10001, v85
	v_add3_u32 v85, v88, v85, s21
	v_lshrrev_b32_e32 v88, 4, v87
	v_and_b32_e32 v88, 0x10001, v88
	v_add3_u32 v87, v87, v88, s21
	v_add_u32_e32 v88, v152, v92
	v_ashrrev_i32_e32 v89, 31, v88
	v_lshrrev_b32_e32 v84, 4, v93
	v_lshrrev_b32_e32 v86, 4, v94
	v_lshlrev_b64 v[88:89], 10, v[88:89]
	v_and_b32_e32 v84, 0x10001, v84
	v_and_b32_e32 v86, 0x10001, v86
	v_lshl_add_u64 v[88:89], s[16:17], 0, v[88:89]
	v_add3_u32 v84, v93, v84, s21
	v_add3_u32 v86, v94, v86, s21
	v_lshl_add_u64 v[88:89], v[88:89], 0, s[42:43]
	v_and_b32_e32 v84, 0xfff0fff0, v84
	v_and_b32_e32 v85, 0xfff0fff0, v85
	v_and_b32_e32 v86, 0xfff0fff0, v86
	v_and_b32_e32 v87, 0xfff0fff0, v87
	v_lshl_add_u64 v[88:89], v[88:89], 0, v[2:3]
	global_store_dwordx4 v[88:89], v[84:87], off
	s_nop 1
	v_cvt_f32_f16_e32 v84, v100
	v_cvt_f32_f16_sdwa v85, v100 dst_sel:DWORD dst_unused:UNUSED_PAD src0_sel:WORD_1
	v_pk_mul_f32 v[84:85], v[32:33], v[84:85]
	s_nop 0
	v_pk_fma_f32 v[80:81], v[80:81], s[38:39], v[84:85] op_sel_hi:[1,0,1]
	s_nop 0
	v_mul_f32_e32 v84, 0x3d372713, v80
	v_mul_f32_e32 v85, 0x3d372713, v81
	v_mul_f32_e32 v84, v80, v84
	v_mul_f32_e32 v85, v81, v85
	v_fma_f32 v84, v80, v84, v80
	v_fma_f32 v85, v81, v85, v81
	v_mul_f32_e32 v84, 0x3f4c422a, v84
	v_mul_f32_e32 v85, 0x3f4c422a, v85
	v_mul_f32_e32 v84, -2.0, v84
	v_mul_f32_e32 v85, -2.0, v85
	v_mul_f32_e32 v84, 0x3fb8aa3b, v84
	v_mul_f32_e32 v85, 0x3fb8aa3b, v85
	v_exp_f32_e32 v84, v84
	v_exp_f32_e32 v85, v85
	v_add_f32_e32 v84, 1.0, v84
	v_add_f32_e32 v85, 1.0, v85
	v_rcp_f32_e32 v84, v84
	v_rcp_f32_e32 v85, v85
	s_nop 0
	v_pk_mul_f32 v[80:81], v[80:81], v[84:85]
	s_nop 0
	v_cvt_pk_f16_f32 v84, v80, v81
	v_cvt_f32_f16_e32 v80, v102
	v_cvt_f32_f16_sdwa v81, v102 dst_sel:DWORD dst_unused:UNUSED_PAD src0_sel:WORD_1
	v_pk_mul_f32 v[80:81], v[28:29], v[80:81]
	s_nop 0
	v_pk_fma_f32 v[76:77], v[76:77], s[38:39], v[80:81] op_sel_hi:[1,0,1]
	s_nop 0
	v_mul_f32_e32 v80, 0x3d372713, v76
	v_mul_f32_e32 v81, 0x3d372713, v77
	v_mul_f32_e32 v80, v76, v80
	v_mul_f32_e32 v81, v77, v81
	v_fma_f32 v80, v76, v80, v76
	v_fma_f32 v81, v77, v81, v77
	v_mul_f32_e32 v80, 0x3f4c422a, v80
	v_mul_f32_e32 v81, 0x3f4c422a, v81
	v_mul_f32_e32 v80, -2.0, v80
	v_mul_f32_e32 v81, -2.0, v81
	v_mul_f32_e32 v80, 0x3fb8aa3b, v80
	v_mul_f32_e32 v81, 0x3fb8aa3b, v81
	v_exp_f32_e32 v80, v80
	v_exp_f32_e32 v81, v81
	v_add_f32_e32 v80, 1.0, v80
	v_add_f32_e32 v81, 1.0, v81
	v_rcp_f32_e32 v80, v80
	v_rcp_f32_e32 v81, v81
	s_nop 0
	v_pk_mul_f32 v[76:77], v[76:77], v[80:81]
	s_nop 0
	v_cvt_pk_f16_f32 v85, v76, v77
	v_cvt_f32_f16_e32 v76, v101
	v_cvt_f32_f16_sdwa v77, v101 dst_sel:DWORD dst_unused:UNUSED_PAD src0_sel:WORD_1
	v_lshl_add_u64 v[100:101], v[184:185], 0, s[10:11]
	s_mov_b64 s[10:11], 0x480000
	v_pk_mul_f32 v[76:77], v[34:35], v[76:77]
	s_nop 0
	v_pk_fma_f32 v[76:77], v[82:83], s[38:39], v[76:77] op_sel_hi:[1,0,1]
	s_nop 0
	v_mul_f32_e32 v80, 0x3d372713, v76
	v_mul_f32_e32 v81, 0x3d372713, v77
	v_mul_f32_e32 v80, v76, v80
	v_mul_f32_e32 v81, v77, v81
	v_fma_f32 v80, v76, v80, v76
	v_fma_f32 v81, v77, v81, v77
	v_mul_f32_e32 v80, 0x3f4c422a, v80
	v_mul_f32_e32 v81, 0x3f4c422a, v81
	v_mul_f32_e32 v80, -2.0, v80
	v_mul_f32_e32 v81, -2.0, v81
	v_mul_f32_e32 v80, 0x3fb8aa3b, v80
	v_mul_f32_e32 v81, 0x3fb8aa3b, v81
	v_exp_f32_e32 v80, v80
	v_exp_f32_e32 v81, v81
	v_add_f32_e32 v80, 1.0, v80
	v_add_f32_e32 v81, 1.0, v81
	v_rcp_f32_e32 v80, v80
	v_rcp_f32_e32 v81, v81
	s_nop 0
	v_pk_mul_f32 v[76:77], v[76:77], v[80:81]
	s_nop 0
	v_cvt_pk_f16_f32 v80, v76, v77
	v_cvt_f32_f16_e32 v76, v103
	v_cvt_f32_f16_sdwa v77, v103 dst_sel:DWORD dst_unused:UNUSED_PAD src0_sel:WORD_1
	v_pk_mul_f32 v[76:77], v[30:31], v[76:77]
	s_nop 0
	v_pk_fma_f32 v[76:77], v[78:79], s[38:39], v[76:77] op_sel_hi:[1,0,1]
	s_nop 0
	v_mul_f32_e32 v78, 0x3d372713, v76
	v_mul_f32_e32 v79, 0x3d372713, v77
	v_mul_f32_e32 v78, v76, v78
	v_mul_f32_e32 v79, v77, v79
	v_fma_f32 v78, v76, v78, v76
	v_fma_f32 v79, v77, v79, v77
	v_mul_f32_e32 v78, 0x3f4c422a, v78
	v_mul_f32_e32 v79, 0x3f4c422a, v79
	v_mul_f32_e32 v78, -2.0, v78
	v_mul_f32_e32 v79, -2.0, v79
	v_mul_f32_e32 v78, 0x3fb8aa3b, v78
	v_mul_f32_e32 v79, 0x3fb8aa3b, v79
	v_exp_f32_e32 v78, v78
	v_exp_f32_e32 v79, v79
	v_add_f32_e32 v78, 1.0, v78
	v_add_f32_e32 v79, 1.0, v79
	v_rcp_f32_e32 v78, v78
	v_rcp_f32_e32 v79, v79
	s_nop 0
	v_pk_mul_f32 v[76:77], v[76:77], v[78:79]
	s_nop 0
	v_cvt_pk_f16_f32 v79, v76, v77
	v_lshrrev_b32_e32 v77, 4, v80
	v_and_b32_e32 v77, 0x10001, v77
	v_add3_u32 v77, v80, v77, s21
	v_lshrrev_b32_e32 v80, 4, v79
	v_and_b32_e32 v80, 0x10001, v80
	v_add3_u32 v79, v79, v80, s21
	v_add_u32_e32 v80, v140, v92
	v_ashrrev_i32_e32 v81, 31, v80
	v_lshrrev_b32_e32 v76, 4, v84
	v_lshrrev_b32_e32 v78, 4, v85
	v_lshlrev_b64 v[80:81], 10, v[80:81]
	v_and_b32_e32 v76, 0x10001, v76
	v_and_b32_e32 v78, 0x10001, v78
	v_lshl_add_u64 v[80:81], s[16:17], 0, v[80:81]
	v_add3_u32 v76, v84, v76, s21
	v_add3_u32 v78, v85, v78, s21
	v_lshl_add_u64 v[80:81], v[80:81], 0, s[42:43]
	v_lshl_add_u64 v[92:93], v[184:185], 0, s[10:11]
	s_mov_b64 s[10:11], 0x500000
	v_and_b32_e32 v76, 0xfff0fff0, v76
	v_and_b32_e32 v77, 0xfff0fff0, v77
	v_and_b32_e32 v78, 0xfff0fff0, v78
	v_and_b32_e32 v79, 0xfff0fff0, v79
	v_lshl_add_u64 v[80:81], v[80:81], 0, v[2:3]
	v_lshl_add_u64 v[84:85], v[184:185], 0, s[10:11]
	s_mov_b64 s[10:11], 0x580000
	global_store_dwordx4 v[80:81], v[76:79], off
	s_nop 1
	v_lshl_add_u64 v[76:77], v[184:185], 0, s[10:11]
	s_mov_b32 s10, 0x580000
	v_add_co_u32_e32 v78, vcc, s10, v184
	s_mov_b32 s10, 0x500000
	s_nop 0
	v_addc_co_u32_e32 v79, vcc, 0, v185, vcc
	global_load_dwordx4 v[80:83], v[78:79], off
	v_add_co_u32_e32 v78, vcc, s10, v184
	s_mov_b32 s10, 0x480000
	s_nop 0
	v_addc_co_u32_e32 v79, vcc, 0, v185, vcc
	global_load_dwordx4 v[88:91], v[78:79], off
	v_add_co_u32_e32 v78, vcc, s10, v184
	s_mov_b32 s10, 0x400000
	s_nop 0
	v_addc_co_u32_e32 v79, vcc, 0, v185, vcc
	global_load_dwordx4 v[96:99], v[78:79], off
	v_add_co_u32_e32 v78, vcc, s10, v184
	s_mov_b32 s10, s18
	s_nop 0
	v_addc_co_u32_e32 v79, vcc, 0, v185, vcc
	global_load_dwordx4 v[106:109], v[78:79], off
	s_nop 0
	global_load_dwordx4 v[76:79], v[76:77], off offset:256
	s_nop 0
	global_load_dwordx4 v[84:87], v[84:85], off offset:256
	s_nop 0
	global_load_dwordx4 v[92:95], v[92:93], off offset:256
	s_nop 0
	global_load_dwordx4 v[100:103], v[100:101], off offset:256
	s_waitcnt vmcnt(0)
	s_nop 0
	v_cvt_f32_f16_e32 v110, v106
	v_cvt_f32_f16_sdwa v111, v106 dst_sel:DWORD dst_unused:UNUSED_PAD src0_sel:WORD_1
	s_and_b64 vcc, exec, s[40:41]
	v_pk_mul_f32 v[110:111], v[32:33], v[110:111]
	s_nop 0
	v_pk_fma_f32 v[72:73], v[72:73], s[38:39], v[110:111] op_sel_hi:[1,0,1]
	s_nop 0
	v_mul_f32_e32 v105, 0x3d372713, v72
	v_mul_f32_e32 v105, v72, v105
	v_fma_f32 v105, v72, v105, v72
	v_mul_f32_e32 v105, 0x3f4c422a, v105
	v_mul_f32_e32 v105, -2.0, v105
	v_mul_f32_e32 v105, 0x3fb8aa3b, v105
	v_exp_f32_e32 v105, v105
	s_nop 0
	v_add_f32_e32 v105, 1.0, v105
	v_rcp_f32_e32 v110, v105
	v_mul_f32_e32 v105, 0x3d372713, v73
	v_mul_f32_e32 v105, v73, v105
	v_fma_f32 v105, v73, v105, v73
	v_mul_f32_e32 v105, 0x3f4c422a, v105
	v_mul_f32_e32 v105, -2.0, v105
	v_mul_f32_e32 v105, 0x3fb8aa3b, v105
	v_exp_f32_e32 v105, v105
	s_nop 0
	v_add_f32_e32 v105, 1.0, v105
	v_rcp_f32_e32 v111, v105
	s_nop 0
	v_pk_mul_f32 v[72:73], v[72:73], v[110:111]
	s_nop 0
	v_cvt_pk_f16_f32 v105, v72, v73
	v_cvt_f32_f16_e32 v72, v108
	v_cvt_f32_f16_sdwa v73, v108 dst_sel:DWORD dst_unused:UNUSED_PAD src0_sel:WORD_1
	v_pk_mul_f32 v[72:73], v[28:29], v[72:73]
	s_nop 0
	v_pk_fma_f32 v[68:69], v[68:69], s[38:39], v[72:73] op_sel_hi:[1,0,1]
	s_nop 0
	v_mul_f32_e32 v72, 0x3d372713, v68
	v_mul_f32_e32 v73, 0x3d372713, v69
	v_mul_f32_e32 v72, v68, v72
	v_mul_f32_e32 v73, v69, v73
	v_fma_f32 v72, v68, v72, v68
	v_fma_f32 v73, v69, v73, v69
	v_mul_f32_e32 v72, 0x3f4c422a, v72
	v_mul_f32_e32 v73, 0x3f4c422a, v73
	v_mul_f32_e32 v72, -2.0, v72
	v_mul_f32_e32 v73, -2.0, v73
	v_mul_f32_e32 v72, 0x3fb8aa3b, v72
	v_mul_f32_e32 v73, 0x3fb8aa3b, v73
	v_exp_f32_e32 v72, v72
	v_exp_f32_e32 v73, v73
	v_add_f32_e32 v72, 1.0, v72
	v_add_f32_e32 v73, 1.0, v73
	v_rcp_f32_e32 v72, v72
	v_rcp_f32_e32 v73, v73
	s_nop 0
	v_pk_mul_f32 v[68:69], v[68:69], v[72:73]
	s_nop 0
	v_cvt_pk_f16_f32 v106, v68, v69
	v_cvt_f32_f16_e32 v68, v107
	v_cvt_f32_f16_sdwa v69, v107 dst_sel:DWORD dst_unused:UNUSED_PAD src0_sel:WORD_1
	v_pk_mul_f32 v[68:69], v[34:35], v[68:69]
	s_nop 0
	v_pk_fma_f32 v[68:69], v[74:75], s[38:39], v[68:69] op_sel_hi:[1,0,1]
	s_nop 0
	v_mul_f32_e32 v72, 0x3d372713, v68
	v_mul_f32_e32 v73, 0x3d372713, v69
	v_mul_f32_e32 v72, v68, v72
	v_mul_f32_e32 v73, v69, v73
	v_fma_f32 v72, v68, v72, v68
	v_fma_f32 v73, v69, v73, v69
	v_mul_f32_e32 v72, 0x3f4c422a, v72
	v_mul_f32_e32 v73, 0x3f4c422a, v73
	v_mul_f32_e32 v72, -2.0, v72
	v_mul_f32_e32 v73, -2.0, v73
	v_mul_f32_e32 v72, 0x3fb8aa3b, v72
	v_mul_f32_e32 v73, 0x3fb8aa3b, v73
	v_exp_f32_e32 v72, v72
	v_exp_f32_e32 v73, v73
	v_add_f32_e32 v72, 1.0, v72
	v_add_f32_e32 v73, 1.0, v73
	v_rcp_f32_e32 v72, v72
	v_rcp_f32_e32 v73, v73
	s_nop 0
	v_pk_mul_f32 v[68:69], v[68:69], v[72:73]
	s_nop 0
	v_cvt_pk_f16_f32 v72, v68, v69
	v_cvt_f32_f16_e32 v68, v109
	v_cvt_f32_f16_sdwa v69, v109 dst_sel:DWORD dst_unused:UNUSED_PAD src0_sel:WORD_1
	v_pk_mul_f32 v[68:69], v[30:31], v[68:69]
	s_nop 0
	v_pk_fma_f32 v[68:69], v[70:71], s[38:39], v[68:69] op_sel_hi:[1,0,1]
	s_nop 0
	v_mul_f32_e32 v70, 0x3d372713, v68
	v_mul_f32_e32 v71, 0x3d372713, v69
	v_mul_f32_e32 v70, v68, v70
	v_mul_f32_e32 v71, v69, v71
	v_fma_f32 v70, v68, v70, v68
	v_fma_f32 v71, v69, v71, v69
	v_mul_f32_e32 v70, 0x3f4c422a, v70
	v_mul_f32_e32 v71, 0x3f4c422a, v71
	v_mul_f32_e32 v70, -2.0, v70
	v_mul_f32_e32 v71, -2.0, v71
	v_mul_f32_e32 v70, 0x3fb8aa3b, v70
	v_mul_f32_e32 v71, 0x3fb8aa3b, v71
	v_exp_f32_e32 v70, v70
	v_exp_f32_e32 v71, v71
	v_add_f32_e32 v70, 1.0, v70
	v_add_f32_e32 v71, 1.0, v71
	v_rcp_f32_e32 v70, v70
	v_rcp_f32_e32 v71, v71
	s_nop 0
	v_pk_mul_f32 v[68:69], v[68:69], v[70:71]
	s_nop 0
	v_cvt_pk_f16_f32 v71, v68, v69
	v_lshrrev_b32_e32 v69, 4, v72
	v_and_b32_e32 v69, 0x10001, v69
	v_add3_u32 v69, v72, v69, s21
	v_lshrrev_b32_e32 v72, 4, v71
	v_and_b32_e32 v72, 0x10001, v72
	v_add3_u32 v71, v71, v72, s21
	v_add_u32_e32 v72, v152, v104
	v_ashrrev_i32_e32 v73, 31, v72
	v_lshrrev_b32_e32 v68, 4, v105
	v_lshrrev_b32_e32 v70, 4, v106
	v_lshlrev_b64 v[72:73], 10, v[72:73]
	v_and_b32_e32 v68, 0x10001, v68
	v_and_b32_e32 v70, 0x10001, v70
	v_lshl_add_u64 v[72:73], s[16:17], 0, v[72:73]
	v_add3_u32 v68, v105, v68, s21
	v_add3_u32 v70, v106, v70, s21
	v_lshl_add_u64 v[72:73], v[72:73], 0, s[42:43]
	v_and_b32_e32 v68, 0xfff0fff0, v68
	v_and_b32_e32 v69, 0xfff0fff0, v69
	v_and_b32_e32 v70, 0xfff0fff0, v70
	v_and_b32_e32 v71, 0xfff0fff0, v71
	v_lshl_add_u64 v[72:73], v[72:73], 0, v[2:3]
	global_store_dwordx4 v[72:73], v[68:71], off
	s_nop 1
	v_cvt_f32_f16_e32 v68, v100
	v_cvt_f32_f16_sdwa v69, v100 dst_sel:DWORD dst_unused:UNUSED_PAD src0_sel:WORD_1
	v_pk_mul_f32 v[68:69], v[32:33], v[68:69]
	s_nop 0
	v_pk_fma_f32 v[64:65], v[64:65], s[38:39], v[68:69] op_sel_hi:[1,0,1]
	s_nop 0
	v_mul_f32_e32 v68, 0x3d372713, v64
	v_mul_f32_e32 v69, 0x3d372713, v65
	v_mul_f32_e32 v68, v64, v68
	v_mul_f32_e32 v69, v65, v69
	v_fma_f32 v68, v64, v68, v64
	v_fma_f32 v69, v65, v69, v65
	v_mul_f32_e32 v68, 0x3f4c422a, v68
	v_mul_f32_e32 v69, 0x3f4c422a, v69
	v_mul_f32_e32 v68, -2.0, v68
	v_mul_f32_e32 v69, -2.0, v69
	v_mul_f32_e32 v68, 0x3fb8aa3b, v68
	v_mul_f32_e32 v69, 0x3fb8aa3b, v69
	v_exp_f32_e32 v68, v68
	v_exp_f32_e32 v69, v69
	v_add_f32_e32 v68, 1.0, v68
	v_add_f32_e32 v69, 1.0, v69
	v_rcp_f32_e32 v68, v68
	v_rcp_f32_e32 v69, v69
	s_nop 0
	v_pk_mul_f32 v[64:65], v[64:65], v[68:69]
	s_nop 0
	v_cvt_pk_f16_f32 v68, v64, v65
	v_cvt_f32_f16_e32 v64, v102
	v_cvt_f32_f16_sdwa v65, v102 dst_sel:DWORD dst_unused:UNUSED_PAD src0_sel:WORD_1
	v_pk_mul_f32 v[64:65], v[28:29], v[64:65]
	s_nop 0
	v_pk_fma_f32 v[60:61], v[60:61], s[38:39], v[64:65] op_sel_hi:[1,0,1]
	s_nop 0
	v_mul_f32_e32 v64, 0x3d372713, v60
	v_mul_f32_e32 v65, 0x3d372713, v61
	v_mul_f32_e32 v64, v60, v64
	v_mul_f32_e32 v65, v61, v65
	v_fma_f32 v64, v60, v64, v60
	v_fma_f32 v65, v61, v65, v61
	v_mul_f32_e32 v64, 0x3f4c422a, v64
	v_mul_f32_e32 v65, 0x3f4c422a, v65
	v_mul_f32_e32 v64, -2.0, v64
	v_mul_f32_e32 v65, -2.0, v65
	v_mul_f32_e32 v64, 0x3fb8aa3b, v64
	v_mul_f32_e32 v65, 0x3fb8aa3b, v65
	v_exp_f32_e32 v64, v64
	v_exp_f32_e32 v65, v65
	v_add_f32_e32 v64, 1.0, v64
	v_add_f32_e32 v65, 1.0, v65
	v_rcp_f32_e32 v64, v64
	v_rcp_f32_e32 v65, v65
	s_nop 0
	v_pk_mul_f32 v[60:61], v[60:61], v[64:65]
	s_nop 0
	v_cvt_pk_f16_f32 v69, v60, v61
	v_cvt_f32_f16_e32 v60, v101
	v_cvt_f32_f16_sdwa v61, v101 dst_sel:DWORD dst_unused:UNUSED_PAD src0_sel:WORD_1
	v_pk_mul_f32 v[60:61], v[34:35], v[60:61]
	s_nop 0
	v_pk_fma_f32 v[60:61], v[66:67], s[38:39], v[60:61] op_sel_hi:[1,0,1]
	s_nop 0
	v_mul_f32_e32 v64, 0x3d372713, v60
	v_mul_f32_e32 v65, 0x3d372713, v61
	v_mul_f32_e32 v64, v60, v64
	v_mul_f32_e32 v65, v61, v65
	v_fma_f32 v64, v60, v64, v60
	v_fma_f32 v65, v61, v65, v61
	v_mul_f32_e32 v64, 0x3f4c422a, v64
	v_mul_f32_e32 v65, 0x3f4c422a, v65
	v_mul_f32_e32 v64, -2.0, v64
	v_mul_f32_e32 v65, -2.0, v65
	v_mul_f32_e32 v64, 0x3fb8aa3b, v64
	v_mul_f32_e32 v65, 0x3fb8aa3b, v65
	v_exp_f32_e32 v64, v64
	v_exp_f32_e32 v65, v65
	v_add_f32_e32 v64, 1.0, v64
	v_add_f32_e32 v65, 1.0, v65
	v_rcp_f32_e32 v64, v64
	v_rcp_f32_e32 v65, v65
	s_nop 0
	v_pk_mul_f32 v[60:61], v[60:61], v[64:65]
	s_nop 0
	v_cvt_pk_f16_f32 v64, v60, v61
	v_cvt_f32_f16_e32 v60, v103
	v_cvt_f32_f16_sdwa v61, v103 dst_sel:DWORD dst_unused:UNUSED_PAD src0_sel:WORD_1
	v_pk_mul_f32 v[60:61], v[30:31], v[60:61]
	s_nop 0
	v_pk_fma_f32 v[60:61], v[62:63], s[38:39], v[60:61] op_sel_hi:[1,0,1]
	s_nop 0
	v_mul_f32_e32 v62, 0x3d372713, v60
	v_mul_f32_e32 v63, 0x3d372713, v61
	v_mul_f32_e32 v62, v60, v62
	v_mul_f32_e32 v63, v61, v63
	v_fma_f32 v62, v60, v62, v60
	v_fma_f32 v63, v61, v63, v61
	v_mul_f32_e32 v62, 0x3f4c422a, v62
	v_mul_f32_e32 v63, 0x3f4c422a, v63
	v_mul_f32_e32 v62, -2.0, v62
	v_mul_f32_e32 v63, -2.0, v63
	v_mul_f32_e32 v62, 0x3fb8aa3b, v62
	v_mul_f32_e32 v63, 0x3fb8aa3b, v63
	v_exp_f32_e32 v62, v62
	v_exp_f32_e32 v63, v63
	v_add_f32_e32 v62, 1.0, v62
	v_add_f32_e32 v63, 1.0, v63
	v_rcp_f32_e32 v62, v62
	v_rcp_f32_e32 v63, v63
	s_nop 0
	v_pk_mul_f32 v[60:61], v[60:61], v[62:63]
	s_nop 0
	v_cvt_pk_f16_f32 v63, v60, v61
	v_lshrrev_b32_e32 v61, 4, v64
	v_and_b32_e32 v61, 0x10001, v61
	v_add3_u32 v61, v64, v61, s21
	v_lshrrev_b32_e32 v64, 4, v63
	v_and_b32_e32 v64, 0x10001, v64
	v_add3_u32 v63, v63, v64, s21
	v_add_u32_e32 v64, v140, v104
	v_ashrrev_i32_e32 v65, 31, v64
	v_lshrrev_b32_e32 v60, 4, v68
	v_lshrrev_b32_e32 v62, 4, v69
	v_lshlrev_b64 v[64:65], 10, v[64:65]
	v_and_b32_e32 v60, 0x10001, v60
	v_and_b32_e32 v62, 0x10001, v62
	v_lshl_add_u64 v[64:65], s[16:17], 0, v[64:65]
	v_add3_u32 v60, v68, v60, s21
	v_add3_u32 v62, v69, v62, s21
	v_lshl_add_u64 v[64:65], v[64:65], 0, s[42:43]
	v_and_b32_e32 v60, 0xfff0fff0, v60
	v_and_b32_e32 v61, 0xfff0fff0, v61
	v_and_b32_e32 v62, 0xfff0fff0, v62
	v_and_b32_e32 v63, 0xfff0fff0, v63
	v_lshl_add_u64 v[64:65], v[64:65], 0, v[2:3]
	global_store_dwordx4 v[64:65], v[60:63], off
	s_nop 1
	v_cvt_f32_f16_e32 v62, v96
	v_cvt_f32_f16_sdwa v63, v96 dst_sel:DWORD dst_unused:UNUSED_PAD src0_sel:WORD_1
	v_add_u32_e32 v60, 0x900, v192
	v_pk_mul_f32 v[62:63], v[32:33], v[62:63]
	s_nop 0
	v_pk_fma_f32 v[56:57], v[56:57], s[38:39], v[62:63] op_sel_hi:[1,0,1]
	s_nop 0
	v_mul_f32_e32 v61, 0x3d372713, v56
	v_mul_f32_e32 v61, v56, v61
	v_fma_f32 v61, v56, v61, v56
	v_mul_f32_e32 v61, 0x3f4c422a, v61
	v_mul_f32_e32 v61, -2.0, v61
	v_mul_f32_e32 v61, 0x3fb8aa3b, v61
	v_exp_f32_e32 v61, v61
	s_nop 0
	v_add_f32_e32 v61, 1.0, v61
	v_rcp_f32_e32 v62, v61
	v_mul_f32_e32 v61, 0x3d372713, v57
	v_mul_f32_e32 v61, v57, v61
	v_fma_f32 v61, v57, v61, v57
	v_mul_f32_e32 v61, 0x3f4c422a, v61
	v_mul_f32_e32 v61, -2.0, v61
	v_mul_f32_e32 v61, 0x3fb8aa3b, v61
	v_exp_f32_e32 v61, v61
	s_nop 0
	v_add_f32_e32 v61, 1.0, v61
	v_rcp_f32_e32 v63, v61
	s_nop 0
	v_pk_mul_f32 v[56:57], v[56:57], v[62:63]
	s_nop 0
	v_cvt_pk_f16_f32 v61, v56, v57
	v_cvt_f32_f16_e32 v56, v98
	v_cvt_f32_f16_sdwa v57, v98 dst_sel:DWORD dst_unused:UNUSED_PAD src0_sel:WORD_1
	v_pk_mul_f32 v[56:57], v[28:29], v[56:57]
	s_nop 0
	v_pk_fma_f32 v[52:53], v[52:53], s[38:39], v[56:57] op_sel_hi:[1,0,1]
	s_nop 0
	v_mul_f32_e32 v56, 0x3d372713, v52
	v_mul_f32_e32 v57, 0x3d372713, v53
	v_mul_f32_e32 v56, v52, v56
	v_mul_f32_e32 v57, v53, v57
	v_fma_f32 v56, v52, v56, v52
	v_fma_f32 v57, v53, v57, v53
	v_mul_f32_e32 v56, 0x3f4c422a, v56
	v_mul_f32_e32 v57, 0x3f4c422a, v57
	v_mul_f32_e32 v56, -2.0, v56
	v_mul_f32_e32 v57, -2.0, v57
	v_mul_f32_e32 v56, 0x3fb8aa3b, v56
	v_mul_f32_e32 v57, 0x3fb8aa3b, v57
	v_exp_f32_e32 v56, v56
	v_exp_f32_e32 v57, v57
	v_add_f32_e32 v56, 1.0, v56
	v_add_f32_e32 v57, 1.0, v57
	v_rcp_f32_e32 v56, v56
	v_rcp_f32_e32 v57, v57
	s_nop 0
	v_pk_mul_f32 v[52:53], v[52:53], v[56:57]
	s_nop 0
	v_cvt_pk_f16_f32 v62, v52, v53
	v_cvt_f32_f16_e32 v52, v97
	v_cvt_f32_f16_sdwa v53, v97 dst_sel:DWORD dst_unused:UNUSED_PAD src0_sel:WORD_1
	v_pk_mul_f32 v[52:53], v[34:35], v[52:53]
	s_nop 0
	v_pk_fma_f32 v[52:53], v[58:59], s[38:39], v[52:53] op_sel_hi:[1,0,1]
	s_nop 0
	v_mul_f32_e32 v56, 0x3d372713, v52
	v_mul_f32_e32 v57, 0x3d372713, v53
	v_mul_f32_e32 v56, v52, v56
	v_mul_f32_e32 v57, v53, v57
	v_fma_f32 v56, v52, v56, v52
	v_fma_f32 v57, v53, v57, v53
	v_mul_f32_e32 v56, 0x3f4c422a, v56
	v_mul_f32_e32 v57, 0x3f4c422a, v57
	v_mul_f32_e32 v56, -2.0, v56
	v_mul_f32_e32 v57, -2.0, v57
	v_mul_f32_e32 v56, 0x3fb8aa3b, v56
	v_mul_f32_e32 v57, 0x3fb8aa3b, v57
	v_exp_f32_e32 v56, v56
	v_exp_f32_e32 v57, v57
	v_add_f32_e32 v56, 1.0, v56
	v_add_f32_e32 v57, 1.0, v57
	v_rcp_f32_e32 v56, v56
	v_rcp_f32_e32 v57, v57
	s_nop 0
	v_pk_mul_f32 v[52:53], v[52:53], v[56:57]
	s_nop 0
	v_cvt_pk_f16_f32 v56, v52, v53
	v_cvt_f32_f16_e32 v52, v99
	v_cvt_f32_f16_sdwa v53, v99 dst_sel:DWORD dst_unused:UNUSED_PAD src0_sel:WORD_1
	v_pk_mul_f32 v[52:53], v[30:31], v[52:53]
	s_nop 0
	v_pk_fma_f32 v[52:53], v[54:55], s[38:39], v[52:53] op_sel_hi:[1,0,1]
	s_nop 0
	v_mul_f32_e32 v54, 0x3d372713, v52
	v_mul_f32_e32 v55, 0x3d372713, v53
	v_mul_f32_e32 v54, v52, v54
	v_mul_f32_e32 v55, v53, v55
	v_fma_f32 v54, v52, v54, v52
	v_fma_f32 v55, v53, v55, v53
	v_mul_f32_e32 v54, 0x3f4c422a, v54
	v_mul_f32_e32 v55, 0x3f4c422a, v55
	v_mul_f32_e32 v54, -2.0, v54
	v_mul_f32_e32 v55, -2.0, v55
	v_mul_f32_e32 v54, 0x3fb8aa3b, v54
	v_mul_f32_e32 v55, 0x3fb8aa3b, v55
	v_exp_f32_e32 v54, v54
	v_exp_f32_e32 v55, v55
	v_add_f32_e32 v54, 1.0, v54
	v_add_f32_e32 v55, 1.0, v55
	v_rcp_f32_e32 v54, v54
	v_rcp_f32_e32 v55, v55
	s_nop 0
	v_pk_mul_f32 v[52:53], v[52:53], v[54:55]
	s_nop 0
	v_cvt_pk_f16_f32 v55, v52, v53
	v_lshrrev_b32_e32 v53, 4, v56
	v_and_b32_e32 v53, 0x10001, v53
	v_add3_u32 v53, v56, v53, s21
	v_lshrrev_b32_e32 v56, 4, v55
	v_and_b32_e32 v56, 0x10001, v56
	v_add3_u32 v55, v55, v56, s21
	v_add_u32_e32 v56, v152, v60
	v_ashrrev_i32_e32 v57, 31, v56
	v_lshrrev_b32_e32 v52, 4, v61
	v_lshrrev_b32_e32 v54, 4, v62
	v_lshlrev_b64 v[56:57], 10, v[56:57]
	v_and_b32_e32 v52, 0x10001, v52
	v_and_b32_e32 v54, 0x10001, v54
	v_lshl_add_u64 v[56:57], s[16:17], 0, v[56:57]
	v_add3_u32 v52, v61, v52, s21
	v_add3_u32 v54, v62, v54, s21
	v_lshl_add_u64 v[56:57], v[56:57], 0, s[42:43]
	v_and_b32_e32 v52, 0xfff0fff0, v52
	v_and_b32_e32 v53, 0xfff0fff0, v53
	v_and_b32_e32 v54, 0xfff0fff0, v54
	v_and_b32_e32 v55, 0xfff0fff0, v55
	v_lshl_add_u64 v[56:57], v[56:57], 0, v[2:3]
	global_store_dwordx4 v[56:57], v[52:55], off
	s_nop 1
	v_cvt_f32_f16_e32 v52, v92
	v_cvt_f32_f16_sdwa v53, v92 dst_sel:DWORD dst_unused:UNUSED_PAD src0_sel:WORD_1
	v_pk_mul_f32 v[52:53], v[32:33], v[52:53]
	s_nop 0
	v_pk_fma_f32 v[48:49], v[48:49], s[38:39], v[52:53] op_sel_hi:[1,0,1]
	s_nop 0
	v_mul_f32_e32 v52, 0x3d372713, v48
	v_mul_f32_e32 v53, 0x3d372713, v49
	v_mul_f32_e32 v52, v48, v52
	v_mul_f32_e32 v53, v49, v53
	v_fma_f32 v52, v48, v52, v48
	v_fma_f32 v53, v49, v53, v49
	v_mul_f32_e32 v52, 0x3f4c422a, v52
	v_mul_f32_e32 v53, 0x3f4c422a, v53
	v_mul_f32_e32 v52, -2.0, v52
	v_mul_f32_e32 v53, -2.0, v53
	v_mul_f32_e32 v52, 0x3fb8aa3b, v52
	v_mul_f32_e32 v53, 0x3fb8aa3b, v53
	v_exp_f32_e32 v52, v52
	v_exp_f32_e32 v53, v53
	v_add_f32_e32 v52, 1.0, v52
	v_add_f32_e32 v53, 1.0, v53
	v_rcp_f32_e32 v52, v52
	v_rcp_f32_e32 v53, v53
	s_nop 0
	v_pk_mul_f32 v[48:49], v[48:49], v[52:53]
	s_nop 0
	v_cvt_pk_f16_f32 v52, v48, v49
	v_cvt_f32_f16_e32 v48, v94
	v_cvt_f32_f16_sdwa v49, v94 dst_sel:DWORD dst_unused:UNUSED_PAD src0_sel:WORD_1
	v_pk_mul_f32 v[48:49], v[28:29], v[48:49]
	s_nop 0
	v_pk_fma_f32 v[44:45], v[44:45], s[38:39], v[48:49] op_sel_hi:[1,0,1]
	s_nop 0
	v_mul_f32_e32 v48, 0x3d372713, v44
	v_mul_f32_e32 v49, 0x3d372713, v45
	v_mul_f32_e32 v48, v44, v48
	v_mul_f32_e32 v49, v45, v49
	v_fma_f32 v48, v44, v48, v44
	v_fma_f32 v49, v45, v49, v45
	v_mul_f32_e32 v48, 0x3f4c422a, v48
	v_mul_f32_e32 v49, 0x3f4c422a, v49
	v_mul_f32_e32 v48, -2.0, v48
	v_mul_f32_e32 v49, -2.0, v49
	v_mul_f32_e32 v48, 0x3fb8aa3b, v48
	v_mul_f32_e32 v49, 0x3fb8aa3b, v49
	v_exp_f32_e32 v48, v48
	v_exp_f32_e32 v49, v49
	v_add_f32_e32 v48, 1.0, v48
	v_add_f32_e32 v49, 1.0, v49
	v_rcp_f32_e32 v48, v48
	v_rcp_f32_e32 v49, v49
	s_nop 0
	v_pk_mul_f32 v[44:45], v[44:45], v[48:49]
	s_nop 0
	v_cvt_pk_f16_f32 v53, v44, v45
	v_cvt_f32_f16_e32 v44, v93
	v_cvt_f32_f16_sdwa v45, v93 dst_sel:DWORD dst_unused:UNUSED_PAD src0_sel:WORD_1
	v_pk_mul_f32 v[44:45], v[34:35], v[44:45]
	s_nop 0
	v_pk_fma_f32 v[44:45], v[50:51], s[38:39], v[44:45] op_sel_hi:[1,0,1]
	s_nop 0
	v_mul_f32_e32 v48, 0x3d372713, v44
	v_mul_f32_e32 v49, 0x3d372713, v45
	v_mul_f32_e32 v48, v44, v48
	v_mul_f32_e32 v49, v45, v49
	v_fma_f32 v48, v44, v48, v44
	v_fma_f32 v49, v45, v49, v45
	v_mul_f32_e32 v48, 0x3f4c422a, v48
	v_mul_f32_e32 v49, 0x3f4c422a, v49
	v_mul_f32_e32 v48, -2.0, v48
	v_mul_f32_e32 v49, -2.0, v49
	v_mul_f32_e32 v48, 0x3fb8aa3b, v48
	v_mul_f32_e32 v49, 0x3fb8aa3b, v49
	v_exp_f32_e32 v48, v48
	v_exp_f32_e32 v49, v49
	v_add_f32_e32 v48, 1.0, v48
	v_add_f32_e32 v49, 1.0, v49
	v_rcp_f32_e32 v48, v48
	v_rcp_f32_e32 v49, v49
	s_nop 0
	v_pk_mul_f32 v[44:45], v[44:45], v[48:49]
	s_nop 0
	v_cvt_pk_f16_f32 v48, v44, v45
	v_cvt_f32_f16_e32 v44, v95
	v_cvt_f32_f16_sdwa v45, v95 dst_sel:DWORD dst_unused:UNUSED_PAD src0_sel:WORD_1
	v_pk_mul_f32 v[44:45], v[30:31], v[44:45]
	s_nop 0
	v_pk_fma_f32 v[44:45], v[46:47], s[38:39], v[44:45] op_sel_hi:[1,0,1]
	s_nop 0
	v_mul_f32_e32 v46, 0x3d372713, v44
	v_mul_f32_e32 v47, 0x3d372713, v45
	v_mul_f32_e32 v46, v44, v46
	v_mul_f32_e32 v47, v45, v47
	v_fma_f32 v46, v44, v46, v44
	v_fma_f32 v47, v45, v47, v45
	v_mul_f32_e32 v46, 0x3f4c422a, v46
	v_mul_f32_e32 v47, 0x3f4c422a, v47
	v_mul_f32_e32 v46, -2.0, v46
	v_mul_f32_e32 v47, -2.0, v47
	v_mul_f32_e32 v46, 0x3fb8aa3b, v46
	v_mul_f32_e32 v47, 0x3fb8aa3b, v47
	v_exp_f32_e32 v46, v46
	v_exp_f32_e32 v47, v47
	v_add_f32_e32 v46, 1.0, v46
	v_add_f32_e32 v47, 1.0, v47
	v_rcp_f32_e32 v46, v46
	v_rcp_f32_e32 v47, v47
	s_nop 0
	v_pk_mul_f32 v[44:45], v[44:45], v[46:47]
	s_nop 0
	v_cvt_pk_f16_f32 v47, v44, v45
	v_lshrrev_b32_e32 v45, 4, v48
	v_and_b32_e32 v45, 0x10001, v45
	v_add3_u32 v45, v48, v45, s21
	v_lshrrev_b32_e32 v48, 4, v47
	v_and_b32_e32 v48, 0x10001, v48
	v_add3_u32 v47, v47, v48, s21
	v_add_u32_e32 v48, v140, v60
	v_ashrrev_i32_e32 v49, 31, v48
	v_lshrrev_b32_e32 v44, 4, v52
	v_lshrrev_b32_e32 v46, 4, v53
	v_lshlrev_b64 v[48:49], 10, v[48:49]
	v_and_b32_e32 v44, 0x10001, v44
	v_and_b32_e32 v46, 0x10001, v46
	v_lshl_add_u64 v[48:49], s[16:17], 0, v[48:49]
	v_add3_u32 v44, v52, v44, s21
	v_add3_u32 v46, v53, v46, s21
	v_lshl_add_u64 v[48:49], v[48:49], 0, s[42:43]
	v_and_b32_e32 v44, 0xfff0fff0, v44
	v_and_b32_e32 v45, 0xfff0fff0, v45
	v_and_b32_e32 v46, 0xfff0fff0, v46
	v_and_b32_e32 v47, 0xfff0fff0, v47
	v_lshl_add_u64 v[48:49], v[48:49], 0, v[2:3]
	global_store_dwordx4 v[48:49], v[44:47], off
	s_nop 1
	v_cvt_f32_f16_e32 v46, v88
	v_cvt_f32_f16_sdwa v47, v88 dst_sel:DWORD dst_unused:UNUSED_PAD src0_sel:WORD_1
	v_add_u32_e32 v44, 0xa00, v192
	v_pk_mul_f32 v[46:47], v[32:33], v[46:47]
	s_nop 0
	v_pk_fma_f32 v[40:41], v[40:41], s[38:39], v[46:47] op_sel_hi:[1,0,1]
	s_nop 0
	v_mul_f32_e32 v45, 0x3d372713, v40
	v_mul_f32_e32 v45, v40, v45
	v_fma_f32 v45, v40, v45, v40
	v_mul_f32_e32 v45, 0x3f4c422a, v45
	v_mul_f32_e32 v45, -2.0, v45
	v_mul_f32_e32 v45, 0x3fb8aa3b, v45
	v_exp_f32_e32 v45, v45
	s_nop 0
	v_add_f32_e32 v45, 1.0, v45
	v_rcp_f32_e32 v46, v45
	v_mul_f32_e32 v45, 0x3d372713, v41
	v_mul_f32_e32 v45, v41, v45
	v_fma_f32 v45, v41, v45, v41
	v_mul_f32_e32 v45, 0x3f4c422a, v45
	v_mul_f32_e32 v45, -2.0, v45
	v_mul_f32_e32 v45, 0x3fb8aa3b, v45
	v_exp_f32_e32 v45, v45
	s_nop 0
	v_add_f32_e32 v45, 1.0, v45
	v_rcp_f32_e32 v47, v45
	s_nop 0
	v_pk_mul_f32 v[40:41], v[40:41], v[46:47]
	s_nop 0
	v_cvt_pk_f16_f32 v45, v40, v41
	v_cvt_f32_f16_e32 v40, v90
	v_cvt_f32_f16_sdwa v41, v90 dst_sel:DWORD dst_unused:UNUSED_PAD src0_sel:WORD_1
	v_pk_mul_f32 v[40:41], v[28:29], v[40:41]
	s_nop 0
	v_pk_fma_f32 v[36:37], v[36:37], s[38:39], v[40:41] op_sel_hi:[1,0,1]
	s_nop 0
	v_mul_f32_e32 v40, 0x3d372713, v36
	v_mul_f32_e32 v41, 0x3d372713, v37
	v_mul_f32_e32 v40, v36, v40
	v_mul_f32_e32 v41, v37, v41
	v_fma_f32 v40, v36, v40, v36
	v_fma_f32 v41, v37, v41, v37
	v_mul_f32_e32 v40, 0x3f4c422a, v40
	v_mul_f32_e32 v41, 0x3f4c422a, v41
	v_mul_f32_e32 v40, -2.0, v40
	v_mul_f32_e32 v41, -2.0, v41
	v_mul_f32_e32 v40, 0x3fb8aa3b, v40
	v_mul_f32_e32 v41, 0x3fb8aa3b, v41
	v_exp_f32_e32 v40, v40
	v_exp_f32_e32 v41, v41
	v_add_f32_e32 v40, 1.0, v40
	v_add_f32_e32 v41, 1.0, v41
	v_rcp_f32_e32 v40, v40
	v_rcp_f32_e32 v41, v41
	s_nop 0
	v_pk_mul_f32 v[36:37], v[36:37], v[40:41]
	s_nop 0
	v_cvt_pk_f16_f32 v46, v36, v37
	v_cvt_f32_f16_e32 v36, v89
	v_cvt_f32_f16_sdwa v37, v89 dst_sel:DWORD dst_unused:UNUSED_PAD src0_sel:WORD_1
	v_pk_mul_f32 v[36:37], v[34:35], v[36:37]
	s_nop 0
	v_pk_fma_f32 v[36:37], v[42:43], s[38:39], v[36:37] op_sel_hi:[1,0,1]
	s_nop 0
	v_mul_f32_e32 v40, 0x3d372713, v36
	v_mul_f32_e32 v41, 0x3d372713, v37
	v_mul_f32_e32 v40, v36, v40
	v_mul_f32_e32 v41, v37, v41
	v_fma_f32 v40, v36, v40, v36
	v_fma_f32 v41, v37, v41, v37
	v_mul_f32_e32 v40, 0x3f4c422a, v40
	v_mul_f32_e32 v41, 0x3f4c422a, v41
	v_mul_f32_e32 v40, -2.0, v40
	v_mul_f32_e32 v41, -2.0, v41
	v_mul_f32_e32 v40, 0x3fb8aa3b, v40
	v_mul_f32_e32 v41, 0x3fb8aa3b, v41
	v_exp_f32_e32 v40, v40
	v_exp_f32_e32 v41, v41
	v_add_f32_e32 v40, 1.0, v40
	v_add_f32_e32 v41, 1.0, v41
	v_rcp_f32_e32 v40, v40
	v_rcp_f32_e32 v41, v41
	s_nop 0
	v_pk_mul_f32 v[36:37], v[36:37], v[40:41]
	s_nop 0
	v_cvt_pk_f16_f32 v40, v36, v37
	v_cvt_f32_f16_e32 v36, v91
	v_cvt_f32_f16_sdwa v37, v91 dst_sel:DWORD dst_unused:UNUSED_PAD src0_sel:WORD_1
	v_pk_mul_f32 v[36:37], v[30:31], v[36:37]
	s_nop 0
	v_pk_fma_f32 v[36:37], v[38:39], s[38:39], v[36:37] op_sel_hi:[1,0,1]
	s_nop 0
	v_mul_f32_e32 v38, 0x3d372713, v36
	v_mul_f32_e32 v39, 0x3d372713, v37
	v_mul_f32_e32 v38, v36, v38
	v_mul_f32_e32 v39, v37, v39
	v_fma_f32 v38, v36, v38, v36
	v_fma_f32 v39, v37, v39, v37
	v_mul_f32_e32 v38, 0x3f4c422a, v38
	v_mul_f32_e32 v39, 0x3f4c422a, v39
	v_mul_f32_e32 v38, -2.0, v38
	v_mul_f32_e32 v39, -2.0, v39
	v_mul_f32_e32 v38, 0x3fb8aa3b, v38
	v_mul_f32_e32 v39, 0x3fb8aa3b, v39
	v_exp_f32_e32 v38, v38
	v_exp_f32_e32 v39, v39
	v_add_f32_e32 v38, 1.0, v38
	v_add_f32_e32 v39, 1.0, v39
	v_rcp_f32_e32 v38, v38
	v_rcp_f32_e32 v39, v39
	s_nop 0
	v_pk_mul_f32 v[36:37], v[36:37], v[38:39]
	s_nop 0
	v_cvt_pk_f16_f32 v39, v36, v37
	v_lshrrev_b32_e32 v37, 4, v40
	v_and_b32_e32 v37, 0x10001, v37
	v_add3_u32 v37, v40, v37, s21
	v_lshrrev_b32_e32 v40, 4, v39
	v_and_b32_e32 v40, 0x10001, v40
	v_add3_u32 v39, v39, v40, s21
	v_add_u32_e32 v40, v152, v44
	v_ashrrev_i32_e32 v41, 31, v40
	v_lshrrev_b32_e32 v36, 4, v45
	v_lshrrev_b32_e32 v38, 4, v46
	v_lshlrev_b64 v[40:41], 10, v[40:41]
	v_and_b32_e32 v36, 0x10001, v36
	v_and_b32_e32 v38, 0x10001, v38
	v_lshl_add_u64 v[40:41], s[16:17], 0, v[40:41]
	v_add3_u32 v36, v45, v36, s21
	v_add3_u32 v38, v46, v38, s21
	v_lshl_add_u64 v[40:41], v[40:41], 0, s[42:43]
	v_and_b32_e32 v36, 0xfff0fff0, v36
	v_and_b32_e32 v37, 0xfff0fff0, v37
	v_and_b32_e32 v38, 0xfff0fff0, v38
	v_and_b32_e32 v39, 0xfff0fff0, v39
	v_lshl_add_u64 v[40:41], v[40:41], 0, v[2:3]
	global_store_dwordx4 v[40:41], v[36:39], off
	s_nop 1
	v_cvt_f32_f16_e32 v36, v84
	v_cvt_f32_f16_sdwa v37, v84 dst_sel:DWORD dst_unused:UNUSED_PAD src0_sel:WORD_1
	v_pk_mul_f32 v[36:37], v[32:33], v[36:37]
	s_nop 0
	v_pk_fma_f32 v[24:25], v[24:25], s[38:39], v[36:37] op_sel_hi:[1,0,1]
	s_nop 0
	v_mul_f32_e32 v36, 0x3d372713, v24
	v_mul_f32_e32 v37, 0x3d372713, v25
	v_mul_f32_e32 v36, v24, v36
	v_mul_f32_e32 v37, v25, v37
	v_fma_f32 v36, v24, v36, v24
	v_fma_f32 v37, v25, v37, v25
	v_mul_f32_e32 v36, 0x3f4c422a, v36
	v_mul_f32_e32 v37, 0x3f4c422a, v37
	v_mul_f32_e32 v36, -2.0, v36
	v_mul_f32_e32 v37, -2.0, v37
	v_mul_f32_e32 v36, 0x3fb8aa3b, v36
	v_mul_f32_e32 v37, 0x3fb8aa3b, v37
	v_exp_f32_e32 v36, v36
	v_exp_f32_e32 v37, v37
	v_add_f32_e32 v36, 1.0, v36
	v_add_f32_e32 v37, 1.0, v37
	v_rcp_f32_e32 v36, v36
	v_rcp_f32_e32 v37, v37
	s_nop 0
	v_pk_mul_f32 v[24:25], v[24:25], v[36:37]
	s_nop 0
	v_cvt_pk_f16_f32 v36, v24, v25
	v_cvt_f32_f16_e32 v24, v86
	v_cvt_f32_f16_sdwa v25, v86 dst_sel:DWORD dst_unused:UNUSED_PAD src0_sel:WORD_1
	v_pk_mul_f32 v[24:25], v[28:29], v[24:25]
	s_nop 0
	v_pk_fma_f32 v[20:21], v[20:21], s[38:39], v[24:25] op_sel_hi:[1,0,1]
	s_nop 0
	v_mul_f32_e32 v24, 0x3d372713, v20
	v_mul_f32_e32 v25, 0x3d372713, v21
	v_mul_f32_e32 v24, v20, v24
	v_mul_f32_e32 v25, v21, v25
	v_fma_f32 v24, v20, v24, v20
	v_fma_f32 v25, v21, v25, v21
	v_mul_f32_e32 v24, 0x3f4c422a, v24
	v_mul_f32_e32 v25, 0x3f4c422a, v25
	v_mul_f32_e32 v24, -2.0, v24
	v_mul_f32_e32 v25, -2.0, v25
	v_mul_f32_e32 v24, 0x3fb8aa3b, v24
	v_mul_f32_e32 v25, 0x3fb8aa3b, v25
	v_exp_f32_e32 v24, v24
	v_exp_f32_e32 v25, v25
	v_add_f32_e32 v24, 1.0, v24
	v_add_f32_e32 v25, 1.0, v25
	v_rcp_f32_e32 v24, v24
	v_rcp_f32_e32 v25, v25
	s_nop 0
	v_pk_mul_f32 v[20:21], v[20:21], v[24:25]
	s_nop 0
	v_cvt_pk_f16_f32 v37, v20, v21
	v_cvt_f32_f16_e32 v20, v85
	v_cvt_f32_f16_sdwa v21, v85 dst_sel:DWORD dst_unused:UNUSED_PAD src0_sel:WORD_1
	v_pk_mul_f32 v[20:21], v[34:35], v[20:21]
	s_nop 0
	v_pk_fma_f32 v[20:21], v[26:27], s[38:39], v[20:21] op_sel_hi:[1,0,1]
	s_nop 0
	v_mul_f32_e32 v24, 0x3d372713, v20
	v_mul_f32_e32 v25, 0x3d372713, v21
	v_mul_f32_e32 v24, v20, v24
	v_mul_f32_e32 v25, v21, v25
	v_fma_f32 v24, v20, v24, v20
	v_fma_f32 v25, v21, v25, v21
	v_mul_f32_e32 v24, 0x3f4c422a, v24
	v_mul_f32_e32 v25, 0x3f4c422a, v25
	v_mul_f32_e32 v24, -2.0, v24
	v_mul_f32_e32 v25, -2.0, v25
	v_mul_f32_e32 v24, 0x3fb8aa3b, v24
	v_mul_f32_e32 v25, 0x3fb8aa3b, v25
	v_exp_f32_e32 v24, v24
	v_exp_f32_e32 v25, v25
	v_add_f32_e32 v24, 1.0, v24
	v_add_f32_e32 v25, 1.0, v25
	v_rcp_f32_e32 v24, v24
	v_rcp_f32_e32 v25, v25
	s_nop 0
	v_pk_mul_f32 v[20:21], v[20:21], v[24:25]
	s_nop 0
	v_cvt_pk_f16_f32 v24, v20, v21
	v_cvt_f32_f16_e32 v20, v87
	v_cvt_f32_f16_sdwa v21, v87 dst_sel:DWORD dst_unused:UNUSED_PAD src0_sel:WORD_1
	v_pk_mul_f32 v[20:21], v[30:31], v[20:21]
	s_nop 0
	v_pk_fma_f32 v[20:21], v[22:23], s[38:39], v[20:21] op_sel_hi:[1,0,1]
	s_nop 0
	v_mul_f32_e32 v22, 0x3d372713, v20
	v_mul_f32_e32 v23, 0x3d372713, v21
	v_mul_f32_e32 v22, v20, v22
	v_mul_f32_e32 v23, v21, v23
	v_fma_f32 v22, v20, v22, v20
	v_fma_f32 v23, v21, v23, v21
	v_mul_f32_e32 v22, 0x3f4c422a, v22
	v_mul_f32_e32 v23, 0x3f4c422a, v23
	v_mul_f32_e32 v22, -2.0, v22
	v_mul_f32_e32 v23, -2.0, v23
	v_mul_f32_e32 v22, 0x3fb8aa3b, v22
	v_mul_f32_e32 v23, 0x3fb8aa3b, v23
	v_exp_f32_e32 v22, v22
	v_exp_f32_e32 v23, v23
	v_add_f32_e32 v22, 1.0, v22
	v_add_f32_e32 v23, 1.0, v23
	v_rcp_f32_e32 v22, v22
	v_rcp_f32_e32 v23, v23
	s_nop 0
	v_pk_mul_f32 v[20:21], v[20:21], v[22:23]
	s_nop 0
	v_cvt_pk_f16_f32 v23, v20, v21
	v_lshrrev_b32_e32 v21, 4, v24
	v_and_b32_e32 v21, 0x10001, v21
	v_add3_u32 v21, v24, v21, s21
	v_lshrrev_b32_e32 v24, 4, v23
	v_and_b32_e32 v24, 0x10001, v24
	v_add3_u32 v23, v23, v24, s21
	v_add_u32_e32 v24, v140, v44
	v_ashrrev_i32_e32 v25, 31, v24
	v_lshrrev_b32_e32 v20, 4, v36
	v_lshrrev_b32_e32 v22, 4, v37
	v_lshlrev_b64 v[24:25], 10, v[24:25]
	v_and_b32_e32 v20, 0x10001, v20
	v_and_b32_e32 v22, 0x10001, v22
	v_lshl_add_u64 v[24:25], s[16:17], 0, v[24:25]
	v_add3_u32 v20, v36, v20, s21
	v_add3_u32 v22, v37, v22, s21
	v_lshl_add_u64 v[24:25], v[24:25], 0, s[42:43]
	v_and_b32_e32 v20, 0xfff0fff0, v20
	v_and_b32_e32 v21, 0xfff0fff0, v21
	v_and_b32_e32 v22, 0xfff0fff0, v22
	v_and_b32_e32 v23, 0xfff0fff0, v23
	v_lshl_add_u64 v[24:25], v[24:25], 0, v[2:3]
	global_store_dwordx4 v[24:25], v[20:23], off
	s_nop 1
	v_cvt_f32_f16_e32 v22, v80
	v_cvt_f32_f16_sdwa v23, v80 dst_sel:DWORD dst_unused:UNUSED_PAD src0_sel:WORD_1
	v_add_u32_e32 v20, 0xb00, v192
	v_pk_mul_f32 v[22:23], v[32:33], v[22:23]
	s_nop 0
	v_pk_fma_f32 v[16:17], v[16:17], s[38:39], v[22:23] op_sel_hi:[1,0,1]
	s_nop 0
	v_mul_f32_e32 v21, 0x3d372713, v16
	v_mul_f32_e32 v21, v16, v21
	v_fma_f32 v21, v16, v21, v16
	v_mul_f32_e32 v21, 0x3f4c422a, v21
	v_mul_f32_e32 v21, -2.0, v21
	v_mul_f32_e32 v21, 0x3fb8aa3b, v21
	v_exp_f32_e32 v21, v21
	s_nop 0
	v_add_f32_e32 v21, 1.0, v21
	v_rcp_f32_e32 v22, v21
	v_mul_f32_e32 v21, 0x3d372713, v17
	v_mul_f32_e32 v21, v17, v21
	v_fma_f32 v21, v17, v21, v17
	v_mul_f32_e32 v21, 0x3f4c422a, v21
	v_mul_f32_e32 v21, -2.0, v21
	v_mul_f32_e32 v21, 0x3fb8aa3b, v21
	v_exp_f32_e32 v21, v21
	s_nop 0
	v_add_f32_e32 v21, 1.0, v21
	v_rcp_f32_e32 v23, v21
	s_nop 0
	v_pk_mul_f32 v[16:17], v[16:17], v[22:23]
	s_nop 0
	v_cvt_pk_f16_f32 v21, v16, v17
	v_cvt_f32_f16_e32 v16, v82
	v_cvt_f32_f16_sdwa v17, v82 dst_sel:DWORD dst_unused:UNUSED_PAD src0_sel:WORD_1
	v_pk_mul_f32 v[16:17], v[28:29], v[16:17]
	s_nop 0
	v_pk_fma_f32 v[12:13], v[12:13], s[38:39], v[16:17] op_sel_hi:[1,0,1]
	s_nop 0
	v_mul_f32_e32 v16, 0x3d372713, v12
	v_mul_f32_e32 v17, 0x3d372713, v13
	v_mul_f32_e32 v16, v12, v16
	v_mul_f32_e32 v17, v13, v17
	v_fma_f32 v16, v12, v16, v12
	v_fma_f32 v17, v13, v17, v13
	v_mul_f32_e32 v16, 0x3f4c422a, v16
	v_mul_f32_e32 v17, 0x3f4c422a, v17
	v_mul_f32_e32 v16, -2.0, v16
	v_mul_f32_e32 v17, -2.0, v17
	v_mul_f32_e32 v16, 0x3fb8aa3b, v16
	v_mul_f32_e32 v17, 0x3fb8aa3b, v17
	v_exp_f32_e32 v16, v16
	v_exp_f32_e32 v17, v17
	v_add_f32_e32 v16, 1.0, v16
	v_add_f32_e32 v17, 1.0, v17
	v_rcp_f32_e32 v16, v16
	v_rcp_f32_e32 v17, v17
	s_nop 0
	v_pk_mul_f32 v[12:13], v[12:13], v[16:17]
	s_nop 0
	v_cvt_pk_f16_f32 v22, v12, v13
	v_cvt_f32_f16_e32 v12, v81
	v_cvt_f32_f16_sdwa v13, v81 dst_sel:DWORD dst_unused:UNUSED_PAD src0_sel:WORD_1
	v_pk_mul_f32 v[12:13], v[34:35], v[12:13]
	s_nop 0
	v_pk_fma_f32 v[12:13], v[18:19], s[38:39], v[12:13] op_sel_hi:[1,0,1]
	s_nop 0
	v_mul_f32_e32 v16, 0x3d372713, v12
	v_mul_f32_e32 v17, 0x3d372713, v13
	v_mul_f32_e32 v16, v12, v16
	v_mul_f32_e32 v17, v13, v17
	v_fma_f32 v16, v12, v16, v12
	v_fma_f32 v17, v13, v17, v13
	v_mul_f32_e32 v16, 0x3f4c422a, v16
	v_mul_f32_e32 v17, 0x3f4c422a, v17
	v_mul_f32_e32 v16, -2.0, v16
	v_mul_f32_e32 v17, -2.0, v17
	v_mul_f32_e32 v16, 0x3fb8aa3b, v16
	v_mul_f32_e32 v17, 0x3fb8aa3b, v17
	v_exp_f32_e32 v16, v16
	v_exp_f32_e32 v17, v17
	v_add_f32_e32 v16, 1.0, v16
	v_add_f32_e32 v17, 1.0, v17
	v_rcp_f32_e32 v16, v16
	v_rcp_f32_e32 v17, v17
	s_nop 0
	v_pk_mul_f32 v[12:13], v[12:13], v[16:17]
	s_nop 0
	v_cvt_pk_f16_f32 v16, v12, v13
	v_cvt_f32_f16_e32 v12, v83
	v_cvt_f32_f16_sdwa v13, v83 dst_sel:DWORD dst_unused:UNUSED_PAD src0_sel:WORD_1
	v_pk_mul_f32 v[12:13], v[30:31], v[12:13]
	s_nop 0
	v_pk_fma_f32 v[12:13], v[14:15], s[38:39], v[12:13] op_sel_hi:[1,0,1]
	s_nop 0
	v_mul_f32_e32 v14, 0x3d372713, v12
	v_mul_f32_e32 v15, 0x3d372713, v13
	v_mul_f32_e32 v14, v12, v14
	v_mul_f32_e32 v15, v13, v15
	v_fma_f32 v14, v12, v14, v12
	v_fma_f32 v15, v13, v15, v13
	v_mul_f32_e32 v14, 0x3f4c422a, v14
	v_mul_f32_e32 v15, 0x3f4c422a, v15
	v_mul_f32_e32 v14, -2.0, v14
	v_mul_f32_e32 v15, -2.0, v15
	v_mul_f32_e32 v14, 0x3fb8aa3b, v14
	v_mul_f32_e32 v15, 0x3fb8aa3b, v15
	v_exp_f32_e32 v14, v14
	v_exp_f32_e32 v15, v15
	v_add_f32_e32 v14, 1.0, v14
	v_add_f32_e32 v15, 1.0, v15
	v_rcp_f32_e32 v14, v14
	v_rcp_f32_e32 v15, v15
	s_nop 0
	v_pk_mul_f32 v[12:13], v[12:13], v[14:15]
	s_nop 0
	v_cvt_pk_f16_f32 v15, v12, v13
	v_lshrrev_b32_e32 v13, 4, v16
	v_and_b32_e32 v13, 0x10001, v13
	v_add3_u32 v13, v16, v13, s21
	v_lshrrev_b32_e32 v16, 4, v15
	v_and_b32_e32 v16, 0x10001, v16
	v_add3_u32 v15, v15, v16, s21
	v_add_u32_e32 v16, v152, v20
	v_ashrrev_i32_e32 v17, 31, v16
	v_lshrrev_b32_e32 v12, 4, v21
	v_lshrrev_b32_e32 v14, 4, v22
	v_lshlrev_b64 v[16:17], 10, v[16:17]
	v_and_b32_e32 v12, 0x10001, v12
	v_and_b32_e32 v14, 0x10001, v14
	v_lshl_add_u64 v[16:17], s[16:17], 0, v[16:17]
	v_add3_u32 v12, v21, v12, s21
	v_add3_u32 v14, v22, v14, s21
	v_lshl_add_u64 v[16:17], v[16:17], 0, s[42:43]
	v_and_b32_e32 v12, 0xfff0fff0, v12
	v_and_b32_e32 v13, 0xfff0fff0, v13
	v_and_b32_e32 v14, 0xfff0fff0, v14
	v_and_b32_e32 v15, 0xfff0fff0, v15
	v_lshl_add_u64 v[16:17], v[16:17], 0, v[2:3]
	global_store_dwordx4 v[16:17], v[12:15], off
	s_nop 1
	v_cvt_f32_f16_e32 v12, v76
	v_cvt_f32_f16_sdwa v13, v76 dst_sel:DWORD dst_unused:UNUSED_PAD src0_sel:WORD_1
	v_pk_mul_f32 v[12:13], v[32:33], v[12:13]
	s_nop 0
	v_pk_fma_f32 v[8:9], v[8:9], s[38:39], v[12:13] op_sel_hi:[1,0,1]
	s_nop 0
	v_mul_f32_e32 v12, 0x3d372713, v8
	v_mul_f32_e32 v13, 0x3d372713, v9
	v_mul_f32_e32 v12, v8, v12
	v_mul_f32_e32 v13, v9, v13
	v_fma_f32 v12, v8, v12, v8
	v_fma_f32 v13, v9, v13, v9
	v_mul_f32_e32 v12, 0x3f4c422a, v12
	v_mul_f32_e32 v13, 0x3f4c422a, v13
	v_mul_f32_e32 v12, -2.0, v12
	v_mul_f32_e32 v13, -2.0, v13
	v_mul_f32_e32 v12, 0x3fb8aa3b, v12
	v_mul_f32_e32 v13, 0x3fb8aa3b, v13
	v_exp_f32_e32 v12, v12
	v_exp_f32_e32 v13, v13
	v_add_f32_e32 v12, 1.0, v12
	v_add_f32_e32 v13, 1.0, v13
	v_rcp_f32_e32 v12, v12
	v_rcp_f32_e32 v13, v13
	s_nop 0
	v_pk_mul_f32 v[8:9], v[8:9], v[12:13]
	s_nop 0
	v_cvt_pk_f16_f32 v12, v8, v9
	v_cvt_f32_f16_e32 v8, v78
	v_cvt_f32_f16_sdwa v9, v78 dst_sel:DWORD dst_unused:UNUSED_PAD src0_sel:WORD_1
	v_pk_mul_f32 v[8:9], v[28:29], v[8:9]
	s_nop 0
	v_pk_fma_f32 v[4:5], v[4:5], s[38:39], v[8:9] op_sel_hi:[1,0,1]
	s_nop 0
	v_mul_f32_e32 v8, 0x3d372713, v4
	v_mul_f32_e32 v9, 0x3d372713, v5
	v_mul_f32_e32 v8, v4, v8
	v_mul_f32_e32 v9, v5, v9
	v_fma_f32 v8, v4, v8, v4
	v_fma_f32 v9, v5, v9, v5
	v_mul_f32_e32 v8, 0x3f4c422a, v8
	v_mul_f32_e32 v9, 0x3f4c422a, v9
	v_mul_f32_e32 v8, -2.0, v8
	v_mul_f32_e32 v9, -2.0, v9
	v_mul_f32_e32 v8, 0x3fb8aa3b, v8
	v_mul_f32_e32 v9, 0x3fb8aa3b, v9
	v_exp_f32_e32 v8, v8
	v_exp_f32_e32 v9, v9
	v_add_f32_e32 v8, 1.0, v8
	v_add_f32_e32 v9, 1.0, v9
	v_rcp_f32_e32 v8, v8
	v_rcp_f32_e32 v9, v9
	s_nop 0
	v_pk_mul_f32 v[4:5], v[4:5], v[8:9]
	s_nop 0
	v_cvt_pk_f16_f32 v13, v4, v5
	v_cvt_f32_f16_e32 v4, v77
	v_cvt_f32_f16_sdwa v5, v77 dst_sel:DWORD dst_unused:UNUSED_PAD src0_sel:WORD_1
	v_pk_mul_f32 v[4:5], v[34:35], v[4:5]
	s_nop 0
	v_pk_fma_f32 v[4:5], v[10:11], s[38:39], v[4:5] op_sel_hi:[1,0,1]
	s_nop 0
	v_mul_f32_e32 v8, 0x3d372713, v4
	v_mul_f32_e32 v9, 0x3d372713, v5
	v_mul_f32_e32 v8, v4, v8
	v_mul_f32_e32 v9, v5, v9
	v_fma_f32 v8, v4, v8, v4
	v_fma_f32 v9, v5, v9, v5
	v_mul_f32_e32 v8, 0x3f4c422a, v8
	v_mul_f32_e32 v9, 0x3f4c422a, v9
	v_mul_f32_e32 v8, -2.0, v8
	v_mul_f32_e32 v9, -2.0, v9
	v_mul_f32_e32 v8, 0x3fb8aa3b, v8
	v_mul_f32_e32 v9, 0x3fb8aa3b, v9
	v_exp_f32_e32 v8, v8
	v_exp_f32_e32 v9, v9
	v_add_f32_e32 v8, 1.0, v8
	v_add_f32_e32 v9, 1.0, v9
	v_rcp_f32_e32 v8, v8
	v_rcp_f32_e32 v9, v9
	s_nop 0
	v_pk_mul_f32 v[4:5], v[4:5], v[8:9]
	s_nop 0
	v_cvt_pk_f16_f32 v8, v4, v5
	v_cvt_f32_f16_e32 v4, v79
	v_cvt_f32_f16_sdwa v5, v79 dst_sel:DWORD dst_unused:UNUSED_PAD src0_sel:WORD_1
	v_pk_mul_f32 v[4:5], v[30:31], v[4:5]
	s_nop 0
	v_pk_fma_f32 v[4:5], v[6:7], s[38:39], v[4:5] op_sel_hi:[1,0,1]
	s_mov_b64 s[38:39], s[36:37]
	v_mul_f32_e32 v6, 0x3d372713, v4
	v_mul_f32_e32 v7, 0x3d372713, v5
	v_mul_f32_e32 v6, v4, v6
	v_mul_f32_e32 v7, v5, v7
	v_fma_f32 v6, v4, v6, v4
	v_fma_f32 v7, v5, v7, v5
	v_mul_f32_e32 v6, 0x3f4c422a, v6
	v_mul_f32_e32 v7, 0x3f4c422a, v7
	v_mul_f32_e32 v6, -2.0, v6
	v_mul_f32_e32 v7, -2.0, v7
	v_mul_f32_e32 v6, 0x3fb8aa3b, v6
	v_mul_f32_e32 v7, 0x3fb8aa3b, v7
	v_exp_f32_e32 v6, v6
	v_exp_f32_e32 v7, v7
	v_add_f32_e32 v6, 1.0, v6
	v_add_f32_e32 v7, 1.0, v7
	v_rcp_f32_e32 v6, v6
	v_rcp_f32_e32 v7, v7
	s_nop 0
	v_pk_mul_f32 v[4:5], v[4:5], v[6:7]
	s_nop 0
	v_cvt_pk_f16_f32 v7, v4, v5
	v_lshrrev_b32_e32 v5, 4, v8
	v_and_b32_e32 v5, 0x10001, v5
	v_add3_u32 v5, v8, v5, s21
	v_lshrrev_b32_e32 v8, 4, v7
	v_and_b32_e32 v8, 0x10001, v8
	v_add3_u32 v7, v7, v8, s21
	v_add_u32_e32 v8, v140, v20
	v_ashrrev_i32_e32 v9, 31, v8
	v_lshrrev_b32_e32 v4, 4, v12
	v_lshrrev_b32_e32 v6, 4, v13
	v_lshlrev_b64 v[8:9], 10, v[8:9]
	v_and_b32_e32 v4, 0x10001, v4
	v_and_b32_e32 v6, 0x10001, v6
	v_lshl_add_u64 v[8:9], s[16:17], 0, v[8:9]
	v_add3_u32 v4, v12, v4, s21
	v_add3_u32 v6, v13, v6, s21
	v_lshl_add_u64 v[8:9], v[8:9], 0, s[42:43]
	v_and_b32_e32 v4, 0xfff0fff0, v4
	v_and_b32_e32 v5, 0xfff0fff0, v5
	v_and_b32_e32 v6, 0xfff0fff0, v6
	v_and_b32_e32 v7, 0xfff0fff0, v7
	v_lshl_add_u64 v[8:9], v[8:9], 0, v[2:3]
	global_store_dwordx4 v[8:9], v[4:7], off
	s_mov_b32 s16, s47
	s_cbranch_vccz .LBB0_1338
	s_waitcnt vmcnt(0)
	s_cmpk_gt_u32 s5, 0xff
	s_cbranch_scc1 .LBB0_1345
	s_barrier

.LBB0_1664:
	s_add_u32 s15, s46, 0xfffe0080
	s_addc_u32 s29, s47, -1
	s_add_i32 s30, 0, 0x10000
	v_add_u32_e32 v56, s30, v208
	ds_read_b128 v[32:35], v56
	ds_read_b128 v[40:43], v56 offset:1024
	ds_read_b128 v[48:51], v56 offset:2048
	ds_read_b128 v[56:59], v56 offset:3072
	s_cmp_eq_u32 s14, 4
	s_cselect_b32 s49, s43, s29
	s_cselect_b32 s48, s42, s15
	s_cselect_b32 s39, s45, s11
	s_cselect_b32 s38, s44, s10
	s_add_i32 m0, s8, 0xc000
	ds_read_b128 v[108:111], v209
	ds_read_b128 v[120:123], v209 offset:1024
	ds_read_b128 v[132:135], v209 offset:2048
	ds_read_b128 v[144:147], v209 offset:3072
	ds_read_b128 v[156:159], v209 offset:4096
	ds_read_b128 v[168:171], v209 offset:5120
	ds_read_b128 v[172:175], v209 offset:6144
	ds_read_b128 v[176:179], v209 offset:7168
	global_load_lds_dwordx4 v186, s[46:47]
	s_add_i32 m0, s8, 0xe000
	s_nop 0
	global_load_lds_dwordx4 v188, s[46:47]
	s_waitcnt vmcnt(10)
	s_barrier
	s_waitcnt lgkmcnt(0)
	v_mfma_f32_16x16x32_f16 v[164:167], v[32:35], v[108:111], v[164:167]
	v_mfma_f32_16x16x32_f16 v[160:163], v[48:51], v[108:111], v[160:163]
	v_mfma_f32_16x16x32_f16 v[140:143], v[32:35], v[132:135], v[140:143]
	v_mfma_f32_16x16x32_f16 v[136:139], v[48:51], v[132:135], v[136:139]
	v_mfma_f32_16x16x32_f16 v[116:119], v[32:35], v[156:159], v[116:119]
	v_mfma_f32_16x16x32_f16 v[112:115], v[48:51], v[156:159], v[112:115]
	v_mfma_f32_16x16x32_f16 v[96:99], v[32:35], v[172:175], v[96:99]
	v_mfma_f32_16x16x32_f16 v[92:95], v[48:51], v[172:175], v[92:95]
	v_mfma_f32_16x16x32_f16 v[164:167], v[40:43], v[120:123], v[164:167]
	v_mfma_f32_16x16x32_f16 v[160:163], v[56:59], v[120:123], v[160:163]
	v_mfma_f32_16x16x32_f16 v[140:143], v[40:43], v[144:147], v[140:143]
	v_mfma_f32_16x16x32_f16 v[136:139], v[56:59], v[144:147], v[136:139]
	v_mfma_f32_16x16x32_f16 v[116:119], v[40:43], v[168:171], v[116:119]
	v_mfma_f32_16x16x32_f16 v[112:115], v[56:59], v[168:171], v[112:115]
	v_mfma_f32_16x16x32_f16 v[96:99], v[40:43], v[176:179], v[96:99]
	v_mfma_f32_16x16x32_f16 v[92:95], v[56:59], v[176:179], v[92:95]
	s_barrier
	s_add_i32 s15, 0, 0x14000
	v_add_u32_e32 v202, s15, v208
	s_add_i32 s29, s30, s7
	ds_read_b128 v[190:193], v202
	ds_read_b128 v[194:197], v202 offset:1024
	ds_read_b128 v[198:201], v202 offset:2048
	ds_read_b128 v[210:213], v202 offset:3072
	v_lshl_add_u64 v[202:203], s[38:39], 0, v[2:3]
	s_mov_b32 m0, s29
	v_lshl_add_u64 v[218:219], s[38:39], 0, v[184:185]
	global_load_lds_dwordx4 v[202:203], off
	s_add_i32 m0, s29, 0x2000
	s_nop 0
	global_load_lds_dwordx4 v[218:219], off
	s_waitcnt vmcnt(10)
	s_barrier
	s_waitcnt lgkmcnt(0)
	v_mfma_f32_16x16x32_f16 v[152:155], v[190:193], v[108:111], v[152:155]
	v_mfma_f32_16x16x32_f16 v[108:111], v[198:201], v[108:111], v[148:151]
	v_mfma_f32_16x16x32_f16 v[124:127], v[198:201], v[132:135], v[124:127]
	v_mfma_f32_16x16x32_f16 v[104:107], v[190:193], v[156:159], v[104:107]
	v_mfma_f32_16x16x32_f16 v[100:103], v[198:201], v[156:159], v[100:103]
	v_mfma_f32_16x16x32_f16 v[88:91], v[190:193], v[172:175], v[88:91]
	v_mfma_f32_16x16x32_f16 v[84:87], v[198:201], v[172:175], v[84:87]
	v_mfma_f32_16x16x32_f16 v[152:155], v[194:197], v[120:123], v[152:155]
	v_mfma_f32_16x16x32_f16 v[108:111], v[210:213], v[120:123], v[108:111]
	v_mfma_f32_16x16x32_f16 v[120:123], v[190:193], v[132:135], v[128:131]
	v_mfma_f32_16x16x32_f16 v[124:127], v[210:213], v[144:147], v[124:127]
	v_mfma_f32_16x16x32_f16 v[104:107], v[194:197], v[168:171], v[104:107]
	v_mfma_f32_16x16x32_f16 v[100:103], v[210:213], v[168:171], v[100:103]
	v_mfma_f32_16x16x32_f16 v[88:91], v[194:197], v[176:179], v[88:91]
	v_mfma_f32_16x16x32_f16 v[84:87], v[210:213], v[176:179], v[84:87]
	v_mfma_f32_16x16x32_f16 v[120:123], v[194:197], v[144:147], v[120:123]
	s_mov_b32 m0, s8
	v_lshl_add_u64 v[220:221], s[48:49], 0, v[180:181]
	s_barrier
	ds_read_b128 v[128:131], v209 offset:16384
	ds_read_b128 v[132:135], v209 offset:17408
	ds_read_b128 v[144:147], v209 offset:18432
	ds_read_b128 v[148:151], v209 offset:19456
	ds_read_b128 v[156:159], v209 offset:20480
	ds_read_b128 v[168:171], v209 offset:21504
	ds_read_b128 v[172:175], v209 offset:22528
	ds_read_b128 v[176:179], v209 offset:23552
	global_load_lds_dwordx4 v[220:221], off
	v_lshl_add_u64 v[232:233], s[48:49], 0, v[182:183]
	s_mov_b32 m0, s9
	s_nop 0
	global_load_lds_dwordx4 v[232:233], off
	s_waitcnt vmcnt(10)
	s_barrier
	s_waitcnt lgkmcnt(0)
	v_mfma_f32_16x16x32_f16 v[80:83], v[32:35], v[128:131], v[80:83]
	v_mfma_f32_16x16x32_f16 v[76:79], v[48:51], v[128:131], v[76:79]
	v_mfma_f32_16x16x32_f16 v[64:67], v[32:35], v[144:147], v[64:67]
	v_mfma_f32_16x16x32_f16 v[60:63], v[48:51], v[144:147], v[60:63]
	v_mfma_f32_16x16x32_f16 v[36:39], v[32:35], v[156:159], v[36:39]
	v_mfma_f32_16x16x32_f16 v[28:31], v[48:51], v[156:159], v[28:31]
	v_mfma_f32_16x16x32_f16 v[16:19], v[32:35], v[172:175], v[16:19]
	v_mfma_f32_16x16x32_f16 v[12:15], v[48:51], v[172:175], v[12:15]
	v_mfma_f32_16x16x32_f16 v[80:83], v[40:43], v[132:135], v[80:83]
	v_mfma_f32_16x16x32_f16 v[76:79], v[56:59], v[132:135], v[76:79]
	v_mfma_f32_16x16x32_f16 v[64:67], v[40:43], v[148:151], v[64:67]
	v_mfma_f32_16x16x32_f16 v[60:63], v[56:59], v[148:151], v[60:63]
	v_mfma_f32_16x16x32_f16 v[36:39], v[40:43], v[168:171], v[36:39]
	v_mfma_f32_16x16x32_f16 v[28:31], v[56:59], v[168:171], v[28:31]
	v_mfma_f32_16x16x32_f16 v[16:19], v[40:43], v[176:179], v[16:19]
	v_mfma_f32_16x16x32_f16 v[12:15], v[56:59], v[176:179], v[12:15]
	s_barrier
	s_add_u32 s30, s38, 0x20000
	s_addc_u32 s31, s39, 0
	s_add_i32 s15, s15, s7
	v_lshl_add_u64 v[32:33], s[30:31], 0, v[2:3]
	s_mov_b32 m0, s15
	s_nop 0
	global_load_lds_dwordx4 v[32:33], off
	s_add_i32 m0, s15, 0x2000
	s_nop 0
	global_load_lds_dwordx4 v184, s[30:31]
	s_waitcnt vmcnt(10)
	s_barrier
	v_mfma_f32_16x16x32_f16 v[44:47], v[198:201], v[144:147], v[44:47]
	v_mfma_f32_16x16x32_f16 v[24:27], v[190:193], v[156:159], v[24:27]
	v_mfma_f32_16x16x32_f16 v[20:23], v[198:201], v[156:159], v[20:23]
	v_mfma_f32_16x16x32_f16 v[8:11], v[190:193], v[172:175], v[8:11]
	v_mfma_f32_16x16x32_f16 v[4:7], v[198:201], v[172:175], v[4:7]
	v_mfma_f32_16x16x32_f16 v[32:35], v[190:193], v[128:131], v[72:75]
	v_mfma_f32_16x16x32_f16 v[40:43], v[198:201], v[128:131], v[68:71]
	v_mfma_f32_16x16x32_f16 v[48:51], v[190:193], v[144:147], v[52:55]
	v_mfma_f32_16x16x32_f16 v[44:47], v[210:213], v[148:151], v[44:47]
	v_mfma_f32_16x16x32_f16 v[24:27], v[194:197], v[168:171], v[24:27]
	v_mfma_f32_16x16x32_f16 v[20:23], v[210:213], v[168:171], v[20:23]
	v_mfma_f32_16x16x32_f16 v[8:11], v[194:197], v[176:179], v[8:11]
	v_mfma_f32_16x16x32_f16 v[4:7], v[210:213], v[176:179], v[4:7]
	v_mfma_f32_16x16x32_f16 v[32:35], v[194:197], v[132:135], v[32:35]
	v_mfma_f32_16x16x32_f16 v[40:43], v[210:213], v[132:135], v[40:43]
	v_mfma_f32_16x16x32_f16 v[48:51], v[194:197], v[148:151], v[48:51]
	s_add_i32 s15, 0, 0x18000
	v_add_u32_e32 v72, s15, v208
	s_barrier
	ds_read_b128 v[52:55], v72
	ds_read_b128 v[56:59], v72 offset:1024
	ds_read_b128 v[68:71], v72 offset:2048
	ds_read_b128 v[72:75], v72 offset:3072
	s_add_u32 s30, s48, 0x20000
	s_addc_u32 s31, s49, 0
	s_mov_b32 m0, s12
	ds_read_b128 v[128:131], v209 offset:32768
	ds_read_b128 v[132:135], v209 offset:33792
	ds_read_b128 v[144:147], v209 offset:34816
	ds_read_b128 v[156:159], v209 offset:35840
	ds_read_b128 v[168:171], v209 offset:36864
	ds_read_b128 v[172:175], v209 offset:37888
	ds_read_b128 v[176:179], v209 offset:38912
	ds_read_b128 v[190:193], v209 offset:39936
	global_load_lds_dwordx4 v180, s[30:31]
	s_mov_b32 m0, s13
	s_nop 0
	global_load_lds_dwordx4 v182, s[30:31]
	s_waitcnt vmcnt(10)
	s_barrier
	s_waitcnt lgkmcnt(0)
	v_mfma_f32_16x16x32_f16 v[148:151], v[52:55], v[128:131], v[164:167]
	v_mfma_f32_16x16x32_f16 v[164:167], v[56:59], v[132:135], v[148:151]
	v_mfma_f32_16x16x32_f16 v[148:151], v[68:71], v[128:131], v[160:163]
	v_mfma_f32_16x16x32_f16 v[140:143], v[52:55], v[144:147], v[140:143]
	v_mfma_f32_16x16x32_f16 v[136:139], v[68:71], v[144:147], v[136:139]
	v_mfma_f32_16x16x32_f16 v[116:119], v[52:55], v[168:171], v[116:119]
	v_mfma_f32_16x16x32_f16 v[112:115], v[68:71], v[168:171], v[112:115]
	v_mfma_f32_16x16x32_f16 v[96:99], v[52:55], v[176:179], v[96:99]
	v_mfma_f32_16x16x32_f16 v[92:95], v[68:71], v[176:179], v[92:95]
	v_mfma_f32_16x16x32_f16 v[160:163], v[72:75], v[132:135], v[148:151]
	v_mfma_f32_16x16x32_f16 v[140:143], v[56:59], v[156:159], v[140:143]
	v_mfma_f32_16x16x32_f16 v[136:139], v[72:75], v[156:159], v[136:139]
	v_mfma_f32_16x16x32_f16 v[116:119], v[56:59], v[172:175], v[116:119]
	v_mfma_f32_16x16x32_f16 v[112:115], v[72:75], v[172:175], v[112:115]
	v_mfma_f32_16x16x32_f16 v[96:99], v[56:59], v[190:193], v[96:99]
	v_mfma_f32_16x16x32_f16 v[92:95], v[72:75], v[190:193], v[92:95]
	s_barrier
	s_add_i32 s29, 0, 0x1c000
	v_add_u32_e32 v148, s29, v208
	s_add_i32 s15, s15, s7
	ds_read_b128 v[194:197], v148
	ds_read_b128 v[198:201], v148 offset:1024
	ds_read_b128 v[210:213], v148 offset:2048
	ds_read_b128 v[214:217], v148 offset:3072
	v_lshl_add_u64 v[148:149], v[202:203], 0, s[88:89]
	s_mov_b32 m0, s15
	s_nop 0
	global_load_lds_dwordx4 v[148:149], off
	v_lshl_add_u64 v[148:149], v[218:219], 0, s[88:89]
	s_add_i32 m0, s15, 0x2000
	s_nop 0
	global_load_lds_dwordx4 v[148:149], off
	s_waitcnt vmcnt(10)
	s_barrier
	s_waitcnt lgkmcnt(0)
	v_mfma_f32_16x16x32_f16 v[148:151], v[194:197], v[128:131], v[152:155]
	v_mfma_f32_16x16x32_f16 v[108:111], v[210:213], v[128:131], v[108:111]
	v_mfma_f32_16x16x32_f16 v[152:155], v[198:201], v[132:135], v[148:151]
	v_mfma_f32_16x16x32_f16 v[148:151], v[214:217], v[132:135], v[108:111]
	v_mfma_f32_16x16x32_f16 v[108:111], v[194:197], v[144:147], v[120:123]
	v_mfma_f32_16x16x32_f16 v[128:131], v[198:201], v[156:159], v[108:111]
	v_mfma_f32_16x16x32_f16 v[108:111], v[210:213], v[144:147], v[124:127]
	v_mfma_f32_16x16x32_f16 v[104:107], v[194:197], v[168:171], v[104:107]
	v_mfma_f32_16x16x32_f16 v[100:103], v[210:213], v[168:171], v[100:103]
	v_mfma_f32_16x16x32_f16 v[88:91], v[194:197], v[176:179], v[88:91]
	v_mfma_f32_16x16x32_f16 v[84:87], v[210:213], v[176:179], v[84:87]
	v_mfma_f32_16x16x32_f16 v[124:127], v[214:217], v[156:159], v[108:111]
	v_mfma_f32_16x16x32_f16 v[104:107], v[198:201], v[172:175], v[104:107]
	v_mfma_f32_16x16x32_f16 v[100:103], v[214:217], v[172:175], v[100:103]
	v_mfma_f32_16x16x32_f16 v[88:91], v[198:201], v[190:193], v[88:91]
	v_mfma_f32_16x16x32_f16 v[84:87], v[214:217], v[190:193], v[84:87]
	s_mov_b32 m0, s50
	v_lshl_add_u64 v[190:191], v[220:221], 0, s[88:89]
	s_barrier
	ds_read_b128 v[108:111], v209 offset:49152
	ds_read_b128 v[120:123], v209 offset:50176
	ds_read_b128 v[132:135], v209 offset:51200
	ds_read_b128 v[144:147], v209 offset:52224
	ds_read_b128 v[156:159], v209 offset:53248
	ds_read_b128 v[168:171], v209 offset:54272
	ds_read_b128 v[172:175], v209 offset:55296
	ds_read_b128 v[176:179], v209 offset:56320
	global_load_lds_dwordx4 v[190:191], off
	v_lshl_add_u64 v[190:191], v[232:233], 0, s[88:89]
	s_mov_b32 m0, s51
	s_nop 0
	global_load_lds_dwordx4 v[190:191], off
	s_waitcnt vmcnt(10)
	s_barrier
	s_waitcnt lgkmcnt(0)
	v_mfma_f32_16x16x32_f16 v[80:83], v[52:55], v[108:111], v[80:83]
	v_mfma_f32_16x16x32_f16 v[76:79], v[68:71], v[108:111], v[76:79]
	v_mfma_f32_16x16x32_f16 v[64:67], v[52:55], v[132:135], v[64:67]
	v_mfma_f32_16x16x32_f16 v[60:63], v[68:71], v[132:135], v[60:63]
	v_mfma_f32_16x16x32_f16 v[36:39], v[52:55], v[156:159], v[36:39]
	v_mfma_f32_16x16x32_f16 v[28:31], v[68:71], v[156:159], v[28:31]
	v_mfma_f32_16x16x32_f16 v[16:19], v[52:55], v[172:175], v[16:19]
	v_mfma_f32_16x16x32_f16 v[12:15], v[68:71], v[172:175], v[12:15]
	v_mfma_f32_16x16x32_f16 v[80:83], v[56:59], v[120:123], v[80:83]
	v_mfma_f32_16x16x32_f16 v[76:79], v[72:75], v[120:123], v[76:79]
	v_mfma_f32_16x16x32_f16 v[64:67], v[56:59], v[144:147], v[64:67]
	v_mfma_f32_16x16x32_f16 v[60:63], v[72:75], v[144:147], v[60:63]
	v_mfma_f32_16x16x32_f16 v[36:39], v[56:59], v[168:171], v[36:39]
	v_mfma_f32_16x16x32_f16 v[28:31], v[72:75], v[168:171], v[28:31]
	v_mfma_f32_16x16x32_f16 v[16:19], v[56:59], v[176:179], v[16:19]
	v_mfma_f32_16x16x32_f16 v[12:15], v[72:75], v[176:179], v[12:15]
	s_barrier
	s_add_u32 s30, s38, 0x20080
	s_addc_u32 s31, s39, 0
	s_add_i32 s15, s29, s7
	v_lshl_add_u64 v[52:53], s[30:31], 0, v[2:3]
	s_mov_b32 m0, s15
	s_nop 0
	global_load_lds_dwordx4 v[52:53], off
	s_add_i32 m0, s15, 0x2000
	s_nop 0
	global_load_lds_dwordx4 v184, s[30:31]
	s_waitcnt vmcnt(10)
	s_barrier
	v_mfma_f32_16x16x32_f16 v[32:35], v[194:197], v[108:111], v[32:35]
	v_mfma_f32_16x16x32_f16 v[72:75], v[198:201], v[120:123], v[32:35]
	v_mfma_f32_16x16x32_f16 v[32:35], v[210:213], v[108:111], v[40:43]
	v_mfma_f32_16x16x32_f16 v[68:71], v[214:217], v[120:123], v[32:35]
	v_mfma_f32_16x16x32_f16 v[32:35], v[194:197], v[132:135], v[48:51]
	v_mfma_f32_16x16x32_f16 v[52:55], v[198:201], v[144:147], v[32:35]
	v_mfma_f32_16x16x32_f16 v[32:35], v[210:213], v[132:135], v[44:47]
	v_mfma_f32_16x16x32_f16 v[24:27], v[194:197], v[156:159], v[24:27]
	v_mfma_f32_16x16x32_f16 v[20:23], v[210:213], v[156:159], v[20:23]
	v_mfma_f32_16x16x32_f16 v[8:11], v[194:197], v[172:175], v[8:11]
	v_mfma_f32_16x16x32_f16 v[4:7], v[210:213], v[172:175], v[4:7]
	v_mfma_f32_16x16x32_f16 v[44:47], v[214:217], v[144:147], v[32:35]
	v_mfma_f32_16x16x32_f16 v[24:27], v[198:201], v[168:171], v[24:27]
	v_mfma_f32_16x16x32_f16 v[20:23], v[214:217], v[168:171], v[20:23]
	v_mfma_f32_16x16x32_f16 v[8:11], v[198:201], v[176:179], v[8:11]
	v_mfma_f32_16x16x32_f16 v[4:7], v[214:217], v[176:179], v[4:7]
	s_add_i32 s14, s14, 2
	s_add_u32 s46, s46, 0x100
	s_addc_u32 s47, s47, 0
	s_add_u32 s10, s10, 0x100
	s_addc_u32 s11, s11, 0
	s_cmp_gt_u32 s14, 5
	s_barrier
	s_cbranch_scc0 .LBB0_1664
	s_lshl_b32 s11, s16, 8
	v_mov_b32_e32 v110, v206
	v_mov_b32_e32 v32, v207
	s_lshl_b32 s10, s26, 8
	s_or_b32 s11, s11, s27
	s_add_i32 s10, s10, s17
	v_lshl_add_u32 v108, v32, 3, s11
	v_ashrrev_i32_e32 v109, 31, v108
	v_add_u32_e32 v194, s10, v110
	v_readlane_b32 s10, v253, 25
	v_lshlrev_b64 v[190:191], 1, v[108:109]
	v_readlane_b32 s11, v253, 26
	v_ashrrev_i32_e32 v195, 31, v194
	v_add_u32_e32 v200, 16, v194
	v_lshl_add_u64 v[32:33], v[108:109], 2, s[18:19]
	v_lshl_add_u64 v[192:193], s[10:11], 0, v[190:191]
	v_lshlrev_b64 v[108:109], 10, v[194:195]
	v_ashrrev_i32_e32 v201, 31, v200
	v_add_u32_e32 v198, 32, v194
	flat_load_dwordx4 v[56:59], v[32:33]
	flat_load_dwordx4 v[48:51], v[32:33] offset:16
	flat_load_dwordx4 v[40:43], v[32:33] offset:512
	s_nop 0
	flat_load_dwordx4 v[32:35], v[32:33] offset:528
	v_lshl_add_u64 v[176:177], v[192:193], 0, v[108:109]
	v_lshlrev_b64 v[108:109], 10, v[200:201]
	v_ashrrev_i32_e32 v199, 31, v198
	v_add_u32_e32 v196, 48, v194
	v_lshl_add_u64 v[168:169], v[192:193], 0, v[108:109]
	v_lshlrev_b64 v[108:109], 10, v[198:199]
	v_ashrrev_i32_e32 v197, 31, v196
	v_lshl_add_u64 v[144:145], v[192:193], 0, v[108:109]
	v_lshlrev_b64 v[108:109], 10, v[196:197]
	v_lshl_add_u64 v[120:121], v[192:193], 0, v[108:109]
	global_load_dwordx4 v[108:111], v[120:121], off offset:256
	s_nop 0
	global_load_dwordx4 v[120:123], v[120:121], off
	s_nop 0
	global_load_dwordx4 v[132:135], v[144:145], off offset:256
	s_nop 0
	global_load_dwordx4 v[144:147], v[144:145], off
	s_nop 0
	global_load_dwordx4 v[156:159], v[168:169], off offset:256
	s_nop 0
	global_load_dwordx4 v[168:171], v[168:169], off
	s_nop 0
	global_load_dwordx4 v[172:175], v[176:177], off offset:256
	s_nop 0
	global_load_dwordx4 v[176:179], v[176:177], off
	v_readlane_b32 s10, v253, 40
	v_lshlrev_b64 v[202:203], 12, v[194:195]
	v_readlane_b32 s11, v253, 41
	s_and_b64 vcc, exec, s[40:41]
	s_mov_b32 s16, s34
	s_mov_b32 s26, s36
	s_mov_b64 s[48:49], s[44:45]
	s_mov_b64 s[38:39], s[42:43]
	s_waitcnt vmcnt(0)
	s_waitcnt lgkmcnt(0)
	v_add_f32_e32 v164, v164, v56
	v_add_f32_e32 v165, v165, v57
	v_mul_f32_e32 v164, 0xbfb8aa3b, v164
	v_mul_f32_e32 v165, 0xbfb8aa3b, v165
	v_exp_f32_e32 v164, v164
	v_exp_f32_e32 v165, v165
	v_add_f32_e32 v160, v160, v48
	v_add_f32_e32 v161, v161, v49
	v_add_f32_e32 v164, 1.0, v164
	v_mul_f32_e32 v160, 0xbfb8aa3b, v160
	v_add_f32_e32 v165, 1.0, v165
	v_mul_f32_e32 v161, 0xbfb8aa3b, v161
	v_rcp_f32_e32 v164, v164
	v_exp_f32_e32 v160, v160
	v_rcp_f32_e32 v165, v165
	v_cvt_f32_f16_e32 v210, v176
	v_cvt_f32_f16_sdwa v211, v176 dst_sel:DWORD dst_unused:UNUSED_PAD src0_sel:WORD_1
	v_exp_f32_e32 v161, v161
	v_add_f32_e32 v160, 1.0, v160
	v_rcp_f32_e32 v160, v160
	v_pk_mul_f32 v[164:165], v[164:165], v[210:211]
	v_add_f32_e32 v161, 1.0, v161
	v_cvt_pk_f16_f32 v176, v164, v165
	v_rcp_f32_e32 v161, v161
	v_cvt_f32_f16_e32 v164, v178
	v_cvt_f32_f16_sdwa v165, v178 dst_sel:DWORD dst_unused:UNUSED_PAD src0_sel:WORD_1
	v_add_f32_e32 v152, v152, v40
	v_add_f32_e32 v153, v153, v41
	v_mul_f32_e32 v152, 0xbfb8aa3b, v152
	v_pk_mul_f32 v[160:161], v[160:161], v[164:165]
	v_cvt_f32_f16_e32 v164, v177
	v_cvt_pk_f16_f32 v178, v160, v161
	v_add_f32_e32 v161, v162, v50
	v_mul_f32_e32 v161, 0xbfb8aa3b, v161
	v_exp_f32_e32 v161, v161
	v_add_f32_e32 v160, v166, v58
	v_mul_f32_e32 v160, 0xbfb8aa3b, v160
	v_exp_f32_e32 v160, v160
	v_add_f32_e32 v161, 1.0, v161
	v_rcp_f32_e32 v162, v161
	v_add_f32_e32 v161, v167, v59
	v_mul_f32_e32 v161, 0xbfb8aa3b, v161
	v_exp_f32_e32 v161, v161
	v_add_f32_e32 v160, 1.0, v160
	v_rcp_f32_e32 v160, v160
	v_cvt_f32_f16_sdwa v165, v177 dst_sel:DWORD dst_unused:UNUSED_PAD src0_sel:WORD_1
	v_add_f32_e32 v161, 1.0, v161
	v_rcp_f32_e32 v161, v161
	v_mul_f32_e32 v153, 0xbfb8aa3b, v153
	v_exp_f32_e32 v152, v152
	v_exp_f32_e32 v153, v153
	v_pk_mul_f32 v[160:161], v[160:161], v[164:165]
	v_add_f32_e32 v148, v148, v32
	v_cvt_pk_f16_f32 v164, v160, v161
	v_add_f32_e32 v160, v163, v51
	v_mul_f32_e32 v160, 0xbfb8aa3b, v160
	v_exp_f32_e32 v160, v160
	v_cvt_f32_f16_sdwa v161, v179 dst_sel:DWORD dst_unused:UNUSED_PAD src0_sel:WORD_1
	v_add_f32_e32 v149, v149, v33
	v_add_f32_e32 v152, 1.0, v152
	v_add_f32_e32 v160, 1.0, v160
	v_rcp_f32_e32 v163, v160
	v_cvt_f32_f16_e32 v160, v179
	v_mul_f32_e32 v148, 0xbfb8aa3b, v148
	v_add_f32_e32 v153, 1.0, v153
	v_mul_f32_e32 v149, 0xbfb8aa3b, v149
	v_pk_mul_f32 v[160:161], v[162:163], v[160:161]
	v_rcp_f32_e32 v152, v152
	v_cvt_pk_f16_f32 v160, v160, v161
	v_lshrrev_b32_e32 v161, 4, v176
	v_and_b32_e32 v161, 0x10001, v161
	v_add3_u32 v161, v176, v161, s21
	v_and_b32_e32 v162, 0xfff0fff0, v161
	v_lshrrev_b32_e32 v161, 4, v164
	v_and_b32_e32 v161, 0x10001, v161
	v_add3_u32 v161, v164, v161, s21
	v_and_b32_e32 v163, 0xfff0fff0, v161
	v_lshrrev_b32_e32 v161, 4, v178
	v_and_b32_e32 v161, 0x10001, v161
	v_add3_u32 v161, v178, v161, s21
	v_and_b32_e32 v164, 0xfff0fff0, v161
	v_lshrrev_b32_e32 v161, 4, v160
	v_and_b32_e32 v161, 0x10001, v161
	v_add3_u32 v160, v160, v161, s21
	v_and_b32_e32 v165, 0xfff0fff0, v160
	v_lshl_add_u64 v[160:161], s[10:11], 0, v[202:203]
	v_lshl_add_u64 v[160:161], v[160:161], 0, v[190:191]
	global_store_dwordx4 v[160:161], v[162:165], off
	v_exp_f32_e32 v148, v148
	v_rcp_f32_e32 v153, v153
	v_cvt_f32_f16_e32 v162, v172
	v_cvt_f32_f16_sdwa v163, v172 dst_sel:DWORD dst_unused:UNUSED_PAD src0_sel:WORD_1
	v_exp_f32_e32 v149, v149
	v_add_f32_e32 v148, 1.0, v148
	v_rcp_f32_e32 v148, v148
	v_pk_mul_f32 v[152:153], v[152:153], v[162:163]
	v_add_f32_e32 v149, 1.0, v149
	v_cvt_pk_f16_f32 v162, v152, v153
	v_rcp_f32_e32 v149, v149
	v_cvt_f32_f16_e32 v152, v174
	v_cvt_f32_f16_sdwa v153, v174 dst_sel:DWORD dst_unused:UNUSED_PAD src0_sel:WORD_1
	v_add_f32_e32 v140, v140, v56
	v_add_f32_e32 v141, v141, v57
	v_mul_f32_e32 v140, 0xbfb8aa3b, v140
	v_pk_mul_f32 v[148:149], v[148:149], v[152:153]
	v_cvt_f32_f16_e32 v152, v173
	v_cvt_pk_f16_f32 v163, v148, v149
	v_add_f32_e32 v149, v150, v34
	v_mul_f32_e32 v149, 0xbfb8aa3b, v149
	v_exp_f32_e32 v149, v149
	v_add_f32_e32 v148, v154, v42
	v_mul_f32_e32 v148, 0xbfb8aa3b, v148
	v_exp_f32_e32 v148, v148
	v_add_f32_e32 v149, 1.0, v149
	v_rcp_f32_e32 v150, v149
	v_add_f32_e32 v149, v155, v43
	v_mul_f32_e32 v149, 0xbfb8aa3b, v149
	v_exp_f32_e32 v149, v149
	v_add_f32_e32 v148, 1.0, v148
	v_rcp_f32_e32 v148, v148
	v_cvt_f32_f16_sdwa v153, v173 dst_sel:DWORD dst_unused:UNUSED_PAD src0_sel:WORD_1
	v_add_f32_e32 v149, 1.0, v149
	v_rcp_f32_e32 v149, v149
	v_mul_f32_e32 v141, 0xbfb8aa3b, v141
	v_exp_f32_e32 v140, v140
	v_exp_f32_e32 v141, v141
	v_pk_mul_f32 v[148:149], v[148:149], v[152:153]
	v_add_f32_e32 v136, v136, v48
	v_cvt_pk_f16_f32 v152, v148, v149
	v_add_f32_e32 v148, v151, v35
	v_mul_f32_e32 v148, 0xbfb8aa3b, v148
	v_exp_f32_e32 v148, v148
	v_cvt_f32_f16_sdwa v149, v175 dst_sel:DWORD dst_unused:UNUSED_PAD src0_sel:WORD_1
	v_add_f32_e32 v137, v137, v49
	v_add_f32_e32 v140, 1.0, v140
	v_add_f32_e32 v148, 1.0, v148
	v_rcp_f32_e32 v151, v148
	v_cvt_f32_f16_e32 v148, v175
	v_mul_f32_e32 v136, 0xbfb8aa3b, v136
	v_add_f32_e32 v141, 1.0, v141
	v_mul_f32_e32 v137, 0xbfb8aa3b, v137
	v_pk_mul_f32 v[148:149], v[150:151], v[148:149]
	v_lshrrev_b32_e32 v150, 4, v163
	v_cvt_pk_f16_f32 v151, v148, v149
	v_lshrrev_b32_e32 v149, 4, v152
	v_and_b32_e32 v149, 0x10001, v149
	v_lshrrev_b32_e32 v148, 4, v162
	v_add3_u32 v149, v152, v149, s21
	v_lshrrev_b32_e32 v152, 4, v151
	v_and_b32_e32 v148, 0x10001, v148
	v_and_b32_e32 v150, 0x10001, v150
	v_and_b32_e32 v152, 0x10001, v152
	v_add3_u32 v148, v162, v148, s21
	v_add3_u32 v150, v163, v150, s21
	v_add3_u32 v151, v151, v152, s21
	v_and_b32_e32 v148, 0xfff0fff0, v148
	v_and_b32_e32 v149, 0xfff0fff0, v149
	v_and_b32_e32 v150, 0xfff0fff0, v150
	v_and_b32_e32 v151, 0xfff0fff0, v151
	global_store_dwordx4 v[160:161], v[148:151], off offset:256
	v_rcp_f32_e32 v140, v140
	v_exp_f32_e32 v136, v136
	v_rcp_f32_e32 v141, v141
	v_cvt_f32_f16_e32 v150, v168
	v_cvt_f32_f16_sdwa v151, v168 dst_sel:DWORD dst_unused:UNUSED_PAD src0_sel:WORD_1
	v_exp_f32_e32 v137, v137
	v_add_f32_e32 v136, 1.0, v136
	v_rcp_f32_e32 v136, v136
	v_pk_mul_f32 v[140:141], v[140:141], v[150:151]
	v_add_f32_e32 v137, 1.0, v137
	v_cvt_pk_f16_f32 v150, v140, v141
	v_rcp_f32_e32 v137, v137
	v_cvt_f32_f16_e32 v140, v170
	v_cvt_f32_f16_sdwa v141, v170 dst_sel:DWORD dst_unused:UNUSED_PAD src0_sel:WORD_1
	v_add_f32_e32 v128, v128, v40
	v_add_f32_e32 v129, v129, v41
	v_mul_f32_e32 v128, 0xbfb8aa3b, v128
	v_pk_mul_f32 v[136:137], v[136:137], v[140:141]
	v_cvt_f32_f16_e32 v140, v169
	v_cvt_pk_f16_f32 v151, v136, v137
	v_add_f32_e32 v137, v138, v50
	v_mul_f32_e32 v137, 0xbfb8aa3b, v137
	v_exp_f32_e32 v137, v137
	v_add_f32_e32 v136, v142, v58
	v_mul_f32_e32 v136, 0xbfb8aa3b, v136
	v_exp_f32_e32 v136, v136
	v_add_f32_e32 v137, 1.0, v137
	v_rcp_f32_e32 v138, v137
	v_add_f32_e32 v137, v143, v59
	v_mul_f32_e32 v137, 0xbfb8aa3b, v137
	v_exp_f32_e32 v137, v137
	v_add_f32_e32 v136, 1.0, v136
	v_rcp_f32_e32 v136, v136
	v_cvt_f32_f16_sdwa v141, v169 dst_sel:DWORD dst_unused:UNUSED_PAD src0_sel:WORD_1
	v_add_f32_e32 v137, 1.0, v137
	v_rcp_f32_e32 v137, v137
	v_mul_f32_e32 v129, 0xbfb8aa3b, v129
	v_exp_f32_e32 v128, v128
	v_exp_f32_e32 v129, v129
	v_pk_mul_f32 v[136:137], v[136:137], v[140:141]
	v_lshlrev_b64 v[148:149], 12, v[200:201]
	v_cvt_pk_f16_f32 v140, v136, v137
	v_add_f32_e32 v136, v139, v51
	v_mul_f32_e32 v136, 0xbfb8aa3b, v136
	v_exp_f32_e32 v136, v136
	v_cvt_f32_f16_sdwa v137, v171 dst_sel:DWORD dst_unused:UNUSED_PAD src0_sel:WORD_1
	v_add_f32_e32 v124, v124, v32
	v_add_f32_e32 v125, v125, v33
	v_add_f32_e32 v136, 1.0, v136
	v_rcp_f32_e32 v139, v136
	v_cvt_f32_f16_e32 v136, v171
	v_add_f32_e32 v128, 1.0, v128
	v_mul_f32_e32 v124, 0xbfb8aa3b, v124
	v_add_f32_e32 v129, 1.0, v129
	v_pk_mul_f32 v[136:137], v[138:139], v[136:137]
	v_mul_f32_e32 v125, 0xbfb8aa3b, v125
	v_cvt_pk_f16_f32 v136, v136, v137
	v_lshrrev_b32_e32 v137, 4, v150
	v_and_b32_e32 v137, 0x10001, v137
	v_add3_u32 v137, v150, v137, s21
	v_and_b32_e32 v138, 0xfff0fff0, v137
	v_lshrrev_b32_e32 v137, 4, v140
	v_and_b32_e32 v137, 0x10001, v137
	v_add3_u32 v137, v140, v137, s21
	v_and_b32_e32 v139, 0xfff0fff0, v137
	v_lshrrev_b32_e32 v137, 4, v151
	v_and_b32_e32 v137, 0x10001, v137
	v_add3_u32 v137, v151, v137, s21
	v_and_b32_e32 v140, 0xfff0fff0, v137
	v_lshrrev_b32_e32 v137, 4, v136
	v_and_b32_e32 v137, 0x10001, v137
	v_add3_u32 v136, v136, v137, s21
	v_and_b32_e32 v141, 0xfff0fff0, v136
	v_lshl_add_u64 v[136:137], s[10:11], 0, v[148:149]
	v_lshl_add_u64 v[136:137], v[136:137], 0, v[190:191]
	global_store_dwordx4 v[136:137], v[138:141], off
	v_rcp_f32_e32 v128, v128
	v_exp_f32_e32 v124, v124
	v_rcp_f32_e32 v129, v129
	v_cvt_f32_f16_e32 v138, v156
	v_cvt_f32_f16_sdwa v139, v156 dst_sel:DWORD dst_unused:UNUSED_PAD src0_sel:WORD_1
	v_exp_f32_e32 v125, v125
	v_add_f32_e32 v124, 1.0, v124
	v_rcp_f32_e32 v124, v124
	v_pk_mul_f32 v[128:129], v[128:129], v[138:139]
	v_add_f32_e32 v125, 1.0, v125
	v_cvt_pk_f16_f32 v138, v128, v129
	v_rcp_f32_e32 v125, v125
	v_cvt_f32_f16_e32 v128, v158
	v_cvt_f32_f16_sdwa v129, v158 dst_sel:DWORD dst_unused:UNUSED_PAD src0_sel:WORD_1
	v_add_f32_e32 v116, v116, v56
	v_add_f32_e32 v117, v117, v57
	v_mul_f32_e32 v116, 0xbfb8aa3b, v116
	v_pk_mul_f32 v[124:125], v[124:125], v[128:129]
	v_cvt_f32_f16_e32 v128, v157
	v_cvt_pk_f16_f32 v139, v124, v125
	v_add_f32_e32 v125, v126, v34
	v_mul_f32_e32 v125, 0xbfb8aa3b, v125
	v_exp_f32_e32 v125, v125
	v_add_f32_e32 v124, v130, v42
	v_mul_f32_e32 v124, 0xbfb8aa3b, v124
	v_exp_f32_e32 v124, v124
	v_add_f32_e32 v125, 1.0, v125
	v_rcp_f32_e32 v126, v125
	v_add_f32_e32 v125, v131, v43
	v_mul_f32_e32 v125, 0xbfb8aa3b, v125
	v_exp_f32_e32 v125, v125
	v_add_f32_e32 v124, 1.0, v124
	v_rcp_f32_e32 v124, v124
	v_cvt_f32_f16_sdwa v129, v157 dst_sel:DWORD dst_unused:UNUSED_PAD src0_sel:WORD_1
	v_add_f32_e32 v125, 1.0, v125
	v_rcp_f32_e32 v125, v125
	v_mul_f32_e32 v117, 0xbfb8aa3b, v117
	v_exp_f32_e32 v116, v116
	v_exp_f32_e32 v117, v117
	v_pk_mul_f32 v[124:125], v[124:125], v[128:129]
	v_add_f32_e32 v112, v112, v48
	v_cvt_pk_f16_f32 v128, v124, v125
	v_add_f32_e32 v124, v127, v35
	v_mul_f32_e32 v124, 0xbfb8aa3b, v124
	v_exp_f32_e32 v124, v124
	v_cvt_f32_f16_sdwa v125, v159 dst_sel:DWORD dst_unused:UNUSED_PAD src0_sel:WORD_1
	v_add_f32_e32 v113, v113, v49
	v_add_f32_e32 v116, 1.0, v116
	v_add_f32_e32 v124, 1.0, v124
	v_rcp_f32_e32 v127, v124
	v_cvt_f32_f16_e32 v124, v159
	v_mul_f32_e32 v112, 0xbfb8aa3b, v112
	v_add_f32_e32 v117, 1.0, v117
	v_mul_f32_e32 v113, 0xbfb8aa3b, v113
	v_pk_mul_f32 v[124:125], v[126:127], v[124:125]
	v_lshrrev_b32_e32 v126, 4, v139
	v_cvt_pk_f16_f32 v127, v124, v125
	v_lshrrev_b32_e32 v125, 4, v128
	v_and_b32_e32 v125, 0x10001, v125
	v_lshrrev_b32_e32 v124, 4, v138
	v_add3_u32 v125, v128, v125, s21
	v_lshrrev_b32_e32 v128, 4, v127
	v_and_b32_e32 v124, 0x10001, v124
	v_and_b32_e32 v126, 0x10001, v126
	v_and_b32_e32 v128, 0x10001, v128
	v_add3_u32 v124, v138, v124, s21
	v_add3_u32 v126, v139, v126, s21
	v_add3_u32 v127, v127, v128, s21
	v_and_b32_e32 v124, 0xfff0fff0, v124
	v_and_b32_e32 v125, 0xfff0fff0, v125
	v_and_b32_e32 v126, 0xfff0fff0, v126
	v_and_b32_e32 v127, 0xfff0fff0, v127
	global_store_dwordx4 v[136:137], v[124:127], off offset:256
	v_rcp_f32_e32 v116, v116
	v_exp_f32_e32 v112, v112
	v_rcp_f32_e32 v117, v117
	v_cvt_f32_f16_e32 v126, v144
	v_cvt_f32_f16_sdwa v127, v144 dst_sel:DWORD dst_unused:UNUSED_PAD src0_sel:WORD_1
	v_exp_f32_e32 v113, v113
	v_add_f32_e32 v112, 1.0, v112
	v_rcp_f32_e32 v112, v112
	v_pk_mul_f32 v[116:117], v[116:117], v[126:127]
	v_add_f32_e32 v113, 1.0, v113
	v_cvt_pk_f16_f32 v126, v116, v117
	v_rcp_f32_e32 v113, v113
	v_cvt_f32_f16_e32 v116, v146
	v_cvt_f32_f16_sdwa v117, v146 dst_sel:DWORD dst_unused:UNUSED_PAD src0_sel:WORD_1
	v_add_f32_e32 v104, v104, v40
	v_add_f32_e32 v105, v105, v41
	v_mul_f32_e32 v104, 0xbfb8aa3b, v104
	v_pk_mul_f32 v[112:113], v[112:113], v[116:117]
	v_cvt_f32_f16_e32 v116, v145
	v_cvt_pk_f16_f32 v127, v112, v113
	v_add_f32_e32 v113, v114, v50
	v_mul_f32_e32 v113, 0xbfb8aa3b, v113
	v_exp_f32_e32 v113, v113
	v_add_f32_e32 v112, v118, v58
	v_mul_f32_e32 v112, 0xbfb8aa3b, v112
	v_exp_f32_e32 v112, v112
	v_add_f32_e32 v113, 1.0, v113
	v_rcp_f32_e32 v114, v113
	v_add_f32_e32 v113, v119, v59
	v_mul_f32_e32 v113, 0xbfb8aa3b, v113
	v_exp_f32_e32 v113, v113
	v_add_f32_e32 v112, 1.0, v112
	v_rcp_f32_e32 v112, v112
	v_cvt_f32_f16_sdwa v117, v145 dst_sel:DWORD dst_unused:UNUSED_PAD src0_sel:WORD_1
	v_add_f32_e32 v113, 1.0, v113
	v_rcp_f32_e32 v113, v113
	v_mul_f32_e32 v105, 0xbfb8aa3b, v105
	v_exp_f32_e32 v104, v104
	v_exp_f32_e32 v105, v105
	v_pk_mul_f32 v[112:113], v[112:113], v[116:117]
	v_lshlrev_b64 v[124:125], 12, v[198:199]
	v_cvt_pk_f16_f32 v116, v112, v113
	v_add_f32_e32 v112, v115, v51
	v_mul_f32_e32 v112, 0xbfb8aa3b, v112
	v_exp_f32_e32 v112, v112
	v_cvt_f32_f16_sdwa v113, v147 dst_sel:DWORD dst_unused:UNUSED_PAD src0_sel:WORD_1
	v_add_f32_e32 v100, v100, v32
	v_add_f32_e32 v101, v101, v33
	v_add_f32_e32 v112, 1.0, v112
	v_rcp_f32_e32 v115, v112
	v_cvt_f32_f16_e32 v112, v147
	v_add_f32_e32 v104, 1.0, v104
	v_mul_f32_e32 v100, 0xbfb8aa3b, v100
	v_add_f32_e32 v105, 1.0, v105
	v_pk_mul_f32 v[112:113], v[114:115], v[112:113]
	v_mul_f32_e32 v101, 0xbfb8aa3b, v101
	v_cvt_pk_f16_f32 v112, v112, v113
	v_lshrrev_b32_e32 v113, 4, v126
	v_and_b32_e32 v113, 0x10001, v113
	v_add3_u32 v113, v126, v113, s21
	v_and_b32_e32 v114, 0xfff0fff0, v113
	v_lshrrev_b32_e32 v113, 4, v116
	v_and_b32_e32 v113, 0x10001, v113
	v_add3_u32 v113, v116, v113, s21
	v_and_b32_e32 v115, 0xfff0fff0, v113
	v_lshrrev_b32_e32 v113, 4, v127
	v_and_b32_e32 v113, 0x10001, v113
	v_add3_u32 v113, v127, v113, s21
	v_and_b32_e32 v116, 0xfff0fff0, v113
	v_lshrrev_b32_e32 v113, 4, v112
	v_and_b32_e32 v113, 0x10001, v113
	v_add3_u32 v112, v112, v113, s21
	v_and_b32_e32 v117, 0xfff0fff0, v112
	v_lshl_add_u64 v[112:113], s[10:11], 0, v[124:125]
	v_lshl_add_u64 v[112:113], v[112:113], 0, v[190:191]
	global_store_dwordx4 v[112:113], v[114:117], off
	v_rcp_f32_e32 v104, v104
	v_exp_f32_e32 v100, v100
	v_rcp_f32_e32 v105, v105
	v_cvt_f32_f16_e32 v114, v132
	v_cvt_f32_f16_sdwa v115, v132 dst_sel:DWORD dst_unused:UNUSED_PAD src0_sel:WORD_1
	v_exp_f32_e32 v101, v101
	v_add_f32_e32 v100, 1.0, v100
	v_rcp_f32_e32 v100, v100
	v_pk_mul_f32 v[104:105], v[104:105], v[114:115]
	v_add_f32_e32 v101, 1.0, v101
	v_cvt_pk_f16_f32 v114, v104, v105
	v_rcp_f32_e32 v101, v101
	v_cvt_f32_f16_e32 v104, v134
	v_cvt_f32_f16_sdwa v105, v134 dst_sel:DWORD dst_unused:UNUSED_PAD src0_sel:WORD_1
	v_add_f32_e32 v96, v96, v56
	v_add_f32_e32 v97, v97, v57
	v_mul_f32_e32 v96, 0xbfb8aa3b, v96
	v_pk_mul_f32 v[100:101], v[100:101], v[104:105]
	v_cvt_f32_f16_e32 v104, v133
	v_cvt_pk_f16_f32 v115, v100, v101
	v_add_f32_e32 v101, v102, v34
	v_mul_f32_e32 v101, 0xbfb8aa3b, v101
	v_exp_f32_e32 v101, v101
	v_add_f32_e32 v100, v106, v42
	v_mul_f32_e32 v100, 0xbfb8aa3b, v100
	v_exp_f32_e32 v100, v100
	v_add_f32_e32 v101, 1.0, v101
	v_rcp_f32_e32 v102, v101
	v_add_f32_e32 v101, v107, v43
	v_mul_f32_e32 v101, 0xbfb8aa3b, v101
	v_exp_f32_e32 v101, v101
	v_add_f32_e32 v100, 1.0, v100
	v_rcp_f32_e32 v100, v100
	v_cvt_f32_f16_sdwa v105, v133 dst_sel:DWORD dst_unused:UNUSED_PAD src0_sel:WORD_1
	v_add_f32_e32 v101, 1.0, v101
	v_rcp_f32_e32 v101, v101
	v_mul_f32_e32 v97, 0xbfb8aa3b, v97
	v_exp_f32_e32 v96, v96
	v_exp_f32_e32 v97, v97
	v_pk_mul_f32 v[100:101], v[100:101], v[104:105]
	v_add_f32_e32 v92, v92, v48
	v_cvt_pk_f16_f32 v104, v100, v101
	v_add_f32_e32 v100, v103, v35
	v_mul_f32_e32 v100, 0xbfb8aa3b, v100
	v_exp_f32_e32 v100, v100
	v_cvt_f32_f16_sdwa v101, v135 dst_sel:DWORD dst_unused:UNUSED_PAD src0_sel:WORD_1
	v_add_f32_e32 v93, v93, v49
	v_add_f32_e32 v96, 1.0, v96
	v_add_f32_e32 v100, 1.0, v100
	v_rcp_f32_e32 v103, v100
	v_cvt_f32_f16_e32 v100, v135
	v_mul_f32_e32 v92, 0xbfb8aa3b, v92
	v_add_f32_e32 v97, 1.0, v97
	v_mul_f32_e32 v93, 0xbfb8aa3b, v93
	v_pk_mul_f32 v[100:101], v[102:103], v[100:101]
	v_lshrrev_b32_e32 v102, 4, v115
	v_cvt_pk_f16_f32 v103, v100, v101
	v_lshrrev_b32_e32 v101, 4, v104
	v_and_b32_e32 v101, 0x10001, v101
	v_lshrrev_b32_e32 v100, 4, v114
	v_add3_u32 v101, v104, v101, s21
	v_lshrrev_b32_e32 v104, 4, v103
	v_and_b32_e32 v100, 0x10001, v100
	v_and_b32_e32 v102, 0x10001, v102
	v_and_b32_e32 v104, 0x10001, v104
	v_add3_u32 v100, v114, v100, s21
	v_add3_u32 v102, v115, v102, s21
	v_add3_u32 v103, v103, v104, s21
	v_and_b32_e32 v100, 0xfff0fff0, v100
	v_and_b32_e32 v101, 0xfff0fff0, v101
	v_and_b32_e32 v102, 0xfff0fff0, v102
	v_and_b32_e32 v103, 0xfff0fff0, v103
	global_store_dwordx4 v[112:113], v[100:103], off offset:256
	v_rcp_f32_e32 v96, v96
	v_exp_f32_e32 v92, v92
	v_rcp_f32_e32 v97, v97
	v_cvt_f32_f16_e32 v102, v120
	v_cvt_f32_f16_sdwa v103, v120 dst_sel:DWORD dst_unused:UNUSED_PAD src0_sel:WORD_1
	v_exp_f32_e32 v93, v93
	v_add_f32_e32 v92, 1.0, v92
	v_rcp_f32_e32 v92, v92
	v_pk_mul_f32 v[96:97], v[96:97], v[102:103]
	v_add_f32_e32 v93, 1.0, v93
	v_cvt_pk_f16_f32 v102, v96, v97
	v_rcp_f32_e32 v93, v93
	v_cvt_f32_f16_e32 v96, v122
	v_cvt_f32_f16_sdwa v97, v122 dst_sel:DWORD dst_unused:UNUSED_PAD src0_sel:WORD_1
	v_add_f32_e32 v88, v88, v40
	v_add_f32_e32 v89, v89, v41
	v_mul_f32_e32 v88, 0xbfb8aa3b, v88
	v_pk_mul_f32 v[92:93], v[92:93], v[96:97]
	v_cvt_f32_f16_e32 v96, v121
	v_cvt_pk_f16_f32 v103, v92, v93
	v_add_f32_e32 v93, v94, v50
	v_mul_f32_e32 v93, 0xbfb8aa3b, v93
	v_exp_f32_e32 v93, v93
	v_add_f32_e32 v92, v98, v58
	v_mul_f32_e32 v92, 0xbfb8aa3b, v92
	v_exp_f32_e32 v92, v92
	v_add_f32_e32 v93, 1.0, v93
	v_rcp_f32_e32 v94, v93
	v_add_f32_e32 v93, v99, v59
	v_mul_f32_e32 v93, 0xbfb8aa3b, v93
	v_exp_f32_e32 v93, v93
	v_add_f32_e32 v92, 1.0, v92
	v_rcp_f32_e32 v92, v92
	v_cvt_f32_f16_sdwa v97, v121 dst_sel:DWORD dst_unused:UNUSED_PAD src0_sel:WORD_1
	v_add_f32_e32 v93, 1.0, v93
	v_rcp_f32_e32 v93, v93
	v_mul_f32_e32 v89, 0xbfb8aa3b, v89
	v_exp_f32_e32 v88, v88
	v_exp_f32_e32 v89, v89
	v_pk_mul_f32 v[92:93], v[92:93], v[96:97]
	v_lshlrev_b64 v[100:101], 12, v[196:197]
	v_cvt_pk_f16_f32 v96, v92, v93
	v_add_f32_e32 v92, v95, v51
	v_mul_f32_e32 v92, 0xbfb8aa3b, v92
	v_exp_f32_e32 v92, v92
	v_cvt_f32_f16_sdwa v93, v123 dst_sel:DWORD dst_unused:UNUSED_PAD src0_sel:WORD_1
	v_add_f32_e32 v84, v84, v32
	v_add_f32_e32 v85, v85, v33
	v_add_f32_e32 v92, 1.0, v92
	v_rcp_f32_e32 v95, v92
	v_cvt_f32_f16_e32 v92, v123
	v_add_f32_e32 v88, 1.0, v88
	v_mul_f32_e32 v84, 0xbfb8aa3b, v84
	v_add_f32_e32 v89, 1.0, v89
	v_pk_mul_f32 v[92:93], v[94:95], v[92:93]
	v_mul_f32_e32 v85, 0xbfb8aa3b, v85
	v_cvt_pk_f16_f32 v92, v92, v93
	v_lshrrev_b32_e32 v93, 4, v102
	v_and_b32_e32 v93, 0x10001, v93
	v_add3_u32 v93, v102, v93, s21
	v_and_b32_e32 v94, 0xfff0fff0, v93
	v_lshrrev_b32_e32 v93, 4, v96
	v_and_b32_e32 v93, 0x10001, v93
	v_add3_u32 v93, v96, v93, s21
	v_and_b32_e32 v95, 0xfff0fff0, v93
	v_lshrrev_b32_e32 v93, 4, v103
	v_and_b32_e32 v93, 0x10001, v93
	v_add3_u32 v93, v103, v93, s21
	v_and_b32_e32 v96, 0xfff0fff0, v93
	v_lshrrev_b32_e32 v93, 4, v92
	v_and_b32_e32 v93, 0x10001, v93
	v_add3_u32 v92, v92, v93, s21
	v_and_b32_e32 v97, 0xfff0fff0, v92
	v_lshl_add_u64 v[92:93], s[10:11], 0, v[100:101]
	v_lshl_add_u64 v[92:93], v[92:93], 0, v[190:191]
	global_store_dwordx4 v[92:93], v[94:97], off
	v_rcp_f32_e32 v88, v88
	v_exp_f32_e32 v84, v84
	v_rcp_f32_e32 v89, v89
	v_cvt_f32_f16_e32 v94, v108
	v_cvt_f32_f16_sdwa v95, v108 dst_sel:DWORD dst_unused:UNUSED_PAD src0_sel:WORD_1
	v_exp_f32_e32 v85, v85
	v_add_f32_e32 v84, 1.0, v84
	v_rcp_f32_e32 v84, v84
	v_pk_mul_f32 v[88:89], v[88:89], v[94:95]
	v_add_f32_e32 v85, 1.0, v85
	v_cvt_pk_f16_f32 v94, v88, v89
	v_rcp_f32_e32 v85, v85
	v_cvt_f32_f16_e32 v88, v110
	v_cvt_f32_f16_sdwa v89, v110 dst_sel:DWORD dst_unused:UNUSED_PAD src0_sel:WORD_1
	v_add_u32_e32 v118, 0x80, v194
	v_ashrrev_i32_e32 v119, 31, v118
	v_add_u32_e32 v116, 0x90, v194
	v_pk_mul_f32 v[84:85], v[84:85], v[88:89]
	v_cvt_f32_f16_e32 v88, v109
	v_cvt_pk_f16_f32 v95, v84, v85
	v_add_f32_e32 v85, v86, v34
	v_mul_f32_e32 v85, 0xbfb8aa3b, v85
	v_exp_f32_e32 v85, v85
	v_add_f32_e32 v84, v90, v42
	v_mul_f32_e32 v84, 0xbfb8aa3b, v84
	v_exp_f32_e32 v84, v84
	v_add_f32_e32 v85, 1.0, v85
	v_rcp_f32_e32 v86, v85
	v_add_f32_e32 v85, v91, v43
	v_mul_f32_e32 v85, 0xbfb8aa3b, v85
	v_exp_f32_e32 v85, v85
	v_add_f32_e32 v84, 1.0, v84
	v_rcp_f32_e32 v84, v84
	v_cvt_f32_f16_sdwa v89, v109 dst_sel:DWORD dst_unused:UNUSED_PAD src0_sel:WORD_1
	v_add_f32_e32 v85, 1.0, v85
	v_rcp_f32_e32 v85, v85
	v_ashrrev_i32_e32 v117, 31, v116
	v_add_u32_e32 v114, 0xa0, v194
	v_ashrrev_i32_e32 v115, 31, v114
	v_pk_mul_f32 v[84:85], v[84:85], v[88:89]
	v_add_u32_e32 v112, 0xb0, v194
	v_cvt_pk_f16_f32 v88, v84, v85
	v_add_f32_e32 v84, v87, v35
	v_mul_f32_e32 v84, 0xbfb8aa3b, v84
	v_exp_f32_e32 v84, v84
	v_cvt_f32_f16_sdwa v85, v111 dst_sel:DWORD dst_unused:UNUSED_PAD src0_sel:WORD_1
	v_ashrrev_i32_e32 v113, 31, v112
	v_add_f32_e32 v80, v80, v56
	v_add_f32_e32 v84, 1.0, v84
	v_rcp_f32_e32 v87, v84
	v_cvt_f32_f16_e32 v84, v111
	v_add_f32_e32 v81, v81, v57
	v_mul_f32_e32 v80, 0xbfb8aa3b, v80
	v_mul_f32_e32 v81, 0xbfb8aa3b, v81
	v_pk_mul_f32 v[84:85], v[86:87], v[84:85]
	v_lshrrev_b32_e32 v86, 4, v95
	v_cvt_pk_f16_f32 v87, v84, v85
	v_lshrrev_b32_e32 v85, 4, v88
	v_and_b32_e32 v85, 0x10001, v85
	v_lshrrev_b32_e32 v84, 4, v94
	v_add3_u32 v85, v88, v85, s21
	v_lshrrev_b32_e32 v88, 4, v87
	v_and_b32_e32 v84, 0x10001, v84
	v_and_b32_e32 v86, 0x10001, v86
	v_and_b32_e32 v88, 0x10001, v88
	v_add3_u32 v84, v94, v84, s21
	v_add3_u32 v86, v95, v86, s21
	v_add3_u32 v87, v87, v88, s21
	v_and_b32_e32 v84, 0xfff0fff0, v84
	v_and_b32_e32 v85, 0xfff0fff0, v85
	v_and_b32_e32 v86, 0xfff0fff0, v86
	v_and_b32_e32 v87, 0xfff0fff0, v87
	global_store_dwordx4 v[92:93], v[84:87], off offset:256
	v_exp_f32_e32 v80, v80
	v_exp_f32_e32 v81, v81
	v_lshlrev_b64 v[84:85], 10, v[118:119]
	v_lshl_add_u64 v[120:121], v[192:193], 0, v[84:85]
	v_lshlrev_b64 v[84:85], 10, v[116:117]
	v_lshl_add_u64 v[104:105], v[192:193], 0, v[84:85]
	v_lshlrev_b64 v[84:85], 10, v[114:115]
	v_lshl_add_u64 v[96:97], v[192:193], 0, v[84:85]
	v_lshlrev_b64 v[84:85], 10, v[112:113]
	v_lshl_add_u64 v[88:89], v[192:193], 0, v[84:85]
	global_load_dwordx4 v[84:87], v[88:89], off offset:256
	s_nop 0
	global_load_dwordx4 v[88:91], v[88:89], off
	s_nop 0
	global_load_dwordx4 v[92:95], v[96:97], off offset:256
	s_nop 0
	global_load_dwordx4 v[96:99], v[96:97], off
	s_nop 0
	global_load_dwordx4 v[100:103], v[104:105], off offset:256
	s_nop 0
	global_load_dwordx4 v[104:107], v[104:105], off
	s_nop 0
	global_load_dwordx4 v[108:111], v[120:121], off offset:256
	s_nop 0
	global_load_dwordx4 v[120:123], v[120:121], off
	v_add_f32_e32 v76, v76, v48
	v_add_f32_e32 v77, v77, v49
	v_add_f32_e32 v80, 1.0, v80
	v_mul_f32_e32 v76, 0xbfb8aa3b, v76
	v_add_f32_e32 v81, 1.0, v81
	v_mul_f32_e32 v77, 0xbfb8aa3b, v77
	s_waitcnt vmcnt(0)
	v_rcp_f32_e32 v80, v80
	v_exp_f32_e32 v76, v76
	v_rcp_f32_e32 v81, v81
	v_cvt_f32_f16_e32 v124, v120
	v_cvt_f32_f16_sdwa v125, v120 dst_sel:DWORD dst_unused:UNUSED_PAD src0_sel:WORD_1
	v_exp_f32_e32 v77, v77
	v_add_f32_e32 v76, 1.0, v76
	v_rcp_f32_e32 v76, v76
	v_pk_mul_f32 v[80:81], v[80:81], v[124:125]
	v_add_f32_e32 v77, 1.0, v77
	v_cvt_pk_f16_f32 v120, v80, v81
	v_rcp_f32_e32 v77, v77
	v_cvt_f32_f16_e32 v80, v122
	v_cvt_f32_f16_sdwa v81, v122 dst_sel:DWORD dst_unused:UNUSED_PAD src0_sel:WORD_1
	v_add_f32_e32 v72, v72, v40
	v_add_f32_e32 v73, v73, v41
	v_mul_f32_e32 v72, 0xbfb8aa3b, v72
	v_pk_mul_f32 v[76:77], v[76:77], v[80:81]
	v_cvt_f32_f16_e32 v80, v121
	v_cvt_pk_f16_f32 v122, v76, v77
	v_add_f32_e32 v77, v78, v50
	v_mul_f32_e32 v77, 0xbfb8aa3b, v77
	v_exp_f32_e32 v77, v77
	v_add_f32_e32 v76, v82, v58
	v_mul_f32_e32 v76, 0xbfb8aa3b, v76
	v_exp_f32_e32 v76, v76
	v_add_f32_e32 v77, 1.0, v77
	v_rcp_f32_e32 v78, v77
	v_add_f32_e32 v77, v83, v59
	v_mul_f32_e32 v77, 0xbfb8aa3b, v77
	v_exp_f32_e32 v77, v77
	v_add_f32_e32 v76, 1.0, v76
	v_rcp_f32_e32 v76, v76
	v_cvt_f32_f16_sdwa v81, v121 dst_sel:DWORD dst_unused:UNUSED_PAD src0_sel:WORD_1
	v_add_f32_e32 v77, 1.0, v77
	v_rcp_f32_e32 v77, v77
	v_mul_f32_e32 v73, 0xbfb8aa3b, v73
	v_exp_f32_e32 v72, v72
	v_exp_f32_e32 v73, v73
	v_pk_mul_f32 v[76:77], v[76:77], v[80:81]
	v_lshlrev_b64 v[118:119], 12, v[118:119]
	v_cvt_pk_f16_f32 v80, v76, v77
	v_add_f32_e32 v76, v79, v51
	v_mul_f32_e32 v76, 0xbfb8aa3b, v76
	v_exp_f32_e32 v76, v76
	v_cvt_f32_f16_sdwa v77, v123 dst_sel:DWORD dst_unused:UNUSED_PAD src0_sel:WORD_1
	v_add_f32_e32 v68, v68, v32
	v_add_f32_e32 v69, v69, v33
	v_add_f32_e32 v76, 1.0, v76
	v_rcp_f32_e32 v79, v76
	v_cvt_f32_f16_e32 v76, v123
	v_add_f32_e32 v72, 1.0, v72
	v_mul_f32_e32 v68, 0xbfb8aa3b, v68
	v_add_f32_e32 v73, 1.0, v73
	v_pk_mul_f32 v[76:77], v[78:79], v[76:77]
	v_mul_f32_e32 v69, 0xbfb8aa3b, v69
	v_cvt_pk_f16_f32 v76, v76, v77
	v_lshrrev_b32_e32 v77, 4, v120
	v_and_b32_e32 v77, 0x10001, v77
	v_add3_u32 v77, v120, v77, s21
	v_and_b32_e32 v78, 0xfff0fff0, v77
	v_lshrrev_b32_e32 v77, 4, v80
	v_and_b32_e32 v77, 0x10001, v77
	v_add3_u32 v77, v80, v77, s21
	v_and_b32_e32 v79, 0xfff0fff0, v77
	v_lshrrev_b32_e32 v77, 4, v122
	v_and_b32_e32 v77, 0x10001, v77
	v_add3_u32 v77, v122, v77, s21
	v_and_b32_e32 v80, 0xfff0fff0, v77
	v_lshrrev_b32_e32 v77, 4, v76
	v_and_b32_e32 v77, 0x10001, v77
	v_add3_u32 v76, v76, v77, s21
	v_and_b32_e32 v81, 0xfff0fff0, v76
	v_lshl_add_u64 v[76:77], s[10:11], 0, v[118:119]
	v_lshl_add_u64 v[76:77], v[76:77], 0, v[190:191]
	global_store_dwordx4 v[76:77], v[78:81], off
	v_rcp_f32_e32 v72, v72
	v_exp_f32_e32 v68, v68
	v_rcp_f32_e32 v73, v73
	v_cvt_f32_f16_e32 v78, v108
	v_cvt_f32_f16_sdwa v79, v108 dst_sel:DWORD dst_unused:UNUSED_PAD src0_sel:WORD_1
	v_exp_f32_e32 v69, v69
	v_add_f32_e32 v68, 1.0, v68
	v_rcp_f32_e32 v68, v68
	v_pk_mul_f32 v[72:73], v[72:73], v[78:79]
	v_add_f32_e32 v69, 1.0, v69
	v_cvt_pk_f16_f32 v78, v72, v73
	v_rcp_f32_e32 v69, v69
	v_cvt_f32_f16_e32 v72, v110
	v_cvt_f32_f16_sdwa v73, v110 dst_sel:DWORD dst_unused:UNUSED_PAD src0_sel:WORD_1
	v_add_f32_e32 v64, v64, v56
	v_add_f32_e32 v65, v65, v57
	v_mul_f32_e32 v64, 0xbfb8aa3b, v64
	v_pk_mul_f32 v[68:69], v[68:69], v[72:73]
	v_cvt_f32_f16_e32 v72, v109
	v_cvt_pk_f16_f32 v79, v68, v69
	v_add_f32_e32 v69, v70, v34
	v_mul_f32_e32 v69, 0xbfb8aa3b, v69
	v_exp_f32_e32 v69, v69
	v_add_f32_e32 v68, v74, v42
	v_mul_f32_e32 v68, 0xbfb8aa3b, v68
	v_exp_f32_e32 v68, v68
	v_add_f32_e32 v69, 1.0, v69
	v_rcp_f32_e32 v70, v69
	v_add_f32_e32 v69, v75, v43
	v_mul_f32_e32 v69, 0xbfb8aa3b, v69
	v_exp_f32_e32 v69, v69
	v_add_f32_e32 v68, 1.0, v68
	v_rcp_f32_e32 v68, v68
	v_cvt_f32_f16_sdwa v73, v109 dst_sel:DWORD dst_unused:UNUSED_PAD src0_sel:WORD_1
	v_add_f32_e32 v69, 1.0, v69
	v_rcp_f32_e32 v69, v69
	v_mul_f32_e32 v65, 0xbfb8aa3b, v65
	v_exp_f32_e32 v64, v64
	v_exp_f32_e32 v65, v65
	v_pk_mul_f32 v[68:69], v[68:69], v[72:73]
	v_add_f32_e32 v60, v60, v48
	v_cvt_pk_f16_f32 v72, v68, v69
	v_add_f32_e32 v68, v71, v35
	v_mul_f32_e32 v68, 0xbfb8aa3b, v68
	v_exp_f32_e32 v68, v68
	v_cvt_f32_f16_sdwa v69, v111 dst_sel:DWORD dst_unused:UNUSED_PAD src0_sel:WORD_1
	v_add_f32_e32 v61, v61, v49
	v_add_f32_e32 v64, 1.0, v64
	v_add_f32_e32 v68, 1.0, v68
	v_rcp_f32_e32 v71, v68
	v_cvt_f32_f16_e32 v68, v111
	v_mul_f32_e32 v60, 0xbfb8aa3b, v60
	v_add_f32_e32 v65, 1.0, v65
	v_mul_f32_e32 v61, 0xbfb8aa3b, v61
	v_pk_mul_f32 v[68:69], v[70:71], v[68:69]
	v_lshrrev_b32_e32 v70, 4, v79
	v_cvt_pk_f16_f32 v71, v68, v69
	v_lshrrev_b32_e32 v69, 4, v72
	v_and_b32_e32 v69, 0x10001, v69
	v_lshrrev_b32_e32 v68, 4, v78
	v_add3_u32 v69, v72, v69, s21
	v_lshrrev_b32_e32 v72, 4, v71
	v_and_b32_e32 v68, 0x10001, v68
	v_and_b32_e32 v70, 0x10001, v70
	v_and_b32_e32 v72, 0x10001, v72
	v_add3_u32 v68, v78, v68, s21
	v_add3_u32 v70, v79, v70, s21
	v_add3_u32 v71, v71, v72, s21
	v_and_b32_e32 v68, 0xfff0fff0, v68
	v_and_b32_e32 v69, 0xfff0fff0, v69
	v_and_b32_e32 v70, 0xfff0fff0, v70
	v_and_b32_e32 v71, 0xfff0fff0, v71
	global_store_dwordx4 v[76:77], v[68:71], off offset:256
	v_rcp_f32_e32 v64, v64
	v_exp_f32_e32 v60, v60
	v_rcp_f32_e32 v65, v65
	v_cvt_f32_f16_e32 v70, v104
	v_cvt_f32_f16_sdwa v71, v104 dst_sel:DWORD dst_unused:UNUSED_PAD src0_sel:WORD_1
	v_exp_f32_e32 v61, v61
	v_add_f32_e32 v60, 1.0, v60
	v_rcp_f32_e32 v60, v60
	v_pk_mul_f32 v[64:65], v[64:65], v[70:71]
	v_add_f32_e32 v61, 1.0, v61
	v_cvt_pk_f16_f32 v70, v64, v65
	v_rcp_f32_e32 v61, v61
	v_cvt_f32_f16_e32 v64, v106
	v_cvt_f32_f16_sdwa v65, v106 dst_sel:DWORD dst_unused:UNUSED_PAD src0_sel:WORD_1
	v_add_f32_e32 v52, v52, v40
	v_add_f32_e32 v53, v53, v41
	v_mul_f32_e32 v52, 0xbfb8aa3b, v52
	v_pk_mul_f32 v[60:61], v[60:61], v[64:65]
	v_cvt_f32_f16_e32 v64, v105
	v_cvt_pk_f16_f32 v71, v60, v61
	v_add_f32_e32 v61, v62, v50
	v_mul_f32_e32 v61, 0xbfb8aa3b, v61
	v_exp_f32_e32 v61, v61
	v_add_f32_e32 v60, v66, v58
	v_mul_f32_e32 v60, 0xbfb8aa3b, v60
	v_exp_f32_e32 v60, v60
	v_add_f32_e32 v61, 1.0, v61
	v_rcp_f32_e32 v62, v61
	v_add_f32_e32 v61, v67, v59
	v_mul_f32_e32 v61, 0xbfb8aa3b, v61
	v_exp_f32_e32 v61, v61
	v_add_f32_e32 v60, 1.0, v60
	v_rcp_f32_e32 v60, v60
	v_cvt_f32_f16_sdwa v65, v105 dst_sel:DWORD dst_unused:UNUSED_PAD src0_sel:WORD_1
	v_add_f32_e32 v61, 1.0, v61
	v_rcp_f32_e32 v61, v61
	v_mul_f32_e32 v53, 0xbfb8aa3b, v53
	v_exp_f32_e32 v52, v52
	v_exp_f32_e32 v53, v53
	v_pk_mul_f32 v[60:61], v[60:61], v[64:65]
	v_lshlrev_b64 v[68:69], 12, v[116:117]
	v_cvt_pk_f16_f32 v64, v60, v61
	v_add_f32_e32 v60, v63, v51
	v_mul_f32_e32 v60, 0xbfb8aa3b, v60
	v_exp_f32_e32 v60, v60
	v_cvt_f32_f16_sdwa v61, v107 dst_sel:DWORD dst_unused:UNUSED_PAD src0_sel:WORD_1
	v_add_f32_e32 v44, v44, v32
	v_add_f32_e32 v45, v45, v33
	v_add_f32_e32 v60, 1.0, v60
	v_rcp_f32_e32 v63, v60
	v_cvt_f32_f16_e32 v60, v107
	v_add_f32_e32 v52, 1.0, v52
	v_mul_f32_e32 v44, 0xbfb8aa3b, v44
	v_add_f32_e32 v53, 1.0, v53
	v_pk_mul_f32 v[60:61], v[62:63], v[60:61]
	v_mul_f32_e32 v45, 0xbfb8aa3b, v45
	v_cvt_pk_f16_f32 v60, v60, v61
	v_lshrrev_b32_e32 v61, 4, v70
	v_and_b32_e32 v61, 0x10001, v61
	v_add3_u32 v61, v70, v61, s21
	v_and_b32_e32 v62, 0xfff0fff0, v61
	v_lshrrev_b32_e32 v61, 4, v64
	v_and_b32_e32 v61, 0x10001, v61
	v_add3_u32 v61, v64, v61, s21
	v_and_b32_e32 v63, 0xfff0fff0, v61
	v_lshrrev_b32_e32 v61, 4, v71
	v_and_b32_e32 v61, 0x10001, v61
	v_add3_u32 v61, v71, v61, s21
	v_and_b32_e32 v64, 0xfff0fff0, v61
	v_lshrrev_b32_e32 v61, 4, v60
	v_and_b32_e32 v61, 0x10001, v61
	v_add3_u32 v60, v60, v61, s21
	v_and_b32_e32 v65, 0xfff0fff0, v60
	v_lshl_add_u64 v[60:61], s[10:11], 0, v[68:69]
	v_lshl_add_u64 v[60:61], v[60:61], 0, v[190:191]
	global_store_dwordx4 v[60:61], v[62:65], off
	v_rcp_f32_e32 v52, v52
	v_exp_f32_e32 v44, v44
	v_rcp_f32_e32 v53, v53
	v_cvt_f32_f16_e32 v62, v100
	v_cvt_f32_f16_sdwa v63, v100 dst_sel:DWORD dst_unused:UNUSED_PAD src0_sel:WORD_1
	v_exp_f32_e32 v45, v45
	v_add_f32_e32 v44, 1.0, v44
	v_rcp_f32_e32 v44, v44
	v_pk_mul_f32 v[52:53], v[52:53], v[62:63]
	v_add_f32_e32 v45, 1.0, v45
	v_cvt_pk_f16_f32 v62, v52, v53
	v_rcp_f32_e32 v45, v45
	v_cvt_f32_f16_e32 v52, v102
	v_cvt_f32_f16_sdwa v53, v102 dst_sel:DWORD dst_unused:UNUSED_PAD src0_sel:WORD_1
	v_add_f32_e32 v36, v36, v56
	v_add_f32_e32 v37, v37, v57
	v_mul_f32_e32 v36, 0xbfb8aa3b, v36
	v_pk_mul_f32 v[44:45], v[44:45], v[52:53]
	v_cvt_f32_f16_e32 v52, v101
	v_cvt_pk_f16_f32 v63, v44, v45
	v_add_f32_e32 v45, v46, v34
	v_mul_f32_e32 v45, 0xbfb8aa3b, v45
	v_exp_f32_e32 v45, v45
	v_add_f32_e32 v44, v54, v42
	v_mul_f32_e32 v44, 0xbfb8aa3b, v44
	v_exp_f32_e32 v44, v44
	v_add_f32_e32 v45, 1.0, v45
	v_rcp_f32_e32 v46, v45
	v_add_f32_e32 v45, v55, v43
	v_mul_f32_e32 v45, 0xbfb8aa3b, v45
	v_exp_f32_e32 v45, v45
	v_add_f32_e32 v44, 1.0, v44
	v_rcp_f32_e32 v44, v44
	v_cvt_f32_f16_sdwa v53, v101 dst_sel:DWORD dst_unused:UNUSED_PAD src0_sel:WORD_1
	v_add_f32_e32 v45, 1.0, v45
	v_rcp_f32_e32 v45, v45
	v_mul_f32_e32 v37, 0xbfb8aa3b, v37
	v_exp_f32_e32 v36, v36
	v_exp_f32_e32 v37, v37
	v_pk_mul_f32 v[44:45], v[44:45], v[52:53]
	v_add_f32_e32 v28, v28, v48
	v_cvt_pk_f16_f32 v52, v44, v45
	v_add_f32_e32 v44, v47, v35
	v_mul_f32_e32 v44, 0xbfb8aa3b, v44
	v_exp_f32_e32 v44, v44
	v_cvt_f32_f16_sdwa v45, v103 dst_sel:DWORD dst_unused:UNUSED_PAD src0_sel:WORD_1
	v_add_f32_e32 v29, v29, v49
	v_add_f32_e32 v36, 1.0, v36
	v_add_f32_e32 v44, 1.0, v44
	v_rcp_f32_e32 v47, v44
	v_cvt_f32_f16_e32 v44, v103
	v_mul_f32_e32 v28, 0xbfb8aa3b, v28
	v_add_f32_e32 v37, 1.0, v37
	v_mul_f32_e32 v29, 0xbfb8aa3b, v29
	v_pk_mul_f32 v[44:45], v[46:47], v[44:45]
	v_lshrrev_b32_e32 v46, 4, v63
	v_cvt_pk_f16_f32 v47, v44, v45
	v_lshrrev_b32_e32 v45, 4, v52
	v_and_b32_e32 v45, 0x10001, v45
	v_lshrrev_b32_e32 v44, 4, v62
	v_add3_u32 v45, v52, v45, s21
	v_lshrrev_b32_e32 v52, 4, v47
	v_and_b32_e32 v44, 0x10001, v44
	v_and_b32_e32 v46, 0x10001, v46
	v_and_b32_e32 v52, 0x10001, v52
	v_add3_u32 v44, v62, v44, s21
	v_add3_u32 v46, v63, v46, s21
	v_add3_u32 v47, v47, v52, s21
	v_and_b32_e32 v44, 0xfff0fff0, v44
	v_and_b32_e32 v45, 0xfff0fff0, v45
	v_and_b32_e32 v46, 0xfff0fff0, v46
	v_and_b32_e32 v47, 0xfff0fff0, v47
	global_store_dwordx4 v[60:61], v[44:47], off offset:256
	v_rcp_f32_e32 v36, v36
	v_exp_f32_e32 v28, v28
	v_rcp_f32_e32 v37, v37
	v_cvt_f32_f16_e32 v46, v96
	v_cvt_f32_f16_sdwa v47, v96 dst_sel:DWORD dst_unused:UNUSED_PAD src0_sel:WORD_1
	v_exp_f32_e32 v29, v29
	v_add_f32_e32 v28, 1.0, v28
	v_rcp_f32_e32 v28, v28
	v_pk_mul_f32 v[36:37], v[36:37], v[46:47]
	v_add_f32_e32 v29, 1.0, v29
	v_cvt_pk_f16_f32 v46, v36, v37
	v_rcp_f32_e32 v29, v29
	v_cvt_f32_f16_e32 v36, v98
	v_cvt_f32_f16_sdwa v37, v98 dst_sel:DWORD dst_unused:UNUSED_PAD src0_sel:WORD_1
	v_add_f32_e32 v24, v24, v40
	v_add_f32_e32 v25, v25, v41
	v_mul_f32_e32 v24, 0xbfb8aa3b, v24
	v_pk_mul_f32 v[28:29], v[28:29], v[36:37]
	v_cvt_f32_f16_e32 v36, v97
	v_cvt_pk_f16_f32 v47, v28, v29
	v_add_f32_e32 v29, v30, v50
	v_mul_f32_e32 v29, 0xbfb8aa3b, v29
	v_exp_f32_e32 v29, v29
	v_add_f32_e32 v28, v38, v58
	v_mul_f32_e32 v28, 0xbfb8aa3b, v28
	v_exp_f32_e32 v28, v28
	v_add_f32_e32 v29, 1.0, v29
	v_rcp_f32_e32 v30, v29
	v_add_f32_e32 v29, v39, v59
	v_mul_f32_e32 v29, 0xbfb8aa3b, v29
	v_exp_f32_e32 v29, v29
	v_add_f32_e32 v28, 1.0, v28
	v_rcp_f32_e32 v28, v28
	v_cvt_f32_f16_sdwa v37, v97 dst_sel:DWORD dst_unused:UNUSED_PAD src0_sel:WORD_1
	v_add_f32_e32 v29, 1.0, v29
	v_rcp_f32_e32 v29, v29
	v_mul_f32_e32 v25, 0xbfb8aa3b, v25
	v_exp_f32_e32 v24, v24
	v_exp_f32_e32 v25, v25
	v_pk_mul_f32 v[28:29], v[28:29], v[36:37]
	v_add_f32_e32 v20, v20, v32
	v_cvt_pk_f16_f32 v37, v28, v29
	v_add_f32_e32 v28, v31, v51
	v_mul_f32_e32 v28, 0xbfb8aa3b, v28
	v_exp_f32_e32 v28, v28
	v_cvt_f32_f16_sdwa v29, v99 dst_sel:DWORD dst_unused:UNUSED_PAD src0_sel:WORD_1
	v_add_f32_e32 v21, v21, v33
	v_add_f32_e32 v24, 1.0, v24
	v_add_f32_e32 v28, 1.0, v28
	v_rcp_f32_e32 v31, v28
	v_cvt_f32_f16_e32 v28, v99
	v_mul_f32_e32 v20, 0xbfb8aa3b, v20
	v_add_f32_e32 v25, 1.0, v25
	v_mul_f32_e32 v21, 0xbfb8aa3b, v21
	v_pk_mul_f32 v[28:29], v[30:31], v[28:29]
	v_rcp_f32_e32 v24, v24
	v_exp_f32_e32 v20, v20
	v_rcp_f32_e32 v25, v25
	v_cvt_f32_f16_e32 v30, v92
	v_cvt_f32_f16_sdwa v31, v92 dst_sel:DWORD dst_unused:UNUSED_PAD src0_sel:WORD_1
	v_exp_f32_e32 v21, v21
	v_add_f32_e32 v20, 1.0, v20
	v_rcp_f32_e32 v20, v20
	v_pk_mul_f32 v[24:25], v[24:25], v[30:31]
	v_add_f32_e32 v21, 1.0, v21
	v_cvt_pk_f16_f32 v30, v24, v25
	v_rcp_f32_e32 v21, v21
	v_cvt_f32_f16_e32 v24, v94
	v_cvt_f32_f16_sdwa v25, v94 dst_sel:DWORD dst_unused:UNUSED_PAD src0_sel:WORD_1
	v_cvt_pk_f16_f32 v28, v28, v29
	v_lshrrev_b32_e32 v29, 4, v46
	v_and_b32_e32 v29, 0x10001, v29
	v_pk_mul_f32 v[20:21], v[20:21], v[24:25]
	v_cvt_f32_f16_e32 v24, v93
	v_cvt_pk_f16_f32 v31, v20, v21
	v_add_f32_e32 v21, v22, v34
	v_mul_f32_e32 v21, 0xbfb8aa3b, v21
	v_exp_f32_e32 v21, v21
	v_add_f32_e32 v20, v26, v42
	v_mul_f32_e32 v20, 0xbfb8aa3b, v20
	v_exp_f32_e32 v20, v20
	v_add_f32_e32 v21, 1.0, v21
	v_rcp_f32_e32 v22, v21
	v_add_f32_e32 v21, v27, v43
	v_mul_f32_e32 v21, 0xbfb8aa3b, v21
	v_exp_f32_e32 v21, v21
	v_add_f32_e32 v20, 1.0, v20
	v_rcp_f32_e32 v20, v20
	v_cvt_f32_f16_sdwa v25, v93 dst_sel:DWORD dst_unused:UNUSED_PAD src0_sel:WORD_1
	v_add_f32_e32 v21, 1.0, v21
	v_rcp_f32_e32 v21, v21
	v_add3_u32 v29, v46, v29, s21
	v_and_b32_e32 v36, 0xfff0fff0, v29
	v_lshrrev_b32_e32 v29, 4, v37
	v_pk_mul_f32 v[20:21], v[20:21], v[24:25]
	v_and_b32_e32 v29, 0x10001, v29
	v_cvt_pk_f16_f32 v24, v20, v21
	v_add_f32_e32 v20, v23, v35
	v_mul_f32_e32 v20, 0xbfb8aa3b, v20
	v_exp_f32_e32 v20, v20
	v_cvt_f32_f16_sdwa v21, v95 dst_sel:DWORD dst_unused:UNUSED_PAD src0_sel:WORD_1
	v_add3_u32 v29, v37, v29, s21
	v_and_b32_e32 v37, 0xfff0fff0, v29
	v_add_f32_e32 v20, 1.0, v20
	v_rcp_f32_e32 v23, v20
	v_cvt_f32_f16_e32 v20, v95
	v_lshrrev_b32_e32 v29, 4, v47
	v_and_b32_e32 v29, 0x10001, v29
	v_add_f32_e32 v16, v16, v56
	v_pk_mul_f32 v[20:21], v[22:23], v[20:21]
	v_add_f32_e32 v17, v17, v57
	v_add3_u32 v29, v47, v29, s21
	v_cvt_pk_f16_f32 v23, v20, v21
	v_lshrrev_b32_e32 v21, 4, v24
	v_mul_f32_e32 v16, 0xbfb8aa3b, v16
	v_mul_f32_e32 v17, 0xbfb8aa3b, v17
	v_and_b32_e32 v38, 0xfff0fff0, v29
	v_lshrrev_b32_e32 v29, 4, v28
	v_and_b32_e32 v21, 0x10001, v21
	v_exp_f32_e32 v16, v16
	v_exp_f32_e32 v17, v17
	v_and_b32_e32 v29, 0x10001, v29
	v_lshrrev_b32_e32 v20, 4, v30
	v_add3_u32 v21, v24, v21, s21
	v_lshrrev_b32_e32 v22, 4, v31
	v_lshrrev_b32_e32 v24, 4, v23
	v_lshlrev_b64 v[44:45], 12, v[114:115]
	v_add3_u32 v28, v28, v29, s21
	v_and_b32_e32 v20, 0x10001, v20
	v_and_b32_e32 v22, 0x10001, v22
	v_and_b32_e32 v24, 0x10001, v24
	v_and_b32_e32 v39, 0xfff0fff0, v28
	v_lshl_add_u64 v[28:29], s[10:11], 0, v[44:45]
	v_add3_u32 v20, v30, v20, s21
	v_add3_u32 v22, v31, v22, s21
	v_add3_u32 v23, v23, v24, s21
	v_add_f32_e32 v12, v12, v48
	v_add_f32_e32 v13, v13, v49
	v_lshl_add_u64 v[28:29], v[28:29], 0, v[190:191]
	v_and_b32_e32 v20, 0xfff0fff0, v20
	v_and_b32_e32 v21, 0xfff0fff0, v21
	v_and_b32_e32 v22, 0xfff0fff0, v22
	v_and_b32_e32 v23, 0xfff0fff0, v23
	v_add_f32_e32 v16, 1.0, v16
	v_mul_f32_e32 v12, 0xbfb8aa3b, v12
	v_add_f32_e32 v17, 1.0, v17
	v_mul_f32_e32 v13, 0xbfb8aa3b, v13
	global_store_dwordx4 v[28:29], v[20:23], off offset:256
	v_rcp_f32_e32 v16, v16
	v_exp_f32_e32 v12, v12
	v_rcp_f32_e32 v17, v17
	v_cvt_f32_f16_e32 v22, v88
	v_cvt_f32_f16_sdwa v23, v88 dst_sel:DWORD dst_unused:UNUSED_PAD src0_sel:WORD_1
	v_exp_f32_e32 v13, v13
	v_add_f32_e32 v12, 1.0, v12
	v_rcp_f32_e32 v12, v12
	v_pk_mul_f32 v[16:17], v[16:17], v[22:23]
	v_add_f32_e32 v13, 1.0, v13
	v_cvt_pk_f16_f32 v22, v16, v17
	v_rcp_f32_e32 v13, v13
	v_cvt_f32_f16_e32 v16, v90
	v_cvt_f32_f16_sdwa v17, v90 dst_sel:DWORD dst_unused:UNUSED_PAD src0_sel:WORD_1
	v_add_f32_e32 v8, v8, v40
	v_add_f32_e32 v9, v9, v41
	v_mul_f32_e32 v8, 0xbfb8aa3b, v8
	v_pk_mul_f32 v[12:13], v[12:13], v[16:17]
	v_cvt_f32_f16_e32 v16, v89
	v_cvt_pk_f16_f32 v23, v12, v13
	v_add_f32_e32 v13, v14, v50
	v_mul_f32_e32 v13, 0xbfb8aa3b, v13
	v_exp_f32_e32 v13, v13
	v_add_f32_e32 v12, v18, v58
	v_mul_f32_e32 v12, 0xbfb8aa3b, v12
	v_exp_f32_e32 v12, v12
	v_add_f32_e32 v13, 1.0, v13
	v_rcp_f32_e32 v14, v13
	v_add_f32_e32 v13, v19, v59
	v_mul_f32_e32 v13, 0xbfb8aa3b, v13
	v_exp_f32_e32 v13, v13
	v_add_f32_e32 v12, 1.0, v12
	v_rcp_f32_e32 v12, v12
	v_cvt_f32_f16_sdwa v17, v89 dst_sel:DWORD dst_unused:UNUSED_PAD src0_sel:WORD_1
	v_add_f32_e32 v13, 1.0, v13
	v_rcp_f32_e32 v13, v13
	v_mul_f32_e32 v9, 0xbfb8aa3b, v9
	v_exp_f32_e32 v8, v8
	v_exp_f32_e32 v9, v9
	v_pk_mul_f32 v[12:13], v[12:13], v[16:17]
	v_lshlrev_b64 v[20:21], 12, v[112:113]
	v_cvt_pk_f16_f32 v16, v12, v13
	v_add_f32_e32 v12, v15, v51
	v_mul_f32_e32 v12, 0xbfb8aa3b, v12
	v_exp_f32_e32 v12, v12
	v_cvt_f32_f16_sdwa v13, v91 dst_sel:DWORD dst_unused:UNUSED_PAD src0_sel:WORD_1
	v_add_f32_e32 v4, v4, v32
	v_add_f32_e32 v5, v5, v33
	v_add_f32_e32 v12, 1.0, v12
	v_rcp_f32_e32 v15, v12
	v_cvt_f32_f16_e32 v12, v91
	v_add_f32_e32 v8, 1.0, v8
	v_mul_f32_e32 v4, 0xbfb8aa3b, v4
	v_add_f32_e32 v9, 1.0, v9
	v_pk_mul_f32 v[12:13], v[14:15], v[12:13]
	v_mul_f32_e32 v5, 0xbfb8aa3b, v5
	v_cvt_pk_f16_f32 v12, v12, v13
	v_lshrrev_b32_e32 v13, 4, v22
	v_and_b32_e32 v13, 0x10001, v13
	v_add3_u32 v13, v22, v13, s21
	v_and_b32_e32 v14, 0xfff0fff0, v13
	v_lshrrev_b32_e32 v13, 4, v16
	v_and_b32_e32 v13, 0x10001, v13
	v_add3_u32 v13, v16, v13, s21
	v_and_b32_e32 v15, 0xfff0fff0, v13
	v_lshrrev_b32_e32 v13, 4, v23
	v_and_b32_e32 v13, 0x10001, v13
	v_add3_u32 v13, v23, v13, s21
	v_and_b32_e32 v16, 0xfff0fff0, v13
	v_lshrrev_b32_e32 v13, 4, v12
	v_and_b32_e32 v13, 0x10001, v13
	v_add3_u32 v12, v12, v13, s21
	v_and_b32_e32 v17, 0xfff0fff0, v12
	v_lshl_add_u64 v[12:13], s[10:11], 0, v[20:21]
	v_lshl_add_u64 v[12:13], v[12:13], 0, v[190:191]
	global_store_dwordx4 v[12:13], v[14:17], off
	v_rcp_f32_e32 v8, v8
	v_exp_f32_e32 v4, v4
	v_rcp_f32_e32 v9, v9
	v_cvt_f32_f16_e32 v14, v84
	v_cvt_f32_f16_sdwa v15, v84 dst_sel:DWORD dst_unused:UNUSED_PAD src0_sel:WORD_1
	v_exp_f32_e32 v5, v5
	v_add_f32_e32 v4, 1.0, v4
	v_rcp_f32_e32 v4, v4
	v_pk_mul_f32 v[8:9], v[8:9], v[14:15]
	v_add_f32_e32 v5, 1.0, v5
	v_cvt_pk_f16_f32 v14, v8, v9
	v_rcp_f32_e32 v5, v5
	v_cvt_f32_f16_e32 v8, v86
	v_cvt_f32_f16_sdwa v9, v86 dst_sel:DWORD dst_unused:UNUSED_PAD src0_sel:WORD_1
	global_store_dwordx4 v[28:29], v[36:39], off
	v_pk_mul_f32 v[4:5], v[4:5], v[8:9]
	s_nop 0
	v_cvt_pk_f16_f32 v15, v4, v5
	v_add_f32_e32 v5, v6, v34
	v_mul_f32_e32 v5, 0xbfb8aa3b, v5
	v_exp_f32_e32 v5, v5
	v_add_f32_e32 v4, v10, v42
	v_mul_f32_e32 v4, 0xbfb8aa3b, v4
	v_exp_f32_e32 v4, v4
	v_add_f32_e32 v5, 1.0, v5
	v_rcp_f32_e32 v6, v5
	v_add_f32_e32 v5, v11, v43
	v_mul_f32_e32 v5, 0xbfb8aa3b, v5
	v_exp_f32_e32 v5, v5
	v_add_f32_e32 v4, 1.0, v4
	v_rcp_f32_e32 v4, v4
	v_cvt_f32_f16_e32 v8, v85
	v_add_f32_e32 v5, 1.0, v5
	v_rcp_f32_e32 v5, v5
	v_cvt_f32_f16_sdwa v9, v85 dst_sel:DWORD dst_unused:UNUSED_PAD src0_sel:WORD_1
	v_pk_mul_f32 v[4:5], v[4:5], v[8:9]
	s_nop 0
	v_cvt_pk_f16_f32 v8, v4, v5
	v_add_f32_e32 v4, v7, v35
	v_mul_f32_e32 v4, 0xbfb8aa3b, v4
	v_exp_f32_e32 v4, v4
	v_cvt_f32_f16_sdwa v5, v87 dst_sel:DWORD dst_unused:UNUSED_PAD src0_sel:WORD_1
	v_add_f32_e32 v4, 1.0, v4
	v_rcp_f32_e32 v7, v4
	v_cvt_f32_f16_e32 v4, v87
	v_pk_mul_f32 v[4:5], v[6:7], v[4:5]
	s_nop 0
	v_cvt_pk_f16_f32 v7, v4, v5
	v_lshrrev_b32_e32 v5, 4, v8
	v_and_b32_e32 v5, 0x10001, v5
	v_lshrrev_b32_e32 v4, 4, v14
	v_add3_u32 v5, v8, v5, s21
	v_lshrrev_b32_e32 v6, 4, v15
	v_lshrrev_b32_e32 v8, 4, v7
	v_and_b32_e32 v4, 0x10001, v4
	v_and_b32_e32 v6, 0x10001, v6
	v_and_b32_e32 v8, 0x10001, v8
	v_add3_u32 v4, v14, v4, s21
	v_add3_u32 v6, v15, v6, s21
	v_add3_u32 v7, v7, v8, s21
	v_and_b32_e32 v4, 0xfff0fff0, v4
	v_and_b32_e32 v5, 0xfff0fff0, v5
	v_and_b32_e32 v6, 0xfff0fff0, v6
	v_and_b32_e32 v7, 0xfff0fff0, v7
	global_store_dwordx4 v[12:13], v[4:7], off offset:256
	s_cbranch_vccz .LBB0_1657
	s_waitcnt vmcnt(0)
	s_cmpk_gt_u32 s4, 0xff
	s_cbranch_scc1 .LBB0_1668
	s_barrier

.LBB0_1742:
	s_add_i32 s19, 0, 0x10000
	v_add_u32_e32 v237, s19, v235
	ds_read_b128 v[134:137], v237
	ds_read_b128 v[138:141], v237 offset:1024
	ds_read_b128 v[142:145], v237 offset:2048
	ds_read_b128 v[146:149], v237 offset:3072
	v_lshl_add_u64 v[198:199], v[132:133], 0, s[16:17]
	s_add_i32 s14, s7, 0xc000
	v_lshl_add_u64 v[182:183], v[198:199], 0, s[26:27]
	s_mov_b32 m0, s14
	v_lshl_add_u64 v[242:243], v[200:201], 0, s[16:17]
	s_add_i32 s15, s7, 0xe000
	ds_read_b128 v[150:153], v236
	ds_read_b128 v[154:157], v236 offset:1024
	ds_read_b128 v[158:161], v236 offset:2048
	ds_read_b128 v[162:165], v236 offset:3072
	ds_read_b128 v[166:169], v236 offset:4096
	ds_read_b128 v[170:173], v236 offset:5120
	ds_read_b128 v[174:177], v236 offset:6144
	ds_read_b128 v[178:181], v236 offset:7168
	global_load_lds_dwordx4 v[182:183], off
	v_lshl_add_u64 v[182:183], v[242:243], 0, s[26:27]
	s_mov_b32 m0, s15
	s_nop 0
	global_load_lds_dwordx4 v[182:183], off
	s_waitcnt vmcnt(10)
	s_barrier
	s_waitcnt lgkmcnt(0)
	v_mfma_f32_16x16x32_f16 v[80:83], v[134:137], v[150:153], v[80:83]
	v_mfma_f32_16x16x32_f16 v[72:75], v[142:145], v[150:153], v[72:75]
	v_mfma_f32_16x16x32_f16 v[56:59], v[134:137], v[158:161], v[56:59]
	v_mfma_f32_16x16x32_f16 v[68:71], v[142:145], v[158:161], v[68:71]
	v_mfma_f32_16x16x32_f16 v[128:131], v[134:137], v[166:169], v[128:131]
	v_mfma_f32_16x16x32_f16 v[124:127], v[142:145], v[166:169], v[124:127]
	v_mfma_f32_16x16x32_f16 v[116:119], v[134:137], v[174:177], v[116:119]
	v_mfma_f32_16x16x32_f16 v[108:111], v[142:145], v[174:177], v[108:111]
	v_mfma_f32_16x16x32_f16 v[80:83], v[138:141], v[154:157], v[80:83]
	v_mfma_f32_16x16x32_f16 v[72:75], v[146:149], v[154:157], v[72:75]
	v_mfma_f32_16x16x32_f16 v[56:59], v[138:141], v[162:165], v[56:59]
	v_mfma_f32_16x16x32_f16 v[68:71], v[146:149], v[162:165], v[68:71]
	v_mfma_f32_16x16x32_f16 v[128:131], v[138:141], v[170:173], v[128:131]
	v_mfma_f32_16x16x32_f16 v[124:127], v[146:149], v[170:173], v[124:127]
	v_mfma_f32_16x16x32_f16 v[116:119], v[138:141], v[178:181], v[116:119]
	v_mfma_f32_16x16x32_f16 v[108:111], v[146:149], v[178:181], v[108:111]
	s_barrier
	s_add_i32 s63, 0, 0x14000
	v_lshl_add_u64 v[244:245], v[202:203], 0, s[16:17]
	s_add_i32 s19, s19, s5
	v_add_u32_e32 v238, s63, v235
	v_lshl_add_u64 v[240:241], v[244:245], 0, s[30:31]
	s_mov_b32 m0, s19
	v_lshl_add_u64 v[246:247], v[220:221], 0, s[16:17]
	s_add_i32 s37, s19, 0x2000
	ds_read_b128 v[182:185], v238
	ds_read_b128 v[186:189], v238 offset:1024
	ds_read_b128 v[190:193], v238 offset:2048
	ds_read_b128 v[194:197], v238 offset:3072
	global_load_lds_dwordx4 v[240:241], off
	v_lshl_add_u64 v[240:241], v[246:247], 0, s[30:31]
	s_mov_b32 m0, s37
	s_nop 0
	global_load_lds_dwordx4 v[240:241], off
	s_waitcnt vmcnt(10)
	s_barrier
	s_waitcnt lgkmcnt(0)
	v_mfma_f32_16x16x32_f16 v[52:55], v[182:185], v[150:153], v[52:55]
	v_mfma_f32_16x16x32_f16 v[40:43], v[190:193], v[150:153], v[40:43]
	v_mfma_f32_16x16x32_f16 v[36:39], v[182:185], v[158:161], v[36:39]
	v_mfma_f32_16x16x32_f16 v[28:31], v[190:193], v[158:161], v[28:31]
	v_mfma_f32_16x16x32_f16 v[120:123], v[182:185], v[166:169], v[120:123]
	v_mfma_f32_16x16x32_f16 v[112:115], v[190:193], v[166:169], v[112:115]
	v_mfma_f32_16x16x32_f16 v[104:107], v[182:185], v[174:177], v[104:107]
	v_mfma_f32_16x16x32_f16 v[100:103], v[190:193], v[174:177], v[100:103]
	v_mfma_f32_16x16x32_f16 v[52:55], v[186:189], v[154:157], v[52:55]
	v_mfma_f32_16x16x32_f16 v[40:43], v[194:197], v[154:157], v[40:43]
	v_mfma_f32_16x16x32_f16 v[36:39], v[186:189], v[162:165], v[36:39]
	v_mfma_f32_16x16x32_f16 v[28:31], v[194:197], v[162:165], v[28:31]
	v_mfma_f32_16x16x32_f16 v[120:123], v[186:189], v[170:173], v[120:123]
	v_mfma_f32_16x16x32_f16 v[112:115], v[194:197], v[170:173], v[112:115]
	v_mfma_f32_16x16x32_f16 v[104:107], v[186:189], v[178:181], v[104:107]
	v_mfma_f32_16x16x32_f16 v[100:103], v[194:197], v[178:181], v[100:103]
	s_mov_b32 m0, s7
	v_lshl_add_u64 v[240:241], v[198:199], 0, s[30:31]
	s_barrier
	ds_read_b128 v[150:153], v236 offset:16384
	ds_read_b128 v[154:157], v236 offset:17408
	ds_read_b128 v[158:161], v236 offset:18432
	ds_read_b128 v[162:165], v236 offset:19456
	ds_read_b128 v[166:169], v236 offset:20480
	ds_read_b128 v[170:173], v236 offset:21504
	ds_read_b128 v[174:177], v236 offset:22528
	ds_read_b128 v[178:181], v236 offset:23552
	global_load_lds_dwordx4 v[240:241], off
	v_lshl_add_u64 v[240:241], v[242:243], 0, s[30:31]
	s_mov_b32 m0, s8
	s_nop 0
	global_load_lds_dwordx4 v[240:241], off
	s_waitcnt vmcnt(10)
	s_barrier
	s_waitcnt lgkmcnt(0)
	v_mfma_f32_16x16x32_f16 v[96:99], v[134:137], v[150:153], v[96:99]
	v_mfma_f32_16x16x32_f16 v[92:95], v[142:145], v[150:153], v[92:95]
	v_mfma_f32_16x16x32_f16 v[76:79], v[134:137], v[158:161], v[76:79]
	v_mfma_f32_16x16x32_f16 v[64:67], v[142:145], v[158:161], v[64:67]
	v_mfma_f32_16x16x32_f16 v[44:47], v[134:137], v[166:169], v[44:47]
	v_mfma_f32_16x16x32_f16 v[32:35], v[142:145], v[166:169], v[32:35]
	v_mfma_f32_16x16x32_f16 v[16:19], v[134:137], v[174:177], v[16:19]
	v_mfma_f32_16x16x32_f16 v[12:15], v[142:145], v[174:177], v[12:15]
	v_mfma_f32_16x16x32_f16 v[96:99], v[138:141], v[154:157], v[96:99]
	v_mfma_f32_16x16x32_f16 v[92:95], v[146:149], v[154:157], v[92:95]
	v_mfma_f32_16x16x32_f16 v[76:79], v[138:141], v[162:165], v[76:79]
	v_mfma_f32_16x16x32_f16 v[64:67], v[146:149], v[162:165], v[64:67]
	v_mfma_f32_16x16x32_f16 v[44:47], v[138:141], v[170:173], v[44:47]
	v_mfma_f32_16x16x32_f16 v[32:35], v[146:149], v[170:173], v[32:35]
	v_mfma_f32_16x16x32_f16 v[16:19], v[138:141], v[178:181], v[16:19]
	v_mfma_f32_16x16x32_f16 v[12:15], v[146:149], v[178:181], v[12:15]
	s_barrier
	s_add_i32 s63, s63, s5
	v_lshl_add_u64 v[134:135], v[244:245], 0, s[84:85]
	s_mov_b32 m0, s63
	s_add_i32 s68, s63, 0x2000
	global_load_lds_dwordx4 v[134:135], off
	v_lshl_add_u64 v[134:135], v[246:247], 0, s[84:85]
	s_mov_b32 m0, s68
	s_nop 0
	global_load_lds_dwordx4 v[134:135], off
	s_waitcnt vmcnt(10)
	s_barrier
	v_mfma_f32_16x16x32_f16 v[88:91], v[182:185], v[150:153], v[88:91]
	v_mfma_f32_16x16x32_f16 v[84:87], v[190:193], v[150:153], v[84:87]
	v_mfma_f32_16x16x32_f16 v[60:63], v[182:185], v[158:161], v[60:63]
	v_mfma_f32_16x16x32_f16 v[48:51], v[190:193], v[158:161], v[48:51]
	v_mfma_f32_16x16x32_f16 v[24:27], v[182:185], v[166:169], v[24:27]
	v_mfma_f32_16x16x32_f16 v[20:23], v[190:193], v[166:169], v[20:23]
	v_mfma_f32_16x16x32_f16 v[8:11], v[182:185], v[174:177], v[8:11]
	v_mfma_f32_16x16x32_f16 v[4:7], v[190:193], v[174:177], v[4:7]
	v_mfma_f32_16x16x32_f16 v[88:91], v[186:189], v[154:157], v[88:91]
	v_mfma_f32_16x16x32_f16 v[84:87], v[194:197], v[154:157], v[84:87]
	v_mfma_f32_16x16x32_f16 v[60:63], v[186:189], v[162:165], v[60:63]
	v_mfma_f32_16x16x32_f16 v[48:51], v[194:197], v[162:165], v[48:51]
	v_mfma_f32_16x16x32_f16 v[24:27], v[186:189], v[170:173], v[24:27]
	v_mfma_f32_16x16x32_f16 v[20:23], v[194:197], v[170:173], v[20:23]
	v_mfma_f32_16x16x32_f16 v[8:11], v[186:189], v[178:181], v[8:11]
	v_mfma_f32_16x16x32_f16 v[4:7], v[194:197], v[178:181], v[4:7]
	s_add_i32 s69, 0, 0x18000
	v_add_u32_e32 v239, s69, v235
	s_barrier
	ds_read_b128 v[134:137], v239
	ds_read_b128 v[138:141], v239 offset:1024
	ds_read_b128 v[142:145], v239 offset:2048
	ds_read_b128 v[146:149], v239 offset:3072
	s_mov_b32 m0, s9
	v_lshl_add_u64 v[182:183], v[198:199], 0, s[84:85]
	ds_read_b128 v[150:153], v236 offset:32768
	ds_read_b128 v[154:157], v236 offset:33792
	ds_read_b128 v[158:161], v236 offset:34816
	ds_read_b128 v[162:165], v236 offset:35840
	ds_read_b128 v[166:169], v236 offset:36864
	ds_read_b128 v[170:173], v236 offset:37888
	ds_read_b128 v[174:177], v236 offset:38912
	ds_read_b128 v[178:181], v236 offset:39936
	global_load_lds_dwordx4 v[182:183], off
	v_lshl_add_u64 v[182:183], v[242:243], 0, s[84:85]
	s_mov_b32 m0, s12
	s_nop 0
	global_load_lds_dwordx4 v[182:183], off
	s_waitcnt vmcnt(10)
	s_barrier
	s_waitcnt lgkmcnt(0)
	v_mfma_f32_16x16x32_f16 v[80:83], v[134:137], v[150:153], v[80:83]
	v_mfma_f32_16x16x32_f16 v[72:75], v[142:145], v[150:153], v[72:75]
	v_mfma_f32_16x16x32_f16 v[56:59], v[134:137], v[158:161], v[56:59]
	v_mfma_f32_16x16x32_f16 v[68:71], v[142:145], v[158:161], v[68:71]
	v_mfma_f32_16x16x32_f16 v[128:131], v[134:137], v[166:169], v[128:131]
	v_mfma_f32_16x16x32_f16 v[124:127], v[142:145], v[166:169], v[124:127]
	v_mfma_f32_16x16x32_f16 v[116:119], v[134:137], v[174:177], v[116:119]
	v_mfma_f32_16x16x32_f16 v[108:111], v[142:145], v[174:177], v[108:111]
	v_mfma_f32_16x16x32_f16 v[80:83], v[138:141], v[154:157], v[80:83]
	v_mfma_f32_16x16x32_f16 v[72:75], v[146:149], v[154:157], v[72:75]
	v_mfma_f32_16x16x32_f16 v[56:59], v[138:141], v[162:165], v[56:59]
	v_mfma_f32_16x16x32_f16 v[68:71], v[146:149], v[162:165], v[68:71]
	v_mfma_f32_16x16x32_f16 v[128:131], v[138:141], v[170:173], v[128:131]
	v_mfma_f32_16x16x32_f16 v[124:127], v[146:149], v[170:173], v[124:127]
	v_mfma_f32_16x16x32_f16 v[116:119], v[138:141], v[178:181], v[116:119]
	v_mfma_f32_16x16x32_f16 v[108:111], v[146:149], v[178:181], v[108:111]
	s_barrier
	s_add_i32 s71, 0, 0x1c000
	s_add_i32 s69, s69, s5
	v_add_u32_e32 v240, s71, v235
	v_lshl_add_u64 v[248:249], v[244:245], 0, s[78:79]
	s_mov_b32 m0, s69
	s_add_i32 s70, s69, 0x2000
	ds_read_b128 v[182:185], v240
	ds_read_b128 v[186:189], v240 offset:1024
	ds_read_b128 v[190:193], v240 offset:2048
	ds_read_b128 v[194:197], v240 offset:3072
	global_load_lds_dwordx4 v[248:249], off
	v_lshl_add_u64 v[248:249], v[246:247], 0, s[78:79]
	s_mov_b32 m0, s70
	s_nop 0
	global_load_lds_dwordx4 v[248:249], off
	s_waitcnt vmcnt(10)
	s_barrier
	s_waitcnt lgkmcnt(0)
	v_mfma_f32_16x16x32_f16 v[52:55], v[182:185], v[150:153], v[52:55]
	v_mfma_f32_16x16x32_f16 v[40:43], v[190:193], v[150:153], v[40:43]
	v_mfma_f32_16x16x32_f16 v[36:39], v[182:185], v[158:161], v[36:39]
	v_mfma_f32_16x16x32_f16 v[28:31], v[190:193], v[158:161], v[28:31]
	v_mfma_f32_16x16x32_f16 v[120:123], v[182:185], v[166:169], v[120:123]
	v_mfma_f32_16x16x32_f16 v[112:115], v[190:193], v[166:169], v[112:115]
	v_mfma_f32_16x16x32_f16 v[104:107], v[182:185], v[174:177], v[104:107]
	v_mfma_f32_16x16x32_f16 v[100:103], v[190:193], v[174:177], v[100:103]
	v_mfma_f32_16x16x32_f16 v[52:55], v[186:189], v[154:157], v[52:55]
	v_mfma_f32_16x16x32_f16 v[40:43], v[194:197], v[154:157], v[40:43]
	v_mfma_f32_16x16x32_f16 v[36:39], v[186:189], v[162:165], v[36:39]
	v_mfma_f32_16x16x32_f16 v[28:31], v[194:197], v[162:165], v[28:31]
	v_mfma_f32_16x16x32_f16 v[120:123], v[186:189], v[170:173], v[120:123]
	v_mfma_f32_16x16x32_f16 v[112:115], v[194:197], v[170:173], v[112:115]
	v_mfma_f32_16x16x32_f16 v[104:107], v[186:189], v[178:181], v[104:107]
	v_mfma_f32_16x16x32_f16 v[100:103], v[194:197], v[178:181], v[100:103]
	s_mov_b32 m0, s39
	v_lshl_add_u64 v[198:199], v[198:199], 0, s[78:79]
	s_barrier
	ds_read_b128 v[150:153], v236 offset:49152
	ds_read_b128 v[154:157], v236 offset:50176
	ds_read_b128 v[158:161], v236 offset:51200
	ds_read_b128 v[162:165], v236 offset:52224
	ds_read_b128 v[166:169], v236 offset:53248
	ds_read_b128 v[170:173], v236 offset:54272
	ds_read_b128 v[174:177], v236 offset:55296
	ds_read_b128 v[178:181], v236 offset:56320
	global_load_lds_dwordx4 v[198:199], off
	v_lshl_add_u64 v[198:199], v[242:243], 0, s[78:79]
	s_mov_b32 m0, s47
	s_nop 0
	global_load_lds_dwordx4 v[198:199], off
	s_waitcnt vmcnt(10)
	s_barrier
	s_waitcnt lgkmcnt(0)
	v_mfma_f32_16x16x32_f16 v[96:99], v[134:137], v[150:153], v[96:99]
	v_mfma_f32_16x16x32_f16 v[92:95], v[142:145], v[150:153], v[92:95]
	v_mfma_f32_16x16x32_f16 v[76:79], v[134:137], v[158:161], v[76:79]
	v_mfma_f32_16x16x32_f16 v[64:67], v[142:145], v[158:161], v[64:67]
	v_mfma_f32_16x16x32_f16 v[44:47], v[134:137], v[166:169], v[44:47]
	v_mfma_f32_16x16x32_f16 v[32:35], v[142:145], v[166:169], v[32:35]
	v_mfma_f32_16x16x32_f16 v[16:19], v[134:137], v[174:177], v[16:19]
	v_mfma_f32_16x16x32_f16 v[12:15], v[142:145], v[174:177], v[12:15]
	v_mfma_f32_16x16x32_f16 v[96:99], v[138:141], v[154:157], v[96:99]
	v_mfma_f32_16x16x32_f16 v[92:95], v[146:149], v[154:157], v[92:95]
	v_mfma_f32_16x16x32_f16 v[76:79], v[138:141], v[162:165], v[76:79]
	v_mfma_f32_16x16x32_f16 v[64:67], v[146:149], v[162:165], v[64:67]
	v_mfma_f32_16x16x32_f16 v[44:47], v[138:141], v[170:173], v[44:47]
	v_mfma_f32_16x16x32_f16 v[32:35], v[146:149], v[170:173], v[32:35]
	v_mfma_f32_16x16x32_f16 v[16:19], v[138:141], v[178:181], v[16:19]
	v_mfma_f32_16x16x32_f16 v[12:15], v[146:149], v[178:181], v[12:15]
	s_barrier
	s_add_i32 s71, s71, s5
	v_lshl_add_u64 v[134:135], v[244:245], 0, vcc
	s_mov_b32 m0, s71
	s_add_i32 s76, s71, 0x2000
	global_load_lds_dwordx4 v[134:135], off
	v_lshl_add_u64 v[134:135], v[246:247], 0, vcc
	s_mov_b32 m0, s76
	s_nop 0
	global_load_lds_dwordx4 v[134:135], off
	s_waitcnt vmcnt(10)
	s_barrier
	v_mfma_f32_16x16x32_f16 v[88:91], v[182:185], v[150:153], v[88:91]
	v_mfma_f32_16x16x32_f16 v[84:87], v[190:193], v[150:153], v[84:87]
	v_mfma_f32_16x16x32_f16 v[60:63], v[182:185], v[158:161], v[60:63]
	v_mfma_f32_16x16x32_f16 v[48:51], v[190:193], v[158:161], v[48:51]
	v_mfma_f32_16x16x32_f16 v[24:27], v[182:185], v[166:169], v[24:27]
	v_mfma_f32_16x16x32_f16 v[20:23], v[190:193], v[166:169], v[20:23]
	v_mfma_f32_16x16x32_f16 v[8:11], v[182:185], v[174:177], v[8:11]
	v_mfma_f32_16x16x32_f16 v[4:7], v[190:193], v[174:177], v[4:7]
	v_mfma_f32_16x16x32_f16 v[88:91], v[186:189], v[154:157], v[88:91]
	v_mfma_f32_16x16x32_f16 v[84:87], v[194:197], v[154:157], v[84:87]
	v_mfma_f32_16x16x32_f16 v[60:63], v[186:189], v[162:165], v[60:63]
	v_mfma_f32_16x16x32_f16 v[48:51], v[194:197], v[162:165], v[48:51]
	v_mfma_f32_16x16x32_f16 v[24:27], v[186:189], v[170:173], v[24:27]
	v_mfma_f32_16x16x32_f16 v[20:23], v[194:197], v[170:173], v[20:23]
	v_mfma_f32_16x16x32_f16 v[8:11], v[186:189], v[178:181], v[8:11]
	v_mfma_f32_16x16x32_f16 v[4:7], v[194:197], v[178:181], v[4:7]
	s_add_i32 s10, s10, 2
	s_add_u32 s16, s16, 0x100
	s_addc_u32 s17, s17, 0
	s_cmp_lt_u32 s10, 6
	s_barrier
	s_cbranch_scc1 .LBB0_1742
	s_ashr_i32 s78, s48, 31
	s_mul_i32 s10, s46, 0x42
	s_mul_hi_i32 s11, s46, 0x42
	s_add_u32 s10, s10, s48
	v_mov_b32_e32 v132, v233
	v_mov_b32_e32 v133, v234
	s_addc_u32 s11, s11, s78
	s_lshl_b64 s[10:11], s[10:11], 17
	v_readlane_b32 s16, v252, 45
	v_lshlrev_b32_e32 v133, 3, v133
	s_add_u32 s16, s16, s10
	v_readlane_b32 s10, v252, 46
	v_lshlrev_b32_e32 v132, 8, v132
	s_addc_u32 s17, s10, s11
	v_add3_u32 v188, v132, s49, v133
	s_add_u32 s26, s16, 0x4200000
	v_ashrrev_i32_e32 v189, 31, v188
	s_addc_u32 s27, s17, 0
	v_lshlrev_b64 v[132:133], 1, v[188:189]
	v_lshl_add_u64 v[134:135], s[16:17], 0, v[132:133]
	v_lshl_add_u64 v[136:137], s[26:27], 0, v[132:133]
	v_add_u32_e32 v132, 0x1000, v188
	v_ashrrev_i32_e32 v133, 31, v132
	v_lshlrev_b64 v[132:133], 1, v[132:133]
	v_lshl_add_u64 v[138:139], s[16:17], 0, v[132:133]
	v_lshl_add_u64 v[176:177], s[26:27], 0, v[132:133]
	v_add_u32_e32 v132, 0x1080, v188
	v_ashrrev_i32_e32 v133, 31, v132
	v_lshlrev_b64 v[132:133], 1, v[132:133]
	v_lshl_add_u64 v[148:149], s[16:17], 0, v[132:133]
	v_lshl_add_u64 v[168:169], s[26:27], 0, v[132:133]
	v_add_u32_e32 v132, 0x2000, v188
	v_ashrrev_i32_e32 v133, 31, v132
	v_lshlrev_b64 v[132:133], 1, v[132:133]
	v_lshl_add_u64 v[144:145], s[16:17], 0, v[132:133]
	v_lshl_add_u64 v[156:157], s[26:27], 0, v[132:133]
	v_add_u32_e32 v132, 0x2080, v188
	v_ashrrev_i32_e32 v133, 31, v132
	v_lshlrev_b64 v[132:133], 1, v[132:133]
	v_lshl_add_u64 v[146:147], s[16:17], 0, v[132:133]
	v_lshl_add_u64 v[158:159], s[26:27], 0, v[132:133]
	v_add_u32_e32 v132, 0x3000, v188
	v_ashrrev_i32_e32 v133, 31, v132
	v_lshlrev_b64 v[132:133], 1, v[132:133]
	v_lshl_add_u64 v[140:141], s[16:17], 0, v[132:133]
	v_lshl_add_u64 v[150:151], s[26:27], 0, v[132:133]
	v_add_u32_e32 v132, 0x3080, v188
	v_ashrrev_i32_e32 v133, 31, v132
	v_lshlrev_b64 v[132:133], 1, v[132:133]
	v_lshl_add_u64 v[142:143], s[16:17], 0, v[132:133]
	v_lshl_add_u64 v[164:165], s[26:27], 0, v[132:133]
	global_load_dwordx4 v[180:183], v[134:135], off offset:256
	global_load_dwordx4 v[190:193], v[134:135], off
	s_nop 0
	global_load_dwordx4 v[132:135], v[142:143], off
	s_nop 0
	global_load_dwordx4 v[140:143], v[140:141], off
	s_nop 0
	global_load_dwordx4 v[152:155], v[146:147], off
	s_nop 0
	global_load_dwordx4 v[144:147], v[144:145], off
	s_nop 0
	global_load_dwordx4 v[160:163], v[148:149], off
	global_load_dwordx4 v[172:175], v[138:139], off
	global_load_dwordx4 v[184:187], v[136:137], off offset:256
	global_load_dwordx4 v[194:197], v[136:137], off
	s_nop 0
	global_load_dwordx4 v[136:139], v[164:165], off
	s_nop 0
	global_load_dwordx4 v[148:151], v[150:151], off
	s_nop 0
	global_load_dwordx4 v[164:167], v[158:159], off
	s_nop 0
	global_load_dwordx4 v[156:159], v[156:157], off
	s_nop 0
	global_load_dwordx4 v[168:171], v[168:169], off
	s_nop 0
	global_load_dwordx4 v[176:179], v[176:177], off
	s_mov_b32 s10, 6
	s_mov_b64 s[30:31], 0x500
	s_mov_b64 s[84:85], 0x80500
	s_mov_b64 vcc, 0x580
	s_mov_b64 s[52:53], 0x80580
	s_waitcnt vmcnt(0)
	s_nop 0
	v_cvt_f32_f16_e32 v189, v190
	v_rcp_f32_e32 v198, v189
	v_cvt_f32_f16_e32 v189, v192
	v_cvt_f32_f16_e32 v244, v194
	v_cvt_f32_f16_sdwa v245, v194 dst_sel:DWORD dst_unused:UNUSED_PAD src0_sel:WORD_1
	v_cvt_f32_f16_e32 v194, v195
	v_rcp_f32_e32 v242, v189
	v_cvt_f32_f16_sdwa v189, v190 dst_sel:DWORD dst_unused:UNUSED_PAD src0_sel:WORD_1
	v_cvt_f32_f16_sdwa v195, v195 dst_sel:DWORD dst_unused:UNUSED_PAD src0_sel:WORD_1
	v_cvt_f32_f16_e32 v246, v196
	v_cvt_f32_f16_sdwa v247, v196 dst_sel:DWORD dst_unused:UNUSED_PAD src0_sel:WORD_1
	v_rcp_f32_e32 v199, v189
	v_cvt_f32_f16_sdwa v189, v192 dst_sel:DWORD dst_unused:UNUSED_PAD src0_sel:WORD_1
	v_cvt_f32_f16_e32 v196, v186
	v_pk_mul_f32 v[198:199], v[198:199], v[244:245]
	v_rcp_f32_e32 v243, v189
	v_cvt_f32_f16_e32 v189, v191
	v_pk_mul_f32 v[80:81], v[80:81], v[198:199]
	v_rcp_f32_e32 v190, v189
	v_cvt_f32_f16_e32 v189, v193
	v_rcp_f32_e32 v192, v189
	v_cvt_f32_f16_sdwa v189, v191 dst_sel:DWORD dst_unused:UNUSED_PAD src0_sel:WORD_1
	v_rcp_f32_e32 v191, v189
	v_cvt_f32_f16_sdwa v189, v193 dst_sel:DWORD dst_unused:UNUSED_PAD src0_sel:WORD_1
	v_pk_mul_f32 v[190:191], v[190:191], v[194:195]
	s_nop 0
	v_pk_mul_f32 v[82:83], v[82:83], v[190:191]
	v_rcp_f32_e32 v193, v189
	v_cvt_f32_f16_e32 v190, v197
	v_cvt_f32_f16_sdwa v191, v197 dst_sel:DWORD dst_unused:UNUSED_PAD src0_sel:WORD_1
	v_cvt_f32_f16_e32 v189, v180
	v_cvt_f32_f16_sdwa v180, v180 dst_sel:DWORD dst_unused:UNUSED_PAD src0_sel:WORD_1
	v_pk_mul_f32 v[194:195], v[242:243], v[246:247]
	v_pk_mul_f32 v[190:191], v[192:193], v[190:191]
	v_pk_mul_f32 v[72:73], v[72:73], v[194:195]
	v_pk_mul_f32 v[74:75], v[74:75], v[190:191]
	v_rcp_f32_e32 v191, v180
	v_cvt_f32_f16_sdwa v180, v182 dst_sel:DWORD dst_unused:UNUSED_PAD src0_sel:WORD_1
	v_cvt_f32_f16_e32 v194, v184
	v_cvt_f32_f16_sdwa v195, v184 dst_sel:DWORD dst_unused:UNUSED_PAD src0_sel:WORD_1
	v_cvt_f32_f16_e32 v184, v185
	v_rcp_f32_e32 v193, v180
	v_cvt_f32_f16_e32 v180, v181
	v_cvt_f32_f16_sdwa v181, v181 dst_sel:DWORD dst_unused:UNUSED_PAD src0_sel:WORD_1
	v_cvt_f32_f16_sdwa v185, v185 dst_sel:DWORD dst_unused:UNUSED_PAD src0_sel:WORD_1
	v_rcp_f32_e32 v190, v189
	v_rcp_f32_e32 v180, v180
	v_rcp_f32_e32 v181, v181
	v_cvt_f32_f16_e32 v189, v182
	v_cvt_f32_f16_e32 v182, v183
	v_cvt_f32_f16_sdwa v197, v186 dst_sel:DWORD dst_unused:UNUSED_PAD src0_sel:WORD_1
	v_pk_mul_f32 v[180:181], v[180:181], v[184:185]
	v_rcp_f32_e32 v192, v189
	v_pk_mul_f32 v[54:55], v[54:55], v[180:181]
	v_cvt_f32_f16_sdwa v180, v183 dst_sel:DWORD dst_unused:UNUSED_PAD src0_sel:WORD_1
	v_rcp_f32_e32 v182, v182
	v_cvt_f32_f16_sdwa v181, v187 dst_sel:DWORD dst_unused:UNUSED_PAD src0_sel:WORD_1
	v_pk_mul_f32 v[184:185], v[192:193], v[196:197]
	v_rcp_f32_e32 v183, v180
	v_cvt_f32_f16_e32 v180, v187
	v_pk_mul_f32 v[40:41], v[40:41], v[184:185]
	v_cvt_f32_f16_e32 v184, v176
	v_cvt_f32_f16_sdwa v185, v176 dst_sel:DWORD dst_unused:UNUSED_PAD src0_sel:WORD_1
	v_pk_mul_f32 v[180:181], v[182:183], v[180:181]
	v_cvt_f32_f16_e32 v176, v177
	v_pk_mul_f32 v[42:43], v[42:43], v[180:181]
	v_cvt_f32_f16_e32 v180, v172
	v_cvt_f32_f16_e32 v181, v174
	v_cvt_f32_f16_sdwa v172, v172 dst_sel:DWORD dst_unused:UNUSED_PAD src0_sel:WORD_1
	v_cvt_f32_f16_sdwa v177, v177 dst_sel:DWORD dst_unused:UNUSED_PAD src0_sel:WORD_1
	v_cvt_f32_f16_e32 v186, v178
	v_rcp_f32_e32 v182, v181
	v_rcp_f32_e32 v181, v172
	v_cvt_f32_f16_sdwa v172, v174 dst_sel:DWORD dst_unused:UNUSED_PAD src0_sel:WORD_1
	v_cvt_f32_f16_e32 v174, v175
	v_cvt_f32_f16_sdwa v187, v178 dst_sel:DWORD dst_unused:UNUSED_PAD src0_sel:WORD_1
	v_cvt_f32_f16_e32 v178, v170
	v_rcp_f32_e32 v183, v172
	v_cvt_f32_f16_e32 v172, v173
	v_cvt_f32_f16_sdwa v173, v173 dst_sel:DWORD dst_unused:UNUSED_PAD src0_sel:WORD_1
	v_rcp_f32_e32 v174, v174
	v_rcp_f32_e32 v180, v180
	v_rcp_f32_e32 v172, v172
	v_rcp_f32_e32 v173, v173
	v_pk_mul_f32 v[190:191], v[190:191], v[194:195]
	v_pk_mul_f32 v[180:181], v[180:181], v[184:185]
	v_pk_mul_f32 v[52:53], v[52:53], v[190:191]
	v_pk_mul_f32 v[172:173], v[172:173], v[176:177]
	v_pk_mul_f32 v[176:177], v[182:183], v[186:187]
	v_pk_mul_f32 v[58:59], v[58:59], v[172:173]
	v_cvt_f32_f16_sdwa v172, v175 dst_sel:DWORD dst_unused:UNUSED_PAD src0_sel:WORD_1
	v_cvt_f32_f16_sdwa v173, v179 dst_sel:DWORD dst_unused:UNUSED_PAD src0_sel:WORD_1
	v_pk_mul_f32 v[68:69], v[68:69], v[176:177]
	v_cvt_f32_f16_e32 v176, v168
	v_rcp_f32_e32 v175, v172
	v_cvt_f32_f16_e32 v172, v179
	v_cvt_f32_f16_sdwa v177, v168 dst_sel:DWORD dst_unused:UNUSED_PAD src0_sel:WORD_1
	v_cvt_f32_f16_e32 v168, v169
	v_cvt_f32_f16_sdwa v169, v169 dst_sel:DWORD dst_unused:UNUSED_PAD src0_sel:WORD_1
	v_pk_mul_f32 v[172:173], v[174:175], v[172:173]
	v_cvt_f32_f16_sdwa v179, v170 dst_sel:DWORD dst_unused:UNUSED_PAD src0_sel:WORD_1
	v_pk_mul_f32 v[70:71], v[70:71], v[172:173]
	v_cvt_f32_f16_e32 v172, v160
	v_cvt_f32_f16_e32 v173, v162
	v_cvt_f32_f16_sdwa v160, v160 dst_sel:DWORD dst_unused:UNUSED_PAD src0_sel:WORD_1
	v_cvt_f32_f16_e32 v170, v158
	v_rcp_f32_e32 v172, v172
	v_rcp_f32_e32 v174, v173
	v_rcp_f32_e32 v173, v160
	v_cvt_f32_f16_sdwa v160, v162 dst_sel:DWORD dst_unused:UNUSED_PAD src0_sel:WORD_1
	v_cvt_f32_f16_e32 v162, v163
	v_pk_mul_f32 v[56:57], v[56:57], v[180:181]
	v_pk_mul_f32 v[172:173], v[172:173], v[176:177]
	v_rcp_f32_e32 v175, v160
	v_cvt_f32_f16_e32 v160, v161
	v_cvt_f32_f16_sdwa v161, v161 dst_sel:DWORD dst_unused:UNUSED_PAD src0_sel:WORD_1
	v_rcp_f32_e32 v162, v162
	v_pk_mul_f32 v[36:37], v[36:37], v[172:173]
	v_rcp_f32_e32 v160, v160
	v_rcp_f32_e32 v161, v161
	s_nop 0
	v_pk_mul_f32 v[160:161], v[160:161], v[168:169]
	s_nop 0
	v_pk_mul_f32 v[38:39], v[38:39], v[160:161]
	v_cvt_f32_f16_sdwa v160, v163 dst_sel:DWORD dst_unused:UNUSED_PAD src0_sel:WORD_1
	v_cvt_f32_f16_sdwa v161, v171 dst_sel:DWORD dst_unused:UNUSED_PAD src0_sel:WORD_1
	v_pk_mul_f32 v[168:169], v[174:175], v[178:179]
	v_rcp_f32_e32 v163, v160
	v_cvt_f32_f16_e32 v160, v171
	v_pk_mul_f32 v[28:29], v[28:29], v[168:169]
	v_cvt_f32_f16_sdwa v171, v158 dst_sel:DWORD dst_unused:UNUSED_PAD src0_sel:WORD_1
	v_pk_mul_f32 v[160:161], v[162:163], v[160:161]
	s_nop 0
	v_pk_mul_f32 v[30:31], v[30:31], v[160:161]
	v_cvt_f32_f16_e32 v160, v144
	v_cvt_f32_f16_e32 v161, v146
	v_cvt_f32_f16_sdwa v144, v144 dst_sel:DWORD dst_unused:UNUSED_PAD src0_sel:WORD_1
	v_cvt_f32_f16_e32 v162, v156
	v_rcp_f32_e32 v160, v160
	v_rcp_f32_e32 v168, v161
	v_rcp_f32_e32 v161, v144
	v_cvt_f32_f16_sdwa v144, v146 dst_sel:DWORD dst_unused:UNUSED_PAD src0_sel:WORD_1
	v_cvt_f32_f16_sdwa v163, v156 dst_sel:DWORD dst_unused:UNUSED_PAD src0_sel:WORD_1
	v_cvt_f32_f16_e32 v156, v157
	v_cvt_f32_f16_sdwa v157, v157 dst_sel:DWORD dst_unused:UNUSED_PAD src0_sel:WORD_1
	v_rcp_f32_e32 v169, v144
	v_cvt_f32_f16_e32 v144, v145
	v_cvt_f32_f16_sdwa v145, v145 dst_sel:DWORD dst_unused:UNUSED_PAD src0_sel:WORD_1
	v_pk_mul_f32 v[160:161], v[160:161], v[162:163]
	v_cvt_f32_f16_e32 v146, v147
	v_rcp_f32_e32 v144, v144
	v_rcp_f32_e32 v145, v145
	v_pk_mul_f32 v[160:161], v[128:129], v[160:161]
	v_cvt_f32_f16_sdwa v128, v147 dst_sel:DWORD dst_unused:UNUSED_PAD src0_sel:WORD_1
	v_rcp_f32_e32 v146, v146
	v_pk_mul_f32 v[144:145], v[144:145], v[156:157]
	v_cvt_f32_f16_sdwa v129, v159 dst_sel:DWORD dst_unused:UNUSED_PAD src0_sel:WORD_1
	v_pk_mul_f32 v[162:163], v[130:131], v[144:145]
	v_rcp_f32_e32 v147, v128
	v_cvt_f32_f16_e32 v128, v159
	v_pk_mul_f32 v[130:131], v[168:169], v[170:171]
	v_cvt_f32_f16_e32 v145, v155
	v_pk_mul_f32 v[156:157], v[124:125], v[130:131]
	v_cvt_f32_f16_e32 v125, v154
	v_pk_mul_f32 v[128:129], v[146:147], v[128:129]
	v_cvt_f32_f16_e32 v124, v152
	v_pk_mul_f32 v[158:159], v[126:127], v[128:129]
	v_rcp_f32_e32 v126, v125
	v_cvt_f32_f16_sdwa v125, v152 dst_sel:DWORD dst_unused:UNUSED_PAD src0_sel:WORD_1
	v_cvt_f32_f16_e32 v144, v153
	v_rcp_f32_e32 v152, v145
	v_cvt_f32_f16_sdwa v145, v153 dst_sel:DWORD dst_unused:UNUSED_PAD src0_sel:WORD_1
	v_rcp_f32_e32 v124, v124
	v_rcp_f32_e32 v125, v125
	v_cvt_f32_f16_e32 v128, v164
	v_cvt_f32_f16_sdwa v129, v164 dst_sel:DWORD dst_unused:UNUSED_PAD src0_sel:WORD_1
	v_cvt_f32_f16_sdwa v127, v154 dst_sel:DWORD dst_unused:UNUSED_PAD src0_sel:WORD_1
	v_rcp_f32_e32 v144, v144
	v_rcp_f32_e32 v145, v145
	v_cvt_f32_f16_e32 v146, v165
	v_cvt_f32_f16_sdwa v147, v165 dst_sel:DWORD dst_unused:UNUSED_PAD src0_sel:WORD_1
	v_pk_mul_f32 v[124:125], v[124:125], v[128:129]
	v_rcp_f32_e32 v127, v127
	v_cvt_f32_f16_e32 v130, v166
	v_cvt_f32_f16_sdwa v131, v166 dst_sel:DWORD dst_unused:UNUSED_PAD src0_sel:WORD_1
	v_pk_mul_f32 v[128:129], v[144:145], v[146:147]
	v_pk_mul_f32 v[144:145], v[120:121], v[124:125]
	v_cvt_f32_f16_sdwa v120, v155 dst_sel:DWORD dst_unused:UNUSED_PAD src0_sel:WORD_1
	v_pk_mul_f32 v[146:147], v[122:123], v[128:129]
	v_cvt_f32_f16_sdwa v121, v167 dst_sel:DWORD dst_unused:UNUSED_PAD src0_sel:WORD_1
	v_pk_mul_f32 v[122:123], v[126:127], v[130:131]
	v_rcp_f32_e32 v153, v120
	v_cvt_f32_f16_e32 v120, v167
	v_pk_mul_f32 v[124:125], v[112:113], v[122:123]
	v_cvt_f32_f16_e32 v113, v142
	v_cvt_f32_f16_e32 v112, v140
	v_pk_mul_f32 v[120:121], v[152:153], v[120:121]
	v_cvt_f32_f16_e32 v129, v143
	v_pk_mul_f32 v[126:127], v[114:115], v[120:121]
	v_rcp_f32_e32 v114, v113
	v_cvt_f32_f16_sdwa v113, v140 dst_sel:DWORD dst_unused:UNUSED_PAD src0_sel:WORD_1
	v_rcp_f32_e32 v112, v112
	v_cvt_f32_f16_e32 v120, v148
	v_cvt_f32_f16_sdwa v121, v148 dst_sel:DWORD dst_unused:UNUSED_PAD src0_sel:WORD_1
	v_rcp_f32_e32 v113, v113
	v_cvt_f32_f16_sdwa v115, v142 dst_sel:DWORD dst_unused:UNUSED_PAD src0_sel:WORD_1
	v_cvt_f32_f16_e32 v122, v150
	v_cvt_f32_f16_sdwa v123, v150 dst_sel:DWORD dst_unused:UNUSED_PAD src0_sel:WORD_1
	v_pk_mul_f32 v[112:113], v[112:113], v[120:121]
	v_rcp_f32_e32 v115, v115
	v_pk_mul_f32 v[152:153], v[116:117], v[112:113]
	v_cvt_f32_f16_sdwa v112, v143 dst_sel:DWORD dst_unused:UNUSED_PAD src0_sel:WORD_1
	v_cvt_f32_f16_e32 v128, v141
	v_rcp_f32_e32 v130, v129
	v_cvt_f32_f16_sdwa v129, v141 dst_sel:DWORD dst_unused:UNUSED_PAD src0_sel:WORD_1
	v_rcp_f32_e32 v131, v112
	v_cvt_f32_f16_e32 v112, v151
	v_cvt_f32_f16_sdwa v113, v151 dst_sel:DWORD dst_unused:UNUSED_PAD src0_sel:WORD_1
	v_pk_mul_f32 v[114:115], v[114:115], v[122:123]
	v_rcp_f32_e32 v128, v128
	v_rcp_f32_e32 v129, v129
	v_cvt_f32_f16_e32 v140, v149
	v_cvt_f32_f16_sdwa v141, v149 dst_sel:DWORD dst_unused:UNUSED_PAD src0_sel:WORD_1
	v_pk_mul_f32 v[148:149], v[108:109], v[114:115]
	v_cvt_f32_f16_e32 v109, v134
	v_cvt_f32_f16_e32 v117, v135
	v_pk_mul_f32 v[112:113], v[130:131], v[112:113]
	v_pk_mul_f32 v[120:121], v[128:129], v[140:141]
	v_pk_mul_f32 v[150:151], v[110:111], v[112:113]
	v_cvt_f32_f16_e32 v108, v132
	v_rcp_f32_e32 v110, v109
	v_cvt_f32_f16_sdwa v109, v132 dst_sel:DWORD dst_unused:UNUSED_PAD src0_sel:WORD_1
	v_pk_mul_f32 v[154:155], v[118:119], v[120:121]
	v_cvt_f32_f16_e32 v116, v133
	v_rcp_f32_e32 v118, v117
	v_cvt_f32_f16_sdwa v117, v133 dst_sel:DWORD dst_unused:UNUSED_PAD src0_sel:WORD_1
	v_rcp_f32_e32 v108, v108
	v_rcp_f32_e32 v109, v109
	v_cvt_f32_f16_e32 v112, v136
	v_cvt_f32_f16_sdwa v113, v136 dst_sel:DWORD dst_unused:UNUSED_PAD src0_sel:WORD_1
	v_rcp_f32_e32 v116, v116
	v_rcp_f32_e32 v117, v117
	v_cvt_f32_f16_e32 v120, v137
	v_cvt_f32_f16_sdwa v121, v137 dst_sel:DWORD dst_unused:UNUSED_PAD src0_sel:WORD_1
	v_cvt_f32_f16_sdwa v111, v134 dst_sel:DWORD dst_unused:UNUSED_PAD src0_sel:WORD_1
	v_pk_mul_f32 v[108:109], v[108:109], v[112:113]
	v_cvt_f32_f16_e32 v114, v138
	v_pk_mul_f32 v[112:113], v[116:117], v[120:121]
	v_pk_mul_f32 v[120:121], v[104:105], v[108:109]
	v_cvt_f32_f16_sdwa v104, v135 dst_sel:DWORD dst_unused:UNUSED_PAD src0_sel:WORD_1
	v_rcp_f32_e32 v111, v111
	v_cvt_f32_f16_sdwa v115, v138 dst_sel:DWORD dst_unused:UNUSED_PAD src0_sel:WORD_1
	v_cvt_f32_f16_sdwa v105, v139 dst_sel:DWORD dst_unused:UNUSED_PAD src0_sel:WORD_1
	v_rcp_f32_e32 v119, v104
	v_cvt_f32_f16_e32 v104, v139
	v_pk_mul_f32 v[122:123], v[106:107], v[112:113]
	v_pk_mul_f32 v[106:107], v[110:111], v[114:115]
	v_pk_mul_f32 v[104:105], v[118:119], v[104:105]
	v_pk_mul_f32 v[116:117], v[100:101], v[106:107]
	v_add_u32_e32 v100, 0x8000, v188
	v_ashrrev_i32_e32 v101, 31, v100
	v_lshlrev_b64 v[100:101], 1, v[100:101]
	v_pk_mul_f32 v[118:119], v[102:103], v[104:105]
	v_lshl_add_u64 v[104:105], s[16:17], 0, v[100:101]
	v_lshl_add_u64 v[112:113], s[26:27], 0, v[100:101]
	v_add_u32_e32 v100, 0x8080, v188
	v_ashrrev_i32_e32 v101, 31, v100
	v_lshlrev_b64 v[100:101], 1, v[100:101]
	v_lshl_add_u64 v[102:103], s[16:17], 0, v[100:101]
	v_lshl_add_u64 v[114:115], s[26:27], 0, v[100:101]
	v_add_u32_e32 v100, 0x9000, v188
	v_ashrrev_i32_e32 v101, 31, v100
	v_lshlrev_b64 v[100:101], 1, v[100:101]
	v_lshl_add_u64 v[106:107], s[16:17], 0, v[100:101]
	v_lshl_add_u64 v[190:191], s[26:27], 0, v[100:101]
	v_add_u32_e32 v100, 0x9080, v188
	v_ashrrev_i32_e32 v101, 31, v100
	v_lshlrev_b64 v[100:101], 1, v[100:101]
	v_lshl_add_u64 v[140:141], s[16:17], 0, v[100:101]
	v_lshl_add_u64 v[180:181], s[26:27], 0, v[100:101]
	v_add_u32_e32 v100, 0xa000, v188
	v_ashrrev_i32_e32 v101, 31, v100
	v_lshlrev_b64 v[100:101], 1, v[100:101]
	v_lshl_add_u64 v[136:137], s[16:17], 0, v[100:101]
	v_lshl_add_u64 v[176:177], s[26:27], 0, v[100:101]
	v_add_u32_e32 v100, 0xa080, v188
	v_ashrrev_i32_e32 v101, 31, v100
	v_lshlrev_b64 v[100:101], 1, v[100:101]
	v_lshl_add_u64 v[132:133], s[16:17], 0, v[100:101]
	v_lshl_add_u64 v[172:173], s[26:27], 0, v[100:101]
	v_add_u32_e32 v100, 0xb000, v188
	v_ashrrev_i32_e32 v101, 31, v100
	v_lshlrev_b64 v[100:101], 1, v[100:101]
	v_lshl_add_u64 v[128:129], s[16:17], 0, v[100:101]
	v_lshl_add_u64 v[168:169], s[26:27], 0, v[100:101]
	v_add_u32_e32 v100, 0xb080, v188
	v_ashrrev_i32_e32 v101, 31, v100
	v_lshlrev_b64 v[100:101], 1, v[100:101]
	v_lshl_add_u64 v[108:109], s[16:17], 0, v[100:101]
	v_lshl_add_u64 v[164:165], s[26:27], 0, v[100:101]
	global_load_dwordx4 v[108:111], v[108:109], off
	s_nop 0
	global_load_dwordx4 v[128:131], v[128:129], off
	s_nop 0
	global_load_dwordx4 v[132:135], v[132:133], off
	s_nop 0
	global_load_dwordx4 v[136:139], v[136:137], off
	s_nop 0
	global_load_dwordx4 v[140:143], v[140:141], off
	s_nop 0
	global_load_dwordx4 v[184:187], v[106:107], off
	s_nop 0
	global_load_dwordx4 v[100:103], v[102:103], off
	s_nop 0
	global_load_dwordx4 v[104:107], v[104:105], off
	s_nop 0
	global_load_dwordx4 v[164:167], v[164:165], off
	s_nop 0
	global_load_dwordx4 v[168:171], v[168:169], off
	s_nop 0
	global_load_dwordx4 v[172:175], v[172:173], off
	s_nop 0
	global_load_dwordx4 v[176:179], v[176:177], off
	s_nop 0
	global_load_dwordx4 v[180:183], v[180:181], off
	s_nop 0
	global_load_dwordx4 v[188:191], v[190:191], off
	s_nop 0
	global_load_dwordx4 v[192:195], v[114:115], off
	global_load_dwordx4 v[196:199], v[112:113], off
	s_waitcnt vmcnt(0)
	s_nop 0
	v_cvt_f32_f16_e32 v112, v104
	v_cvt_f32_f16_e32 v113, v106
	v_cvt_f32_f16_sdwa v104, v104 dst_sel:DWORD dst_unused:UNUSED_PAD src0_sel:WORD_1
	v_rcp_f32_e32 v242, v113
	v_rcp_f32_e32 v113, v104
	v_cvt_f32_f16_sdwa v104, v106 dst_sel:DWORD dst_unused:UNUSED_PAD src0_sel:WORD_1
	v_rcp_f32_e32 v112, v112
	v_cvt_f32_f16_e32 v114, v196
	v_cvt_f32_f16_sdwa v115, v196 dst_sel:DWORD dst_unused:UNUSED_PAD src0_sel:WORD_1
	v_rcp_f32_e32 v243, v104
	v_cvt_f32_f16_e32 v104, v105
	v_cvt_f32_f16_sdwa v105, v105 dst_sel:DWORD dst_unused:UNUSED_PAD src0_sel:WORD_1
	v_cvt_f32_f16_e32 v196, v197
	v_cvt_f32_f16_sdwa v197, v197 dst_sel:DWORD dst_unused:UNUSED_PAD src0_sel:WORD_1
	v_rcp_f32_e32 v104, v104
	v_rcp_f32_e32 v105, v105
	v_pk_mul_f32 v[112:113], v[112:113], v[114:115]
	v_cvt_f32_f16_e32 v244, v198
	v_cvt_f32_f16_sdwa v245, v198 dst_sel:DWORD dst_unused:UNUSED_PAD src0_sel:WORD_1
	v_cvt_f32_f16_e32 v106, v107
	v_pk_mul_f32 v[112:113], v[96:97], v[112:113]
	v_cvt_f32_f16_sdwa v96, v107 dst_sel:DWORD dst_unused:UNUSED_PAD src0_sel:WORD_1
	v_pk_mul_f32 v[104:105], v[104:105], v[196:197]
	v_rcp_f32_e32 v106, v106
	v_pk_mul_f32 v[114:115], v[98:99], v[104:105]
	v_rcp_f32_e32 v107, v96
	v_cvt_f32_f16_e32 v96, v199
	v_cvt_f32_f16_sdwa v97, v199 dst_sel:DWORD dst_unused:UNUSED_PAD src0_sel:WORD_1
	v_pk_mul_f32 v[98:99], v[242:243], v[244:245]
	s_mov_b64 s[16:17], 0
	v_pk_mul_f32 v[104:105], v[92:93], v[98:99]
	v_cvt_f32_f16_e32 v93, v102
	v_pk_mul_f32 v[96:97], v[106:107], v[96:97]
	v_cvt_f32_f16_e32 v92, v100
	v_pk_mul_f32 v[106:107], v[94:95], v[96:97]
	v_rcp_f32_e32 v96, v93
	v_cvt_f32_f16_sdwa v93, v100 dst_sel:DWORD dst_unused:UNUSED_PAD src0_sel:WORD_1
	v_rcp_f32_e32 v92, v92
	v_cvt_f32_f16_e32 v94, v192
	v_cvt_f32_f16_sdwa v95, v192 dst_sel:DWORD dst_unused:UNUSED_PAD src0_sel:WORD_1
	v_rcp_f32_e32 v93, v93
	v_cvt_f32_f16_sdwa v97, v102 dst_sel:DWORD dst_unused:UNUSED_PAD src0_sel:WORD_1
	v_cvt_f32_f16_e32 v102, v103
	v_cvt_f32_f16_e32 v100, v101
	v_pk_mul_f32 v[92:93], v[92:93], v[94:95]
	v_cvt_f32_f16_sdwa v101, v101 dst_sel:DWORD dst_unused:UNUSED_PAD src0_sel:WORD_1
	v_pk_mul_f32 v[92:93], v[88:89], v[92:93]
	v_cvt_f32_f16_sdwa v88, v103 dst_sel:DWORD dst_unused:UNUSED_PAD src0_sel:WORD_1
	v_rcp_f32_e32 v102, v102
	v_cvt_f32_f16_sdwa v89, v195 dst_sel:DWORD dst_unused:UNUSED_PAD src0_sel:WORD_1
	v_rcp_f32_e32 v100, v100
	v_rcp_f32_e32 v103, v88
	v_cvt_f32_f16_e32 v88, v195
	v_rcp_f32_e32 v101, v101
	v_cvt_f32_f16_e32 v192, v193
	v_cvt_f32_f16_sdwa v193, v193 dst_sel:DWORD dst_unused:UNUSED_PAD src0_sel:WORD_1
	v_rcp_f32_e32 v97, v97
	v_cvt_f32_f16_e32 v98, v194
	v_cvt_f32_f16_sdwa v99, v194 dst_sel:DWORD dst_unused:UNUSED_PAD src0_sel:WORD_1
	v_pk_mul_f32 v[88:89], v[102:103], v[88:89]
	v_pk_mul_f32 v[94:95], v[100:101], v[192:193]
	v_pk_mul_f32 v[86:87], v[86:87], v[88:89]
	v_cvt_f32_f16_e32 v89, v186
	v_cvt_f32_f16_e32 v101, v187
	v_pk_mul_f32 v[94:95], v[90:91], v[94:95]
	v_pk_mul_f32 v[90:91], v[96:97], v[98:99]
	v_cvt_f32_f16_e32 v88, v184
	v_pk_mul_f32 v[84:85], v[84:85], v[90:91]
	v_rcp_f32_e32 v90, v89
	v_cvt_f32_f16_sdwa v89, v184 dst_sel:DWORD dst_unused:UNUSED_PAD src0_sel:WORD_1
	v_cvt_f32_f16_e32 v100, v185
	v_rcp_f32_e32 v184, v101
	v_cvt_f32_f16_sdwa v101, v185 dst_sel:DWORD dst_unused:UNUSED_PAD src0_sel:WORD_1
	v_rcp_f32_e32 v88, v88
	v_rcp_f32_e32 v89, v89
	v_cvt_f32_f16_e32 v96, v188
	v_cvt_f32_f16_sdwa v97, v188 dst_sel:DWORD dst_unused:UNUSED_PAD src0_sel:WORD_1
	v_cvt_f32_f16_sdwa v91, v186 dst_sel:DWORD dst_unused:UNUSED_PAD src0_sel:WORD_1
	v_rcp_f32_e32 v100, v100
	v_rcp_f32_e32 v101, v101
	v_cvt_f32_f16_e32 v102, v189
	v_cvt_f32_f16_sdwa v103, v189 dst_sel:DWORD dst_unused:UNUSED_PAD src0_sel:WORD_1
	v_pk_mul_f32 v[88:89], v[88:89], v[96:97]
	v_rcp_f32_e32 v91, v91
	v_cvt_f32_f16_e32 v98, v190
	v_cvt_f32_f16_sdwa v99, v190 dst_sel:DWORD dst_unused:UNUSED_PAD src0_sel:WORD_1
	v_pk_mul_f32 v[96:97], v[100:101], v[102:103]
	v_pk_mul_f32 v[100:101], v[76:77], v[88:89]
	v_cvt_f32_f16_sdwa v76, v187 dst_sel:DWORD dst_unused:UNUSED_PAD src0_sel:WORD_1
	v_pk_mul_f32 v[102:103], v[78:79], v[96:97]
	v_cvt_f32_f16_sdwa v77, v191 dst_sel:DWORD dst_unused:UNUSED_PAD src0_sel:WORD_1
	v_pk_mul_f32 v[78:79], v[90:91], v[98:99]
	v_rcp_f32_e32 v185, v76
	v_cvt_f32_f16_e32 v76, v191
	v_pk_mul_f32 v[96:97], v[64:65], v[78:79]
	v_cvt_f32_f16_e32 v65, v142
	v_cvt_f32_f16_e32 v79, v143
	v_pk_mul_f32 v[76:77], v[184:185], v[76:77]
	v_cvt_f32_f16_e32 v64, v140
	v_pk_mul_f32 v[98:99], v[66:67], v[76:77]
	v_rcp_f32_e32 v66, v65
	v_cvt_f32_f16_sdwa v65, v140 dst_sel:DWORD dst_unused:UNUSED_PAD src0_sel:WORD_1
	v_cvt_f32_f16_e32 v78, v141
	v_rcp_f32_e32 v90, v79
	v_cvt_f32_f16_sdwa v79, v141 dst_sel:DWORD dst_unused:UNUSED_PAD src0_sel:WORD_1
	v_rcp_f32_e32 v64, v64
	v_rcp_f32_e32 v65, v65
	v_cvt_f32_f16_e32 v76, v180
	v_cvt_f32_f16_sdwa v77, v180 dst_sel:DWORD dst_unused:UNUSED_PAD src0_sel:WORD_1
	v_rcp_f32_e32 v78, v78
	v_rcp_f32_e32 v79, v79
	v_cvt_f32_f16_e32 v140, v181
	v_cvt_f32_f16_sdwa v141, v181 dst_sel:DWORD dst_unused:UNUSED_PAD src0_sel:WORD_1
	v_cvt_f32_f16_sdwa v67, v142 dst_sel:DWORD dst_unused:UNUSED_PAD src0_sel:WORD_1
	v_pk_mul_f32 v[64:65], v[64:65], v[76:77]
	v_cvt_f32_f16_e32 v88, v182
	v_pk_mul_f32 v[76:77], v[78:79], v[140:141]
	v_rcp_f32_e32 v67, v67
	v_cvt_f32_f16_sdwa v89, v182 dst_sel:DWORD dst_unused:UNUSED_PAD src0_sel:WORD_1
	v_pk_mul_f32 v[78:79], v[62:63], v[76:77]
	v_pk_mul_f32 v[76:77], v[60:61], v[64:65]
	v_cvt_f32_f16_sdwa v60, v143 dst_sel:DWORD dst_unused:UNUSED_PAD src0_sel:WORD_1
	v_cvt_f32_f16_sdwa v61, v183 dst_sel:DWORD dst_unused:UNUSED_PAD src0_sel:WORD_1
	v_pk_mul_f32 v[62:63], v[66:67], v[88:89]
	v_cvt_f32_f16_e32 v89, v139
	v_rcp_f32_e32 v91, v60
	v_cvt_f32_f16_e32 v60, v183
	v_pk_mul_f32 v[64:65], v[48:49], v[62:63]
	v_cvt_f32_f16_e32 v49, v138
	v_cvt_f32_f16_e32 v48, v136
	v_pk_mul_f32 v[60:61], v[90:91], v[60:61]
	v_cvt_f32_f16_e32 v88, v137
	v_pk_mul_f32 v[66:67], v[50:51], v[60:61]
	v_rcp_f32_e32 v50, v49
	v_cvt_f32_f16_sdwa v49, v136 dst_sel:DWORD dst_unused:UNUSED_PAD src0_sel:WORD_1
	v_rcp_f32_e32 v48, v48
	v_cvt_f32_f16_e32 v60, v176
	v_cvt_f32_f16_sdwa v61, v176 dst_sel:DWORD dst_unused:UNUSED_PAD src0_sel:WORD_1
	v_rcp_f32_e32 v49, v49
	v_rcp_f32_e32 v90, v89
	v_cvt_f32_f16_sdwa v89, v137 dst_sel:DWORD dst_unused:UNUSED_PAD src0_sel:WORD_1
	v_cvt_f32_f16_sdwa v51, v138 dst_sel:DWORD dst_unused:UNUSED_PAD src0_sel:WORD_1
	v_rcp_f32_e32 v88, v88
	v_cvt_f32_f16_e32 v136, v177
	v_rcp_f32_e32 v89, v89
	v_cvt_f32_f16_sdwa v137, v177 dst_sel:DWORD dst_unused:UNUSED_PAD src0_sel:WORD_1
	v_pk_mul_f32 v[48:49], v[48:49], v[60:61]
	v_rcp_f32_e32 v51, v51
	v_cvt_f32_f16_e32 v62, v178
	v_cvt_f32_f16_sdwa v63, v178 dst_sel:DWORD dst_unused:UNUSED_PAD src0_sel:WORD_1
	v_pk_mul_f32 v[140:141], v[44:45], v[48:49]
	v_cvt_f32_f16_sdwa v44, v139 dst_sel:DWORD dst_unused:UNUSED_PAD src0_sel:WORD_1
	v_pk_mul_f32 v[60:61], v[88:89], v[136:137]
	v_cvt_f32_f16_sdwa v45, v179 dst_sel:DWORD dst_unused:UNUSED_PAD src0_sel:WORD_1
	v_pk_mul_f32 v[142:143], v[46:47], v[60:61]
	v_rcp_f32_e32 v91, v44
	v_cvt_f32_f16_e32 v44, v179
	v_pk_mul_f32 v[46:47], v[50:51], v[62:63]
	v_cvt_f32_f16_e32 v49, v135
	v_pk_mul_f32 v[136:137], v[32:33], v[46:47]
	v_cvt_f32_f16_e32 v33, v134
	v_pk_mul_f32 v[44:45], v[90:91], v[44:45]
	v_cvt_f32_f16_e32 v32, v132
	v_pk_mul_f32 v[138:139], v[34:35], v[44:45]
	v_rcp_f32_e32 v34, v33
	v_cvt_f32_f16_sdwa v33, v132 dst_sel:DWORD dst_unused:UNUSED_PAD src0_sel:WORD_1
	v_cvt_f32_f16_e32 v48, v133
	v_rcp_f32_e32 v50, v49
	v_cvt_f32_f16_sdwa v49, v133 dst_sel:DWORD dst_unused:UNUSED_PAD src0_sel:WORD_1
	v_rcp_f32_e32 v32, v32
	v_rcp_f32_e32 v33, v33
	v_cvt_f32_f16_e32 v44, v172
	v_cvt_f32_f16_sdwa v45, v172 dst_sel:DWORD dst_unused:UNUSED_PAD src0_sel:WORD_1
	v_cvt_f32_f16_sdwa v35, v134 dst_sel:DWORD dst_unused:UNUSED_PAD src0_sel:WORD_1
	v_rcp_f32_e32 v48, v48
	v_rcp_f32_e32 v49, v49
	v_cvt_f32_f16_e32 v60, v173
	v_cvt_f32_f16_sdwa v61, v173 dst_sel:DWORD dst_unused:UNUSED_PAD src0_sel:WORD_1
	v_pk_mul_f32 v[32:33], v[32:33], v[44:45]
	v_rcp_f32_e32 v35, v35
	v_cvt_f32_f16_e32 v46, v174
	v_cvt_f32_f16_sdwa v47, v174 dst_sel:DWORD dst_unused:UNUSED_PAD src0_sel:WORD_1
	v_pk_mul_f32 v[44:45], v[48:49], v[60:61]
	v_pk_mul_f32 v[60:61], v[24:25], v[32:33]
	v_cvt_f32_f16_sdwa v24, v135 dst_sel:DWORD dst_unused:UNUSED_PAD src0_sel:WORD_1
	v_pk_mul_f32 v[62:63], v[26:27], v[44:45]
	v_cvt_f32_f16_sdwa v25, v175 dst_sel:DWORD dst_unused:UNUSED_PAD src0_sel:WORD_1
	v_pk_mul_f32 v[26:27], v[34:35], v[46:47]
	v_rcp_f32_e32 v51, v24
	v_cvt_f32_f16_e32 v24, v175
	v_pk_mul_f32 v[48:49], v[20:21], v[26:27]
	v_cvt_f32_f16_e32 v21, v130
	v_cvt_f32_f16_e32 v20, v128
	v_pk_mul_f32 v[24:25], v[50:51], v[24:25]
	v_cvt_f32_f16_e32 v33, v131
	v_pk_mul_f32 v[50:51], v[22:23], v[24:25]
	v_rcp_f32_e32 v22, v21
	v_cvt_f32_f16_sdwa v21, v128 dst_sel:DWORD dst_unused:UNUSED_PAD src0_sel:WORD_1
	v_rcp_f32_e32 v20, v20
	v_cvt_f32_f16_e32 v24, v168
	v_cvt_f32_f16_sdwa v25, v168 dst_sel:DWORD dst_unused:UNUSED_PAD src0_sel:WORD_1
	v_rcp_f32_e32 v21, v21
	v_cvt_f32_f16_e32 v32, v129
	v_rcp_f32_e32 v34, v33
	v_cvt_f32_f16_sdwa v33, v129 dst_sel:DWORD dst_unused:UNUSED_PAD src0_sel:WORD_1
	v_cvt_f32_f16_sdwa v23, v130 dst_sel:DWORD dst_unused:UNUSED_PAD src0_sel:WORD_1
	v_rcp_f32_e32 v32, v32
	v_cvt_f32_f16_e32 v44, v169
	v_rcp_f32_e32 v33, v33
	v_cvt_f32_f16_sdwa v45, v169 dst_sel:DWORD dst_unused:UNUSED_PAD src0_sel:WORD_1
	v_pk_mul_f32 v[20:21], v[20:21], v[24:25]
	v_rcp_f32_e32 v23, v23
	v_cvt_f32_f16_e32 v26, v170
	v_cvt_f32_f16_sdwa v27, v170 dst_sel:DWORD dst_unused:UNUSED_PAD src0_sel:WORD_1
	v_pk_mul_f32 v[132:133], v[16:17], v[20:21]
	v_cvt_f32_f16_sdwa v16, v131 dst_sel:DWORD dst_unused:UNUSED_PAD src0_sel:WORD_1
	v_pk_mul_f32 v[24:25], v[32:33], v[44:45]
	v_cvt_f32_f16_sdwa v17, v171 dst_sel:DWORD dst_unused:UNUSED_PAD src0_sel:WORD_1
	v_pk_mul_f32 v[134:135], v[18:19], v[24:25]
	v_rcp_f32_e32 v35, v16
	v_cvt_f32_f16_e32 v16, v171
	v_pk_mul_f32 v[18:19], v[22:23], v[26:27]
	v_cvt_f32_f16_e32 v21, v111
	v_pk_mul_f32 v[128:129], v[12:13], v[18:19]
	v_cvt_f32_f16_e32 v13, v110
	v_pk_mul_f32 v[16:17], v[34:35], v[16:17]
	v_cvt_f32_f16_e32 v12, v108
	v_pk_mul_f32 v[130:131], v[14:15], v[16:17]
	v_rcp_f32_e32 v14, v13
	v_cvt_f32_f16_sdwa v13, v108 dst_sel:DWORD dst_unused:UNUSED_PAD src0_sel:WORD_1
	v_rcp_f32_e32 v12, v12
	v_cvt_f32_f16_e32 v16, v164
	v_cvt_f32_f16_sdwa v17, v164 dst_sel:DWORD dst_unused:UNUSED_PAD src0_sel:WORD_1
	v_rcp_f32_e32 v13, v13
	v_cvt_f32_f16_e32 v20, v109
	v_rcp_f32_e32 v22, v21
	v_cvt_f32_f16_sdwa v21, v109 dst_sel:DWORD dst_unused:UNUSED_PAD src0_sel:WORD_1
	v_pk_mul_f32 v[12:13], v[12:13], v[16:17]
	v_cvt_f32_f16_sdwa v15, v110 dst_sel:DWORD dst_unused:UNUSED_PAD src0_sel:WORD_1
	v_pk_mul_f32 v[32:33], v[8:9], v[12:13]
	v_cvt_f32_f16_sdwa v8, v111 dst_sel:DWORD dst_unused:UNUSED_PAD src0_sel:WORD_1
	v_rcp_f32_e32 v20, v20
	v_rcp_f32_e32 v21, v21
	v_cvt_f32_f16_e32 v24, v165
	v_cvt_f32_f16_sdwa v25, v165 dst_sel:DWORD dst_unused:UNUSED_PAD src0_sel:WORD_1
	v_rcp_f32_e32 v15, v15
	v_cvt_f32_f16_e32 v18, v166
	v_cvt_f32_f16_sdwa v19, v166 dst_sel:DWORD dst_unused:UNUSED_PAD src0_sel:WORD_1
	v_rcp_f32_e32 v23, v8
	v_cvt_f32_f16_e32 v8, v167
	v_cvt_f32_f16_sdwa v9, v167 dst_sel:DWORD dst_unused:UNUSED_PAD src0_sel:WORD_1
	v_pk_mul_f32 v[16:17], v[20:21], v[24:25]
	s_mov_b64 s[26:27], 0x80480
	v_pk_mul_f32 v[34:35], v[10:11], v[16:17]
	v_pk_mul_f32 v[10:11], v[14:15], v[18:19]
	v_pk_mul_f32 v[8:9], v[22:23], v[8:9]
	v_pk_mul_f32 v[44:45], v[4:5], v[10:11]
	v_pk_mul_f32 v[46:47], v[6:7], v[8:9]
	v_lshl_add_u64 v[4:5], s[34:35], 0, v[210:211]
.LBB0_1744:
	ds_read_b128 v[6:9], v237
	ds_read_b128 v[10:13], v237 offset:1024
	ds_read_b128 v[14:17], v237 offset:2048
	ds_read_b128 v[18:21], v237 offset:3072
	v_lshl_add_u64 v[246:247], v[4:5], 0, s[16:17]
	s_mov_b32 m0, s14
	v_lshl_add_u64 v[26:27], v[246:247], 0, s[26:27]
	v_lshl_add_u64 v[248:249], v[200:201], 0, s[16:17]
	ds_read_b128 v[22:25], v236
	ds_read_b128 v[88:91], v236 offset:1024
	ds_read_b128 v[108:111], v236 offset:2048
	ds_read_b128 v[164:167], v236 offset:3072
	ds_read_b128 v[168:171], v236 offset:4096
	ds_read_b128 v[172:175], v236 offset:5120
	ds_read_b128 v[176:179], v236 offset:6144
	ds_read_b128 v[180:183], v236 offset:7168
	global_load_lds_dwordx4 v[26:27], off
	v_lshl_add_u64 v[26:27], v[248:249], 0, s[26:27]
	s_mov_b32 m0, s15
	s_nop 0
	global_load_lds_dwordx4 v[26:27], off
	s_waitcnt vmcnt(10)
	s_barrier
	s_waitcnt lgkmcnt(0)
	v_mfma_f32_16x16x32_f16 v[80:83], v[6:9], v[22:25], v[80:83]
	v_mfma_f32_16x16x32_f16 v[72:75], v[14:17], v[22:25], v[72:75]
	v_mfma_f32_16x16x32_f16 v[56:59], v[6:9], v[108:111], v[56:59]
	v_mfma_f32_16x16x32_f16 v[68:71], v[14:17], v[108:111], v[68:71]
	v_mfma_f32_16x16x32_f16 v[160:163], v[6:9], v[168:171], v[160:163]
	v_mfma_f32_16x16x32_f16 v[156:159], v[14:17], v[168:171], v[156:159]
	v_mfma_f32_16x16x32_f16 v[152:155], v[6:9], v[176:179], v[152:155]
	v_mfma_f32_16x16x32_f16 v[148:151], v[14:17], v[176:179], v[148:151]
	v_mfma_f32_16x16x32_f16 v[80:83], v[10:13], v[88:91], v[80:83]
	v_mfma_f32_16x16x32_f16 v[72:75], v[18:21], v[88:91], v[72:75]
	v_mfma_f32_16x16x32_f16 v[56:59], v[10:13], v[164:167], v[56:59]
	v_mfma_f32_16x16x32_f16 v[68:71], v[18:21], v[164:167], v[68:71]
	v_mfma_f32_16x16x32_f16 v[160:163], v[10:13], v[172:175], v[160:163]
	v_mfma_f32_16x16x32_f16 v[156:159], v[18:21], v[172:175], v[156:159]
	v_mfma_f32_16x16x32_f16 v[152:155], v[10:13], v[180:183], v[152:155]
	v_mfma_f32_16x16x32_f16 v[148:151], v[18:21], v[180:183], v[148:151]
	s_barrier
	v_lshl_add_u64 v[224:225], v[202:203], 0, s[16:17]
	s_mov_b32 m0, s19
	v_lshl_add_u64 v[26:27], v[224:225], 0, s[30:31]
	v_lshl_add_u64 v[226:227], v[220:221], 0, s[16:17]
	ds_read_b128 v[184:187], v238
	ds_read_b128 v[188:191], v238 offset:1024
	ds_read_b128 v[192:195], v238 offset:2048
	ds_read_b128 v[196:199], v238 offset:3072
	global_load_lds_dwordx4 v[26:27], off
	v_lshl_add_u64 v[26:27], v[226:227], 0, s[30:31]
	s_mov_b32 m0, s37
	s_nop 0
	global_load_lds_dwordx4 v[26:27], off
	s_waitcnt vmcnt(10)
	s_barrier
	s_waitcnt lgkmcnt(0)
	v_mfma_f32_16x16x32_f16 v[52:55], v[184:187], v[22:25], v[52:55]
	v_mfma_f32_16x16x32_f16 v[22:25], v[192:195], v[22:25], v[40:43]
	v_mfma_f32_16x16x32_f16 v[40:43], v[184:187], v[168:171], v[144:147]
	v_mfma_f32_16x16x32_f16 v[52:55], v[188:191], v[88:91], v[52:55]
	v_mfma_f32_16x16x32_f16 v[22:25], v[196:199], v[88:91], v[22:25]
	v_mfma_f32_16x16x32_f16 v[88:91], v[188:191], v[172:175], v[40:43]
	v_mfma_f32_16x16x32_f16 v[40:43], v[192:195], v[168:171], v[124:127]
	v_mfma_f32_16x16x32_f16 v[36:39], v[184:187], v[108:111], v[36:39]
	v_mfma_f32_16x16x32_f16 v[26:29], v[192:195], v[108:111], v[28:31]
	v_mfma_f32_16x16x32_f16 v[108:111], v[196:199], v[172:175], v[40:43]
	v_mfma_f32_16x16x32_f16 v[40:43], v[184:187], v[176:179], v[120:123]
	v_mfma_f32_16x16x32_f16 v[120:123], v[188:191], v[180:183], v[40:43]
	v_mfma_f32_16x16x32_f16 v[40:43], v[192:195], v[176:179], v[116:119]
	v_mfma_f32_16x16x32_f16 v[36:39], v[188:191], v[164:167], v[36:39]
	v_mfma_f32_16x16x32_f16 v[26:29], v[196:199], v[164:167], v[26:29]
	v_mfma_f32_16x16x32_f16 v[116:119], v[196:199], v[180:183], v[40:43]
	s_mov_b32 m0, s7
	v_lshl_add_u64 v[30:31], v[246:247], 0, s[30:31]
	s_barrier
	s_nop 0
	ds_read_b128 v[40:43], v236 offset:16384
	ds_read_b128 v[124:127], v236 offset:17408
	ds_read_b128 v[144:147], v236 offset:18432
	ds_read_b128 v[164:167], v236 offset:19456
	ds_read_b128 v[168:171], v236 offset:20480
	ds_read_b128 v[172:175], v236 offset:21504
	ds_read_b128 v[176:179], v236 offset:22528
	ds_read_b128 v[180:183], v236 offset:23552
	global_load_lds_dwordx4 v[30:31], off
	v_lshl_add_u64 v[30:31], v[248:249], 0, s[30:31]
	s_mov_b32 m0, s8
	s_nop 0
	global_load_lds_dwordx4 v[30:31], off
	s_waitcnt vmcnt(10)
	s_barrier
	s_waitcnt lgkmcnt(0)
	v_mfma_f32_16x16x32_f16 v[112:115], v[6:9], v[40:43], v[112:115]
	v_mfma_f32_16x16x32_f16 v[104:107], v[14:17], v[40:43], v[104:107]
	v_mfma_f32_16x16x32_f16 v[100:103], v[6:9], v[144:147], v[100:103]
	v_mfma_f32_16x16x32_f16 v[96:99], v[14:17], v[144:147], v[96:99]
	v_mfma_f32_16x16x32_f16 v[140:143], v[6:9], v[168:171], v[140:143]
	v_mfma_f32_16x16x32_f16 v[136:139], v[14:17], v[168:171], v[136:139]
	v_mfma_f32_16x16x32_f16 v[6:9], v[6:9], v[176:179], v[132:135]
	v_mfma_f32_16x16x32_f16 v[112:115], v[10:13], v[124:127], v[112:115]
	v_mfma_f32_16x16x32_f16 v[104:107], v[18:21], v[124:127], v[104:107]
	v_mfma_f32_16x16x32_f16 v[100:103], v[10:13], v[164:167], v[100:103]
	v_mfma_f32_16x16x32_f16 v[96:99], v[18:21], v[164:167], v[96:99]
	v_mfma_f32_16x16x32_f16 v[140:143], v[10:13], v[172:175], v[140:143]
	v_mfma_f32_16x16x32_f16 v[136:139], v[18:21], v[172:175], v[136:139]
	v_mfma_f32_16x16x32_f16 v[6:9], v[10:13], v[180:183], v[6:9]
	v_mfma_f32_16x16x32_f16 v[10:13], v[14:17], v[176:179], v[128:131]
	v_mfma_f32_16x16x32_f16 v[10:13], v[18:21], v[180:183], v[10:13]
	s_barrier
	s_mov_b32 m0, s63
	v_lshl_add_u64 v[14:15], v[224:225], 0, s[84:85]
	global_load_lds_dwordx4 v[14:15], off
	v_lshl_add_u64 v[14:15], v[226:227], 0, s[84:85]
	s_mov_b32 m0, s68
	s_nop 0
	global_load_lds_dwordx4 v[14:15], off
	s_waitcnt vmcnt(10)
	s_barrier
	v_mfma_f32_16x16x32_f16 v[14:17], v[184:187], v[40:43], v[92:95]
	v_mfma_f32_16x16x32_f16 v[18:21], v[192:195], v[40:43], v[84:87]
	v_mfma_f32_16x16x32_f16 v[40:43], v[184:187], v[144:147], v[76:79]
	v_mfma_f32_16x16x32_f16 v[76:79], v[188:191], v[164:167], v[40:43]
	v_mfma_f32_16x16x32_f16 v[40:43], v[192:195], v[144:147], v[64:67]
	v_mfma_f32_16x16x32_f16 v[64:67], v[196:199], v[164:167], v[40:43]
	v_mfma_f32_16x16x32_f16 v[40:43], v[184:187], v[168:171], v[60:63]
	v_mfma_f32_16x16x32_f16 v[60:63], v[188:191], v[172:175], v[40:43]
	v_mfma_f32_16x16x32_f16 v[40:43], v[192:195], v[168:171], v[48:51]
	v_mfma_f32_16x16x32_f16 v[48:51], v[196:199], v[172:175], v[40:43]
	v_mfma_f32_16x16x32_f16 v[30:33], v[184:187], v[176:179], v[32:35]
	v_mfma_f32_16x16x32_f16 v[40:43], v[192:195], v[176:179], v[44:47]
	v_mfma_f32_16x16x32_f16 v[32:35], v[188:191], v[180:183], v[30:33]
	v_mfma_f32_16x16x32_f16 v[44:47], v[196:199], v[180:183], v[40:43]
	v_mfma_f32_16x16x32_f16 v[14:17], v[188:191], v[124:127], v[14:17]
	v_mfma_f32_16x16x32_f16 v[18:21], v[196:199], v[124:127], v[18:21]
	s_barrier
	ds_read_b128 v[84:87], v239
	ds_read_b128 v[92:95], v239 offset:1024
	ds_read_b128 v[128:131], v239 offset:2048
	ds_read_b128 v[164:167], v239 offset:3072
	s_mov_b32 m0, s9
	v_lshl_add_u64 v[30:31], v[246:247], 0, s[84:85]
	ds_read_b128 v[40:43], v236 offset:32768
	ds_read_b128 v[124:127], v236 offset:33792
	ds_read_b128 v[132:135], v236 offset:34816
	ds_read_b128 v[144:147], v236 offset:35840
	ds_read_b128 v[168:171], v236 offset:36864
	ds_read_b128 v[172:175], v236 offset:37888
	ds_read_b128 v[176:179], v236 offset:38912
	ds_read_b128 v[180:183], v236 offset:39936
	global_load_lds_dwordx4 v[30:31], off
	v_lshl_add_u64 v[30:31], v[248:249], 0, s[84:85]
	s_mov_b32 m0, s12
	s_nop 0
	global_load_lds_dwordx4 v[30:31], off
	s_waitcnt vmcnt(10)
	s_barrier
	s_waitcnt lgkmcnt(0)
	v_mfma_f32_16x16x32_f16 v[80:83], v[84:87], v[40:43], v[80:83]
	v_mfma_f32_16x16x32_f16 v[72:75], v[128:131], v[40:43], v[72:75]
	v_mfma_f32_16x16x32_f16 v[56:59], v[84:87], v[132:135], v[56:59]
	v_mfma_f32_16x16x32_f16 v[68:71], v[128:131], v[132:135], v[68:71]
	v_mfma_f32_16x16x32_f16 v[160:163], v[84:87], v[168:171], v[160:163]
	v_mfma_f32_16x16x32_f16 v[156:159], v[128:131], v[168:171], v[156:159]
	v_mfma_f32_16x16x32_f16 v[152:155], v[84:87], v[176:179], v[152:155]
	v_mfma_f32_16x16x32_f16 v[148:151], v[128:131], v[176:179], v[148:151]
	v_mfma_f32_16x16x32_f16 v[80:83], v[92:95], v[124:127], v[80:83]
	v_mfma_f32_16x16x32_f16 v[72:75], v[164:167], v[124:127], v[72:75]
	v_mfma_f32_16x16x32_f16 v[56:59], v[92:95], v[144:147], v[56:59]
	v_mfma_f32_16x16x32_f16 v[68:71], v[164:167], v[144:147], v[68:71]
	v_mfma_f32_16x16x32_f16 v[160:163], v[92:95], v[172:175], v[160:163]
	v_mfma_f32_16x16x32_f16 v[156:159], v[164:167], v[172:175], v[156:159]
	v_mfma_f32_16x16x32_f16 v[152:155], v[92:95], v[180:183], v[152:155]
	v_mfma_f32_16x16x32_f16 v[148:151], v[164:167], v[180:183], v[148:151]
	s_barrier
	s_mov_b32 m0, s69
	v_lshl_add_u64 v[30:31], v[224:225], 0, vcc
	ds_read_b128 v[184:187], v240
	ds_read_b128 v[188:191], v240 offset:1024
	ds_read_b128 v[192:195], v240 offset:2048
	ds_read_b128 v[196:199], v240 offset:3072
	global_load_lds_dwordx4 v[30:31], off
	v_lshl_add_u64 v[30:31], v[226:227], 0, vcc
	s_mov_b32 m0, s70
	s_nop 0
	global_load_lds_dwordx4 v[30:31], off
	s_waitcnt vmcnt(10)
	s_barrier
	s_waitcnt lgkmcnt(0)
	v_mfma_f32_16x16x32_f16 v[22:25], v[192:195], v[40:43], v[22:25]
	v_mfma_f32_16x16x32_f16 v[52:55], v[184:187], v[40:43], v[52:55]
	v_mfma_f32_16x16x32_f16 v[40:43], v[196:199], v[124:127], v[22:25]
	v_mfma_f32_16x16x32_f16 v[22:25], v[184:187], v[132:135], v[36:39]
	v_mfma_f32_16x16x32_f16 v[36:39], v[188:191], v[144:147], v[22:25]
	v_mfma_f32_16x16x32_f16 v[22:25], v[192:195], v[132:135], v[26:29]
	v_mfma_f32_16x16x32_f16 v[28:31], v[196:199], v[144:147], v[22:25]
	v_mfma_f32_16x16x32_f16 v[22:25], v[184:187], v[168:171], v[88:91]
	v_mfma_f32_16x16x32_f16 v[144:147], v[188:191], v[172:175], v[22:25]
	v_mfma_f32_16x16x32_f16 v[22:25], v[192:195], v[168:171], v[108:111]
	v_mfma_f32_16x16x32_f16 v[52:55], v[188:191], v[124:127], v[52:55]
	v_mfma_f32_16x16x32_f16 v[124:127], v[196:199], v[172:175], v[22:25]
	v_mfma_f32_16x16x32_f16 v[22:25], v[184:187], v[176:179], v[120:123]
	v_mfma_f32_16x16x32_f16 v[120:123], v[188:191], v[180:183], v[22:25]
	v_mfma_f32_16x16x32_f16 v[22:25], v[192:195], v[176:179], v[116:119]
	v_mfma_f32_16x16x32_f16 v[116:119], v[196:199], v[180:183], v[22:25]
	s_mov_b32 m0, s39
	v_lshl_add_u64 v[26:27], v[246:247], 0, vcc
	s_barrier
	s_nop 2
	ds_read_b128 v[22:25], v236 offset:49152
	ds_read_b128 v[88:91], v236 offset:50176
	ds_read_b128 v[108:111], v236 offset:51200
	ds_read_b128 v[168:171], v236 offset:52224
	ds_read_b128 v[172:175], v236 offset:53248
	ds_read_b128 v[176:179], v236 offset:54272
	ds_read_b128 v[180:183], v236 offset:55296
	ds_read_b128 v[242:245], v236 offset:56320
	global_load_lds_dwordx4 v[26:27], off
	v_lshl_add_u64 v[26:27], v[248:249], 0, vcc
	s_mov_b32 m0, s47
	s_nop 0
	global_load_lds_dwordx4 v[26:27], off
	s_waitcnt vmcnt(10)
	s_barrier
	s_waitcnt lgkmcnt(0)
	v_mfma_f32_16x16x32_f16 v[132:135], v[84:87], v[172:175], v[140:143]
	v_mfma_f32_16x16x32_f16 v[140:143], v[92:95], v[176:179], v[132:135]
	v_mfma_f32_16x16x32_f16 v[132:135], v[128:131], v[172:175], v[136:139]
	v_mfma_f32_16x16x32_f16 v[6:9], v[84:87], v[180:183], v[6:9]
	v_mfma_f32_16x16x32_f16 v[112:115], v[84:87], v[22:25], v[112:115]
	v_mfma_f32_16x16x32_f16 v[104:107], v[128:131], v[22:25], v[104:107]
	v_mfma_f32_16x16x32_f16 v[100:103], v[84:87], v[108:111], v[100:103]
	v_mfma_f32_16x16x32_f16 v[96:99], v[128:131], v[108:111], v[96:99]
	v_mfma_f32_16x16x32_f16 v[136:139], v[164:167], v[176:179], v[132:135]
	v_mfma_f32_16x16x32_f16 v[132:135], v[92:95], v[242:245], v[6:9]
	v_mfma_f32_16x16x32_f16 v[6:9], v[128:131], v[180:183], v[10:13]
	v_mfma_f32_16x16x32_f16 v[112:115], v[92:95], v[88:91], v[112:115]
	v_mfma_f32_16x16x32_f16 v[104:107], v[164:167], v[88:91], v[104:107]
	v_mfma_f32_16x16x32_f16 v[100:103], v[92:95], v[168:171], v[100:103]
	v_mfma_f32_16x16x32_f16 v[96:99], v[164:167], v[168:171], v[96:99]
	v_mfma_f32_16x16x32_f16 v[128:131], v[164:167], v[242:245], v[6:9]
	s_barrier
	s_mov_b32 m0, s71
	v_lshl_add_u64 v[6:7], v[224:225], 0, s[52:53]
	global_load_lds_dwordx4 v[6:7], off
	v_lshl_add_u64 v[6:7], v[226:227], 0, s[52:53]
	s_mov_b32 m0, s76
	s_nop 0
	global_load_lds_dwordx4 v[6:7], off
	s_waitcnt vmcnt(10)
	s_barrier
	v_mfma_f32_16x16x32_f16 v[6:9], v[184:187], v[22:25], v[14:17]
	v_mfma_f32_16x16x32_f16 v[92:95], v[188:191], v[88:91], v[6:9]
	v_mfma_f32_16x16x32_f16 v[6:9], v[192:195], v[22:25], v[18:21]
	v_mfma_f32_16x16x32_f16 v[84:87], v[196:199], v[88:91], v[6:9]
	v_mfma_f32_16x16x32_f16 v[6:9], v[184:187], v[108:111], v[76:79]
	v_mfma_f32_16x16x32_f16 v[76:79], v[188:191], v[168:171], v[6:9]
	v_mfma_f32_16x16x32_f16 v[6:9], v[192:195], v[108:111], v[64:67]
	v_mfma_f32_16x16x32_f16 v[64:67], v[196:199], v[168:171], v[6:9]
	v_mfma_f32_16x16x32_f16 v[6:9], v[184:187], v[172:175], v[60:63]
	v_mfma_f32_16x16x32_f16 v[60:63], v[188:191], v[176:179], v[6:9]
	v_mfma_f32_16x16x32_f16 v[6:9], v[192:195], v[172:175], v[48:51]
	v_mfma_f32_16x16x32_f16 v[48:51], v[196:199], v[176:179], v[6:9]
	v_mfma_f32_16x16x32_f16 v[6:9], v[184:187], v[180:183], v[32:35]
	v_mfma_f32_16x16x32_f16 v[32:35], v[188:191], v[242:245], v[6:9]
	v_mfma_f32_16x16x32_f16 v[6:9], v[192:195], v[180:183], v[44:47]
	v_mfma_f32_16x16x32_f16 v[44:47], v[196:199], v[242:245], v[6:9]
	s_add_i32 s10, s10, 2
	s_add_u32 s16, s16, 0x100
	s_addc_u32 s17, s17, 0
	s_cmp_lt_u32 s10, 14
	s_barrier
	s_cbranch_scc1 .LBB0_1744
	s_add_i32 s10, s46, 8
	s_mul_hi_i32 s11, s10, 0x42
	s_mulk_i32 s10, 0x42
	s_add_u32 s10, s10, s48
	v_mov_b32_e32 v4, v233
	v_mov_b32_e32 v5, v234
	s_addc_u32 s11, s11, s78
	s_lshl_b64 s[10:11], s[10:11], 17
	v_readlane_b32 s16, v252, 45
	v_lshlrev_b32_e32 v5, 3, v5
	s_add_u32 s16, s16, s10
	v_readlane_b32 s10, v252, 46
	v_lshlrev_b32_e32 v4, 8, v4
	s_addc_u32 s17, s10, s11
	v_add3_u32 v196, v4, s49, v5
	s_add_u32 s26, s16, 0x4200000
	v_ashrrev_i32_e32 v197, 31, v196
	s_addc_u32 s27, s17, 0
	v_lshlrev_b64 v[4:5], 1, v[196:197]
	v_lshl_add_u64 v[6:7], s[16:17], 0, v[4:5]
	v_lshl_add_u64 v[12:13], s[26:27], 0, v[4:5]
	v_add_u32_e32 v4, 0x1000, v196
	v_ashrrev_i32_e32 v5, 31, v4
	v_lshlrev_b64 v[4:5], 1, v[4:5]
	v_lshl_add_u64 v[14:15], s[16:17], 0, v[4:5]
	v_lshl_add_u64 v[20:21], s[26:27], 0, v[4:5]
	v_add_u32_e32 v4, 0x1080, v196
	v_ashrrev_i32_e32 v5, 31, v4
	v_lshlrev_b64 v[4:5], 1, v[4:5]
	v_lshl_add_u64 v[22:23], s[16:17], 0, v[4:5]
	v_lshl_add_u64 v[26:27], s[26:27], 0, v[4:5]
	v_add_u32_e32 v4, 0x2000, v196
	v_ashrrev_i32_e32 v5, 31, v4
	v_lshlrev_b64 v[4:5], 1, v[4:5]
	v_lshl_add_u64 v[24:25], s[16:17], 0, v[4:5]
	v_lshl_add_u64 v[168:169], s[26:27], 0, v[4:5]
	v_add_u32_e32 v4, 0x2080, v196
	v_ashrrev_i32_e32 v5, 31, v4
	v_lshlrev_b64 v[4:5], 1, v[4:5]
	v_lshl_add_u64 v[16:17], s[16:17], 0, v[4:5]
	v_lshl_add_u64 v[170:171], s[26:27], 0, v[4:5]
	v_add_u32_e32 v4, 0x3000, v196
	v_ashrrev_i32_e32 v5, 31, v4
	v_lshlrev_b64 v[4:5], 1, v[4:5]
	v_lshl_add_u64 v[8:9], s[16:17], 0, v[4:5]
	v_lshl_add_u64 v[176:177], s[26:27], 0, v[4:5]
	v_add_u32_e32 v4, 0x3080, v196
	v_ashrrev_i32_e32 v5, 31, v4
	v_lshlrev_b64 v[4:5], 1, v[4:5]
	v_lshl_add_u64 v[10:11], s[16:17], 0, v[4:5]
	v_lshl_add_u64 v[164:165], s[26:27], 0, v[4:5]
	global_load_dwordx4 v[192:195], v[6:7], off offset:256
	global_load_dwordx4 v[108:111], v[6:7], off
	s_nop 0
	global_load_dwordx4 v[4:7], v[10:11], off
	s_nop 0
	global_load_dwordx4 v[8:11], v[8:9], off
	s_nop 0
	global_load_dwordx4 v[16:19], v[16:17], off
	s_nop 0
	global_load_dwordx4 v[172:175], v[24:25], off
	global_load_dwordx4 v[180:183], v[22:23], off
	global_load_dwordx4 v[188:191], v[14:15], off
	global_load_dwordx4 v[88:91], v[12:13], off offset:256
	global_load_dwordx4 v[198:201], v[12:13], off
	s_nop 0
	global_load_dwordx4 v[164:167], v[164:165], off
	s_nop 0
	global_load_dwordx4 v[12:15], v[176:177], off
	global_load_dwordx4 v[22:25], v[170:171], off
	s_nop 0
	global_load_dwordx4 v[168:171], v[168:169], off
	s_nop 0
	global_load_dwordx4 v[176:179], v[26:27], off
	global_load_dwordx4 v[184:187], v[20:21], off
	s_mov_b32 s29, 14
	s_waitcnt vmcnt(0)
	s_nop 0
	v_cvt_f32_f16_e32 v21, v110
	v_cvt_f32_f16_e32 v20, v108
	v_rcp_f32_e32 v26, v21
	v_cvt_f32_f16_sdwa v21, v108 dst_sel:DWORD dst_unused:UNUSED_PAD src0_sel:WORD_1
	v_rcp_f32_e32 v20, v20
	v_cvt_f32_f16_e32 v202, v198
	v_cvt_f32_f16_sdwa v203, v198 dst_sel:DWORD dst_unused:UNUSED_PAD src0_sel:WORD_1
	v_rcp_f32_e32 v21, v21
	v_cvt_f32_f16_sdwa v27, v110 dst_sel:DWORD dst_unused:UNUSED_PAD src0_sel:WORD_1
	v_cvt_f32_f16_e32 v110, v111
	v_cvt_f32_f16_e32 v108, v109
	v_pk_mul_f32 v[20:21], v[20:21], v[202:203]
	v_cvt_f32_f16_sdwa v109, v109 dst_sel:DWORD dst_unused:UNUSED_PAD src0_sel:WORD_1
	v_pk_mul_f32 v[80:81], v[80:81], v[20:21]
	v_cvt_f32_f16_sdwa v20, v111 dst_sel:DWORD dst_unused:UNUSED_PAD src0_sel:WORD_1
	v_rcp_f32_e32 v110, v110
	v_cvt_f32_f16_sdwa v21, v201 dst_sel:DWORD dst_unused:UNUSED_PAD src0_sel:WORD_1
	v_rcp_f32_e32 v27, v27
	v_rcp_f32_e32 v111, v20
	v_cvt_f32_f16_e32 v20, v201
	v_cvt_f32_f16_e32 v220, v200
	v_cvt_f32_f16_sdwa v221, v200 dst_sel:DWORD dst_unused:UNUSED_PAD src0_sel:WORD_1
	v_rcp_f32_e32 v108, v108
	v_rcp_f32_e32 v109, v109
	v_cvt_f32_f16_e32 v198, v199
	v_cvt_f32_f16_sdwa v199, v199 dst_sel:DWORD dst_unused:UNUSED_PAD src0_sel:WORD_1
	v_pk_mul_f32 v[20:21], v[110:111], v[20:21]
	v_pk_mul_f32 v[26:27], v[26:27], v[220:221]
	v_pk_mul_f32 v[110:111], v[74:75], v[20:21]
	v_cvt_f32_f16_e32 v21, v194
	v_cvt_f32_f16_e32 v75, v195
	v_pk_mul_f32 v[108:109], v[108:109], v[198:199]
	v_cvt_f32_f16_e32 v20, v192
	v_pk_mul_f32 v[82:83], v[82:83], v[108:109]
	v_pk_mul_f32 v[108:109], v[72:73], v[26:27]
	v_rcp_f32_e32 v26, v21
	v_cvt_f32_f16_sdwa v21, v192 dst_sel:DWORD dst_unused:UNUSED_PAD src0_sel:WORD_1
	v_cvt_f32_f16_e32 v72, v88
	v_cvt_f32_f16_sdwa v73, v88 dst_sel:DWORD dst_unused:UNUSED_PAD src0_sel:WORD_1
	v_cvt_f32_f16_e32 v74, v193
	v_rcp_f32_e32 v88, v75
	v_cvt_f32_f16_sdwa v75, v193 dst_sel:DWORD dst_unused:UNUSED_PAD src0_sel:WORD_1
	v_rcp_f32_e32 v20, v20
	v_rcp_f32_e32 v21, v21
	v_rcp_f32_e32 v74, v74
	v_rcp_f32_e32 v75, v75
	v_cvt_f32_f16_e32 v192, v89
	v_cvt_f32_f16_sdwa v193, v89 dst_sel:DWORD dst_unused:UNUSED_PAD src0_sel:WORD_1
	v_pk_mul_f32 v[20:21], v[20:21], v[72:73]
	v_cvt_f32_f16_sdwa v27, v194 dst_sel:DWORD dst_unused:UNUSED_PAD src0_sel:WORD_1
	v_cvt_f32_f16_e32 v198, v90
	v_pk_mul_f32 v[72:73], v[74:75], v[192:193]
	v_cvt_f32_f16_sdwa v199, v90 dst_sel:DWORD dst_unused:UNUSED_PAD src0_sel:WORD_1
	v_pk_mul_f32 v[74:75], v[54:55], v[72:73]
	v_pk_mul_f32 v[72:73], v[52:53], v[20:21]
	v_cvt_f32_f16_sdwa v20, v195 dst_sel:DWORD dst_unused:UNUSED_PAD src0_sel:WORD_1
	v_cvt_f32_f16_sdwa v21, v91 dst_sel:DWORD dst_unused:UNUSED_PAD src0_sel:WORD_1
	v_rcp_f32_e32 v27, v27
	v_cvt_f32_f16_e32 v53, v191
	v_rcp_f32_e32 v89, v20
	v_cvt_f32_f16_e32 v20, v91
	v_pk_mul_f32 v[26:27], v[26:27], v[198:199]
	v_rcp_f32_e32 v54, v53
	v_cvt_f32_f16_e32 v52, v189
	v_pk_mul_f32 v[20:21], v[88:89], v[20:21]
	v_pk_mul_f32 v[88:89], v[40:41], v[26:27]
	v_pk_mul_f32 v[90:91], v[42:43], v[20:21]
	v_cvt_f32_f16_e32 v21, v190
	v_cvt_f32_f16_e32 v20, v188
	v_cvt_f32_f16_e32 v40, v184
	v_cvt_f32_f16_sdwa v41, v184 dst_sel:DWORD dst_unused:UNUSED_PAD src0_sel:WORD_1
	v_rcp_f32_e32 v26, v21
	v_cvt_f32_f16_sdwa v21, v188 dst_sel:DWORD dst_unused:UNUSED_PAD src0_sel:WORD_1
	v_rcp_f32_e32 v20, v20
	v_cvt_f32_f16_sdwa v27, v190 dst_sel:DWORD dst_unused:UNUSED_PAD src0_sel:WORD_1
	v_cvt_f32_f16_e32 v42, v186
	v_rcp_f32_e32 v21, v21
	v_cvt_f32_f16_sdwa v43, v186 dst_sel:DWORD dst_unused:UNUSED_PAD src0_sel:WORD_1
	v_rcp_f32_e32 v27, v27
	v_cvt_f32_f16_sdwa v53, v189 dst_sel:DWORD dst_unused:UNUSED_PAD src0_sel:WORD_1
	v_pk_mul_f32 v[20:21], v[20:21], v[40:41]
	v_rcp_f32_e32 v52, v52
	v_pk_mul_f32 v[56:57], v[56:57], v[20:21]
	v_cvt_f32_f16_sdwa v20, v191 dst_sel:DWORD dst_unused:UNUSED_PAD src0_sel:WORD_1
	v_cvt_f32_f16_sdwa v21, v187 dst_sel:DWORD dst_unused:UNUSED_PAD src0_sel:WORD_1
	v_pk_mul_f32 v[26:27], v[26:27], v[42:43]
	v_cvt_f32_f16_e32 v43, v183
	v_rcp_f32_e32 v55, v20
	v_cvt_f32_f16_e32 v20, v187
	v_rcp_f32_e32 v53, v53
	v_cvt_f32_f16_e32 v184, v185
	v_cvt_f32_f16_sdwa v185, v185 dst_sel:DWORD dst_unused:UNUSED_PAD src0_sel:WORD_1
	v_pk_mul_f32 v[20:21], v[54:55], v[20:21]
	v_pk_mul_f32 v[68:69], v[68:69], v[26:27]
	v_pk_mul_f32 v[70:71], v[70:71], v[20:21]
	v_cvt_f32_f16_e32 v21, v182
	v_cvt_f32_f16_e32 v20, v180
	v_cvt_f32_f16_e32 v42, v181
	v_rcp_f32_e32 v54, v43
	v_rcp_f32_e32 v26, v21
	v_cvt_f32_f16_sdwa v21, v180 dst_sel:DWORD dst_unused:UNUSED_PAD src0_sel:WORD_1
	v_cvt_f32_f16_sdwa v43, v181 dst_sel:DWORD dst_unused:UNUSED_PAD src0_sel:WORD_1
	v_pk_mul_f32 v[40:41], v[52:53], v[184:185]
	v_rcp_f32_e32 v20, v20
	v_pk_mul_f32 v[58:59], v[58:59], v[40:41]
	v_rcp_f32_e32 v21, v21
	v_cvt_f32_f16_e32 v40, v176
	v_cvt_f32_f16_sdwa v41, v176 dst_sel:DWORD dst_unused:UNUSED_PAD src0_sel:WORD_1
	v_rcp_f32_e32 v42, v42
	v_rcp_f32_e32 v43, v43
	v_cvt_f32_f16_e32 v176, v177
	v_cvt_f32_f16_sdwa v177, v177 dst_sel:DWORD dst_unused:UNUSED_PAD src0_sel:WORD_1
	v_pk_mul_f32 v[20:21], v[20:21], v[40:41]
	v_cvt_f32_f16_sdwa v27, v182 dst_sel:DWORD dst_unused:UNUSED_PAD src0_sel:WORD_1
	v_cvt_f32_f16_e32 v52, v178
	v_pk_mul_f32 v[40:41], v[42:43], v[176:177]
	v_cvt_f32_f16_sdwa v53, v178 dst_sel:DWORD dst_unused:UNUSED_PAD src0_sel:WORD_1
	v_pk_mul_f32 v[42:43], v[38:39], v[40:41]
	v_pk_mul_f32 v[40:41], v[36:37], v[20:21]
	v_cvt_f32_f16_sdwa v20, v183 dst_sel:DWORD dst_unused:UNUSED_PAD src0_sel:WORD_1
	v_cvt_f32_f16_sdwa v21, v179 dst_sel:DWORD dst_unused:UNUSED_PAD src0_sel:WORD_1
	v_rcp_f32_e32 v27, v27
	v_cvt_f32_f16_e32 v36, v170
	v_rcp_f32_e32 v55, v20
	v_cvt_f32_f16_e32 v20, v179
	v_pk_mul_f32 v[26:27], v[26:27], v[52:53]
	v_cvt_f32_f16_sdwa v37, v170 dst_sel:DWORD dst_unused:UNUSED_PAD src0_sel:WORD_1
	v_pk_mul_f32 v[52:53], v[28:29], v[26:27]
	v_pk_mul_f32 v[20:21], v[54:55], v[20:21]
	v_cvt_f32_f16_e32 v28, v168
	v_pk_mul_f32 v[54:55], v[30:31], v[20:21]
	v_cvt_f32_f16_e32 v21, v174
	v_cvt_f32_f16_e32 v31, v175
	v_cvt_f32_f16_e32 v20, v172
	v_cvt_f32_f16_e32 v30, v173
	v_rcp_f32_e32 v26, v21
	v_cvt_f32_f16_sdwa v21, v172 dst_sel:DWORD dst_unused:UNUSED_PAD src0_sel:WORD_1
	v_rcp_f32_e32 v38, v31
	v_cvt_f32_f16_sdwa v31, v173 dst_sel:DWORD dst_unused:UNUSED_PAD src0_sel:WORD_1
	v_rcp_f32_e32 v20, v20
	v_rcp_f32_e32 v21, v21
	v_cvt_f32_f16_sdwa v29, v168 dst_sel:DWORD dst_unused:UNUSED_PAD src0_sel:WORD_1
	v_rcp_f32_e32 v30, v30
	v_rcp_f32_e32 v31, v31
	v_cvt_f32_f16_e32 v168, v169
	v_cvt_f32_f16_sdwa v169, v169 dst_sel:DWORD dst_unused:UNUSED_PAD src0_sel:WORD_1
	v_pk_mul_f32 v[20:21], v[20:21], v[28:29]
	v_cvt_f32_f16_sdwa v27, v174 dst_sel:DWORD dst_unused:UNUSED_PAD src0_sel:WORD_1
	v_pk_mul_f32 v[28:29], v[30:31], v[168:169]
	v_rcp_f32_e32 v27, v27
	v_pk_mul_f32 v[30:31], v[162:163], v[28:29]
	v_pk_mul_f32 v[28:29], v[160:161], v[20:21]
	v_cvt_f32_f16_sdwa v20, v175 dst_sel:DWORD dst_unused:UNUSED_PAD src0_sel:WORD_1
	v_cvt_f32_f16_sdwa v21, v171 dst_sel:DWORD dst_unused:UNUSED_PAD src0_sel:WORD_1
	v_pk_mul_f32 v[26:27], v[26:27], v[36:37]
	v_rcp_f32_e32 v39, v20
	v_cvt_f32_f16_e32 v20, v171
	v_pk_mul_f32 v[36:37], v[156:157], v[26:27]
	v_cvt_f32_f16_e32 v156, v22
	v_cvt_f32_f16_sdwa v157, v22 dst_sel:DWORD dst_unused:UNUSED_PAD src0_sel:WORD_1
	v_pk_mul_f32 v[20:21], v[38:39], v[20:21]
	v_cvt_f32_f16_e32 v22, v23
	v_pk_mul_f32 v[38:39], v[158:159], v[20:21]
	v_cvt_f32_f16_e32 v20, v16
	v_cvt_f32_f16_e32 v21, v18
	v_cvt_f32_f16_sdwa v16, v16 dst_sel:DWORD dst_unused:UNUSED_PAD src0_sel:WORD_1
	v_cvt_f32_f16_sdwa v23, v23 dst_sel:DWORD dst_unused:UNUSED_PAD src0_sel:WORD_1
	v_cvt_f32_f16_e32 v158, v24
	v_rcp_f32_e32 v26, v21
	v_rcp_f32_e32 v21, v16
	v_cvt_f32_f16_sdwa v16, v18 dst_sel:DWORD dst_unused:UNUSED_PAD src0_sel:WORD_1
	v_cvt_f32_f16_e32 v18, v19
	v_cvt_f32_f16_sdwa v159, v24 dst_sel:DWORD dst_unused:UNUSED_PAD src0_sel:WORD_1
	v_rcp_f32_e32 v20, v20
	v_rcp_f32_e32 v27, v16
	v_cvt_f32_f16_e32 v16, v17
	v_cvt_f32_f16_sdwa v17, v17 dst_sel:DWORD dst_unused:UNUSED_PAD src0_sel:WORD_1
	v_rcp_f32_e32 v18, v18
	v_pk_mul_f32 v[20:21], v[20:21], v[156:157]
	v_rcp_f32_e32 v16, v16
	v_rcp_f32_e32 v17, v17
	v_pk_mul_f32 v[20:21], v[144:145], v[20:21]
	v_cvt_f32_f16_e32 v144, v165
	v_cvt_f32_f16_sdwa v145, v165 dst_sel:DWORD dst_unused:UNUSED_PAD src0_sel:WORD_1
	v_pk_mul_f32 v[16:17], v[16:17], v[22:23]
	s_nop 0
	v_pk_mul_f32 v[22:23], v[146:147], v[16:17]
	v_cvt_f32_f16_sdwa v16, v19 dst_sel:DWORD dst_unused:UNUSED_PAD src0_sel:WORD_1
	v_cvt_f32_f16_sdwa v17, v25 dst_sel:DWORD dst_unused:UNUSED_PAD src0_sel:WORD_1
	v_rcp_f32_e32 v19, v16
	v_cvt_f32_f16_e32 v16, v25
	v_pk_mul_f32 v[24:25], v[26:27], v[158:159]
	v_pk_mul_f32 v[16:17], v[18:19], v[16:17]
	s_nop 0
	v_pk_mul_f32 v[26:27], v[126:127], v[16:17]
	v_cvt_f32_f16_e32 v16, v8
	v_cvt_f32_f16_e32 v17, v10
	v_cvt_f32_f16_sdwa v8, v8 dst_sel:DWORD dst_unused:UNUSED_PAD src0_sel:WORD_1
	v_pk_mul_f32 v[24:25], v[124:125], v[24:25]
	v_cvt_f32_f16_e32 v18, v12
	v_rcp_f32_e32 v124, v17
	v_rcp_f32_e32 v17, v8
	v_cvt_f32_f16_sdwa v8, v10 dst_sel:DWORD dst_unused:UNUSED_PAD src0_sel:WORD_1
	v_cvt_f32_f16_sdwa v19, v12 dst_sel:DWORD dst_unused:UNUSED_PAD src0_sel:WORD_1
	v_cvt_f32_f16_e32 v12, v13
	v_cvt_f32_f16_sdwa v13, v13 dst_sel:DWORD dst_unused:UNUSED_PAD src0_sel:WORD_1
	v_rcp_f32_e32 v125, v8
	v_cvt_f32_f16_e32 v8, v9
	v_cvt_f32_f16_sdwa v9, v9 dst_sel:DWORD dst_unused:UNUSED_PAD src0_sel:WORD_1
	v_rcp_f32_e32 v16, v16
	v_cvt_f32_f16_e32 v10, v11
	v_rcp_f32_e32 v8, v8
	v_rcp_f32_e32 v9, v9
	v_pk_mul_f32 v[16:17], v[16:17], v[18:19]
	v_rcp_f32_e32 v10, v10
	v_cvt_f32_f16_e32 v126, v14
	v_pk_mul_f32 v[8:9], v[8:9], v[12:13]
	v_cvt_f32_f16_sdwa v127, v14 dst_sel:DWORD dst_unused:UNUSED_PAD src0_sel:WORD_1
	v_pk_mul_f32 v[18:19], v[154:155], v[8:9]
	v_cvt_f32_f16_sdwa v8, v11 dst_sel:DWORD dst_unused:UNUSED_PAD src0_sel:WORD_1
	v_cvt_f32_f16_sdwa v9, v15 dst_sel:DWORD dst_unused:UNUSED_PAD src0_sel:WORD_1
	v_pk_mul_f32 v[12:13], v[124:125], v[126:127]
	v_cvt_f32_f16_e32 v126, v166
	v_rcp_f32_e32 v11, v8
	v_cvt_f32_f16_e32 v8, v15
	v_cvt_f32_f16_sdwa v127, v166 dst_sel:DWORD dst_unused:UNUSED_PAD src0_sel:WORD_1
	v_pk_mul_f32 v[16:17], v[152:153], v[16:17]
	v_pk_mul_f32 v[12:13], v[148:149], v[12:13]
	v_pk_mul_f32 v[8:9], v[10:11], v[8:9]
	v_cvt_f32_f16_e32 v10, v164
	v_pk_mul_f32 v[14:15], v[150:151], v[8:9]
	v_cvt_f32_f16_e32 v8, v4
	v_cvt_f32_f16_e32 v9, v6
	v_cvt_f32_f16_sdwa v4, v4 dst_sel:DWORD dst_unused:UNUSED_PAD src0_sel:WORD_1
	v_cvt_f32_f16_sdwa v11, v164 dst_sel:DWORD dst_unused:UNUSED_PAD src0_sel:WORD_1
	v_rcp_f32_e32 v8, v8
	v_rcp_f32_e32 v124, v9
	v_rcp_f32_e32 v9, v4
	v_cvt_f32_f16_sdwa v4, v6 dst_sel:DWORD dst_unused:UNUSED_PAD src0_sel:WORD_1
	v_cvt_f32_f16_e32 v6, v7
	v_pk_mul_f32 v[8:9], v[8:9], v[10:11]
	v_rcp_f32_e32 v125, v4
	v_cvt_f32_f16_e32 v4, v5
	v_cvt_f32_f16_sdwa v5, v5 dst_sel:DWORD dst_unused:UNUSED_PAD src0_sel:WORD_1
	v_rcp_f32_e32 v6, v6
	v_pk_mul_f32 v[8:9], v[120:121], v[8:9]
	v_rcp_f32_e32 v4, v4
	v_rcp_f32_e32 v5, v5
	v_pk_mul_f32 v[120:121], v[124:125], v[126:127]
	v_pk_mul_f32 v[4:5], v[4:5], v[144:145]
	s_nop 0
	v_pk_mul_f32 v[10:11], v[122:123], v[4:5]
	v_cvt_f32_f16_sdwa v4, v7 dst_sel:DWORD dst_unused:UNUSED_PAD src0_sel:WORD_1
	v_cvt_f32_f16_sdwa v5, v167 dst_sel:DWORD dst_unused:UNUSED_PAD src0_sel:WORD_1
	v_rcp_f32_e32 v7, v4
	v_cvt_f32_f16_e32 v4, v167
	v_pk_mul_f32 v[4:5], v[6:7], v[4:5]
	s_nop 0
	v_pk_mul_f32 v[6:7], v[118:119], v[4:5]
	v_add_u32_e32 v118, 0x8080, v196
	v_ashrrev_i32_e32 v119, 31, v118
	v_lshlrev_b64 v[118:119], 1, v[118:119]
	v_pk_mul_f32 v[4:5], v[116:117], v[120:121]
	v_lshl_add_u64 v[120:121], s[16:17], 0, v[118:119]
	v_lshl_add_u64 v[124:125], s[26:27], 0, v[118:119]
	v_add_u32_e32 v118, 0x9000, v196
	v_ashrrev_i32_e32 v119, 31, v118
	v_lshlrev_b64 v[118:119], 1, v[118:119]
	v_lshl_add_u64 v[126:127], s[16:17], 0, v[118:119]
	v_lshl_add_u64 v[192:193], s[26:27], 0, v[118:119]
	v_add_u32_e32 v118, 0x9080, v196
	v_ashrrev_i32_e32 v119, 31, v118
	v_lshlrev_b64 v[118:119], 1, v[118:119]
	v_lshl_add_u64 v[144:145], s[16:17], 0, v[118:119]
	v_lshl_add_u64 v[184:185], s[26:27], 0, v[118:119]
	v_add_u32_e32 v118, 0xa000, v196
	v_ashrrev_i32_e32 v119, 31, v118
	v_lshlrev_b64 v[118:119], 1, v[118:119]
	v_lshl_add_u64 v[146:147], s[16:17], 0, v[118:119]
	v_lshl_add_u64 v[176:177], s[26:27], 0, v[118:119]
	v_add_u32_e32 v118, 0xa080, v196
	v_ashrrev_i32_e32 v119, 31, v118
	v_lshlrev_b64 v[118:119], 1, v[118:119]
	v_lshl_add_u64 v[152:153], s[16:17], 0, v[118:119]
	v_lshl_add_u64 v[168:169], s[26:27], 0, v[118:119]
	v_add_u32_e32 v118, 0xb000, v196
	v_ashrrev_i32_e32 v119, 31, v118
	v_lshlrev_b64 v[118:119], 1, v[118:119]
	v_lshl_add_u64 v[154:155], s[16:17], 0, v[118:119]
	v_lshl_add_u64 v[160:161], s[26:27], 0, v[118:119]
	v_add_u32_e32 v118, 0xb080, v196
	v_add_u32_e32 v116, 0x8000, v196
	v_ashrrev_i32_e32 v119, 31, v118
	v_ashrrev_i32_e32 v117, 31, v116
	v_lshlrev_b64 v[118:119], 1, v[118:119]
	v_lshlrev_b64 v[116:117], 1, v[116:117]
	v_lshl_add_u64 v[148:149], s[16:17], 0, v[118:119]
	v_lshl_add_u64 v[162:163], s[26:27], 0, v[118:119]
	v_lshl_add_u64 v[122:123], s[16:17], 0, v[116:117]
	v_lshl_add_u64 v[116:117], s[26:27], 0, v[116:117]
	global_load_dwordx4 v[148:151], v[148:149], off
	s_nop 0
	global_load_dwordx4 v[156:159], v[154:155], off
	global_load_dwordx4 v[164:167], v[152:153], off
	global_load_dwordx4 v[172:175], v[146:147], off
	global_load_dwordx4 v[180:183], v[144:145], off
	global_load_dwordx4 v[188:191], v[126:127], off
	s_nop 0
	global_load_dwordx4 v[118:121], v[120:121], off
	s_nop 0
	global_load_dwordx4 v[144:147], v[122:123], off
	global_load_dwordx4 v[152:155], v[162:163], off
	s_nop 0
	global_load_dwordx4 v[160:163], v[160:161], off
	s_nop 0
	global_load_dwordx4 v[168:171], v[168:169], off
	s_nop 0
	global_load_dwordx4 v[176:179], v[176:177], off
	s_nop 0
	global_load_dwordx4 v[184:187], v[184:185], off
	s_nop 0
	global_load_dwordx4 v[192:195], v[192:193], off
	s_nop 0
	global_load_dwordx4 v[196:199], v[124:125], off
	global_load_dwordx4 v[200:203], v[116:117], off
	s_waitcnt vmcnt(0)
	s_nop 0
	v_cvt_f32_f16_e32 v117, v146
	v_cvt_f32_f16_e32 v127, v147
	v_cvt_f32_f16_e32 v116, v144
	v_cvt_f32_f16_e32 v126, v145
	v_rcp_f32_e32 v122, v117
	v_cvt_f32_f16_sdwa v117, v144 dst_sel:DWORD dst_unused:UNUSED_PAD src0_sel:WORD_1
	v_rcp_f32_e32 v144, v127
	v_cvt_f32_f16_sdwa v127, v145 dst_sel:DWORD dst_unused:UNUSED_PAD src0_sel:WORD_1
	v_rcp_f32_e32 v116, v116
	v_rcp_f32_e32 v117, v117
	v_cvt_f32_f16_e32 v124, v200
	v_cvt_f32_f16_sdwa v125, v200 dst_sel:DWORD dst_unused:UNUSED_PAD src0_sel:WORD_1
	v_rcp_f32_e32 v126, v126
	v_rcp_f32_e32 v127, v127
	v_cvt_f32_f16_e32 v200, v201
	v_cvt_f32_f16_sdwa v201, v201 dst_sel:DWORD dst_unused:UNUSED_PAD src0_sel:WORD_1
	v_cvt_f32_f16_sdwa v123, v146 dst_sel:DWORD dst_unused:UNUSED_PAD src0_sel:WORD_1
	v_pk_mul_f32 v[116:117], v[116:117], v[124:125]
	v_cvt_f32_f16_e32 v220, v202
	v_pk_mul_f32 v[124:125], v[126:127], v[200:201]
	v_rcp_f32_e32 v123, v123
	v_pk_mul_f32 v[126:127], v[114:115], v[124:125]
	v_pk_mul_f32 v[124:125], v[112:113], v[116:117]
	v_cvt_f32_f16_sdwa v112, v147 dst_sel:DWORD dst_unused:UNUSED_PAD src0_sel:WORD_1
	v_cvt_f32_f16_sdwa v221, v202 dst_sel:DWORD dst_unused:UNUSED_PAD src0_sel:WORD_1
	v_cvt_f32_f16_sdwa v113, v203 dst_sel:DWORD dst_unused:UNUSED_PAD src0_sel:WORD_1
	v_cvt_f32_f16_e32 v117, v121
	v_rcp_f32_e32 v145, v112
	v_cvt_f32_f16_e32 v112, v203
	v_pk_mul_f32 v[114:115], v[122:123], v[220:221]
	v_cvt_f32_f16_e32 v116, v119
	s_add_u32 s16, s34, 0x80880
	v_pk_mul_f32 v[112:113], v[144:145], v[112:113]
	v_pk_mul_f32 v[144:145], v[104:105], v[114:115]
	v_cvt_f32_f16_e32 v105, v120
	v_pk_mul_f32 v[146:147], v[106:107], v[112:113]
	v_cvt_f32_f16_e32 v104, v118
	v_cvt_f32_f16_sdwa v107, v120 dst_sel:DWORD dst_unused:UNUSED_PAD src0_sel:WORD_1
	v_rcp_f32_e32 v106, v105
	v_cvt_f32_f16_sdwa v105, v118 dst_sel:DWORD dst_unused:UNUSED_PAD src0_sel:WORD_1
	v_rcp_f32_e32 v120, v117
	v_cvt_f32_f16_sdwa v117, v119 dst_sel:DWORD dst_unused:UNUSED_PAD src0_sel:WORD_1
	v_rcp_f32_e32 v104, v104
	v_rcp_f32_e32 v105, v105
	v_cvt_f32_f16_e32 v112, v196
	v_cvt_f32_f16_sdwa v113, v196 dst_sel:DWORD dst_unused:UNUSED_PAD src0_sel:WORD_1
	v_rcp_f32_e32 v116, v116
	v_rcp_f32_e32 v117, v117
	v_cvt_f32_f16_e32 v118, v197
	v_cvt_f32_f16_sdwa v119, v197 dst_sel:DWORD dst_unused:UNUSED_PAD src0_sel:WORD_1
	v_pk_mul_f32 v[104:105], v[104:105], v[112:113]
	v_rcp_f32_e32 v107, v107
	v_cvt_f32_f16_e32 v114, v198
	v_pk_mul_f32 v[112:113], v[116:117], v[118:119]
	v_pk_mul_f32 v[116:117], v[92:93], v[104:105]
	v_cvt_f32_f16_sdwa v92, v121 dst_sel:DWORD dst_unused:UNUSED_PAD src0_sel:WORD_1
	v_cvt_f32_f16_sdwa v115, v198 dst_sel:DWORD dst_unused:UNUSED_PAD src0_sel:WORD_1
	v_cvt_f32_f16_sdwa v93, v199 dst_sel:DWORD dst_unused:UNUSED_PAD src0_sel:WORD_1
	v_pk_mul_f32 v[118:119], v[94:95], v[112:113]
	v_rcp_f32_e32 v121, v92
	v_cvt_f32_f16_e32 v92, v199
	v_pk_mul_f32 v[94:95], v[106:107], v[114:115]
	v_cvt_f32_f16_e32 v105, v191
	v_cvt_f32_f16_e32 v104, v189
	v_pk_mul_f32 v[92:93], v[120:121], v[92:93]
	v_pk_mul_f32 v[120:121], v[84:85], v[94:95]
	v_cvt_f32_f16_e32 v85, v190
	v_pk_mul_f32 v[122:123], v[86:87], v[92:93]
	v_cvt_f32_f16_e32 v84, v188
	v_rcp_f32_e32 v112, v105
	v_rcp_f32_e32 v86, v85
	v_cvt_f32_f16_sdwa v85, v188 dst_sel:DWORD dst_unused:UNUSED_PAD src0_sel:WORD_1
	v_cvt_f32_f16_sdwa v105, v189 dst_sel:DWORD dst_unused:UNUSED_PAD src0_sel:WORD_1
	v_rcp_f32_e32 v84, v84
	v_cvt_f32_f16_e32 v92, v192
	v_rcp_f32_e32 v85, v85
	v_cvt_f32_f16_sdwa v93, v192 dst_sel:DWORD dst_unused:UNUSED_PAD src0_sel:WORD_1
	v_rcp_f32_e32 v104, v104
	v_rcp_f32_e32 v105, v105
	v_cvt_f32_f16_e32 v106, v193
	v_cvt_f32_f16_sdwa v107, v193 dst_sel:DWORD dst_unused:UNUSED_PAD src0_sel:WORD_1
	v_pk_mul_f32 v[84:85], v[84:85], v[92:93]
	v_cvt_f32_f16_sdwa v87, v190 dst_sel:DWORD dst_unused:UNUSED_PAD src0_sel:WORD_1
	v_cvt_f32_f16_e32 v94, v194
	v_pk_mul_f32 v[92:93], v[104:105], v[106:107]
	v_pk_mul_f32 v[104:105], v[100:101], v[84:85]
	v_cvt_f32_f16_sdwa v84, v191 dst_sel:DWORD dst_unused:UNUSED_PAD src0_sel:WORD_1
	v_cvt_f32_f16_sdwa v85, v195 dst_sel:DWORD dst_unused:UNUSED_PAD src0_sel:WORD_1
	v_rcp_f32_e32 v87, v87
	v_cvt_f32_f16_sdwa v95, v194 dst_sel:DWORD dst_unused:UNUSED_PAD src0_sel:WORD_1
	v_rcp_f32_e32 v113, v84
	v_cvt_f32_f16_e32 v84, v195
	v_pk_mul_f32 v[106:107], v[102:103], v[92:93]
	v_pk_mul_f32 v[86:87], v[86:87], v[94:95]
	v_cvt_f32_f16_e32 v92, v184
	v_pk_mul_f32 v[84:85], v[112:113], v[84:85]
	v_pk_mul_f32 v[112:113], v[96:97], v[86:87]
	v_pk_mul_f32 v[114:115], v[98:99], v[84:85]
	v_cvt_f32_f16_e32 v85, v182
	v_cvt_f32_f16_e32 v97, v183
	v_cvt_f32_f16_e32 v84, v180
	v_cvt_f32_f16_e32 v96, v181
	v_rcp_f32_e32 v86, v85
	v_cvt_f32_f16_sdwa v85, v180 dst_sel:DWORD dst_unused:UNUSED_PAD src0_sel:WORD_1
	v_rcp_f32_e32 v100, v97
	v_cvt_f32_f16_sdwa v97, v181 dst_sel:DWORD dst_unused:UNUSED_PAD src0_sel:WORD_1
	v_rcp_f32_e32 v84, v84
	v_rcp_f32_e32 v85, v85
	v_cvt_f32_f16_sdwa v93, v184 dst_sel:DWORD dst_unused:UNUSED_PAD src0_sel:WORD_1
	v_rcp_f32_e32 v96, v96
	v_rcp_f32_e32 v97, v97
	v_cvt_f32_f16_e32 v98, v185
	v_cvt_f32_f16_sdwa v99, v185 dst_sel:DWORD dst_unused:UNUSED_PAD src0_sel:WORD_1
	v_cvt_f32_f16_sdwa v87, v182 dst_sel:DWORD dst_unused:UNUSED_PAD src0_sel:WORD_1
	v_pk_mul_f32 v[84:85], v[84:85], v[92:93]
	v_cvt_f32_f16_e32 v94, v186
	v_pk_mul_f32 v[92:93], v[96:97], v[98:99]
	v_pk_mul_f32 v[96:97], v[76:77], v[84:85]
	v_cvt_f32_f16_sdwa v76, v183 dst_sel:DWORD dst_unused:UNUSED_PAD src0_sel:WORD_1
	v_rcp_f32_e32 v87, v87
	v_cvt_f32_f16_sdwa v95, v186 dst_sel:DWORD dst_unused:UNUSED_PAD src0_sel:WORD_1
	v_cvt_f32_f16_sdwa v77, v187 dst_sel:DWORD dst_unused:UNUSED_PAD src0_sel:WORD_1
	v_rcp_f32_e32 v101, v76
	v_cvt_f32_f16_e32 v76, v187
	v_pk_mul_f32 v[98:99], v[78:79], v[92:93]
	v_pk_mul_f32 v[78:79], v[86:87], v[94:95]
	v_cvt_f32_f16_e32 v85, v175
	v_pk_mul_f32 v[76:77], v[100:101], v[76:77]
	v_pk_mul_f32 v[100:101], v[64:65], v[78:79]
	v_cvt_f32_f16_e32 v65, v174
	v_pk_mul_f32 v[102:103], v[66:67], v[76:77]
	v_cvt_f32_f16_e32 v64, v172
	v_cvt_f32_f16_e32 v84, v173
	v_rcp_f32_e32 v66, v65
	v_cvt_f32_f16_sdwa v65, v172 dst_sel:DWORD dst_unused:UNUSED_PAD src0_sel:WORD_1
	v_rcp_f32_e32 v92, v85
	v_cvt_f32_f16_sdwa v85, v173 dst_sel:DWORD dst_unused:UNUSED_PAD src0_sel:WORD_1
	v_rcp_f32_e32 v64, v64
	v_rcp_f32_e32 v65, v65
	v_cvt_f32_f16_e32 v76, v176
	v_cvt_f32_f16_sdwa v77, v176 dst_sel:DWORD dst_unused:UNUSED_PAD src0_sel:WORD_1
	v_rcp_f32_e32 v84, v84
	v_rcp_f32_e32 v85, v85
	v_cvt_f32_f16_e32 v86, v177
	v_cvt_f32_f16_sdwa v87, v177 dst_sel:DWORD dst_unused:UNUSED_PAD src0_sel:WORD_1
	v_pk_mul_f32 v[64:65], v[64:65], v[76:77]
	v_cvt_f32_f16_sdwa v67, v174 dst_sel:DWORD dst_unused:UNUSED_PAD src0_sel:WORD_1
	v_cvt_f32_f16_e32 v78, v178
	v_pk_mul_f32 v[76:77], v[84:85], v[86:87]
	v_pk_mul_f32 v[84:85], v[140:141], v[64:65]
	v_cvt_f32_f16_sdwa v64, v175 dst_sel:DWORD dst_unused:UNUSED_PAD src0_sel:WORD_1
	v_cvt_f32_f16_sdwa v65, v179 dst_sel:DWORD dst_unused:UNUSED_PAD src0_sel:WORD_1
	v_rcp_f32_e32 v67, v67
	v_cvt_f32_f16_sdwa v79, v178 dst_sel:DWORD dst_unused:UNUSED_PAD src0_sel:WORD_1
	v_rcp_f32_e32 v93, v64
	v_cvt_f32_f16_e32 v64, v179
	v_pk_mul_f32 v[86:87], v[142:143], v[76:77]
	v_pk_mul_f32 v[66:67], v[66:67], v[78:79]
	v_cvt_f32_f16_sdwa v77, v166 dst_sel:DWORD dst_unused:UNUSED_PAD src0_sel:WORD_1
	v_pk_mul_f32 v[64:65], v[92:93], v[64:65]
	v_pk_mul_f32 v[92:93], v[136:137], v[66:67]
	v_pk_mul_f32 v[94:95], v[138:139], v[64:65]
	v_cvt_f32_f16_e32 v65, v166
	v_cvt_f32_f16_e32 v64, v164
	v_cvt_f32_f16_e32 v137, v167
	v_cvt_f32_f16_e32 v66, v168
	v_rcp_f32_e32 v76, v65
	v_cvt_f32_f16_sdwa v65, v164 dst_sel:DWORD dst_unused:UNUSED_PAD src0_sel:WORD_1
	v_rcp_f32_e32 v64, v64
	v_cvt_f32_f16_sdwa v67, v168 dst_sel:DWORD dst_unused:UNUSED_PAD src0_sel:WORD_1
	v_cvt_f32_f16_e32 v136, v165
	v_rcp_f32_e32 v65, v65
	v_rcp_f32_e32 v138, v137
	v_cvt_f32_f16_sdwa v137, v165 dst_sel:DWORD dst_unused:UNUSED_PAD src0_sel:WORD_1
	v_rcp_f32_e32 v136, v136
	v_cvt_f32_f16_e32 v140, v169
	v_cvt_f32_f16_sdwa v141, v169 dst_sel:DWORD dst_unused:UNUSED_PAD src0_sel:WORD_1
	v_rcp_f32_e32 v137, v137
	v_pk_mul_f32 v[64:65], v[64:65], v[66:67]
	v_rcp_f32_e32 v77, v77
	v_cvt_f32_f16_e32 v78, v170
	v_cvt_f32_f16_sdwa v79, v170 dst_sel:DWORD dst_unused:UNUSED_PAD src0_sel:WORD_1
	v_pk_mul_f32 v[64:65], v[60:61], v[64:65]
	v_cvt_f32_f16_sdwa v60, v167 dst_sel:DWORD dst_unused:UNUSED_PAD src0_sel:WORD_1
	v_pk_mul_f32 v[66:67], v[136:137], v[140:141]
	v_cvt_f32_f16_sdwa v61, v171 dst_sel:DWORD dst_unused:UNUSED_PAD src0_sel:WORD_1
	v_pk_mul_f32 v[66:67], v[62:63], v[66:67]
	v_rcp_f32_e32 v139, v60
	v_cvt_f32_f16_e32 v60, v171
	v_pk_mul_f32 v[62:63], v[76:77], v[78:79]
	v_cvt_f32_f16_e32 v137, v159
	v_pk_mul_f32 v[76:77], v[48:49], v[62:63]
	v_cvt_f32_f16_e32 v49, v158
	v_pk_mul_f32 v[60:61], v[138:139], v[60:61]
	v_cvt_f32_f16_e32 v48, v156
	v_pk_mul_f32 v[78:79], v[50:51], v[60:61]
	v_rcp_f32_e32 v60, v49
	v_cvt_f32_f16_sdwa v49, v156 dst_sel:DWORD dst_unused:UNUSED_PAD src0_sel:WORD_1
	v_rcp_f32_e32 v48, v48
	v_cvt_f32_f16_e32 v50, v160
	v_cvt_f32_f16_sdwa v51, v160 dst_sel:DWORD dst_unused:UNUSED_PAD src0_sel:WORD_1
	v_rcp_f32_e32 v49, v49
	v_cvt_f32_f16_sdwa v61, v158 dst_sel:DWORD dst_unused:UNUSED_PAD src0_sel:WORD_1
	v_cvt_f32_f16_e32 v62, v162
	v_cvt_f32_f16_sdwa v63, v162 dst_sel:DWORD dst_unused:UNUSED_PAD src0_sel:WORD_1
	v_pk_mul_f32 v[48:49], v[48:49], v[50:51]
	v_rcp_f32_e32 v61, v61
	v_pk_mul_f32 v[48:49], v[132:133], v[48:49]
	v_cvt_f32_f16_sdwa v132, v159 dst_sel:DWORD dst_unused:UNUSED_PAD src0_sel:WORD_1
	v_rcp_f32_e32 v138, v137
	v_cvt_f32_f16_sdwa v133, v163 dst_sel:DWORD dst_unused:UNUSED_PAD src0_sel:WORD_1
	v_pk_mul_f32 v[60:61], v[60:61], v[62:63]
	v_rcp_f32_e32 v139, v132
	v_cvt_f32_f16_e32 v132, v163
	v_pk_mul_f32 v[60:61], v[128:129], v[60:61]
	v_cvt_f32_f16_e32 v129, v150
	v_cvt_f32_f16_e32 v136, v157
	v_cvt_f32_f16_sdwa v137, v157 dst_sel:DWORD dst_unused:UNUSED_PAD src0_sel:WORD_1
	v_pk_mul_f32 v[62:63], v[138:139], v[132:133]
	v_cvt_f32_f16_e32 v128, v148
	v_pk_mul_f32 v[62:63], v[130:131], v[62:63]
	v_rcp_f32_e32 v130, v129
	v_cvt_f32_f16_sdwa v129, v148 dst_sel:DWORD dst_unused:UNUSED_PAD src0_sel:WORD_1
	v_rcp_f32_e32 v136, v136
	v_rcp_f32_e32 v137, v137
	v_cvt_f32_f16_e32 v140, v161
	v_cvt_f32_f16_sdwa v141, v161 dst_sel:DWORD dst_unused:UNUSED_PAD src0_sel:WORD_1
	v_rcp_f32_e32 v128, v128
	v_rcp_f32_e32 v129, v129
	v_cvt_f32_f16_e32 v132, v152
	v_cvt_f32_f16_sdwa v133, v152 dst_sel:DWORD dst_unused:UNUSED_PAD src0_sel:WORD_1
	v_pk_mul_f32 v[50:51], v[136:137], v[140:141]
	v_cvt_f32_f16_e32 v137, v151
	v_cvt_f32_f16_sdwa v131, v150 dst_sel:DWORD dst_unused:UNUSED_PAD src0_sel:WORD_1
	v_pk_mul_f32 v[128:129], v[128:129], v[132:133]
	v_cvt_f32_f16_e32 v136, v149
	v_rcp_f32_e32 v138, v137
	v_cvt_f32_f16_sdwa v137, v149 dst_sel:DWORD dst_unused:UNUSED_PAD src0_sel:WORD_1
	v_pk_mul_f32 v[32:33], v[32:33], v[128:129]
	v_cvt_f32_f16_sdwa v128, v151 dst_sel:DWORD dst_unused:UNUSED_PAD src0_sel:WORD_1
	v_pk_mul_f32 v[50:51], v[134:135], v[50:51]
	v_rcp_f32_e32 v131, v131
	v_cvt_f32_f16_e32 v134, v154
	v_cvt_f32_f16_sdwa v135, v154 dst_sel:DWORD dst_unused:UNUSED_PAD src0_sel:WORD_1
	v_rcp_f32_e32 v136, v136
	v_rcp_f32_e32 v137, v137
	v_cvt_f32_f16_e32 v140, v153
	v_cvt_f32_f16_sdwa v141, v153 dst_sel:DWORD dst_unused:UNUSED_PAD src0_sel:WORD_1
	v_rcp_f32_e32 v139, v128
	v_cvt_f32_f16_e32 v128, v155
	v_cvt_f32_f16_sdwa v129, v155 dst_sel:DWORD dst_unused:UNUSED_PAD src0_sel:WORD_1
	s_addc_u32 s17, s35, 0
	v_pk_mul_f32 v[132:133], v[136:137], v[140:141]
	v_pk_mul_f32 v[130:131], v[130:131], v[134:135]
	v_pk_mul_f32 v[128:129], v[138:139], v[128:129]
	s_add_u32 s10, s50, 0x900
	v_pk_mul_f32 v[34:35], v[34:35], v[132:133]
	v_pk_mul_f32 v[46:47], v[46:47], v[128:129]
	v_pk_mul_f32 v[44:45], v[44:45], v[130:131]
	s_addc_u32 s11, s51, 0
.LBB0_1746:
	ds_read_b128 v[128:131], v237
	ds_read_b128 v[132:135], v237 offset:1024
	ds_read_b128 v[136:139], v237 offset:2048
	ds_read_b128 v[140:143], v237 offset:3072
	s_add_u32 s26, s16, 0xfff80080
	s_addc_u32 s27, s17, -1
	s_cmp_eq_u32 s29, 28
	s_cselect_b32 s35, s43, s27
	s_cselect_b32 s34, s42, s26
	s_cselect_b32 s27, s45, s11
	s_cselect_b32 s26, s44, s10
	s_mov_b32 m0, s14
	v_lshl_add_u64 v[180:181], s[16:17], 0, v[210:211]
	ds_read_b128 v[148:151], v236
	ds_read_b128 v[152:155], v236 offset:1024
	ds_read_b128 v[156:159], v236 offset:2048
	ds_read_b128 v[160:163], v236 offset:3072
	ds_read_b128 v[164:167], v236 offset:4096
	ds_read_b128 v[168:171], v236 offset:5120
	ds_read_b128 v[172:175], v236 offset:6144
	ds_read_b128 v[176:179], v236 offset:7168
	global_load_lds_dwordx4 v[180:181], off
	v_lshl_add_u64 v[180:181], s[16:17], 0, v[214:215]
	s_mov_b32 m0, s15
	s_nop 0
	global_load_lds_dwordx4 v[180:181], off
	s_waitcnt vmcnt(10)
	s_barrier
	s_waitcnt lgkmcnt(0)
	v_mfma_f32_16x16x32_f16 v[80:83], v[128:131], v[148:151], v[80:83]
	v_mfma_f32_16x16x32_f16 v[108:111], v[136:139], v[148:151], v[108:111]
	v_mfma_f32_16x16x32_f16 v[56:59], v[128:131], v[156:159], v[56:59]
	v_mfma_f32_16x16x32_f16 v[68:71], v[136:139], v[156:159], v[68:71]
	v_mfma_f32_16x16x32_f16 v[28:31], v[128:131], v[164:167], v[28:31]
	v_mfma_f32_16x16x32_f16 v[36:39], v[136:139], v[164:167], v[36:39]
	v_mfma_f32_16x16x32_f16 v[16:19], v[128:131], v[172:175], v[16:19]
	v_mfma_f32_16x16x32_f16 v[12:15], v[136:139], v[172:175], v[12:15]
	v_mfma_f32_16x16x32_f16 v[80:83], v[132:135], v[152:155], v[80:83]
	v_mfma_f32_16x16x32_f16 v[108:111], v[140:143], v[152:155], v[108:111]
	v_mfma_f32_16x16x32_f16 v[56:59], v[132:135], v[160:163], v[56:59]
	v_mfma_f32_16x16x32_f16 v[68:71], v[140:143], v[160:163], v[68:71]
	v_mfma_f32_16x16x32_f16 v[28:31], v[132:135], v[168:171], v[28:31]
	v_mfma_f32_16x16x32_f16 v[36:39], v[140:143], v[168:171], v[36:39]
	v_mfma_f32_16x16x32_f16 v[16:19], v[132:135], v[176:179], v[16:19]
	v_mfma_f32_16x16x32_f16 v[12:15], v[140:143], v[176:179], v[12:15]
	s_barrier
	s_mov_b32 m0, s19
	v_lshl_add_u64 v[196:197], s[26:27], 0, v[2:3]
	ds_read_b128 v[180:183], v238
	ds_read_b128 v[184:187], v238 offset:1024
	ds_read_b128 v[188:191], v238 offset:2048
	ds_read_b128 v[192:195], v238 offset:3072
	global_load_lds_dwordx4 v[196:197], off
	v_lshl_add_u64 v[198:199], s[26:27], 0, v[206:207]
	s_mov_b32 m0, s37
	s_nop 0
	global_load_lds_dwordx4 v[198:199], off
	s_waitcnt vmcnt(10)
	s_barrier
	s_waitcnt lgkmcnt(0)
	v_mfma_f32_16x16x32_f16 v[72:75], v[180:183], v[148:151], v[72:75]
	v_mfma_f32_16x16x32_f16 v[88:91], v[188:191], v[148:151], v[88:91]
	v_mfma_f32_16x16x32_f16 v[40:43], v[180:183], v[156:159], v[40:43]
	v_mfma_f32_16x16x32_f16 v[52:55], v[188:191], v[156:159], v[52:55]
	v_mfma_f32_16x16x32_f16 v[20:23], v[180:183], v[164:167], v[20:23]
	v_mfma_f32_16x16x32_f16 v[24:27], v[188:191], v[164:167], v[24:27]
	v_mfma_f32_16x16x32_f16 v[8:11], v[180:183], v[172:175], v[8:11]
	v_mfma_f32_16x16x32_f16 v[4:7], v[188:191], v[172:175], v[4:7]
	v_mfma_f32_16x16x32_f16 v[72:75], v[184:187], v[152:155], v[72:75]
	v_mfma_f32_16x16x32_f16 v[88:91], v[192:195], v[152:155], v[88:91]
	v_mfma_f32_16x16x32_f16 v[40:43], v[184:187], v[160:163], v[40:43]
	v_mfma_f32_16x16x32_f16 v[52:55], v[192:195], v[160:163], v[52:55]
	v_mfma_f32_16x16x32_f16 v[20:23], v[184:187], v[168:171], v[20:23]
	v_mfma_f32_16x16x32_f16 v[24:27], v[192:195], v[168:171], v[24:27]
	v_mfma_f32_16x16x32_f16 v[8:11], v[184:187], v[176:179], v[8:11]
	v_mfma_f32_16x16x32_f16 v[4:7], v[192:195], v[176:179], v[4:7]
	s_mov_b32 m0, s7
	v_lshl_add_u64 v[200:201], s[34:35], 0, v[210:211]
	s_barrier
	ds_read_b128 v[148:151], v236 offset:16384
	ds_read_b128 v[152:155], v236 offset:17408
	ds_read_b128 v[156:159], v236 offset:18432
	ds_read_b128 v[160:163], v236 offset:19456
	ds_read_b128 v[164:167], v236 offset:20480
	ds_read_b128 v[168:171], v236 offset:21504
	ds_read_b128 v[172:175], v236 offset:22528
	ds_read_b128 v[176:179], v236 offset:23552
	global_load_lds_dwordx4 v[200:201], off
	v_lshl_add_u64 v[202:203], s[34:35], 0, v[208:209]
	s_mov_b32 m0, s8
	s_nop 0
	global_load_lds_dwordx4 v[202:203], off
	s_waitcnt vmcnt(10)
	s_barrier
	s_waitcnt lgkmcnt(0)
	v_mfma_f32_16x16x32_f16 v[124:127], v[128:131], v[148:151], v[124:127]
	v_mfma_f32_16x16x32_f16 v[144:147], v[136:139], v[148:151], v[144:147]
	v_mfma_f32_16x16x32_f16 v[104:107], v[128:131], v[156:159], v[104:107]
	v_mfma_f32_16x16x32_f16 v[112:115], v[136:139], v[156:159], v[112:115]
	v_mfma_f32_16x16x32_f16 v[84:87], v[128:131], v[164:167], v[84:87]
	v_mfma_f32_16x16x32_f16 v[92:95], v[136:139], v[164:167], v[92:95]
	v_mfma_f32_16x16x32_f16 v[48:51], v[128:131], v[172:175], v[48:51]
	v_mfma_f32_16x16x32_f16 v[60:63], v[136:139], v[172:175], v[60:63]
	v_mfma_f32_16x16x32_f16 v[124:127], v[132:135], v[152:155], v[124:127]
	v_mfma_f32_16x16x32_f16 v[144:147], v[140:143], v[152:155], v[144:147]
	v_mfma_f32_16x16x32_f16 v[104:107], v[132:135], v[160:163], v[104:107]
	v_mfma_f32_16x16x32_f16 v[112:115], v[140:143], v[160:163], v[112:115]
	v_mfma_f32_16x16x32_f16 v[84:87], v[132:135], v[168:171], v[84:87]
	v_mfma_f32_16x16x32_f16 v[92:95], v[140:143], v[168:171], v[92:95]
	v_mfma_f32_16x16x32_f16 v[48:51], v[132:135], v[176:179], v[48:51]
	v_mfma_f32_16x16x32_f16 v[60:63], v[140:143], v[176:179], v[60:63]
	s_barrier
	s_add_u32 s30, s26, 0x80000
	s_addc_u32 s31, s27, 0
	s_mov_b32 m0, s63
	v_lshl_add_u64 v[128:129], s[30:31], 0, v[2:3]
	global_load_lds_dwordx4 v[128:129], off
	v_lshl_add_u64 v[128:129], s[30:31], 0, v[206:207]
	s_mov_b32 m0, s68
	s_nop 0
	global_load_lds_dwordx4 v[128:129], off
	s_waitcnt vmcnt(10)
	s_barrier
	v_mfma_f32_16x16x32_f16 v[116:119], v[180:183], v[148:151], v[116:119]
	v_mfma_f32_16x16x32_f16 v[120:123], v[188:191], v[148:151], v[120:123]
	v_mfma_f32_16x16x32_f16 v[96:99], v[180:183], v[156:159], v[96:99]
	v_mfma_f32_16x16x32_f16 v[100:103], v[188:191], v[156:159], v[100:103]
	v_mfma_f32_16x16x32_f16 v[64:67], v[180:183], v[164:167], v[64:67]
	v_mfma_f32_16x16x32_f16 v[76:79], v[188:191], v[164:167], v[76:79]
	v_mfma_f32_16x16x32_f16 v[32:35], v[180:183], v[172:175], v[32:35]
	v_mfma_f32_16x16x32_f16 v[44:47], v[188:191], v[172:175], v[44:47]
	v_mfma_f32_16x16x32_f16 v[116:119], v[184:187], v[152:155], v[116:119]
	v_mfma_f32_16x16x32_f16 v[120:123], v[192:195], v[152:155], v[120:123]
	v_mfma_f32_16x16x32_f16 v[96:99], v[184:187], v[160:163], v[96:99]
	v_mfma_f32_16x16x32_f16 v[100:103], v[192:195], v[160:163], v[100:103]
	v_mfma_f32_16x16x32_f16 v[64:67], v[184:187], v[168:171], v[64:67]
	v_mfma_f32_16x16x32_f16 v[76:79], v[192:195], v[168:171], v[76:79]
	v_mfma_f32_16x16x32_f16 v[32:35], v[184:187], v[176:179], v[32:35]
	v_mfma_f32_16x16x32_f16 v[44:47], v[192:195], v[176:179], v[44:47]
	s_barrier
	ds_read_b128 v[128:131], v239
	ds_read_b128 v[132:135], v239 offset:1024
	ds_read_b128 v[136:139], v239 offset:2048
	ds_read_b128 v[140:143], v239 offset:3072
	s_add_u32 s30, s34, 0x80000
	s_addc_u32 s31, s35, 0
	s_mov_b32 m0, s9
	v_lshl_add_u64 v[180:181], s[30:31], 0, v[210:211]
	ds_read_b128 v[148:151], v236 offset:32768
	ds_read_b128 v[152:155], v236 offset:33792
	ds_read_b128 v[156:159], v236 offset:34816
	ds_read_b128 v[160:163], v236 offset:35840
	ds_read_b128 v[164:167], v236 offset:36864
	ds_read_b128 v[168:171], v236 offset:37888
	ds_read_b128 v[172:175], v236 offset:38912
	ds_read_b128 v[176:179], v236 offset:39936
	global_load_lds_dwordx4 v[180:181], off
	v_lshl_add_u64 v[180:181], s[30:31], 0, v[208:209]
	s_mov_b32 m0, s12
	s_nop 0
	global_load_lds_dwordx4 v[180:181], off
	s_waitcnt vmcnt(10)
	s_barrier
	s_waitcnt lgkmcnt(0)
	v_mfma_f32_16x16x32_f16 v[80:83], v[128:131], v[148:151], v[80:83]
	v_mfma_f32_16x16x32_f16 v[108:111], v[136:139], v[148:151], v[108:111]
	v_mfma_f32_16x16x32_f16 v[56:59], v[128:131], v[156:159], v[56:59]
	v_mfma_f32_16x16x32_f16 v[68:71], v[136:139], v[156:159], v[68:71]
	v_mfma_f32_16x16x32_f16 v[28:31], v[128:131], v[164:167], v[28:31]
	v_mfma_f32_16x16x32_f16 v[36:39], v[136:139], v[164:167], v[36:39]
	v_mfma_f32_16x16x32_f16 v[16:19], v[128:131], v[172:175], v[16:19]
	v_mfma_f32_16x16x32_f16 v[12:15], v[136:139], v[172:175], v[12:15]
	v_mfma_f32_16x16x32_f16 v[80:83], v[132:135], v[152:155], v[80:83]
	v_mfma_f32_16x16x32_f16 v[108:111], v[140:143], v[152:155], v[108:111]
	v_mfma_f32_16x16x32_f16 v[56:59], v[132:135], v[160:163], v[56:59]
	v_mfma_f32_16x16x32_f16 v[68:71], v[140:143], v[160:163], v[68:71]
	v_mfma_f32_16x16x32_f16 v[28:31], v[132:135], v[168:171], v[28:31]
	v_mfma_f32_16x16x32_f16 v[36:39], v[140:143], v[168:171], v[36:39]
	v_mfma_f32_16x16x32_f16 v[16:19], v[132:135], v[176:179], v[16:19]
	v_mfma_f32_16x16x32_f16 v[12:15], v[140:143], v[176:179], v[12:15]
	s_barrier
	s_mov_b32 m0, s69
	v_lshl_add_u64 v[196:197], v[196:197], 0, s[88:89]
	ds_read_b128 v[180:183], v240
	ds_read_b128 v[184:187], v240 offset:1024
	ds_read_b128 v[188:191], v240 offset:2048
	ds_read_b128 v[192:195], v240 offset:3072
	global_load_lds_dwordx4 v[196:197], off
	v_lshl_add_u64 v[196:197], v[198:199], 0, s[88:89]
	s_mov_b32 m0, s70
	s_nop 0
	global_load_lds_dwordx4 v[196:197], off
	s_waitcnt vmcnt(10)
	s_barrier
	s_waitcnt lgkmcnt(0)
	v_mfma_f32_16x16x32_f16 v[72:75], v[180:183], v[148:151], v[72:75]
	v_mfma_f32_16x16x32_f16 v[88:91], v[188:191], v[148:151], v[88:91]
	v_mfma_f32_16x16x32_f16 v[40:43], v[180:183], v[156:159], v[40:43]
	v_mfma_f32_16x16x32_f16 v[52:55], v[188:191], v[156:159], v[52:55]
	v_mfma_f32_16x16x32_f16 v[20:23], v[180:183], v[164:167], v[20:23]
	v_mfma_f32_16x16x32_f16 v[24:27], v[188:191], v[164:167], v[24:27]
	v_mfma_f32_16x16x32_f16 v[8:11], v[180:183], v[172:175], v[8:11]
	v_mfma_f32_16x16x32_f16 v[4:7], v[188:191], v[172:175], v[4:7]
	v_mfma_f32_16x16x32_f16 v[72:75], v[184:187], v[152:155], v[72:75]
	v_mfma_f32_16x16x32_f16 v[88:91], v[192:195], v[152:155], v[88:91]
	v_mfma_f32_16x16x32_f16 v[40:43], v[184:187], v[160:163], v[40:43]
	v_mfma_f32_16x16x32_f16 v[52:55], v[192:195], v[160:163], v[52:55]
	v_mfma_f32_16x16x32_f16 v[20:23], v[184:187], v[168:171], v[20:23]
	v_mfma_f32_16x16x32_f16 v[24:27], v[192:195], v[168:171], v[24:27]
	v_mfma_f32_16x16x32_f16 v[8:11], v[184:187], v[176:179], v[8:11]
	v_mfma_f32_16x16x32_f16 v[4:7], v[192:195], v[176:179], v[4:7]
	s_mov_b32 m0, s39
	v_lshl_add_u64 v[196:197], v[200:201], 0, s[88:89]
	s_barrier
	ds_read_b128 v[148:151], v236 offset:49152
	ds_read_b128 v[152:155], v236 offset:50176
	ds_read_b128 v[156:159], v236 offset:51200
	ds_read_b128 v[160:163], v236 offset:52224
	ds_read_b128 v[164:167], v236 offset:53248
	ds_read_b128 v[168:171], v236 offset:54272
	ds_read_b128 v[172:175], v236 offset:55296
	ds_read_b128 v[176:179], v236 offset:56320
	global_load_lds_dwordx4 v[196:197], off
	v_lshl_add_u64 v[196:197], v[202:203], 0, s[88:89]
	s_mov_b32 m0, s47
	s_nop 0
	global_load_lds_dwordx4 v[196:197], off
	s_waitcnt vmcnt(10)
	s_barrier
	s_waitcnt lgkmcnt(0)
	v_mfma_f32_16x16x32_f16 v[124:127], v[128:131], v[148:151], v[124:127]
	v_mfma_f32_16x16x32_f16 v[144:147], v[136:139], v[148:151], v[144:147]
	v_mfma_f32_16x16x32_f16 v[104:107], v[128:131], v[156:159], v[104:107]
	v_mfma_f32_16x16x32_f16 v[112:115], v[136:139], v[156:159], v[112:115]
	v_mfma_f32_16x16x32_f16 v[84:87], v[128:131], v[164:167], v[84:87]
	v_mfma_f32_16x16x32_f16 v[92:95], v[136:139], v[164:167], v[92:95]
	v_mfma_f32_16x16x32_f16 v[48:51], v[128:131], v[172:175], v[48:51]
	v_mfma_f32_16x16x32_f16 v[60:63], v[136:139], v[172:175], v[60:63]
	v_mfma_f32_16x16x32_f16 v[124:127], v[132:135], v[152:155], v[124:127]
	v_mfma_f32_16x16x32_f16 v[144:147], v[140:143], v[152:155], v[144:147]
	v_mfma_f32_16x16x32_f16 v[104:107], v[132:135], v[160:163], v[104:107]
	v_mfma_f32_16x16x32_f16 v[112:115], v[140:143], v[160:163], v[112:115]
	v_mfma_f32_16x16x32_f16 v[84:87], v[132:135], v[168:171], v[84:87]
	v_mfma_f32_16x16x32_f16 v[92:95], v[140:143], v[168:171], v[92:95]
	v_mfma_f32_16x16x32_f16 v[48:51], v[132:135], v[176:179], v[48:51]
	v_mfma_f32_16x16x32_f16 v[60:63], v[140:143], v[176:179], v[60:63]
	s_barrier
	s_add_u32 s26, s26, 0x80080
	s_addc_u32 s27, s27, 0
	s_mov_b32 m0, s71
	v_lshl_add_u64 v[128:129], s[26:27], 0, v[2:3]
	global_load_lds_dwordx4 v[128:129], off
	v_lshl_add_u64 v[128:129], s[26:27], 0, v[206:207]
	s_mov_b32 m0, s76
	s_nop 0
	global_load_lds_dwordx4 v[128:129], off
	s_waitcnt vmcnt(10)
	s_barrier
	v_mfma_f32_16x16x32_f16 v[116:119], v[180:183], v[148:151], v[116:119]
	v_mfma_f32_16x16x32_f16 v[120:123], v[188:191], v[148:151], v[120:123]
	v_mfma_f32_16x16x32_f16 v[96:99], v[180:183], v[156:159], v[96:99]
	v_mfma_f32_16x16x32_f16 v[100:103], v[188:191], v[156:159], v[100:103]
	v_mfma_f32_16x16x32_f16 v[64:67], v[180:183], v[164:167], v[64:67]
	v_mfma_f32_16x16x32_f16 v[76:79], v[188:191], v[164:167], v[76:79]
	v_mfma_f32_16x16x32_f16 v[32:35], v[180:183], v[172:175], v[32:35]
	v_mfma_f32_16x16x32_f16 v[44:47], v[188:191], v[172:175], v[44:47]
	v_mfma_f32_16x16x32_f16 v[116:119], v[184:187], v[152:155], v[116:119]
	v_mfma_f32_16x16x32_f16 v[120:123], v[192:195], v[152:155], v[120:123]
	v_mfma_f32_16x16x32_f16 v[96:99], v[184:187], v[160:163], v[96:99]
	v_mfma_f32_16x16x32_f16 v[100:103], v[192:195], v[160:163], v[100:103]
	v_mfma_f32_16x16x32_f16 v[64:67], v[184:187], v[168:171], v[64:67]
	v_mfma_f32_16x16x32_f16 v[76:79], v[192:195], v[168:171], v[76:79]
	v_mfma_f32_16x16x32_f16 v[32:35], v[184:187], v[176:179], v[32:35]
	v_mfma_f32_16x16x32_f16 v[44:47], v[192:195], v[176:179], v[44:47]
	s_add_i32 s29, s29, 2
	s_add_u32 s16, s16, 0x100
	s_addc_u32 s17, s17, 0
	s_add_u32 s10, s10, 0x100
	s_addc_u32 s11, s11, 0
	s_cmp_lt_u32 s29, 30
	s_barrier
	s_cbranch_scc1 .LBB0_1746
	s_add_i32 s10, s46, 16
	s_mul_hi_i32 s11, s10, 0x42
	s_mulk_i32 s10, 0x42
	s_add_u32 s10, s10, s48
	v_mov_b32_e32 v128, v233
	s_addc_u32 s11, s11, s78
	v_mov_b32_e32 v129, v234
	s_lshl_b64 s[10:11], s[10:11], 17
	v_add_u32_e32 v202, s13, v128
	v_lshlrev_b32_e32 v128, 8, v202
	v_lshlrev_b32_e32 v196, 3, v129
	s_add_u32 s10, s4, s10
	s_addc_u32 s11, s6, s11
	v_ashrrev_i32_e32 v197, 31, v196
	v_add_u32_e32 v140, 0x8000, v128
	v_lshl_add_u64 v[130:131], v[196:197], 1, s[10:11]
	v_ashrrev_i32_e32 v141, 31, v140
	v_lshl_add_u64 v[160:161], v[140:141], 1, v[130:131]
	v_add_u32_e32 v140, 0x9000, v128
	v_ashrrev_i32_e32 v129, 31, v128
	v_ashrrev_i32_e32 v141, 31, v140
	v_lshl_add_u64 v[132:133], v[128:129], 1, v[130:131]
	v_add_u32_e32 v134, 0x1000, v128
	v_add_u32_e32 v136, 0x2000, v128
	v_add_u32_e32 v138, 0x3000, v128
	v_lshl_add_u64 v[152:153], v[140:141], 1, v[130:131]
	v_add_u32_e32 v140, 0xa000, v128
	v_add_u32_e32 v128, 0xb000, v128
	v_ashrrev_i32_e32 v135, 31, v134
	v_ashrrev_i32_e32 v137, 31, v136
	v_ashrrev_i32_e32 v139, 31, v138
	v_ashrrev_i32_e32 v141, 31, v140
	v_ashrrev_i32_e32 v129, 31, v128
	v_lshl_add_u64 v[134:135], v[134:135], 1, v[130:131]
	v_lshl_add_u64 v[136:137], v[136:137], 1, v[130:131]
	v_lshl_add_u64 v[138:139], v[138:139], 1, v[130:131]
	v_lshl_add_u64 v[140:141], v[140:141], 1, v[130:131]
	v_lshl_add_u64 v[142:143], v[128:129], 1, v[130:131]
	global_load_dwordx4 v[164:167], v[138:139], off offset:256
	global_load_dwordx4 v[168:171], v[138:139], off
	global_load_dwordx4 v[172:175], v[136:137], off offset:256
	global_load_dwordx4 v[176:179], v[136:137], off
	global_load_dwordx4 v[180:183], v[134:135], off offset:256
	global_load_dwordx4 v[184:187], v[134:135], off
	global_load_dwordx4 v[188:191], v[132:133], off offset:256
	global_load_dwordx4 v[192:195], v[132:133], off
	global_load_dwordx4 v[128:131], v[142:143], off offset:256
	s_nop 0
	global_load_dwordx4 v[132:135], v[142:143], off
	global_load_dwordx4 v[136:139], v[140:141], off offset:256
	s_nop 0
	global_load_dwordx4 v[140:143], v[140:141], off
	s_nop 0
	global_load_dwordx4 v[148:151], v[152:153], off offset:256
	s_nop 0
	global_load_dwordx4 v[152:155], v[152:153], off
	s_nop 0
	global_load_dwordx4 v[156:159], v[160:161], off offset:256
	s_nop 0
	global_load_dwordx4 v[160:163], v[160:161], off
	v_mov_b32_e32 v199, v82
	v_pk_mov_b32 v[82:83], v[82:83], v[108:109] op_sel:[1,0]
	v_lshl_add_u32 v108, s48, 8, v202
	v_mov_b32_e32 v200, v109
	v_ashrrev_i32_e32 v109, 31, v108
	v_mov_b32_e32 v198, v81
	v_mov_b32_e32 v201, v110
	v_lshlrev_b64 v[202:203], 12, v[108:109]
	s_lshl_b32 s10, s46, 8
	s_or_b32 s10, s10, s38
	v_add_u32_e32 v196, s10, v196
	v_readlane_b32 s10, v254, 26
	v_readlane_b32 s11, v254, 27
	v_ashrrev_i32_e32 v197, 31, v196
	s_mov_b32 s46, s18
	s_mov_b32 s48, s36
	s_mov_b64 s[50:51], s[44:45]
	s_mov_b64 s[34:35], s[42:43]
	s_waitcnt vmcnt(0)
	s_nop 0
	v_cvt_f32_f16_e32 v81, v192
	v_cvt_f32_f16_e32 v108, v194
	v_cvt_f32_f16_sdwa v110, v192 dst_sel:DWORD dst_unused:UNUSED_PAD src0_sel:WORD_1
	v_cvt_f32_f16_e32 v220, v193
	v_cvt_f32_f16_sdwa v224, v193 dst_sel:DWORD dst_unused:UNUSED_PAD src0_sel:WORD_1
	v_cvt_f32_f16_sdwa v194, v194 dst_sel:DWORD dst_unused:UNUSED_PAD src0_sel:WORD_1
	v_cvt_f32_f16_e32 v221, v195
	v_rcp_f32_e32 v81, v81
	v_rcp_f32_e32 v109, v108
	v_rcp_f32_e32 v192, v110
	v_rcp_f32_e32 v193, v220
	v_rcp_f32_e32 v108, v224
	v_cvt_f32_f16_sdwa v225, v195 dst_sel:DWORD dst_unused:UNUSED_PAD src0_sel:WORD_1
	v_rcp_f32_e32 v194, v194
	v_rcp_f32_e32 v195, v221
	v_fma_mixlo_f16 v220, v80, v81, 0
	v_pk_mul_f32 v[80:81], v[198:199], v[192:193]
	v_pk_mul_f32 v[82:83], v[82:83], v[108:109]
	v_cvt_pk_f16_f32 v80, v80, v81
	v_cvt_pk_f16_f32 v82, v82, v83
	v_pack_b32_f16 v83, v220, v80
	v_alignbit_b32 v80, v82, v80, 16
	v_pk_mul_f32 v[192:193], v[200:201], v[194:195]
	v_lshrrev_b32_e32 v109, 4, v80
	v_cvt_pk_f16_f32 v81, v192, v193
	v_and_b32_e32 v109, 0x10001, v109
	v_alignbit_b32 v82, v81, v82, 16
	v_add3_u32 v80, v80, v109, s21
	v_rcp_f32_e32 v110, v225
	v_and_b32_e32 v109, 0xfff0fff0, v80
	v_lshrrev_b32_e32 v80, 4, v82
	v_and_b32_e32 v80, 0x10001, v80
	v_add3_u32 v80, v82, v80, s21
	v_cvt_f32_f16_e32 v82, v188
	v_lshrrev_b32_e32 v81, 16, v81
	v_fma_mixhi_f16 v81, v111, v110, 0
	v_and_b32_e32 v110, 0xfff0fff0, v80
	v_lshrrev_b32_e32 v80, 4, v81
	v_lshrrev_b32_e32 v108, 4, v83
	v_and_b32_e32 v80, 0x10001, v80
	v_rcp_f32_e32 v82, v82
	v_and_b32_e32 v108, 0x10001, v108
	v_add3_u32 v80, v81, v80, s21
	v_add3_u32 v83, v83, v108, s21
	v_and_b32_e32 v111, 0xfff0fff0, v80
	v_lshl_add_u64 v[80:81], s[10:11], 0, v[202:203]
	v_and_b32_e32 v108, 0xfff0fff0, v83
	v_lshl_add_u64 v[80:81], v[196:197], 1, v[80:81]
	global_store_dwordx4 v[80:81], v[108:111], off
	v_fma_mixlo_f16 v82, v72, v82, 0
	v_cvt_f32_f16_e32 v72, v190
	v_cvt_f32_f16_sdwa v108, v188 dst_sel:DWORD dst_unused:UNUSED_PAD src0_sel:WORD_1
	v_cvt_f32_f16_sdwa v109, v190 dst_sel:DWORD dst_unused:UNUSED_PAD src0_sel:WORD_1
	v_cvt_f32_f16_e32 v110, v189
	v_rcp_f32_e32 v83, v72
	v_rcp_f32_e32 v108, v108
	v_rcp_f32_e32 v72, v109
	v_rcp_f32_e32 v109, v110
	v_mov_b32_e32 v110, v73
	v_mov_b32_e32 v111, v74
	v_cvt_f32_f16_e32 v73, v191
	v_pk_mul_f32 v[108:109], v[110:111], v[108:109]
	s_mov_b64 s[10:11], 0x10000
	v_cvt_pk_f16_f32 v74, v108, v109
	v_pack_b32_f16 v110, v82, v74
	v_cvt_f32_f16_sdwa v82, v189 dst_sel:DWORD dst_unused:UNUSED_PAD src0_sel:WORD_1
	v_rcp_f32_e32 v73, v73
	v_mov_b32_e32 v108, v89
	v_mov_b32_e32 v109, v90
	v_rcp_f32_e32 v82, v82
	v_pk_mul_f32 v[72:73], v[108:109], v[72:73]
	v_cvt_f32_f16_sdwa v90, v191 dst_sel:DWORD dst_unused:UNUSED_PAD src0_sel:WORD_1
	v_cvt_pk_f16_f32 v89, v72, v73
	v_pk_mov_b32 v[72:73], v[74:75], v[88:89] op_sel:[1,0]
	s_nop 0
	v_pk_mul_f32 v[72:73], v[72:73], v[82:83]
	v_lshrrev_b32_e32 v82, 16, v89
	v_cvt_pk_f16_f32 v72, v72, v73
	v_rcp_f32_e32 v73, v90
	v_alignbit_b32 v74, v72, v74, 16
	v_alignbit_b32 v75, v89, v72, 16
	v_lshrrev_b32_e32 v72, 4, v110
	v_fma_mixhi_f16 v82, v91, v73, 0
	v_lshrrev_b32_e32 v73, 4, v74
	v_and_b32_e32 v73, 0x10001, v73
	v_add3_u32 v73, v74, v73, s21
	v_lshrrev_b32_e32 v74, 4, v75
	v_and_b32_e32 v74, 0x10001, v74
	v_add3_u32 v74, v75, v74, s21
	v_cvt_f32_f16_e32 v75, v184
	v_lshrrev_b32_e32 v83, 4, v82
	v_and_b32_e32 v72, 0x10001, v72
	v_and_b32_e32 v83, 0x10001, v83
	v_rcp_f32_e32 v88, v75
	v_add3_u32 v72, v110, v72, s21
	v_add3_u32 v75, v82, v83, s21
	v_and_b32_e32 v72, 0xfff0fff0, v72
	v_and_b32_e32 v73, 0xfff0fff0, v73
	v_and_b32_e32 v74, 0xfff0fff0, v74
	v_and_b32_e32 v75, 0xfff0fff0, v75
	global_store_dwordx4 v[80:81], v[72:75], off offset:256
	v_cvt_f32_f16_e32 v82, v185
	v_mov_b32_e32 v83, v58
	v_fma_mixlo_f16 v72, v56, v88, 0
	v_cvt_f32_f16_e32 v56, v186
	v_cvt_f32_f16_sdwa v74, v184 dst_sel:DWORD dst_unused:UNUSED_PAD src0_sel:WORD_1
	v_cvt_f32_f16_sdwa v75, v186 dst_sel:DWORD dst_unused:UNUSED_PAD src0_sel:WORD_1
	v_rcp_f32_e32 v73, v56
	v_rcp_f32_e32 v74, v74
	v_rcp_f32_e32 v56, v75
	v_rcp_f32_e32 v75, v82
	v_mov_b32_e32 v82, v57
	v_cvt_f32_f16_e32 v57, v187
	v_pk_mul_f32 v[74:75], v[82:83], v[74:75]
	s_nop 0
	v_cvt_pk_f16_f32 v58, v74, v75
	v_pack_b32_f16 v82, v72, v58
	v_cvt_f32_f16_sdwa v72, v185 dst_sel:DWORD dst_unused:UNUSED_PAD src0_sel:WORD_1
	v_rcp_f32_e32 v57, v57
	v_mov_b32_e32 v74, v69
	v_mov_b32_e32 v75, v70
	v_rcp_f32_e32 v72, v72
	v_pk_mul_f32 v[56:57], v[74:75], v[56:57]
	v_cvt_f32_f16_sdwa v70, v187 dst_sel:DWORD dst_unused:UNUSED_PAD src0_sel:WORD_1
	v_cvt_pk_f16_f32 v69, v56, v57
	v_pk_mov_b32 v[56:57], v[58:59], v[68:69] op_sel:[1,0]
	v_lshrrev_b32_e32 v68, 16, v69
	v_pk_mul_f32 v[56:57], v[56:57], v[72:73]
	s_nop 0
	v_cvt_pk_f16_f32 v56, v56, v57
	v_rcp_f32_e32 v57, v70
	v_alignbit_b32 v58, v56, v58, 16
	v_alignbit_b32 v59, v69, v56, 16
	v_cvt_f32_f16_e32 v70, v180
	v_fma_mixhi_f16 v68, v71, v57, 0
	v_lshrrev_b32_e32 v57, 4, v58
	v_and_b32_e32 v57, 0x10001, v57
	v_add3_u32 v57, v58, v57, s21
	v_lshrrev_b32_e32 v58, 4, v59
	v_and_b32_e32 v58, 0x10001, v58
	v_add3_u32 v58, v59, v58, s21
	v_lshrrev_b32_e32 v59, 4, v68
	v_lshrrev_b32_e32 v56, 4, v82
	v_and_b32_e32 v59, 0x10001, v59
	v_rcp_f32_e32 v72, v70
	v_and_b32_e32 v56, 0x10001, v56
	v_add3_u32 v59, v68, v59, s21
	v_lshl_add_u64 v[68:69], v[80:81], 0, s[10:11]
	s_mov_b32 s10, 0x10000
	v_add3_u32 v56, v82, v56, s21
	v_add_co_u32_e32 v70, vcc, s10, v80
	v_and_b32_e32 v56, 0xfff0fff0, v56
	v_and_b32_e32 v57, 0xfff0fff0, v57
	v_and_b32_e32 v58, 0xfff0fff0, v58
	v_and_b32_e32 v59, 0xfff0fff0, v59
	v_addc_co_u32_e32 v71, vcc, 0, v81, vcc
	global_store_dwordx4 v[70:71], v[56:59], off
	v_cvt_f32_f16_e32 v70, v181
	v_mov_b32_e32 v71, v42
	v_fma_mixlo_f16 v56, v40, v72, 0
	v_cvt_f32_f16_e32 v40, v182
	v_cvt_f32_f16_sdwa v58, v180 dst_sel:DWORD dst_unused:UNUSED_PAD src0_sel:WORD_1
	v_cvt_f32_f16_sdwa v59, v182 dst_sel:DWORD dst_unused:UNUSED_PAD src0_sel:WORD_1
	s_mov_b64 s[10:11], 0x20000
	v_rcp_f32_e32 v57, v40
	v_rcp_f32_e32 v58, v58
	v_rcp_f32_e32 v40, v59
	v_rcp_f32_e32 v59, v70
	v_mov_b32_e32 v70, v41
	v_cvt_f32_f16_e32 v41, v183
	v_pk_mul_f32 v[58:59], v[70:71], v[58:59]
	s_nop 0
	v_cvt_pk_f16_f32 v42, v58, v59
	v_pack_b32_f16 v70, v56, v42
	v_cvt_f32_f16_sdwa v56, v181 dst_sel:DWORD dst_unused:UNUSED_PAD src0_sel:WORD_1
	v_rcp_f32_e32 v41, v41
	v_mov_b32_e32 v58, v53
	v_mov_b32_e32 v59, v54
	v_rcp_f32_e32 v56, v56
	v_pk_mul_f32 v[40:41], v[58:59], v[40:41]
	v_cvt_f32_f16_sdwa v54, v183 dst_sel:DWORD dst_unused:UNUSED_PAD src0_sel:WORD_1
	v_cvt_pk_f16_f32 v53, v40, v41
	v_pk_mov_b32 v[40:41], v[42:43], v[52:53] op_sel:[1,0]
	v_lshrrev_b32_e32 v52, 16, v53
	v_pk_mul_f32 v[40:41], v[40:41], v[56:57]
	s_nop 0
	v_cvt_pk_f16_f32 v40, v40, v41
	v_rcp_f32_e32 v41, v54
	v_alignbit_b32 v42, v40, v42, 16
	v_alignbit_b32 v43, v53, v40, 16
	v_lshrrev_b32_e32 v40, 4, v70
	v_fma_mixhi_f16 v52, v55, v41, 0
	v_lshrrev_b32_e32 v41, 4, v42
	v_and_b32_e32 v41, 0x10001, v41
	v_add3_u32 v41, v42, v41, s21
	v_lshrrev_b32_e32 v42, 4, v43
	v_and_b32_e32 v42, 0x10001, v42
	v_add3_u32 v42, v43, v42, s21
	v_cvt_f32_f16_e32 v43, v176
	v_lshrrev_b32_e32 v53, 4, v52
	v_and_b32_e32 v40, 0x10001, v40
	v_and_b32_e32 v53, 0x10001, v53
	v_rcp_f32_e32 v54, v43
	v_add3_u32 v40, v70, v40, s21
	v_add3_u32 v43, v52, v53, s21
	v_and_b32_e32 v40, 0xfff0fff0, v40
	v_and_b32_e32 v41, 0xfff0fff0, v41
	v_and_b32_e32 v42, 0xfff0fff0, v42
	v_and_b32_e32 v43, 0xfff0fff0, v43
	global_store_dwordx4 v[68:69], v[40:43], off offset:256
	v_cvt_f32_f16_e32 v52, v177
	v_mov_b32_e32 v53, v30
	v_fma_mixlo_f16 v40, v28, v54, 0
	v_cvt_f32_f16_e32 v28, v178
	v_cvt_f32_f16_sdwa v42, v176 dst_sel:DWORD dst_unused:UNUSED_PAD src0_sel:WORD_1
	v_cvt_f32_f16_sdwa v43, v178 dst_sel:DWORD dst_unused:UNUSED_PAD src0_sel:WORD_1
	v_rcp_f32_e32 v41, v28
	v_rcp_f32_e32 v42, v42
	v_rcp_f32_e32 v28, v43
	v_rcp_f32_e32 v43, v52
	v_mov_b32_e32 v52, v29
	v_cvt_f32_f16_e32 v29, v179
	v_pk_mul_f32 v[42:43], v[52:53], v[42:43]
	s_nop 0
	v_cvt_pk_f16_f32 v30, v42, v43
	v_pack_b32_f16 v52, v40, v30
	v_cvt_f32_f16_sdwa v40, v177 dst_sel:DWORD dst_unused:UNUSED_PAD src0_sel:WORD_1
	v_rcp_f32_e32 v29, v29
	v_mov_b32_e32 v42, v37
	v_mov_b32_e32 v43, v38
	v_rcp_f32_e32 v40, v40
	v_pk_mul_f32 v[28:29], v[42:43], v[28:29]
	v_cvt_f32_f16_sdwa v38, v179 dst_sel:DWORD dst_unused:UNUSED_PAD src0_sel:WORD_1
	v_cvt_pk_f16_f32 v37, v28, v29
	v_pk_mov_b32 v[28:29], v[30:31], v[36:37] op_sel:[1,0]
	v_lshrrev_b32_e32 v36, 16, v37
	v_pk_mul_f32 v[28:29], v[28:29], v[40:41]
	s_nop 0
	v_cvt_pk_f16_f32 v28, v28, v29
	v_rcp_f32_e32 v29, v38
	v_alignbit_b32 v30, v28, v30, 16
	v_alignbit_b32 v31, v37, v28, 16
	v_cvt_f32_f16_e32 v38, v172
	v_fma_mixhi_f16 v36, v39, v29, 0
	v_lshrrev_b32_e32 v29, 4, v30
	v_and_b32_e32 v29, 0x10001, v29
	v_add3_u32 v29, v30, v29, s21
	v_lshrrev_b32_e32 v30, 4, v31
	v_and_b32_e32 v30, 0x10001, v30
	v_add3_u32 v30, v31, v30, s21
	v_lshrrev_b32_e32 v31, 4, v36
	v_lshrrev_b32_e32 v28, 4, v52
	v_and_b32_e32 v31, 0x10001, v31
	v_rcp_f32_e32 v40, v38
	v_and_b32_e32 v28, 0x10001, v28
	v_add3_u32 v31, v36, v31, s21
	v_lshl_add_u64 v[36:37], v[80:81], 0, s[10:11]
	s_mov_b32 s10, 0x20000
	v_add3_u32 v28, v52, v28, s21
	v_add_co_u32_e32 v38, vcc, s10, v80
	v_and_b32_e32 v28, 0xfff0fff0, v28
	v_and_b32_e32 v29, 0xfff0fff0, v29
	v_and_b32_e32 v30, 0xfff0fff0, v30
	v_and_b32_e32 v31, 0xfff0fff0, v31
	v_addc_co_u32_e32 v39, vcc, 0, v81, vcc
	global_store_dwordx4 v[38:39], v[28:31], off
	v_cvt_f32_f16_e32 v38, v173
	v_mov_b32_e32 v39, v22
	v_fma_mixlo_f16 v28, v20, v40, 0
	v_cvt_f32_f16_e32 v20, v174
	v_cvt_f32_f16_sdwa v30, v172 dst_sel:DWORD dst_unused:UNUSED_PAD src0_sel:WORD_1
	v_cvt_f32_f16_sdwa v31, v174 dst_sel:DWORD dst_unused:UNUSED_PAD src0_sel:WORD_1
	s_mov_b64 s[10:11], 0x30000
	v_rcp_f32_e32 v29, v20
	v_rcp_f32_e32 v30, v30
	v_rcp_f32_e32 v20, v31
	v_rcp_f32_e32 v31, v38
	v_mov_b32_e32 v38, v21
	v_cvt_f32_f16_e32 v21, v175
	v_pk_mul_f32 v[30:31], v[38:39], v[30:31]
	s_nop 0
	v_cvt_pk_f16_f32 v22, v30, v31
	v_pack_b32_f16 v38, v28, v22
	v_cvt_f32_f16_sdwa v28, v173 dst_sel:DWORD dst_unused:UNUSED_PAD src0_sel:WORD_1
	v_rcp_f32_e32 v21, v21
	v_mov_b32_e32 v30, v25
	v_mov_b32_e32 v31, v26
	v_rcp_f32_e32 v28, v28
	v_pk_mul_f32 v[20:21], v[30:31], v[20:21]
	v_cvt_f32_f16_sdwa v26, v175 dst_sel:DWORD dst_unused:UNUSED_PAD src0_sel:WORD_1
	v_cvt_pk_f16_f32 v25, v20, v21
	v_pk_mov_b32 v[20:21], v[22:23], v[24:25] op_sel:[1,0]
	v_lshrrev_b32_e32 v24, 16, v25
	v_pk_mul_f32 v[20:21], v[20:21], v[28:29]
	s_nop 0
	v_cvt_pk_f16_f32 v20, v20, v21
	v_rcp_f32_e32 v21, v26
	v_alignbit_b32 v22, v20, v22, 16
	v_alignbit_b32 v23, v25, v20, 16
	v_lshrrev_b32_e32 v20, 4, v38
	v_fma_mixhi_f16 v24, v27, v21, 0
	v_lshrrev_b32_e32 v21, 4, v22
	v_and_b32_e32 v21, 0x10001, v21
	v_add3_u32 v21, v22, v21, s21
	v_lshrrev_b32_e32 v22, 4, v23
	v_and_b32_e32 v22, 0x10001, v22
	v_add3_u32 v22, v23, v22, s21
	v_cvt_f32_f16_e32 v23, v168
	v_lshrrev_b32_e32 v25, 4, v24
	v_and_b32_e32 v20, 0x10001, v20
	v_and_b32_e32 v25, 0x10001, v25
	v_rcp_f32_e32 v26, v23
	v_add3_u32 v20, v38, v20, s21
	v_add3_u32 v23, v24, v25, s21
	v_and_b32_e32 v20, 0xfff0fff0, v20
	v_and_b32_e32 v21, 0xfff0fff0, v21
	v_and_b32_e32 v22, 0xfff0fff0, v22
	v_and_b32_e32 v23, 0xfff0fff0, v23
	global_store_dwordx4 v[36:37], v[20:23], off offset:256
	v_cvt_f32_f16_e32 v24, v169
	v_mov_b32_e32 v25, v18
	v_fma_mixlo_f16 v20, v16, v26, 0
	v_cvt_f32_f16_e32 v16, v170
	v_cvt_f32_f16_sdwa v22, v168 dst_sel:DWORD dst_unused:UNUSED_PAD src0_sel:WORD_1
	v_cvt_f32_f16_sdwa v23, v170 dst_sel:DWORD dst_unused:UNUSED_PAD src0_sel:WORD_1
	v_rcp_f32_e32 v21, v16
	v_rcp_f32_e32 v22, v22
	v_rcp_f32_e32 v16, v23
	v_rcp_f32_e32 v23, v24
	v_mov_b32_e32 v24, v17
	v_cvt_f32_f16_e32 v17, v171
	v_pk_mul_f32 v[22:23], v[24:25], v[22:23]
	s_nop 0
	v_cvt_pk_f16_f32 v18, v22, v23
	v_pack_b32_f16 v24, v20, v18
	v_rcp_f32_e32 v17, v17
	v_cvt_f32_f16_sdwa v20, v169 dst_sel:DWORD dst_unused:UNUSED_PAD src0_sel:WORD_1
	v_mov_b32_e32 v22, v13
	v_mov_b32_e32 v23, v14
	v_pk_mul_f32 v[16:17], v[22:23], v[16:17]
	v_rcp_f32_e32 v20, v20
	v_cvt_pk_f16_f32 v14, v16, v17
	v_cvt_f32_f16_sdwa v16, v171 dst_sel:DWORD dst_unused:UNUSED_PAD src0_sel:WORD_1
	v_pk_mov_b32 v[12:13], v[18:19], v[12:13] op_sel:[1,0]
	s_nop 0
	v_pk_mul_f32 v[12:13], v[12:13], v[20:21]
	s_nop 0
	v_cvt_pk_f16_f32 v12, v12, v13
	v_rcp_f32_e32 v13, v16
	v_alignbit_b32 v16, v12, v18, 16
	v_lshrrev_b32_e32 v18, 16, v14
	v_alignbit_b32 v17, v14, v12, 16
	v_fma_mixhi_f16 v18, v15, v13, 0
	v_lshrrev_b32_e32 v15, 4, v18
	v_and_b32_e32 v15, 0x10001, v15
	v_add3_u32 v15, v18, v15, s21
	v_cvt_f32_f16_e32 v18, v164
	v_lshrrev_b32_e32 v13, 4, v16
	v_lshrrev_b32_e32 v14, 4, v17
	v_lshrrev_b32_e32 v12, 4, v24
	v_and_b32_e32 v13, 0x10001, v13
	v_and_b32_e32 v14, 0x10001, v14
	v_rcp_f32_e32 v20, v18
	v_and_b32_e32 v12, 0x10001, v12
	v_add3_u32 v13, v16, v13, s21
	v_add3_u32 v14, v17, v14, s21
	v_lshl_add_u64 v[16:17], v[80:81], 0, s[10:11]
	s_mov_b32 s10, 0x30000
	v_add3_u32 v12, v24, v12, s21
	v_add_co_u32_e32 v18, vcc, s10, v80
	v_and_b32_e32 v12, 0xfff0fff0, v12
	v_and_b32_e32 v13, 0xfff0fff0, v13
	v_and_b32_e32 v14, 0xfff0fff0, v14
	v_and_b32_e32 v15, 0xfff0fff0, v15
	v_addc_co_u32_e32 v19, vcc, 0, v81, vcc
	global_store_dwordx4 v[18:19], v[12:15], off
	v_cvt_f32_f16_e32 v18, v165
	v_mov_b32_e32 v19, v10
	v_fma_mixlo_f16 v12, v8, v20, 0
	v_cvt_f32_f16_e32 v8, v166
	v_cvt_f32_f16_sdwa v14, v164 dst_sel:DWORD dst_unused:UNUSED_PAD src0_sel:WORD_1
	v_cvt_f32_f16_sdwa v15, v166 dst_sel:DWORD dst_unused:UNUSED_PAD src0_sel:WORD_1
	s_mov_b64 s[10:11], 0x80000
	v_rcp_f32_e32 v13, v8
	v_rcp_f32_e32 v14, v14
	v_rcp_f32_e32 v8, v15
	v_rcp_f32_e32 v15, v18
	v_mov_b32_e32 v18, v9
	v_cvt_f32_f16_e32 v9, v167
	v_pk_mul_f32 v[14:15], v[18:19], v[14:15]
	s_nop 0
	v_cvt_pk_f16_f32 v10, v14, v15
	v_pack_b32_f16 v18, v12, v10
	v_rcp_f32_e32 v9, v9
	v_cvt_f32_f16_sdwa v12, v165 dst_sel:DWORD dst_unused:UNUSED_PAD src0_sel:WORD_1
	v_mov_b32_e32 v14, v5
	v_mov_b32_e32 v15, v6
	v_pk_mul_f32 v[8:9], v[14:15], v[8:9]
	v_rcp_f32_e32 v12, v12
	v_cvt_pk_f16_f32 v6, v8, v9
	v_cvt_f32_f16_sdwa v8, v167 dst_sel:DWORD dst_unused:UNUSED_PAD src0_sel:WORD_1
	v_pk_mov_b32 v[4:5], v[10:11], v[4:5] op_sel:[1,0]
	v_mov_b32_e32 v11, v126
	v_pk_mul_f32 v[4:5], v[4:5], v[12:13]
	v_mov_b32_e32 v13, v118
	v_cvt_pk_f16_f32 v4, v4, v5
	v_rcp_f32_e32 v5, v8
	v_alignbit_b32 v8, v4, v10, 16
	v_lshrrev_b32_e32 v10, 16, v6
	v_alignbit_b32 v9, v6, v4, 16
	v_fma_mixhi_f16 v10, v7, v5, 0
	v_cvt_f32_f16_e32 v7, v160
	v_lshrrev_b32_e32 v5, 4, v8
	v_lshrrev_b32_e32 v6, 4, v9
	v_and_b32_e32 v5, 0x10001, v5
	v_and_b32_e32 v6, 0x10001, v6
	v_lshrrev_b32_e32 v4, 4, v18
	v_add3_u32 v5, v8, v5, s21
	v_add3_u32 v6, v9, v6, s21
	v_lshrrev_b32_e32 v8, 4, v10
	v_rcp_f32_e32 v9, v7
	v_and_b32_e32 v4, 0x10001, v4
	v_and_b32_e32 v8, 0x10001, v8
	v_add3_u32 v4, v18, v4, s21
	v_add3_u32 v8, v10, v8, s21
	v_and_b32_e32 v4, 0xfff0fff0, v4
	v_and_b32_e32 v5, 0xfff0fff0, v5
	v_and_b32_e32 v6, 0xfff0fff0, v6
	v_and_b32_e32 v7, 0xfff0fff0, v8
	global_store_dwordx4 v[16:17], v[4:7], off offset:256
	v_mov_b32_e32 v10, v125
	s_nop 0
	v_fma_mixlo_f16 v4, v124, v9, 0
	v_cvt_f32_f16_sdwa v6, v160 dst_sel:DWORD dst_unused:UNUSED_PAD src0_sel:WORD_1
	v_cvt_f32_f16_sdwa v7, v162 dst_sel:DWORD dst_unused:UNUSED_PAD src0_sel:WORD_1
	v_cvt_f32_f16_e32 v9, v161
	v_cvt_f32_f16_e32 v5, v162
	v_rcp_f32_e32 v6, v6
	v_rcp_f32_e32 v8, v7
	v_rcp_f32_e32 v7, v9
	v_cvt_f32_f16_e32 v9, v163
	v_rcp_f32_e32 v5, v5
	v_pk_mul_f32 v[6:7], v[10:11], v[6:7]
	s_nop 0
	v_cvt_pk_f16_f32 v10, v6, v7
	v_pack_b32_f16 v11, v4, v10
	v_cvt_f32_f16_sdwa v4, v161 dst_sel:DWORD dst_unused:UNUSED_PAD src0_sel:WORD_1
	v_rcp_f32_e32 v9, v9
	v_mov_b32_e32 v6, v145
	v_mov_b32_e32 v7, v146
	v_rcp_f32_e32 v4, v4
	v_pk_mul_f32 v[6:7], v[6:7], v[8:9]
	v_cvt_f32_f16_sdwa v9, v163 dst_sel:DWORD dst_unused:UNUSED_PAD src0_sel:WORD_1
	v_cvt_pk_f16_f32 v8, v6, v7
	v_pk_mov_b32 v[6:7], v[126:127], v[144:145] op_sel:[1,0]
	s_nop 0
	v_pk_mul_f32 v[4:5], v[6:7], v[4:5]
	s_nop 0
	v_cvt_pk_f16_f32 v4, v4, v5
	v_rcp_f32_e32 v5, v9
	v_alignbit_b32 v6, v4, v10, 16
	v_alignbit_b32 v7, v8, v4, 16
	v_lshrrev_b32_e32 v8, 16, v8
	v_fma_mixhi_f16 v8, v147, v5, 0
	v_lshrrev_b32_e32 v5, 4, v6
	v_and_b32_e32 v5, 0x10001, v5
	v_add3_u32 v5, v6, v5, s21
	v_lshrrev_b32_e32 v6, 4, v7
	v_and_b32_e32 v6, 0x10001, v6
	v_cvt_f32_f16_e32 v10, v156
	v_add3_u32 v6, v7, v6, s21
	v_lshrrev_b32_e32 v7, 4, v8
	v_lshrrev_b32_e32 v4, 4, v11
	v_and_b32_e32 v7, 0x10001, v7
	v_and_b32_e32 v4, 0x10001, v4
	v_add3_u32 v7, v8, v7, s21
	v_lshl_add_u64 v[8:9], v[80:81], 0, s[10:11]
	s_mov_b32 s10, 0x80000
	v_add3_u32 v4, v11, v4, s21
	v_rcp_f32_e32 v12, v10
	v_add_co_u32_e32 v10, vcc, s10, v80
	v_and_b32_e32 v4, 0xfff0fff0, v4
	v_and_b32_e32 v5, 0xfff0fff0, v5
	v_and_b32_e32 v6, 0xfff0fff0, v6
	v_and_b32_e32 v7, 0xfff0fff0, v7
	v_addc_co_u32_e32 v11, vcc, 0, v81, vcc
	global_store_dwordx4 v[10:11], v[4:7], off
	v_cvt_f32_f16_e32 v11, v157
	s_mov_b64 s[10:11], 0x90000
	v_cvt_f32_f16_sdwa v6, v156 dst_sel:DWORD dst_unused:UNUSED_PAD src0_sel:WORD_1
	v_cvt_f32_f16_sdwa v7, v158 dst_sel:DWORD dst_unused:UNUSED_PAD src0_sel:WORD_1
	v_fma_mixlo_f16 v4, v116, v12, 0
	v_mov_b32_e32 v12, v117
	v_rcp_f32_e32 v6, v6
	v_rcp_f32_e32 v10, v7
	v_rcp_f32_e32 v7, v11
	v_cvt_f32_f16_e32 v11, v159
	v_cvt_f32_f16_e32 v5, v158
	v_pk_mul_f32 v[6:7], v[12:13], v[6:7]
	s_nop 0
	v_cvt_pk_f16_f32 v12, v6, v7
	v_pack_b32_f16 v13, v4, v12
	v_cvt_f32_f16_sdwa v4, v157 dst_sel:DWORD dst_unused:UNUSED_PAD src0_sel:WORD_1
	v_rcp_f32_e32 v11, v11
	v_rcp_f32_e32 v5, v5
	v_mov_b32_e32 v6, v121
	v_mov_b32_e32 v7, v122
	v_rcp_f32_e32 v4, v4
	v_pk_mul_f32 v[6:7], v[6:7], v[10:11]
	v_cvt_f32_f16_sdwa v11, v159 dst_sel:DWORD dst_unused:UNUSED_PAD src0_sel:WORD_1
	v_cvt_pk_f16_f32 v10, v6, v7
	v_pk_mov_b32 v[6:7], v[118:119], v[120:121] op_sel:[1,0]
	s_nop 0
	v_pk_mul_f32 v[4:5], v[6:7], v[4:5]
	s_nop 0
	v_cvt_pk_f16_f32 v4, v4, v5
	v_rcp_f32_e32 v5, v11
	v_alignbit_b32 v6, v4, v12, 16
	v_alignbit_b32 v7, v10, v4, 16
	v_lshrrev_b32_e32 v10, 16, v10
	v_fma_mixhi_f16 v10, v123, v5, 0
	v_lshrrev_b32_e32 v5, 4, v6
	v_and_b32_e32 v5, 0x10001, v5
	v_add3_u32 v5, v6, v5, s21
	v_lshrrev_b32_e32 v6, 4, v7
	v_and_b32_e32 v6, 0x10001, v6
	v_add3_u32 v6, v7, v6, s21
	v_cvt_f32_f16_e32 v7, v152
	v_lshrrev_b32_e32 v4, 4, v13
	v_lshrrev_b32_e32 v11, 4, v10
	v_and_b32_e32 v4, 0x10001, v4
	v_and_b32_e32 v11, 0x10001, v11
	v_add3_u32 v4, v13, v4, s21
	v_rcp_f32_e32 v12, v7
	v_add3_u32 v7, v10, v11, s21
	v_and_b32_e32 v4, 0xfff0fff0, v4
	v_and_b32_e32 v5, 0xfff0fff0, v5
	v_and_b32_e32 v6, 0xfff0fff0, v6
	v_and_b32_e32 v7, 0xfff0fff0, v7
	global_store_dwordx4 v[8:9], v[4:7], off offset:256
	v_cvt_f32_f16_e32 v9, v153
	v_mov_b32_e32 v10, v105
	v_cvt_f32_f16_sdwa v6, v152 dst_sel:DWORD dst_unused:UNUSED_PAD src0_sel:WORD_1
	v_cvt_f32_f16_sdwa v7, v154 dst_sel:DWORD dst_unused:UNUSED_PAD src0_sel:WORD_1
	v_mov_b32_e32 v11, v106
	v_fma_mixlo_f16 v4, v104, v12, 0
	v_rcp_f32_e32 v6, v6
	v_rcp_f32_e32 v8, v7
	v_rcp_f32_e32 v7, v9
	v_cvt_f32_f16_e32 v9, v155
	v_cvt_f32_f16_e32 v5, v154
	v_mov_b32_e32 v13, v98
	v_pk_mul_f32 v[6:7], v[10:11], v[6:7]
	v_rcp_f32_e32 v9, v9
	v_cvt_pk_f16_f32 v10, v6, v7
	v_pack_b32_f16 v11, v4, v10
	v_cvt_f32_f16_sdwa v4, v153 dst_sel:DWORD dst_unused:UNUSED_PAD src0_sel:WORD_1
	v_rcp_f32_e32 v5, v5
	v_mov_b32_e32 v6, v113
	v_mov_b32_e32 v7, v114
	v_rcp_f32_e32 v4, v4
	v_pk_mul_f32 v[6:7], v[6:7], v[8:9]
	v_cvt_f32_f16_sdwa v9, v155 dst_sel:DWORD dst_unused:UNUSED_PAD src0_sel:WORD_1
	v_cvt_pk_f16_f32 v8, v6, v7
	v_pk_mov_b32 v[6:7], v[106:107], v[112:113] op_sel:[1,0]
	s_nop 0
	v_pk_mul_f32 v[4:5], v[6:7], v[4:5]
	s_nop 0
	v_cvt_pk_f16_f32 v4, v4, v5
	v_rcp_f32_e32 v5, v9
	v_alignbit_b32 v6, v4, v10, 16
	v_alignbit_b32 v7, v8, v4, 16
	v_lshrrev_b32_e32 v8, 16, v8
	v_fma_mixhi_f16 v8, v115, v5, 0
	v_lshrrev_b32_e32 v5, 4, v6
	v_and_b32_e32 v5, 0x10001, v5
	v_add3_u32 v5, v6, v5, s21
	v_lshrrev_b32_e32 v6, 4, v7
	v_and_b32_e32 v6, 0x10001, v6
	v_cvt_f32_f16_e32 v10, v148
	v_add3_u32 v6, v7, v6, s21
	v_lshrrev_b32_e32 v7, 4, v8
	v_lshrrev_b32_e32 v4, 4, v11
	v_and_b32_e32 v7, 0x10001, v7
	v_and_b32_e32 v4, 0x10001, v4
	v_add3_u32 v7, v8, v7, s21
	v_lshl_add_u64 v[8:9], v[80:81], 0, s[10:11]
	s_mov_b32 s10, 0x90000
	v_add3_u32 v4, v11, v4, s21
	v_rcp_f32_e32 v12, v10
	v_add_co_u32_e32 v10, vcc, s10, v80
	v_and_b32_e32 v4, 0xfff0fff0, v4
	v_and_b32_e32 v5, 0xfff0fff0, v5
	v_and_b32_e32 v6, 0xfff0fff0, v6
	v_and_b32_e32 v7, 0xfff0fff0, v7
	v_addc_co_u32_e32 v11, vcc, 0, v81, vcc
	global_store_dwordx4 v[10:11], v[4:7], off
	v_cvt_f32_f16_e32 v11, v149
	s_mov_b64 s[10:11], 0xa0000
	v_cvt_f32_f16_sdwa v6, v148 dst_sel:DWORD dst_unused:UNUSED_PAD src0_sel:WORD_1
	v_cvt_f32_f16_sdwa v7, v150 dst_sel:DWORD dst_unused:UNUSED_PAD src0_sel:WORD_1
	v_fma_mixlo_f16 v4, v96, v12, 0
	v_mov_b32_e32 v12, v97
	v_rcp_f32_e32 v6, v6
	v_rcp_f32_e32 v10, v7
	v_rcp_f32_e32 v7, v11
	v_cvt_f32_f16_e32 v11, v151
	v_cvt_f32_f16_e32 v5, v150
	v_pk_mul_f32 v[6:7], v[12:13], v[6:7]
	s_nop 0
	v_cvt_pk_f16_f32 v12, v6, v7
	v_pack_b32_f16 v13, v4, v12
	v_cvt_f32_f16_sdwa v4, v149 dst_sel:DWORD dst_unused:UNUSED_PAD src0_sel:WORD_1
	v_rcp_f32_e32 v11, v11
	v_rcp_f32_e32 v5, v5
	v_mov_b32_e32 v6, v101
	v_mov_b32_e32 v7, v102
	v_rcp_f32_e32 v4, v4
	v_pk_mul_f32 v[6:7], v[6:7], v[10:11]
	v_cvt_f32_f16_sdwa v11, v151 dst_sel:DWORD dst_unused:UNUSED_PAD src0_sel:WORD_1
	v_cvt_pk_f16_f32 v10, v6, v7
	v_pk_mov_b32 v[6:7], v[98:99], v[100:101] op_sel:[1,0]
	s_nop 0
	v_pk_mul_f32 v[4:5], v[6:7], v[4:5]
	s_nop 0
	v_cvt_pk_f16_f32 v4, v4, v5
	v_rcp_f32_e32 v5, v11
	v_alignbit_b32 v6, v4, v12, 16
	v_alignbit_b32 v7, v10, v4, 16
	v_lshrrev_b32_e32 v10, 16, v10
	v_fma_mixhi_f16 v10, v103, v5, 0
	v_lshrrev_b32_e32 v5, 4, v6
	v_and_b32_e32 v5, 0x10001, v5
	v_add3_u32 v5, v6, v5, s21
	v_lshrrev_b32_e32 v6, 4, v7
	v_and_b32_e32 v6, 0x10001, v6
	v_add3_u32 v6, v7, v6, s21
	v_cvt_f32_f16_e32 v7, v140
	v_lshrrev_b32_e32 v4, 4, v13
	v_lshrrev_b32_e32 v11, 4, v10
	v_and_b32_e32 v4, 0x10001, v4
	v_and_b32_e32 v11, 0x10001, v11
	v_add3_u32 v4, v13, v4, s21
	v_rcp_f32_e32 v12, v7
	v_add3_u32 v7, v10, v11, s21
	v_and_b32_e32 v4, 0xfff0fff0, v4
	v_and_b32_e32 v5, 0xfff0fff0, v5
	v_and_b32_e32 v6, 0xfff0fff0, v6
	v_and_b32_e32 v7, 0xfff0fff0, v7
	global_store_dwordx4 v[8:9], v[4:7], off offset:256
	v_cvt_f32_f16_e32 v9, v141
	v_mov_b32_e32 v10, v85
	v_cvt_f32_f16_sdwa v6, v140 dst_sel:DWORD dst_unused:UNUSED_PAD src0_sel:WORD_1
	v_cvt_f32_f16_sdwa v7, v142 dst_sel:DWORD dst_unused:UNUSED_PAD src0_sel:WORD_1
	v_mov_b32_e32 v11, v86
	v_fma_mixlo_f16 v4, v84, v12, 0
	v_rcp_f32_e32 v6, v6
	v_rcp_f32_e32 v8, v7
	v_rcp_f32_e32 v7, v9
	v_cvt_f32_f16_e32 v9, v143
	v_cvt_f32_f16_e32 v5, v142
	v_mov_b32_e32 v13, v66
	v_pk_mul_f32 v[6:7], v[10:11], v[6:7]
	v_rcp_f32_e32 v9, v9
	v_cvt_pk_f16_f32 v10, v6, v7
	v_pack_b32_f16 v11, v4, v10
	v_cvt_f32_f16_sdwa v4, v141 dst_sel:DWORD dst_unused:UNUSED_PAD src0_sel:WORD_1
	v_rcp_f32_e32 v5, v5
	v_mov_b32_e32 v6, v93
	v_mov_b32_e32 v7, v94
	v_rcp_f32_e32 v4, v4
	v_pk_mul_f32 v[6:7], v[6:7], v[8:9]
	v_cvt_f32_f16_sdwa v9, v143 dst_sel:DWORD dst_unused:UNUSED_PAD src0_sel:WORD_1
	v_cvt_pk_f16_f32 v8, v6, v7
	v_pk_mov_b32 v[6:7], v[86:87], v[92:93] op_sel:[1,0]
	s_nop 0
	v_pk_mul_f32 v[4:5], v[6:7], v[4:5]
	s_nop 0
	v_cvt_pk_f16_f32 v4, v4, v5
	v_rcp_f32_e32 v5, v9
	v_alignbit_b32 v6, v4, v10, 16
	v_alignbit_b32 v7, v8, v4, 16
	v_lshrrev_b32_e32 v8, 16, v8
	v_fma_mixhi_f16 v8, v95, v5, 0
	v_lshrrev_b32_e32 v5, 4, v6
	v_and_b32_e32 v5, 0x10001, v5
	v_add3_u32 v5, v6, v5, s21
	v_lshrrev_b32_e32 v6, 4, v7
	v_and_b32_e32 v6, 0x10001, v6
	v_cvt_f32_f16_e32 v10, v136
	v_add3_u32 v6, v7, v6, s21
	v_lshrrev_b32_e32 v7, 4, v8
	v_lshrrev_b32_e32 v4, 4, v11
	v_and_b32_e32 v7, 0x10001, v7
	v_and_b32_e32 v4, 0x10001, v4
	v_add3_u32 v7, v8, v7, s21
	v_lshl_add_u64 v[8:9], v[80:81], 0, s[10:11]
	s_mov_b32 s10, 0xa0000
	v_add3_u32 v4, v11, v4, s21
	v_rcp_f32_e32 v12, v10
	v_add_co_u32_e32 v10, vcc, s10, v80
	v_and_b32_e32 v4, 0xfff0fff0, v4
	v_and_b32_e32 v5, 0xfff0fff0, v5
	v_and_b32_e32 v6, 0xfff0fff0, v6
	v_and_b32_e32 v7, 0xfff0fff0, v7
	v_addc_co_u32_e32 v11, vcc, 0, v81, vcc
	global_store_dwordx4 v[10:11], v[4:7], off
	v_cvt_f32_f16_e32 v11, v137
	s_mov_b64 s[10:11], 0xb0000
	v_cvt_f32_f16_sdwa v6, v136 dst_sel:DWORD dst_unused:UNUSED_PAD src0_sel:WORD_1
	v_cvt_f32_f16_sdwa v7, v138 dst_sel:DWORD dst_unused:UNUSED_PAD src0_sel:WORD_1
	v_fma_mixlo_f16 v4, v64, v12, 0
	v_mov_b32_e32 v12, v65
	v_rcp_f32_e32 v6, v6
	v_rcp_f32_e32 v10, v7
	v_rcp_f32_e32 v7, v11
	v_cvt_f32_f16_e32 v11, v139
	v_cvt_f32_f16_e32 v5, v138
	v_pk_mul_f32 v[6:7], v[12:13], v[6:7]
	s_nop 0
	v_cvt_pk_f16_f32 v12, v6, v7
	v_pack_b32_f16 v13, v4, v12
	v_cvt_f32_f16_sdwa v4, v137 dst_sel:DWORD dst_unused:UNUSED_PAD src0_sel:WORD_1
	v_rcp_f32_e32 v11, v11
	v_rcp_f32_e32 v5, v5
	v_mov_b32_e32 v6, v77
	v_mov_b32_e32 v7, v78
	v_rcp_f32_e32 v4, v4
	v_pk_mul_f32 v[6:7], v[6:7], v[10:11]
	v_cvt_f32_f16_sdwa v11, v139 dst_sel:DWORD dst_unused:UNUSED_PAD src0_sel:WORD_1
	v_cvt_pk_f16_f32 v10, v6, v7
	v_pk_mov_b32 v[6:7], v[66:67], v[76:77] op_sel:[1,0]
	s_nop 0
	v_pk_mul_f32 v[4:5], v[6:7], v[4:5]
	s_nop 0
	v_cvt_pk_f16_f32 v4, v4, v5
	v_rcp_f32_e32 v5, v11
	v_alignbit_b32 v6, v4, v12, 16
	v_alignbit_b32 v7, v10, v4, 16
	v_lshrrev_b32_e32 v10, 16, v10
	v_fma_mixhi_f16 v10, v79, v5, 0
	v_lshrrev_b32_e32 v5, 4, v6
	v_and_b32_e32 v5, 0x10001, v5
	v_add3_u32 v5, v6, v5, s21
	v_lshrrev_b32_e32 v6, 4, v7
	v_and_b32_e32 v6, 0x10001, v6
	v_add3_u32 v6, v7, v6, s21
	v_cvt_f32_f16_e32 v7, v132
	v_lshrrev_b32_e32 v4, 4, v13
	v_lshrrev_b32_e32 v11, 4, v10
	v_and_b32_e32 v4, 0x10001, v4
	v_and_b32_e32 v11, 0x10001, v11
	v_add3_u32 v4, v13, v4, s21
	v_rcp_f32_e32 v12, v7
	v_add3_u32 v7, v10, v11, s21
	v_and_b32_e32 v4, 0xfff0fff0, v4
	v_and_b32_e32 v5, 0xfff0fff0, v5
	v_and_b32_e32 v6, 0xfff0fff0, v6
	v_and_b32_e32 v7, 0xfff0fff0, v7
	global_store_dwordx4 v[8:9], v[4:7], off offset:256
	v_cvt_f32_f16_e32 v9, v133
	v_mov_b32_e32 v10, v49
	v_cvt_f32_f16_sdwa v6, v132 dst_sel:DWORD dst_unused:UNUSED_PAD src0_sel:WORD_1
	v_cvt_f32_f16_sdwa v7, v134 dst_sel:DWORD dst_unused:UNUSED_PAD src0_sel:WORD_1
	v_mov_b32_e32 v11, v50
	v_fma_mixlo_f16 v4, v48, v12, 0
	v_rcp_f32_e32 v6, v6
	v_rcp_f32_e32 v8, v7
	v_rcp_f32_e32 v7, v9
	v_cvt_f32_f16_e32 v9, v135
	v_cvt_f32_f16_e32 v5, v134
	v_mov_b32_e32 v13, v34
	v_pk_mul_f32 v[6:7], v[10:11], v[6:7]
	v_rcp_f32_e32 v9, v9
	v_cvt_pk_f16_f32 v10, v6, v7
	v_pack_b32_f16 v11, v4, v10
	v_cvt_f32_f16_sdwa v4, v133 dst_sel:DWORD dst_unused:UNUSED_PAD src0_sel:WORD_1
	v_rcp_f32_e32 v5, v5
	v_mov_b32_e32 v6, v61
	v_mov_b32_e32 v7, v62
	v_rcp_f32_e32 v4, v4
	v_pk_mul_f32 v[6:7], v[6:7], v[8:9]
	v_cvt_f32_f16_sdwa v9, v135 dst_sel:DWORD dst_unused:UNUSED_PAD src0_sel:WORD_1
	v_cvt_pk_f16_f32 v8, v6, v7
	v_pk_mov_b32 v[6:7], v[50:51], v[60:61] op_sel:[1,0]
	s_nop 0
	v_pk_mul_f32 v[4:5], v[6:7], v[4:5]
	s_nop 0
	v_cvt_pk_f16_f32 v4, v4, v5
	v_rcp_f32_e32 v5, v9
	v_alignbit_b32 v6, v4, v10, 16
	v_alignbit_b32 v7, v8, v4, 16
	v_lshrrev_b32_e32 v8, 16, v8
	v_fma_mixhi_f16 v8, v63, v5, 0
	v_lshrrev_b32_e32 v5, 4, v6
	v_and_b32_e32 v5, 0x10001, v5
	v_add3_u32 v5, v6, v5, s21
	v_lshrrev_b32_e32 v6, 4, v7
	v_and_b32_e32 v6, 0x10001, v6
	v_cvt_f32_f16_e32 v10, v128
	v_add3_u32 v6, v7, v6, s21
	v_lshrrev_b32_e32 v7, 4, v8
	v_lshrrev_b32_e32 v4, 4, v11
	v_and_b32_e32 v7, 0x10001, v7
	v_and_b32_e32 v4, 0x10001, v4
	v_add3_u32 v7, v8, v7, s21
	v_lshl_add_u64 v[8:9], v[80:81], 0, s[10:11]
	s_mov_b32 s10, 0xb0000
	v_add3_u32 v4, v11, v4, s21
	v_rcp_f32_e32 v12, v10
	v_add_co_u32_e32 v10, vcc, s10, v80
	v_and_b32_e32 v4, 0xfff0fff0, v4
	v_and_b32_e32 v5, 0xfff0fff0, v5
	v_and_b32_e32 v6, 0xfff0fff0, v6
	v_and_b32_e32 v7, 0xfff0fff0, v7
	v_addc_co_u32_e32 v11, vcc, 0, v81, vcc
	global_store_dwordx4 v[10:11], v[4:7], off
	v_cvt_f32_f16_e32 v11, v129
	s_andn2_b64 vcc, exec, s[40:41]
	v_cvt_f32_f16_sdwa v6, v128 dst_sel:DWORD dst_unused:UNUSED_PAD src0_sel:WORD_1
	v_cvt_f32_f16_sdwa v7, v130 dst_sel:DWORD dst_unused:UNUSED_PAD src0_sel:WORD_1
	v_fma_mixlo_f16 v4, v32, v12, 0
	v_mov_b32_e32 v12, v33
	v_rcp_f32_e32 v6, v6
	v_rcp_f32_e32 v10, v7
	v_rcp_f32_e32 v7, v11
	v_cvt_f32_f16_e32 v11, v131
	v_cvt_f32_f16_e32 v5, v130
	v_pk_mul_f32 v[6:7], v[12:13], v[6:7]
	s_nop 0
	v_cvt_pk_f16_f32 v12, v6, v7
	v_pack_b32_f16 v13, v4, v12
	v_cvt_f32_f16_sdwa v4, v129 dst_sel:DWORD dst_unused:UNUSED_PAD src0_sel:WORD_1
	v_rcp_f32_e32 v11, v11
	v_rcp_f32_e32 v5, v5
	v_mov_b32_e32 v6, v45
	v_mov_b32_e32 v7, v46
	v_rcp_f32_e32 v4, v4
	v_pk_mul_f32 v[6:7], v[6:7], v[10:11]
	v_cvt_f32_f16_sdwa v11, v131 dst_sel:DWORD dst_unused:UNUSED_PAD src0_sel:WORD_1
	v_cvt_pk_f16_f32 v10, v6, v7
	v_pk_mov_b32 v[6:7], v[34:35], v[44:45] op_sel:[1,0]
	s_nop 0
	v_pk_mul_f32 v[4:5], v[6:7], v[4:5]
	s_nop 0
	v_cvt_pk_f16_f32 v4, v4, v5
	v_rcp_f32_e32 v5, v11
	v_alignbit_b32 v6, v4, v12, 16
	v_alignbit_b32 v7, v10, v4, 16
	v_lshrrev_b32_e32 v10, 16, v10
	v_fma_mixhi_f16 v10, v47, v5, 0
	v_lshrrev_b32_e32 v5, 4, v6
	v_and_b32_e32 v5, 0x10001, v5
	v_add3_u32 v5, v6, v5, s21
	v_lshrrev_b32_e32 v6, 4, v7
	v_and_b32_e32 v6, 0x10001, v6
	v_lshrrev_b32_e32 v4, 4, v13
	v_add3_u32 v6, v7, v6, s21
	v_lshrrev_b32_e32 v7, 4, v10
	v_and_b32_e32 v4, 0x10001, v4
	v_and_b32_e32 v7, 0x10001, v7
	v_add3_u32 v4, v13, v4, s21
	v_add3_u32 v7, v10, v7, s21
	v_and_b32_e32 v4, 0xfff0fff0, v4
	v_and_b32_e32 v5, 0xfff0fff0, v5
	v_and_b32_e32 v6, 0xfff0fff0, v6
	v_and_b32_e32 v7, 0xfff0fff0, v7
	global_store_dwordx4 v[8:9], v[4:7], off offset:256
	s_cbranch_vccnz .LBB0_1739
	s_waitcnt vmcnt(0)
	v_readlane_b32 s4, v251, 63
	s_cmpk_gt_u32 s4, 0xff
	s_cbranch_scc1 .LBB0_1750
	s_barrier

.LBB0_2120:
	s_add_u32 s27, s42, 0xfff80080
	s_addc_u32 s38, s43, -1
	s_add_i32 s46, 0, 0x10000
	v_add_u32_e32 v128, s46, v198
	ds_read_b128 v[108:111], v128
	ds_read_b128 v[112:115], v128 offset:1024
	ds_read_b128 v[120:123], v128 offset:2048
	ds_read_b128 v[128:131], v128 offset:3072
	s_cmp_eq_u32 s17, 28
	s_cselect_b32 s45, s35, s38
	s_cselect_b32 s44, s34, s27
	s_cselect_b32 s39, s37, s15
	s_cselect_b32 s38, s36, s14
	s_add_i32 m0, s6, 0xc000
	ds_read_b128 v[148:151], v199
	ds_read_b128 v[152:155], v199 offset:1024
	ds_read_b128 v[156:159], v199 offset:2048
	ds_read_b128 v[160:163], v199 offset:3072
	ds_read_b128 v[164:167], v199 offset:4096
	ds_read_b128 v[168:171], v199 offset:5120
	ds_read_b128 v[172:175], v199 offset:6144
	ds_read_b128 v[176:179], v199 offset:7168
	global_load_lds_dwordx4 v182, s[42:43]
	s_add_i32 m0, s6, 0xe000
	s_nop 0
	global_load_lds_dwordx4 v184, s[42:43]
	s_waitcnt vmcnt(10)
	s_barrier
	s_waitcnt lgkmcnt(0)
	v_mfma_f32_16x16x32_f16 v[144:147], v[108:111], v[148:151], v[144:147]
	v_mfma_f32_16x16x32_f16 v[140:143], v[120:123], v[148:151], v[140:143]
	v_mfma_f32_16x16x32_f16 v[124:127], v[108:111], v[156:159], v[124:127]
	v_mfma_f32_16x16x32_f16 v[116:119], v[120:123], v[156:159], v[116:119]
	v_mfma_f32_16x16x32_f16 v[96:99], v[108:111], v[164:167], v[96:99]
	v_mfma_f32_16x16x32_f16 v[92:95], v[120:123], v[164:167], v[92:95]
	v_mfma_f32_16x16x32_f16 v[88:91], v[108:111], v[172:175], v[88:91]
	v_mfma_f32_16x16x32_f16 v[80:83], v[120:123], v[172:175], v[80:83]
	v_mfma_f32_16x16x32_f16 v[144:147], v[112:115], v[152:155], v[144:147]
	v_mfma_f32_16x16x32_f16 v[140:143], v[128:131], v[152:155], v[140:143]
	v_mfma_f32_16x16x32_f16 v[124:127], v[112:115], v[160:163], v[124:127]
	v_mfma_f32_16x16x32_f16 v[116:119], v[128:131], v[160:163], v[116:119]
	v_mfma_f32_16x16x32_f16 v[96:99], v[112:115], v[168:171], v[96:99]
	v_mfma_f32_16x16x32_f16 v[92:95], v[128:131], v[168:171], v[92:95]
	v_mfma_f32_16x16x32_f16 v[88:91], v[112:115], v[176:179], v[88:91]
	v_mfma_f32_16x16x32_f16 v[80:83], v[128:131], v[176:179], v[80:83]
	s_barrier
	s_add_i32 s27, 0, 0x14000
	v_add_u32_e32 v194, s27, v198
	s_add_i32 s46, s46, s5
	ds_read_b128 v[186:189], v194
	ds_read_b128 v[190:193], v194 offset:1024
	ds_read_b128 v[200:203], v194 offset:2048
	ds_read_b128 v[206:209], v194 offset:3072
	v_lshl_add_u64 v[194:195], s[38:39], 0, v[2:3]
	s_mov_b32 m0, s46
	v_lshl_add_u64 v[210:211], s[38:39], 0, v[180:181]
	global_load_lds_dwordx4 v[194:195], off
	s_add_i32 m0, s46, 0x2000
	s_nop 0
	global_load_lds_dwordx4 v[210:211], off
	s_waitcnt vmcnt(10)
	s_barrier
	s_waitcnt lgkmcnt(0)
	v_mfma_f32_16x16x32_f16 v[136:139], v[186:189], v[148:151], v[136:139]
	v_mfma_f32_16x16x32_f16 v[132:135], v[200:203], v[148:151], v[132:135]
	v_mfma_f32_16x16x32_f16 v[104:107], v[186:189], v[156:159], v[104:107]
	v_mfma_f32_16x16x32_f16 v[100:103], v[200:203], v[156:159], v[100:103]
	v_mfma_f32_16x16x32_f16 v[84:87], v[186:189], v[164:167], v[84:87]
	v_mfma_f32_16x16x32_f16 v[76:79], v[200:203], v[164:167], v[76:79]
	v_mfma_f32_16x16x32_f16 v[72:75], v[186:189], v[172:175], v[72:75]
	v_mfma_f32_16x16x32_f16 v[68:71], v[200:203], v[172:175], v[68:71]
	v_mfma_f32_16x16x32_f16 v[136:139], v[190:193], v[152:155], v[136:139]
	v_mfma_f32_16x16x32_f16 v[132:135], v[206:209], v[152:155], v[132:135]
	v_mfma_f32_16x16x32_f16 v[104:107], v[190:193], v[160:163], v[104:107]
	v_mfma_f32_16x16x32_f16 v[100:103], v[206:209], v[160:163], v[100:103]
	v_mfma_f32_16x16x32_f16 v[84:87], v[190:193], v[168:171], v[84:87]
	v_mfma_f32_16x16x32_f16 v[76:79], v[206:209], v[168:171], v[76:79]
	v_mfma_f32_16x16x32_f16 v[72:75], v[190:193], v[176:179], v[72:75]
	v_mfma_f32_16x16x32_f16 v[68:71], v[206:209], v[176:179], v[68:71]
	s_mov_b32 m0, s6
	v_lshl_add_u64 v[212:213], s[44:45], 0, v[2:3]
	s_barrier
	ds_read_b128 v[148:151], v199 offset:16384
	ds_read_b128 v[152:155], v199 offset:17408
	ds_read_b128 v[156:159], v199 offset:18432
	ds_read_b128 v[160:163], v199 offset:19456
	ds_read_b128 v[164:167], v199 offset:20480
	ds_read_b128 v[168:171], v199 offset:21504
	ds_read_b128 v[172:175], v199 offset:22528
	ds_read_b128 v[176:179], v199 offset:23552
	global_load_lds_dwordx4 v[212:213], off
	v_lshl_add_u64 v[214:215], s[44:45], 0, v[180:181]
	s_mov_b32 m0, s7
	s_nop 0
	global_load_lds_dwordx4 v[214:215], off
	s_waitcnt vmcnt(10)
	s_barrier
	s_waitcnt lgkmcnt(0)
	v_mfma_f32_16x16x32_f16 v[64:67], v[108:111], v[148:151], v[64:67]
	v_mfma_f32_16x16x32_f16 v[60:63], v[120:123], v[148:151], v[60:63]
	v_mfma_f32_16x16x32_f16 v[48:51], v[108:111], v[156:159], v[48:51]
	v_mfma_f32_16x16x32_f16 v[44:47], v[120:123], v[156:159], v[44:47]
	v_mfma_f32_16x16x32_f16 v[32:35], v[108:111], v[164:167], v[32:35]
	v_mfma_f32_16x16x32_f16 v[28:31], v[120:123], v[164:167], v[28:31]
	v_mfma_f32_16x16x32_f16 v[20:23], v[108:111], v[172:175], v[20:23]
	v_mfma_f32_16x16x32_f16 v[12:15], v[120:123], v[172:175], v[12:15]
	v_mfma_f32_16x16x32_f16 v[64:67], v[112:115], v[152:155], v[64:67]
	v_mfma_f32_16x16x32_f16 v[60:63], v[128:131], v[152:155], v[60:63]
	v_mfma_f32_16x16x32_f16 v[48:51], v[112:115], v[160:163], v[48:51]
	v_mfma_f32_16x16x32_f16 v[44:47], v[128:131], v[160:163], v[44:47]
	v_mfma_f32_16x16x32_f16 v[32:35], v[112:115], v[168:171], v[32:35]
	v_mfma_f32_16x16x32_f16 v[28:31], v[128:131], v[168:171], v[28:31]
	v_mfma_f32_16x16x32_f16 v[20:23], v[112:115], v[176:179], v[20:23]
	v_mfma_f32_16x16x32_f16 v[12:15], v[128:131], v[176:179], v[12:15]
	s_barrier
	s_add_u32 s46, s38, 0x80000
	s_addc_u32 s47, s39, 0
	s_add_i32 s27, s27, s5
	v_lshl_add_u64 v[108:109], s[46:47], 0, v[2:3]
	s_mov_b32 m0, s27
	s_nop 0
	global_load_lds_dwordx4 v[108:109], off
	s_add_i32 m0, s27, 0x2000
	s_nop 0
	global_load_lds_dwordx4 v180, s[46:47]
	s_waitcnt vmcnt(10)
	s_barrier
	v_mfma_f32_16x16x32_f16 v[56:59], v[186:189], v[148:151], v[56:59]
	v_mfma_f32_16x16x32_f16 v[52:55], v[200:203], v[148:151], v[52:55]
	v_mfma_f32_16x16x32_f16 v[40:43], v[186:189], v[156:159], v[40:43]
	v_mfma_f32_16x16x32_f16 v[36:39], v[200:203], v[156:159], v[36:39]
	v_mfma_f32_16x16x32_f16 v[24:27], v[186:189], v[164:167], v[24:27]
	v_mfma_f32_16x16x32_f16 v[16:19], v[200:203], v[164:167], v[16:19]
	v_mfma_f32_16x16x32_f16 v[8:11], v[186:189], v[172:175], v[8:11]
	v_mfma_f32_16x16x32_f16 v[4:7], v[200:203], v[172:175], v[4:7]
	v_mfma_f32_16x16x32_f16 v[56:59], v[190:193], v[152:155], v[56:59]
	v_mfma_f32_16x16x32_f16 v[52:55], v[206:209], v[152:155], v[52:55]
	v_mfma_f32_16x16x32_f16 v[40:43], v[190:193], v[160:163], v[40:43]
	v_mfma_f32_16x16x32_f16 v[36:39], v[206:209], v[160:163], v[36:39]
	v_mfma_f32_16x16x32_f16 v[24:27], v[190:193], v[168:171], v[24:27]
	v_mfma_f32_16x16x32_f16 v[16:19], v[206:209], v[168:171], v[16:19]
	v_mfma_f32_16x16x32_f16 v[8:11], v[190:193], v[176:179], v[8:11]
	v_mfma_f32_16x16x32_f16 v[4:7], v[206:209], v[176:179], v[4:7]
	s_add_i32 s27, 0, 0x18000
	v_add_u32_e32 v128, s27, v198
	s_barrier
	ds_read_b128 v[108:111], v128
	ds_read_b128 v[112:115], v128 offset:1024
	ds_read_b128 v[120:123], v128 offset:2048
	ds_read_b128 v[128:131], v128 offset:3072
	s_add_u32 s44, s44, 0x80000
	s_addc_u32 s45, s45, 0
	s_mov_b32 m0, s8
	v_lshl_add_u64 v[186:187], s[44:45], 0, v[2:3]
	ds_read_b128 v[148:151], v199 offset:32768
	ds_read_b128 v[152:155], v199 offset:33792
	ds_read_b128 v[156:159], v199 offset:34816
	ds_read_b128 v[160:163], v199 offset:35840
	ds_read_b128 v[164:167], v199 offset:36864
	ds_read_b128 v[168:171], v199 offset:37888
	ds_read_b128 v[172:175], v199 offset:38912
	ds_read_b128 v[176:179], v199 offset:39936
	global_load_lds_dwordx4 v[186:187], off
	s_mov_b32 m0, s9
	s_nop 0
	global_load_lds_dwordx4 v180, s[44:45]
	s_waitcnt vmcnt(10)
	s_barrier
	s_waitcnt lgkmcnt(0)
	v_mfma_f32_16x16x32_f16 v[144:147], v[108:111], v[148:151], v[144:147]
	v_mfma_f32_16x16x32_f16 v[140:143], v[120:123], v[148:151], v[140:143]
	v_mfma_f32_16x16x32_f16 v[124:127], v[108:111], v[156:159], v[124:127]
	v_mfma_f32_16x16x32_f16 v[116:119], v[120:123], v[156:159], v[116:119]
	v_mfma_f32_16x16x32_f16 v[96:99], v[108:111], v[164:167], v[96:99]
	v_mfma_f32_16x16x32_f16 v[92:95], v[120:123], v[164:167], v[92:95]
	v_mfma_f32_16x16x32_f16 v[88:91], v[108:111], v[172:175], v[88:91]
	v_mfma_f32_16x16x32_f16 v[80:83], v[120:123], v[172:175], v[80:83]
	v_mfma_f32_16x16x32_f16 v[144:147], v[112:115], v[152:155], v[144:147]
	v_mfma_f32_16x16x32_f16 v[140:143], v[128:131], v[152:155], v[140:143]
	v_mfma_f32_16x16x32_f16 v[124:127], v[112:115], v[160:163], v[124:127]
	v_mfma_f32_16x16x32_f16 v[116:119], v[128:131], v[160:163], v[116:119]
	v_mfma_f32_16x16x32_f16 v[96:99], v[112:115], v[168:171], v[96:99]
	v_mfma_f32_16x16x32_f16 v[92:95], v[128:131], v[168:171], v[92:95]
	v_mfma_f32_16x16x32_f16 v[88:91], v[112:115], v[176:179], v[88:91]
	v_mfma_f32_16x16x32_f16 v[80:83], v[128:131], v[176:179], v[80:83]
	s_barrier
	s_add_i32 s44, 0, 0x1c000
	s_add_i32 s27, s27, s5
	v_add_u32_e32 v206, s44, v198
	v_lshl_add_u64 v[194:195], v[194:195], 0, s[88:89]
	s_mov_b32 m0, s27
	ds_read_b128 v[186:189], v206
	ds_read_b128 v[190:193], v206 offset:1024
	ds_read_b128 v[200:203], v206 offset:2048
	ds_read_b128 v[206:209], v206 offset:3072
	global_load_lds_dwordx4 v[194:195], off
	v_lshl_add_u64 v[194:195], v[210:211], 0, s[88:89]
	s_add_i32 m0, s27, 0x2000
	s_nop 0
	global_load_lds_dwordx4 v[194:195], off
	s_waitcnt vmcnt(10)
	s_barrier
	s_waitcnt lgkmcnt(0)
	v_mfma_f32_16x16x32_f16 v[136:139], v[186:189], v[148:151], v[136:139]
	v_mfma_f32_16x16x32_f16 v[132:135], v[200:203], v[148:151], v[132:135]
	v_mfma_f32_16x16x32_f16 v[104:107], v[186:189], v[156:159], v[104:107]
	v_mfma_f32_16x16x32_f16 v[100:103], v[200:203], v[156:159], v[100:103]
	v_mfma_f32_16x16x32_f16 v[84:87], v[186:189], v[164:167], v[84:87]
	v_mfma_f32_16x16x32_f16 v[76:79], v[200:203], v[164:167], v[76:79]
	v_mfma_f32_16x16x32_f16 v[72:75], v[186:189], v[172:175], v[72:75]
	v_mfma_f32_16x16x32_f16 v[68:71], v[200:203], v[172:175], v[68:71]
	v_mfma_f32_16x16x32_f16 v[136:139], v[190:193], v[152:155], v[136:139]
	v_mfma_f32_16x16x32_f16 v[132:135], v[206:209], v[152:155], v[132:135]
	v_mfma_f32_16x16x32_f16 v[104:107], v[190:193], v[160:163], v[104:107]
	v_mfma_f32_16x16x32_f16 v[100:103], v[206:209], v[160:163], v[100:103]
	v_mfma_f32_16x16x32_f16 v[84:87], v[190:193], v[168:171], v[84:87]
	v_mfma_f32_16x16x32_f16 v[76:79], v[206:209], v[168:171], v[76:79]
	v_mfma_f32_16x16x32_f16 v[72:75], v[190:193], v[176:179], v[72:75]
	v_mfma_f32_16x16x32_f16 v[68:71], v[206:209], v[176:179], v[68:71]
	s_mov_b32 m0, s10
	v_lshl_add_u64 v[194:195], v[212:213], 0, s[88:89]
	s_barrier
	ds_read_b128 v[148:151], v199 offset:49152
	ds_read_b128 v[152:155], v199 offset:50176
	ds_read_b128 v[156:159], v199 offset:51200
	ds_read_b128 v[160:163], v199 offset:52224
	ds_read_b128 v[164:167], v199 offset:53248
	ds_read_b128 v[168:171], v199 offset:54272
	ds_read_b128 v[172:175], v199 offset:55296
	ds_read_b128 v[176:179], v199 offset:56320
	global_load_lds_dwordx4 v[194:195], off
	v_lshl_add_u64 v[194:195], v[214:215], 0, s[88:89]
	s_mov_b32 m0, s11
	s_nop 0
	global_load_lds_dwordx4 v[194:195], off
	s_waitcnt vmcnt(10)
	s_barrier
	s_waitcnt lgkmcnt(0)
	v_mfma_f32_16x16x32_f16 v[64:67], v[108:111], v[148:151], v[64:67]
	v_mfma_f32_16x16x32_f16 v[60:63], v[120:123], v[148:151], v[60:63]
	v_mfma_f32_16x16x32_f16 v[48:51], v[108:111], v[156:159], v[48:51]
	v_mfma_f32_16x16x32_f16 v[44:47], v[120:123], v[156:159], v[44:47]
	v_mfma_f32_16x16x32_f16 v[32:35], v[108:111], v[164:167], v[32:35]
	v_mfma_f32_16x16x32_f16 v[28:31], v[120:123], v[164:167], v[28:31]
	v_mfma_f32_16x16x32_f16 v[20:23], v[108:111], v[172:175], v[20:23]
	v_mfma_f32_16x16x32_f16 v[12:15], v[120:123], v[172:175], v[12:15]
	v_mfma_f32_16x16x32_f16 v[64:67], v[112:115], v[152:155], v[64:67]
	v_mfma_f32_16x16x32_f16 v[60:63], v[128:131], v[152:155], v[60:63]
	v_mfma_f32_16x16x32_f16 v[48:51], v[112:115], v[160:163], v[48:51]
	v_mfma_f32_16x16x32_f16 v[44:47], v[128:131], v[160:163], v[44:47]
	v_mfma_f32_16x16x32_f16 v[32:35], v[112:115], v[168:171], v[32:35]
	v_mfma_f32_16x16x32_f16 v[28:31], v[128:131], v[168:171], v[28:31]
	v_mfma_f32_16x16x32_f16 v[20:23], v[112:115], v[176:179], v[20:23]
	v_mfma_f32_16x16x32_f16 v[12:15], v[128:131], v[176:179], v[12:15]
	s_barrier
	s_add_u32 s38, s38, 0x80080
	s_addc_u32 s39, s39, 0
	s_add_i32 s27, s44, s5
	v_lshl_add_u64 v[108:109], s[38:39], 0, v[2:3]
	s_mov_b32 m0, s27
	s_nop 0
	global_load_lds_dwordx4 v[108:109], off
	s_add_i32 m0, s27, 0x2000
	s_nop 0
	global_load_lds_dwordx4 v180, s[38:39]
	s_waitcnt vmcnt(10)
	s_barrier
	v_mfma_f32_16x16x32_f16 v[56:59], v[186:189], v[148:151], v[56:59]
	v_mfma_f32_16x16x32_f16 v[52:55], v[200:203], v[148:151], v[52:55]
	v_mfma_f32_16x16x32_f16 v[40:43], v[186:189], v[156:159], v[40:43]
	v_mfma_f32_16x16x32_f16 v[36:39], v[200:203], v[156:159], v[36:39]
	v_mfma_f32_16x16x32_f16 v[24:27], v[186:189], v[164:167], v[24:27]
	v_mfma_f32_16x16x32_f16 v[16:19], v[200:203], v[164:167], v[16:19]
	v_mfma_f32_16x16x32_f16 v[8:11], v[186:189], v[172:175], v[8:11]
	v_mfma_f32_16x16x32_f16 v[4:7], v[200:203], v[172:175], v[4:7]
	v_mfma_f32_16x16x32_f16 v[56:59], v[190:193], v[152:155], v[56:59]
	v_mfma_f32_16x16x32_f16 v[52:55], v[206:209], v[152:155], v[52:55]
	v_mfma_f32_16x16x32_f16 v[40:43], v[190:193], v[160:163], v[40:43]
	v_mfma_f32_16x16x32_f16 v[36:39], v[206:209], v[160:163], v[36:39]
	v_mfma_f32_16x16x32_f16 v[24:27], v[190:193], v[168:171], v[24:27]
	v_mfma_f32_16x16x32_f16 v[16:19], v[206:209], v[168:171], v[16:19]
	v_mfma_f32_16x16x32_f16 v[8:11], v[190:193], v[176:179], v[8:11]
	v_mfma_f32_16x16x32_f16 v[4:7], v[206:209], v[176:179], v[4:7]
	s_add_i32 s17, s17, 2
	s_add_u32 s42, s42, 0x100
	s_addc_u32 s43, s43, 0
	s_add_u32 s14, s14, 0x100
	s_addc_u32 s15, s15, 0
	s_cmp_gt_u32 s17, 29
	s_barrier
	s_cbranch_scc0 .LBB0_2120
	s_lshl_b32 s14, s30, 8
	v_mov_b32_e32 v148, v196
	v_mov_b32_e32 v108, v197
	s_add_i32 s17, s14, s12
	s_lshl_b32 s14, s31, 8
	s_or_b32 s14, s14, s13
	v_lshl_add_u32 v108, v108, 2, s14
	s_cmp_lt_i32 s30, 64
	s_movk_i32 s14, 0x3000
	s_cselect_b32 s14, s14, 0x6000
	s_cmp_gt_i32 s30, 31
	s_cselect_b32 s14, s14, 0
	s_lshl_b32 s14, s14, 2
	v_readlane_b32 s15, v251, 41
	s_add_u32 s14, s15, s14
	v_readlane_b32 s15, v251, 42
	v_ashrrev_i32_e32 v109, 31, v108
	s_addc_u32 s15, s15, 0
	v_lshlrev_b64 v[186:187], 2, v[108:109]
	v_lshl_add_u64 v[108:109], s[14:15], 0, v[186:187]
	s_mov_b64 s[14:15], 0x4000
	v_add_u32_e32 v148, s17, v148
	v_lshl_add_u64 v[110:111], v[108:109], 0, s[14:15]
	s_movk_i32 s14, 0x4000
	v_ashrrev_i32_e32 v149, 31, v148
	v_add_co_u32_e32 v108, vcc, s14, v108
	v_lshlrev_b64 v[190:191], 13, v[148:149]
	s_mov_b64 s[14:15], 0x20000
	v_lshl_add_u64 v[224:225], v[190:191], 0, s[14:15]
	s_mov_b64 s[14:15], 0x40000
	v_lshl_add_u64 v[194:195], v[190:191], 0, s[14:15]
	s_mov_b64 s[14:15], 0x60000
	v_addc_co_u32_e32 v109, vcc, 0, v109, vcc
	v_lshl_add_u64 v[188:189], s[18:19], 0, v[186:187]
	v_lshl_add_u64 v[192:193], v[190:191], 0, s[14:15]
	global_load_dwordx4 v[128:131], v[108:109], off
	global_load_dwordx4 v[120:123], v[110:111], off offset:64
	global_load_dwordx4 v[112:115], v[110:111], off offset:512
	s_nop 0
	global_load_dwordx4 v[108:111], v[110:111], off offset:576
	v_lshl_add_u64 v[148:149], v[188:189], 0, v[190:191]
	v_lshl_add_u64 v[150:151], v[188:189], 0, v[224:225]
	v_lshl_add_u64 v[176:177], v[188:189], 0, v[194:195]
	v_lshl_add_u64 v[160:161], v[188:189], 0, v[192:193]
	flat_load_dwordx4 v[200:203], v[150:151] offset:576
	flat_load_dwordx4 v[206:209], v[150:151] offset:512
	flat_load_dwordx4 v[210:213], v[150:151] offset:64
	flat_load_dwordx4 v[214:217], v[150:151]
	flat_load_dwordx4 v[218:221], v[148:149] offset:576
	flat_load_dwordx4 v[232:235], v[148:149] offset:512
	flat_load_dwordx4 v[236:239], v[148:149] offset:64
	flat_load_dwordx4 v[240:243], v[148:149]
	s_nop 0
	flat_load_dwordx4 v[148:151], v[160:161] offset:576
	flat_load_dwordx4 v[152:155], v[160:161] offset:512
	flat_load_dwordx4 v[156:159], v[160:161] offset:64
	s_nop 0
	flat_load_dwordx4 v[160:163], v[160:161]
	s_nop 0
	flat_load_dwordx4 v[164:167], v[176:177] offset:576
	flat_load_dwordx4 v[168:171], v[176:177] offset:512
	flat_load_dwordx4 v[172:175], v[176:177] offset:64
	s_nop 0
	flat_load_dwordx4 v[176:179], v[176:177]
	v_readlane_b32 s14, v250, 25
	v_readlane_b32 s15, v250, 26
	s_mov_b64 s[30:31], 0x100000
	s_and_b64 vcc, exec, s[40:41]
	v_lshl_add_u64 v[226:227], s[14:15], 0, v[190:191]
	v_lshl_add_u64 v[226:227], v[226:227], 0, v[186:187]
	s_mov_b64 s[38:39], s[36:37]
	s_mov_b64 s[42:43], s[34:35]
	s_waitcnt vmcnt(0) lgkmcnt(0)
	s_nop 0
	v_pk_fma_f32 v[134:135], v[134:135], v[110:111], v[220:221]
	v_pk_fma_f32 v[132:133], v[132:133], v[108:109], v[218:219]
	global_store_dwordx4 v[226:227], v[132:135], off offset:576
	v_pk_fma_f32 v[102:103], v[102:103], v[110:111], v[202:203]
	v_pk_fma_f32 v[100:101], v[100:101], v[108:109], v[200:201]
	v_lshl_add_u64 v[132:133], s[14:15], 0, v[224:225]
	v_lshl_add_u64 v[132:133], v[132:133], 0, v[186:187]
	global_store_dwordx4 v[132:133], v[100:103], off offset:576
	v_pk_fma_f32 v[106:107], v[106:107], v[114:115], v[208:209]
	v_pk_fma_f32 v[104:105], v[104:105], v[112:113], v[206:207]
	v_lshl_add_u64 v[100:101], s[14:15], 0, v[194:195]
	v_lshl_add_u64 v[100:101], v[100:101], 0, v[186:187]
	v_pk_fma_f32 v[78:79], v[78:79], v[110:111], v[166:167]
	v_pk_fma_f32 v[76:77], v[76:77], v[108:109], v[164:165]
	global_store_dwordx4 v[132:133], v[104:107], off offset:512
	v_pk_fma_f32 v[86:87], v[86:87], v[114:115], v[170:171]
	v_pk_fma_f32 v[84:85], v[84:85], v[112:113], v[168:169]
	global_store_dwordx4 v[100:101], v[76:79], off offset:576
	v_lshl_add_u64 v[106:107], v[190:191], 0, s[30:31]
	s_mov_b64 s[30:31], 0x120000
	v_lshl_add_u64 v[76:77], s[14:15], 0, v[192:193]
	global_store_dwordx4 v[100:101], v[84:87], off offset:512
	v_pk_fma_f32 v[78:79], v[90:91], v[130:131], v[162:163]
	v_pk_fma_f32 v[72:73], v[72:73], v[112:113], v[152:153]
	v_lshl_add_u64 v[84:85], v[76:77], 0, v[186:187]
	v_pk_fma_f32 v[76:77], v[88:89], v[128:129], v[160:161]
	v_lshl_add_u64 v[152:153], v[190:191], 0, s[30:31]
	s_mov_b64 s[30:31], 0x140000
	v_pk_fma_f32 v[146:147], v[146:147], v[130:131], v[242:243]
	v_pk_fma_f32 v[144:145], v[144:145], v[128:129], v[240:241]
	v_pk_fma_f32 v[142:143], v[142:143], v[122:123], v[238:239]
	v_pk_fma_f32 v[140:141], v[140:141], v[120:121], v[236:237]
	v_pk_fma_f32 v[138:139], v[138:139], v[114:115], v[234:235]
	v_pk_fma_f32 v[136:137], v[136:137], v[112:113], v[232:233]
	v_pk_fma_f32 v[126:127], v[126:127], v[130:131], v[216:217]
	v_pk_fma_f32 v[124:125], v[124:125], v[128:129], v[214:215]
	v_pk_fma_f32 v[118:119], v[118:119], v[122:123], v[212:213]
	v_pk_fma_f32 v[116:117], v[116:117], v[120:121], v[210:211]
	v_pk_fma_f32 v[98:99], v[98:99], v[130:131], v[178:179]
	v_pk_fma_f32 v[96:97], v[96:97], v[128:129], v[176:177]
	v_pk_fma_f32 v[94:95], v[94:95], v[122:123], v[174:175]
	v_pk_fma_f32 v[92:93], v[92:93], v[120:121], v[172:173]
	global_store_dwordx4 v[84:85], v[76:79], off
	v_pk_fma_f32 v[74:75], v[74:75], v[114:115], v[154:155]
	v_pk_fma_f32 v[70:71], v[70:71], v[110:111], v[150:151]
	v_pk_fma_f32 v[78:79], v[82:83], v[122:123], v[158:159]
	v_pk_fma_f32 v[76:77], v[80:81], v[120:121], v[156:157]
	v_pk_fma_f32 v[68:69], v[68:69], v[108:109], v[148:149]
	v_lshl_add_u64 v[154:155], v[190:191], 0, s[30:31]
	s_mov_b64 s[30:31], 0x160000
	global_store_dwordx4 v[226:227], v[144:147], off
	global_store_dwordx4 v[226:227], v[140:143], off offset:64
	global_store_dwordx4 v[226:227], v[136:139], off offset:512
	global_store_dwordx4 v[132:133], v[124:127], off
	global_store_dwordx4 v[132:133], v[116:119], off offset:64
	global_store_dwordx4 v[100:101], v[96:99], off
	global_store_dwordx4 v[100:101], v[92:95], off offset:64
	global_store_dwordx4 v[84:85], v[76:79], off offset:64
	global_store_dwordx4 v[84:85], v[72:75], off offset:512
	global_store_dwordx4 v[84:85], v[68:71], off offset:576
	v_lshl_add_u64 v[100:101], v[190:191], 0, s[30:31]
	v_lshl_add_u64 v[96:97], v[188:189], 0, v[154:155]
	v_lshl_add_u64 v[68:69], v[188:189], 0, v[106:107]
	v_lshl_add_u64 v[70:71], v[188:189], 0, v[152:153]
	v_lshl_add_u64 v[80:81], v[188:189], 0, v[100:101]
	flat_load_dwordx4 v[102:105], v[70:71] offset:576
	flat_load_dwordx4 v[116:119], v[70:71] offset:512
	flat_load_dwordx4 v[124:127], v[70:71] offset:64
	flat_load_dwordx4 v[132:135], v[70:71]
	flat_load_dwordx4 v[136:139], v[68:69] offset:576
	flat_load_dwordx4 v[140:143], v[68:69] offset:512
	flat_load_dwordx4 v[144:147], v[68:69] offset:64
	flat_load_dwordx4 v[148:151], v[68:69]
	s_nop 0
	flat_load_dwordx4 v[68:71], v[80:81] offset:576
	flat_load_dwordx4 v[72:75], v[80:81] offset:512
	flat_load_dwordx4 v[76:79], v[80:81] offset:64
	s_nop 0
	flat_load_dwordx4 v[80:83], v[80:81]
	s_nop 0
	flat_load_dwordx4 v[84:87], v[96:97] offset:576
	flat_load_dwordx4 v[88:91], v[96:97] offset:512
	flat_load_dwordx4 v[92:95], v[96:97] offset:64
	s_nop 0
	flat_load_dwordx4 v[96:99], v[96:97]
	v_lshl_add_u64 v[106:107], s[14:15], 0, v[106:107]
	s_waitcnt vmcnt(0) lgkmcnt(0)
	v_lshl_add_u64 v[106:107], v[106:107], 0, v[186:187]
	v_pk_fma_f32 v[54:55], v[54:55], v[110:111], v[138:139]
	v_pk_fma_f32 v[52:53], v[52:53], v[108:109], v[136:137]
	global_store_dwordx4 v[106:107], v[52:55], off offset:576
	v_pk_fma_f32 v[38:39], v[38:39], v[110:111], v[104:105]
	v_pk_fma_f32 v[36:37], v[36:37], v[108:109], v[102:103]
	v_lshl_add_u64 v[52:53], s[14:15], 0, v[152:153]
	v_lshl_add_u64 v[52:53], v[52:53], 0, v[186:187]
	global_store_dwordx4 v[52:53], v[36:39], off offset:576
	v_pk_fma_f32 v[18:19], v[18:19], v[110:111], v[86:87]
	v_pk_fma_f32 v[16:17], v[16:17], v[108:109], v[84:85]
	v_lshl_add_u64 v[36:37], s[14:15], 0, v[154:155]
	v_lshl_add_u64 v[36:37], v[36:37], 0, v[186:187]
	v_pk_fma_f32 v[26:27], v[26:27], v[114:115], v[90:91]
	v_pk_fma_f32 v[24:25], v[24:25], v[112:113], v[88:89]
	global_store_dwordx4 v[36:37], v[16:19], off offset:576
	v_pk_fma_f32 v[66:67], v[66:67], v[130:131], v[150:151]
	v_pk_fma_f32 v[64:65], v[64:65], v[128:129], v[148:149]
	v_lshl_add_u64 v[16:17], s[14:15], 0, v[100:101]
	v_pk_fma_f32 v[62:63], v[62:63], v[122:123], v[146:147]
	v_pk_fma_f32 v[60:61], v[60:61], v[120:121], v[144:145]
	v_pk_fma_f32 v[58:59], v[58:59], v[114:115], v[142:143]
	v_pk_fma_f32 v[56:57], v[56:57], v[112:113], v[140:141]
	v_pk_fma_f32 v[50:51], v[50:51], v[130:131], v[134:135]
	v_pk_fma_f32 v[48:49], v[48:49], v[128:129], v[132:133]
	v_pk_fma_f32 v[46:47], v[46:47], v[122:123], v[126:127]
	v_pk_fma_f32 v[44:45], v[44:45], v[120:121], v[124:125]
	v_pk_fma_f32 v[42:43], v[42:43], v[114:115], v[118:119]
	v_pk_fma_f32 v[40:41], v[40:41], v[112:113], v[116:117]
	v_pk_fma_f32 v[34:35], v[34:35], v[130:131], v[98:99]
	v_pk_fma_f32 v[32:33], v[32:33], v[128:129], v[96:97]
	v_pk_fma_f32 v[30:31], v[30:31], v[122:123], v[94:95]
	v_pk_fma_f32 v[28:29], v[28:29], v[120:121], v[92:93]
	global_store_dwordx4 v[36:37], v[24:27], off offset:512
	v_pk_fma_f32 v[18:19], v[22:23], v[130:131], v[82:83]
	v_pk_fma_f32 v[14:15], v[14:15], v[122:123], v[78:79]
	v_lshl_add_u64 v[24:25], v[16:17], 0, v[186:187]
	v_pk_fma_f32 v[16:17], v[20:21], v[128:129], v[80:81]
	v_pk_fma_f32 v[12:13], v[12:13], v[120:121], v[76:77]
	v_pk_fma_f32 v[10:11], v[10:11], v[114:115], v[74:75]
	v_pk_fma_f32 v[8:9], v[8:9], v[112:113], v[72:73]
	v_pk_fma_f32 v[6:7], v[6:7], v[110:111], v[70:71]
	v_pk_fma_f32 v[4:5], v[4:5], v[108:109], v[68:69]
	global_store_dwordx4 v[106:107], v[64:67], off
	global_store_dwordx4 v[106:107], v[60:63], off offset:64
	global_store_dwordx4 v[106:107], v[56:59], off offset:512
	global_store_dwordx4 v[52:53], v[48:51], off
	global_store_dwordx4 v[52:53], v[44:47], off offset:64
	global_store_dwordx4 v[52:53], v[40:43], off offset:512
	global_store_dwordx4 v[36:37], v[32:35], off
	global_store_dwordx4 v[36:37], v[28:31], off offset:64
	global_store_dwordx4 v[24:25], v[16:19], off
	global_store_dwordx4 v[24:25], v[12:15], off offset:64
	global_store_dwordx4 v[24:25], v[8:11], off offset:512
	global_store_dwordx4 v[24:25], v[4:7], off offset:576
	s_mov_b32 s31, s16
	s_mov_b32 s30, s26
	s_cbranch_vccz .LBB0_2113
	s_waitcnt vmcnt(0)
	s_cmpk_gt_u32 s4, 0xff
	s_cbranch_scc1 .LBB0_2124
	s_barrier

.LBB0_2133:
	s_add_u32 s38, s40, 0xfff80080
	s_addc_u32 s39, s41, -1
	s_add_i32 s45, 0, 0x10000
	v_add_u32_e32 v144, s45, v158
	ds_read_b128 v[132:135], v144
	ds_read_b128 v[136:139], v144 offset:1024
	ds_read_b128 v[140:143], v144 offset:2048
	ds_read_b128 v[144:147], v144 offset:3072
	s_cmp_eq_u32 s44, 4
	s_cselect_b32 s43, s27, s39
	s_cselect_b32 s42, s26, s38
	s_cselect_b32 s39, s35, s31
	s_cselect_b32 s38, s34, s19
	s_add_i32 m0, s6, 0xc000
	ds_read_b128 v[160:163], v159
	ds_read_b128 v[164:167], v159 offset:1024
	ds_read_b128 v[168:171], v159 offset:2048
	ds_read_b128 v[172:175], v159 offset:3072
	ds_read_b128 v[176:179], v159 offset:4096
	ds_read_b128 v[180:183], v159 offset:5120
	ds_read_b128 v[184:187], v159 offset:6144
	ds_read_b128 v[188:191], v159 offset:7168
	global_load_lds_dwordx4 v150, s[40:41]
	v_lshl_add_u64 v[154:155], s[40:41], 0, v[152:153]
	s_add_i32 m0, s6, 0xe000
	s_nop 0
	global_load_lds_dwordx4 v[154:155], off
	s_waitcnt vmcnt(10)
	s_barrier
	s_waitcnt lgkmcnt(0)
	v_mfma_f32_16x16x32_f16 v[128:131], v[132:135], v[160:163], v[128:131]
	v_mfma_f32_16x16x32_f16 v[124:127], v[140:143], v[160:163], v[124:127]
	v_mfma_f32_16x16x32_f16 v[112:115], v[132:135], v[168:171], v[112:115]
	v_mfma_f32_16x16x32_f16 v[108:111], v[140:143], v[168:171], v[108:111]
	v_mfma_f32_16x16x32_f16 v[96:99], v[132:135], v[176:179], v[96:99]
	v_mfma_f32_16x16x32_f16 v[92:95], v[140:143], v[176:179], v[92:95]
	v_mfma_f32_16x16x32_f16 v[80:83], v[132:135], v[184:187], v[80:83]
	v_mfma_f32_16x16x32_f16 v[76:79], v[140:143], v[184:187], v[76:79]
	v_mfma_f32_16x16x32_f16 v[128:131], v[136:139], v[164:167], v[128:131]
	v_mfma_f32_16x16x32_f16 v[124:127], v[144:147], v[164:167], v[124:127]
	v_mfma_f32_16x16x32_f16 v[112:115], v[136:139], v[172:175], v[112:115]
	v_mfma_f32_16x16x32_f16 v[108:111], v[144:147], v[172:175], v[108:111]
	v_mfma_f32_16x16x32_f16 v[96:99], v[136:139], v[180:183], v[96:99]
	v_mfma_f32_16x16x32_f16 v[92:95], v[144:147], v[180:183], v[92:95]
	v_mfma_f32_16x16x32_f16 v[80:83], v[136:139], v[188:191], v[80:83]
	v_mfma_f32_16x16x32_f16 v[76:79], v[144:147], v[188:191], v[76:79]
	s_barrier
	s_add_i32 s48, 0, 0x14000
	v_add_u32_e32 v154, s48, v158
	s_add_i32 s45, s45, s5
	ds_read_b128 v[192:195], v154
	ds_read_b128 v[196:199], v154 offset:1024
	ds_read_b128 v[200:203], v154 offset:2048
	ds_read_b128 v[206:209], v154 offset:3072
	v_lshl_add_u64 v[154:155], s[38:39], 0, v[2:3]
	s_mov_b32 m0, s45
	v_lshl_add_u64 v[210:211], s[38:39], 0, v[148:149]
	global_load_lds_dwordx4 v[154:155], off
	s_add_i32 m0, s45, 0x2000
	s_nop 0
	global_load_lds_dwordx4 v[210:211], off
	s_waitcnt vmcnt(10)
	s_barrier
	s_waitcnt lgkmcnt(0)
	v_mfma_f32_16x16x32_f16 v[120:123], v[192:195], v[160:163], v[120:123]
	v_mfma_f32_16x16x32_f16 v[116:119], v[200:203], v[160:163], v[116:119]
	v_mfma_f32_16x16x32_f16 v[104:107], v[192:195], v[168:171], v[104:107]
	v_mfma_f32_16x16x32_f16 v[100:103], v[200:203], v[168:171], v[100:103]
	v_mfma_f32_16x16x32_f16 v[88:91], v[192:195], v[176:179], v[88:91]
	v_mfma_f32_16x16x32_f16 v[84:87], v[200:203], v[176:179], v[84:87]
	v_mfma_f32_16x16x32_f16 v[72:75], v[192:195], v[184:187], v[72:75]
	v_mfma_f32_16x16x32_f16 v[68:71], v[200:203], v[184:187], v[68:71]
	v_mfma_f32_16x16x32_f16 v[120:123], v[196:199], v[164:167], v[120:123]
	v_mfma_f32_16x16x32_f16 v[116:119], v[206:209], v[164:167], v[116:119]
	v_mfma_f32_16x16x32_f16 v[104:107], v[196:199], v[172:175], v[104:107]
	v_mfma_f32_16x16x32_f16 v[100:103], v[206:209], v[172:175], v[100:103]
	v_mfma_f32_16x16x32_f16 v[88:91], v[196:199], v[180:183], v[88:91]
	v_mfma_f32_16x16x32_f16 v[84:87], v[206:209], v[180:183], v[84:87]
	v_mfma_f32_16x16x32_f16 v[72:75], v[196:199], v[188:191], v[72:75]
	v_mfma_f32_16x16x32_f16 v[68:71], v[206:209], v[188:191], v[68:71]
	s_mov_b32 m0, s6
	v_lshl_add_u64 v[212:213], s[42:43], 0, v[2:3]
	s_barrier
	ds_read_b128 v[160:163], v159 offset:16384
	ds_read_b128 v[164:167], v159 offset:17408
	ds_read_b128 v[168:171], v159 offset:18432
	ds_read_b128 v[172:175], v159 offset:19456
	ds_read_b128 v[176:179], v159 offset:20480
	ds_read_b128 v[180:183], v159 offset:21504
	ds_read_b128 v[184:187], v159 offset:22528
	ds_read_b128 v[188:191], v159 offset:23552
	global_load_lds_dwordx4 v[212:213], off
	v_lshl_add_u64 v[214:215], s[42:43], 0, v[148:149]
	s_mov_b32 m0, s7
	s_nop 0
	global_load_lds_dwordx4 v[214:215], off
	s_waitcnt vmcnt(10)
	s_barrier
	s_waitcnt lgkmcnt(0)
	v_mfma_f32_16x16x32_f16 v[64:67], v[132:135], v[160:163], v[64:67]
	v_mfma_f32_16x16x32_f16 v[60:63], v[140:143], v[160:163], v[60:63]
	v_mfma_f32_16x16x32_f16 v[56:59], v[132:135], v[168:171], v[56:59]
	v_mfma_f32_16x16x32_f16 v[44:47], v[140:143], v[168:171], v[44:47]
	v_mfma_f32_16x16x32_f16 v[40:43], v[132:135], v[176:179], v[40:43]
	v_mfma_f32_16x16x32_f16 v[28:31], v[140:143], v[176:179], v[28:31]
	v_mfma_f32_16x16x32_f16 v[24:27], v[132:135], v[184:187], v[24:27]
	v_mfma_f32_16x16x32_f16 v[12:15], v[140:143], v[184:187], v[12:15]
	v_mfma_f32_16x16x32_f16 v[64:67], v[136:139], v[164:167], v[64:67]
	v_mfma_f32_16x16x32_f16 v[60:63], v[144:147], v[164:167], v[60:63]
	v_mfma_f32_16x16x32_f16 v[56:59], v[136:139], v[172:175], v[56:59]
	v_mfma_f32_16x16x32_f16 v[44:47], v[144:147], v[172:175], v[44:47]
	v_mfma_f32_16x16x32_f16 v[40:43], v[136:139], v[180:183], v[40:43]
	v_mfma_f32_16x16x32_f16 v[28:31], v[144:147], v[180:183], v[28:31]
	v_mfma_f32_16x16x32_f16 v[24:27], v[136:139], v[188:191], v[24:27]
	v_mfma_f32_16x16x32_f16 v[12:15], v[144:147], v[188:191], v[12:15]
	s_barrier
	s_add_u32 s46, s38, 0x80000
	s_addc_u32 s47, s39, 0
	s_add_i32 s45, s48, s5
	v_lshl_add_u64 v[132:133], s[46:47], 0, v[2:3]
	s_mov_b32 m0, s45
	s_nop 0
	global_load_lds_dwordx4 v[132:133], off
	s_add_i32 m0, s45, 0x2000
	s_nop 0
	global_load_lds_dwordx4 v148, s[46:47]
	s_waitcnt vmcnt(10)
	s_barrier
	v_mfma_f32_16x16x32_f16 v[52:55], v[192:195], v[160:163], v[52:55]
	v_mfma_f32_16x16x32_f16 v[48:51], v[200:203], v[160:163], v[48:51]
	v_mfma_f32_16x16x32_f16 v[36:39], v[192:195], v[168:171], v[36:39]
	v_mfma_f32_16x16x32_f16 v[32:35], v[200:203], v[168:171], v[32:35]
	v_mfma_f32_16x16x32_f16 v[20:23], v[192:195], v[176:179], v[20:23]
	v_mfma_f32_16x16x32_f16 v[16:19], v[200:203], v[176:179], v[16:19]
	v_mfma_f32_16x16x32_f16 v[8:11], v[192:195], v[184:187], v[8:11]
	v_mfma_f32_16x16x32_f16 v[4:7], v[200:203], v[184:187], v[4:7]
	v_mfma_f32_16x16x32_f16 v[52:55], v[196:199], v[164:167], v[52:55]
	v_mfma_f32_16x16x32_f16 v[48:51], v[206:209], v[164:167], v[48:51]
	v_mfma_f32_16x16x32_f16 v[36:39], v[196:199], v[172:175], v[36:39]
	v_mfma_f32_16x16x32_f16 v[32:35], v[206:209], v[172:175], v[32:35]
	v_mfma_f32_16x16x32_f16 v[20:23], v[196:199], v[180:183], v[20:23]
	v_mfma_f32_16x16x32_f16 v[16:19], v[206:209], v[180:183], v[16:19]
	v_mfma_f32_16x16x32_f16 v[8:11], v[196:199], v[188:191], v[8:11]
	v_mfma_f32_16x16x32_f16 v[4:7], v[206:209], v[188:191], v[4:7]
	s_add_i32 s45, 0, 0x18000
	v_add_u32_e32 v144, s45, v158
	s_barrier
	ds_read_b128 v[132:135], v144
	ds_read_b128 v[136:139], v144 offset:1024
	ds_read_b128 v[140:143], v144 offset:2048
	ds_read_b128 v[144:147], v144 offset:3072
	s_add_u32 s42, s42, 0x80000
	s_addc_u32 s43, s43, 0
	s_mov_b32 m0, s8
	v_lshl_add_u64 v[192:193], s[42:43], 0, v[2:3]
	ds_read_b128 v[160:163], v159 offset:32768
	ds_read_b128 v[164:167], v159 offset:33792
	ds_read_b128 v[168:171], v159 offset:34816
	ds_read_b128 v[172:175], v159 offset:35840
	ds_read_b128 v[176:179], v159 offset:36864
	ds_read_b128 v[180:183], v159 offset:37888
	ds_read_b128 v[184:187], v159 offset:38912
	ds_read_b128 v[188:191], v159 offset:39936
	global_load_lds_dwordx4 v[192:193], off
	s_mov_b32 m0, s9
	s_nop 0
	global_load_lds_dwordx4 v148, s[42:43]
	s_waitcnt vmcnt(10)
	s_barrier
	s_waitcnt lgkmcnt(0)
	v_mfma_f32_16x16x32_f16 v[128:131], v[132:135], v[160:163], v[128:131]
	v_mfma_f32_16x16x32_f16 v[124:127], v[140:143], v[160:163], v[124:127]
	v_mfma_f32_16x16x32_f16 v[112:115], v[132:135], v[168:171], v[112:115]
	v_mfma_f32_16x16x32_f16 v[108:111], v[140:143], v[168:171], v[108:111]
	v_mfma_f32_16x16x32_f16 v[96:99], v[132:135], v[176:179], v[96:99]
	v_mfma_f32_16x16x32_f16 v[92:95], v[140:143], v[176:179], v[92:95]
	v_mfma_f32_16x16x32_f16 v[80:83], v[132:135], v[184:187], v[80:83]
	v_mfma_f32_16x16x32_f16 v[76:79], v[140:143], v[184:187], v[76:79]
	v_mfma_f32_16x16x32_f16 v[128:131], v[136:139], v[164:167], v[128:131]
	v_mfma_f32_16x16x32_f16 v[124:127], v[144:147], v[164:167], v[124:127]
	v_mfma_f32_16x16x32_f16 v[112:115], v[136:139], v[172:175], v[112:115]
	v_mfma_f32_16x16x32_f16 v[108:111], v[144:147], v[172:175], v[108:111]
	v_mfma_f32_16x16x32_f16 v[96:99], v[136:139], v[180:183], v[96:99]
	v_mfma_f32_16x16x32_f16 v[92:95], v[144:147], v[180:183], v[92:95]
	v_mfma_f32_16x16x32_f16 v[80:83], v[136:139], v[188:191], v[80:83]
	v_mfma_f32_16x16x32_f16 v[76:79], v[144:147], v[188:191], v[76:79]
	s_barrier
	s_add_i32 s42, 0, 0x1c000
	s_add_i32 s43, s45, s5
	v_add_u32_e32 v206, s42, v158
	v_lshl_add_u64 v[154:155], v[154:155], 0, s[88:89]
	s_mov_b32 m0, s43
	ds_read_b128 v[192:195], v206
	ds_read_b128 v[196:199], v206 offset:1024
	ds_read_b128 v[200:203], v206 offset:2048
	ds_read_b128 v[206:209], v206 offset:3072
	global_load_lds_dwordx4 v[154:155], off
	v_lshl_add_u64 v[154:155], v[210:211], 0, s[88:89]
	s_add_i32 m0, s43, 0x2000
	s_nop 0
	global_load_lds_dwordx4 v[154:155], off
	s_waitcnt vmcnt(10)
	s_barrier
	s_waitcnt lgkmcnt(0)
	v_mfma_f32_16x16x32_f16 v[120:123], v[192:195], v[160:163], v[120:123]
	v_mfma_f32_16x16x32_f16 v[116:119], v[200:203], v[160:163], v[116:119]
	v_mfma_f32_16x16x32_f16 v[104:107], v[192:195], v[168:171], v[104:107]
	v_mfma_f32_16x16x32_f16 v[100:103], v[200:203], v[168:171], v[100:103]
	v_mfma_f32_16x16x32_f16 v[88:91], v[192:195], v[176:179], v[88:91]
	v_mfma_f32_16x16x32_f16 v[84:87], v[200:203], v[176:179], v[84:87]
	v_mfma_f32_16x16x32_f16 v[72:75], v[192:195], v[184:187], v[72:75]
	v_mfma_f32_16x16x32_f16 v[68:71], v[200:203], v[184:187], v[68:71]
	v_mfma_f32_16x16x32_f16 v[120:123], v[196:199], v[164:167], v[120:123]
	v_mfma_f32_16x16x32_f16 v[116:119], v[206:209], v[164:167], v[116:119]
	v_mfma_f32_16x16x32_f16 v[104:107], v[196:199], v[172:175], v[104:107]
	v_mfma_f32_16x16x32_f16 v[100:103], v[206:209], v[172:175], v[100:103]
	v_mfma_f32_16x16x32_f16 v[88:91], v[196:199], v[180:183], v[88:91]
	v_mfma_f32_16x16x32_f16 v[84:87], v[206:209], v[180:183], v[84:87]
	v_mfma_f32_16x16x32_f16 v[72:75], v[196:199], v[188:191], v[72:75]
	v_mfma_f32_16x16x32_f16 v[68:71], v[206:209], v[188:191], v[68:71]
	s_mov_b32 m0, s10
	v_lshl_add_u64 v[154:155], v[212:213], 0, s[88:89]
	s_barrier
	ds_read_b128 v[160:163], v159 offset:49152
	ds_read_b128 v[164:167], v159 offset:50176
	ds_read_b128 v[168:171], v159 offset:51200
	ds_read_b128 v[172:175], v159 offset:52224
	ds_read_b128 v[176:179], v159 offset:53248
	ds_read_b128 v[180:183], v159 offset:54272
	ds_read_b128 v[184:187], v159 offset:55296
	ds_read_b128 v[188:191], v159 offset:56320
	global_load_lds_dwordx4 v[154:155], off
	v_lshl_add_u64 v[154:155], v[214:215], 0, s[88:89]
	s_mov_b32 m0, s11
	s_nop 0
	global_load_lds_dwordx4 v[154:155], off
	s_waitcnt vmcnt(10)
	s_barrier
	s_waitcnt lgkmcnt(0)
	v_mfma_f32_16x16x32_f16 v[64:67], v[132:135], v[160:163], v[64:67]
	v_mfma_f32_16x16x32_f16 v[60:63], v[140:143], v[160:163], v[60:63]
	v_mfma_f32_16x16x32_f16 v[56:59], v[132:135], v[168:171], v[56:59]
	v_mfma_f32_16x16x32_f16 v[44:47], v[140:143], v[168:171], v[44:47]
	v_mfma_f32_16x16x32_f16 v[40:43], v[132:135], v[176:179], v[40:43]
	v_mfma_f32_16x16x32_f16 v[28:31], v[140:143], v[176:179], v[28:31]
	v_mfma_f32_16x16x32_f16 v[24:27], v[132:135], v[184:187], v[24:27]
	v_mfma_f32_16x16x32_f16 v[12:15], v[140:143], v[184:187], v[12:15]
	v_mfma_f32_16x16x32_f16 v[64:67], v[136:139], v[164:167], v[64:67]
	v_mfma_f32_16x16x32_f16 v[60:63], v[144:147], v[164:167], v[60:63]
	v_mfma_f32_16x16x32_f16 v[56:59], v[136:139], v[172:175], v[56:59]
	v_mfma_f32_16x16x32_f16 v[44:47], v[144:147], v[172:175], v[44:47]
	v_mfma_f32_16x16x32_f16 v[40:43], v[136:139], v[180:183], v[40:43]
	v_mfma_f32_16x16x32_f16 v[28:31], v[144:147], v[180:183], v[28:31]
	v_mfma_f32_16x16x32_f16 v[24:27], v[136:139], v[188:191], v[24:27]
	v_mfma_f32_16x16x32_f16 v[12:15], v[144:147], v[188:191], v[12:15]
	s_barrier
	s_add_u32 s38, s38, 0x80080
	s_addc_u32 s39, s39, 0
	s_add_i32 s42, s42, s5
	v_lshl_add_u64 v[132:133], s[38:39], 0, v[2:3]
	s_mov_b32 m0, s42
	s_nop 0
	global_load_lds_dwordx4 v[132:133], off
	s_add_i32 m0, s42, 0x2000
	s_nop 0
	global_load_lds_dwordx4 v148, s[38:39]
	s_waitcnt vmcnt(10)
	s_barrier
	v_mfma_f32_16x16x32_f16 v[52:55], v[192:195], v[160:163], v[52:55]
	v_mfma_f32_16x16x32_f16 v[48:51], v[200:203], v[160:163], v[48:51]
	v_mfma_f32_16x16x32_f16 v[36:39], v[192:195], v[168:171], v[36:39]
	v_mfma_f32_16x16x32_f16 v[32:35], v[200:203], v[168:171], v[32:35]
	v_mfma_f32_16x16x32_f16 v[20:23], v[192:195], v[176:179], v[20:23]
	v_mfma_f32_16x16x32_f16 v[16:19], v[200:203], v[176:179], v[16:19]
	v_mfma_f32_16x16x32_f16 v[8:11], v[192:195], v[184:187], v[8:11]
	v_mfma_f32_16x16x32_f16 v[4:7], v[200:203], v[184:187], v[4:7]
	v_mfma_f32_16x16x32_f16 v[52:55], v[196:199], v[164:167], v[52:55]
	v_mfma_f32_16x16x32_f16 v[48:51], v[206:209], v[164:167], v[48:51]
	v_mfma_f32_16x16x32_f16 v[36:39], v[196:199], v[172:175], v[36:39]
	v_mfma_f32_16x16x32_f16 v[32:35], v[206:209], v[172:175], v[32:35]
	v_mfma_f32_16x16x32_f16 v[20:23], v[196:199], v[180:183], v[20:23]
	v_mfma_f32_16x16x32_f16 v[16:19], v[206:209], v[180:183], v[16:19]
	v_mfma_f32_16x16x32_f16 v[8:11], v[196:199], v[188:191], v[8:11]
	v_mfma_f32_16x16x32_f16 v[4:7], v[206:209], v[188:191], v[4:7]
	s_add_i32 s44, s44, 2
	s_add_u32 s40, s40, 0x100
	s_addc_u32 s41, s41, 0
	s_add_u32 s19, s19, 0x100
	s_addc_u32 s31, s31, 0
	s_cmp_gt_u32 s44, 5
	s_barrier
	s_cbranch_scc0 .LBB0_2133
	s_lshl_b32 s19, s30, 8
	s_lshl_b32 s30, s29, 8
	v_mov_b32_e32 v160, v156
	v_mov_b32_e32 v132, v157
	s_and_b32 s30, s30, 0xff00
	s_or_b32 s30, s30, s12
	v_lshl_add_u32 v132, v132, 2, s30
	v_ashrrev_i32_e32 v133, 31, v132
	v_lshlrev_b64 v[154:155], 2, v[132:133]
	v_lshl_add_u64 v[132:133], s[16:17], 0, v[154:155]
	global_load_dwordx4 v[144:147], v[132:133], off
	global_load_dwordx4 v[140:143], v[132:133], off offset:64
	global_load_dwordx4 v[136:139], v[132:133], off offset:512
	s_nop 0
	global_load_dwordx4 v[132:135], v[132:133], off offset:576
	s_ashr_i32 s30, s29, 8
	s_ashr_i32 s31, s30, 31
	s_add_i32 s19, s13, s19
	s_lshl_b64 s[30:31], s[30:31], 22
	v_readlane_b32 s38, v250, 27
	v_add_u32_e32 v160, s19, v160
	v_readlane_b32 s39, v250, 28
	s_add_u32 s30, s38, s30
	s_addc_u32 s31, s39, s31
	v_ashrrev_i32_e32 v161, 31, v160
	v_lshl_add_u64 v[154:155], s[30:31], 0, v[154:155]
	v_lshlrev_b64 v[160:161], 13, v[160:161]
	v_lshl_add_u64 v[154:155], v[154:155], 0, v[160:161]
	s_mov_b32 s19, 0x20000
	s_mov_b64 s[30:31], 0x20000
	s_mov_b32 s29, s15
	s_mov_b64 s[38:39], s[34:35]
	s_mov_b64 s[40:41], s[26:27]
	s_waitcnt vmcnt(0)
	v_pk_mul_f32 v[130:131], v[130:131], v[146:147]
	v_pk_mul_f32 v[128:129], v[128:129], v[144:145]
	v_pk_mul_f32 v[54:55], v[54:55], v[138:139]
	v_pk_mul_f32 v[118:119], v[118:119], v[134:135]
	v_pk_mul_f32 v[116:117], v[116:117], v[132:133]
	global_store_dwordx4 v[154:155], v[116:119], off offset:576
	v_pk_mul_f32 v[102:103], v[102:103], v[134:135]
	v_pk_mul_f32 v[100:101], v[100:101], v[132:133]
	v_add_co_u32_e32 v118, vcc, s19, v154
	v_lshl_add_u64 v[116:117], v[154:155], 0, s[30:31]
	s_nop 0
	v_addc_co_u32_e32 v119, vcc, 0, v155, vcc
	s_mov_b32 s19, 0x40000
	global_store_dwordx4 v[116:117], v[100:103], off offset:576
	s_mov_b64 s[30:31], 0x40000
	v_pk_mul_f32 v[86:87], v[86:87], v[134:135]
	v_add_co_u32_e32 v102, vcc, s19, v154
	v_lshl_add_u64 v[100:101], v[154:155], 0, s[30:31]
	s_nop 0
	v_addc_co_u32_e32 v103, vcc, 0, v155, vcc
	v_pk_mul_f32 v[84:85], v[84:85], v[132:133]
	s_mov_b32 s19, 0x60000
	global_store_dwordx4 v[100:101], v[84:87], off offset:576
	s_mov_b64 s[30:31], 0x60000
	v_pk_mul_f32 v[70:71], v[70:71], v[134:135]
	v_add_co_u32_e32 v86, vcc, s19, v154
	v_lshl_add_u64 v[84:85], v[154:155], 0, s[30:31]
	s_nop 0
	v_addc_co_u32_e32 v87, vcc, 0, v155, vcc
	v_pk_mul_f32 v[68:69], v[68:69], v[132:133]
	s_mov_b32 s19, 0x100000
	global_store_dwordx4 v[84:85], v[68:71], off offset:576
	s_mov_b64 s[30:31], 0x100000
	v_pk_mul_f32 v[52:53], v[52:53], v[136:137]
	v_add_co_u32_e32 v70, vcc, s19, v154
	v_lshl_add_u64 v[68:69], v[154:155], 0, s[30:31]
	s_nop 0
	v_addc_co_u32_e32 v71, vcc, 0, v155, vcc
	s_mov_b32 s19, 0x120000
	global_store_dwordx4 v[68:69], v[52:55], off offset:512
	s_mov_b64 s[30:31], 0x120000
	v_pk_mul_f32 v[38:39], v[38:39], v[138:139]
	v_add_co_u32_e32 v54, vcc, s19, v154
	v_lshl_add_u64 v[52:53], v[154:155], 0, s[30:31]
	s_nop 0
	v_addc_co_u32_e32 v55, vcc, 0, v155, vcc
	v_pk_mul_f32 v[36:37], v[36:37], v[136:137]
	s_mov_b32 s19, 0x140000
	global_store_dwordx4 v[52:53], v[36:39], off offset:512
	s_mov_b64 s[30:31], 0x140000
	v_pk_mul_f32 v[22:23], v[22:23], v[138:139]
	v_add_co_u32_e32 v38, vcc, s19, v154
	v_lshl_add_u64 v[36:37], v[154:155], 0, s[30:31]
	s_nop 0
	v_addc_co_u32_e32 v39, vcc, 0, v155, vcc
	v_pk_mul_f32 v[20:21], v[20:21], v[136:137]
	s_mov_b32 s19, 0x160000
	global_store_dwordx4 v[36:37], v[20:23], off offset:512
	v_pk_mul_f32 v[50:51], v[50:51], v[134:135]
	v_pk_mul_f32 v[48:49], v[48:49], v[132:133]
	v_add_co_u32_e32 v22, vcc, s19, v154
	v_pk_mul_f32 v[34:35], v[34:35], v[134:135]
	v_pk_mul_f32 v[32:33], v[32:33], v[132:133]
	v_pk_mul_f32 v[18:19], v[18:19], v[134:135]
	v_pk_mul_f32 v[16:17], v[16:17], v[132:133]
	s_mov_b64 s[30:31], 0x160000
	v_addc_co_u32_e32 v23, vcc, 0, v155, vcc
	v_pk_mul_f32 v[126:127], v[126:127], v[142:143]
	v_pk_mul_f32 v[124:125], v[124:125], v[140:141]
	v_pk_mul_f32 v[122:123], v[122:123], v[138:139]
	v_pk_mul_f32 v[120:121], v[120:121], v[136:137]
	v_pk_mul_f32 v[114:115], v[114:115], v[146:147]
	v_pk_mul_f32 v[112:113], v[112:113], v[144:145]
	v_pk_mul_f32 v[110:111], v[110:111], v[142:143]
	v_pk_mul_f32 v[108:109], v[108:109], v[140:141]
	v_pk_mul_f32 v[106:107], v[106:107], v[138:139]
	v_pk_mul_f32 v[104:105], v[104:105], v[136:137]
	v_pk_mul_f32 v[98:99], v[98:99], v[146:147]
	v_pk_mul_f32 v[96:97], v[96:97], v[144:145]
	v_pk_mul_f32 v[94:95], v[94:95], v[142:143]
	v_pk_mul_f32 v[92:93], v[92:93], v[140:141]
	v_pk_mul_f32 v[90:91], v[90:91], v[138:139]
	v_pk_mul_f32 v[88:89], v[88:89], v[136:137]
	v_pk_mul_f32 v[82:83], v[82:83], v[146:147]
	v_pk_mul_f32 v[80:81], v[80:81], v[144:145]
	v_pk_mul_f32 v[78:79], v[78:79], v[142:143]
	v_pk_mul_f32 v[76:77], v[76:77], v[140:141]
	v_pk_mul_f32 v[74:75], v[74:75], v[138:139]
	v_pk_mul_f32 v[72:73], v[72:73], v[136:137]
	v_pk_mul_f32 v[66:67], v[66:67], v[146:147]
	v_pk_mul_f32 v[64:65], v[64:65], v[144:145]
	v_pk_mul_f32 v[62:63], v[62:63], v[142:143]
	v_pk_mul_f32 v[60:61], v[60:61], v[140:141]
	global_store_dwordx4 v[68:69], v[48:51], off offset:576
	v_pk_mul_f32 v[46:47], v[46:47], v[142:143]
	v_pk_mul_f32 v[44:45], v[44:45], v[140:141]
	v_pk_mul_f32 v[50:51], v[58:59], v[146:147]
	v_pk_mul_f32 v[48:49], v[56:57], v[144:145]
	global_store_dwordx4 v[52:53], v[32:35], off offset:576
	v_pk_mul_f32 v[30:31], v[30:31], v[142:143]
	v_pk_mul_f32 v[28:29], v[28:29], v[140:141]
	v_pk_mul_f32 v[34:35], v[42:43], v[146:147]
	v_pk_mul_f32 v[32:33], v[40:41], v[144:145]
	global_store_dwordx4 v[36:37], v[16:19], off offset:576
	v_lshl_add_u64 v[20:21], v[154:155], 0, s[30:31]
	v_pk_mul_f32 v[14:15], v[14:15], v[142:143]
	v_pk_mul_f32 v[18:19], v[26:27], v[146:147]
	v_pk_mul_f32 v[16:17], v[24:25], v[144:145]
	v_pk_mul_f32 v[12:13], v[12:13], v[140:141]
	v_pk_mul_f32 v[10:11], v[10:11], v[138:139]
	v_pk_mul_f32 v[8:9], v[8:9], v[136:137]
	v_pk_mul_f32 v[6:7], v[6:7], v[134:135]
	v_pk_mul_f32 v[4:5], v[4:5], v[132:133]
	s_and_b64 vcc, exec, s[36:37]
	s_mov_b32 s30, s18
	global_store_dwordx4 v[154:155], v[128:131], off
	global_store_dwordx4 v[154:155], v[124:127], off offset:64
	global_store_dwordx4 v[154:155], v[120:123], off offset:512
	global_store_dwordx4 v[118:119], v[112:115], off
	global_store_dwordx4 v[116:117], v[108:111], off offset:64
	global_store_dwordx4 v[116:117], v[104:107], off offset:512
	global_store_dwordx4 v[102:103], v[96:99], off
	global_store_dwordx4 v[100:101], v[92:95], off offset:64
	global_store_dwordx4 v[100:101], v[88:91], off offset:512
	global_store_dwordx4 v[86:87], v[80:83], off
	global_store_dwordx4 v[84:85], v[76:79], off offset:64
	global_store_dwordx4 v[84:85], v[72:75], off offset:512
	global_store_dwordx4 v[70:71], v[64:67], off
	global_store_dwordx4 v[68:69], v[60:63], off offset:64
	global_store_dwordx4 v[54:55], v[48:51], off
	global_store_dwordx4 v[52:53], v[44:47], off offset:64
	global_store_dwordx4 v[38:39], v[32:35], off
	global_store_dwordx4 v[36:37], v[28:31], off offset:64
	global_store_dwordx4 v[22:23], v[16:19], off
	global_store_dwordx4 v[20:21], v[12:15], off offset:64
	global_store_dwordx4 v[20:21], v[8:11], off offset:512
	global_store_dwordx4 v[20:21], v[4:7], off offset:576
	s_cbranch_vccz .LBB0_2130
	s_waitcnt vmcnt(0)
	s_cmpk_gt_u32 s4, 0xff
	s_cbranch_scc1 .LBB0_2137
	s_barrier

.LBB0_2566:
	s_add_u32 s15, s44, 0xfff80080
	s_addc_u32 s17, s45, -1
	s_add_i32 s29, 0, 0x10000
	v_add_u32_e32 v2, s29, v202
	ds_read_b128 v[132:135], v2
	ds_read_b128 v[136:139], v2 offset:1024
	ds_read_b128 v[140:143], v2 offset:2048
	ds_read_b128 v[144:147], v2 offset:3072
	s_cmp_eq_u32 s14, 28
	s_cselect_b32 s47, s85, s17
	s_cselect_b32 s46, s84, s15
	s_cselect_b32 s39, s27, s11
	s_cselect_b32 s38, s26, s10
	s_add_i32 m0, s6, 0xc000
	ds_read_b128 v[148:151], v208
	ds_read_b128 v[152:155], v208 offset:1024
	ds_read_b128 v[156:159], v208 offset:2048
	ds_read_b128 v[160:163], v208 offset:3072
	ds_read_b128 v[164:167], v208 offset:4096
	ds_read_b128 v[168:171], v208 offset:5120
	ds_read_b128 v[172:175], v208 offset:6144
	ds_read_b128 v[188:191], v208 offset:7168
	global_load_lds_dwordx4 v184, s[44:45]
	s_add_i32 m0, s6, 0xe000
	s_nop 0
	global_load_lds_dwordx4 v186, s[44:45]
	s_waitcnt vmcnt(10)
	s_barrier
	s_waitcnt lgkmcnt(0)
	v_mfma_f32_16x16x32_f16 v[128:131], v[132:135], v[148:151], v[128:131]
	v_mfma_f32_16x16x32_f16 v[88:91], v[140:143], v[148:151], v[88:91]
	v_mfma_f32_16x16x32_f16 v[120:123], v[132:135], v[156:159], v[120:123]
	v_mfma_f32_16x16x32_f16 v[92:95], v[140:143], v[156:159], v[92:95]
	v_mfma_f32_16x16x32_f16 v[112:115], v[132:135], v[164:167], v[112:115]
	v_mfma_f32_16x16x32_f16 v[80:83], v[140:143], v[164:167], v[80:83]
	v_mfma_f32_16x16x32_f16 v[104:107], v[132:135], v[172:175], v[104:107]
	v_mfma_f32_16x16x32_f16 v[68:71], v[140:143], v[172:175], v[68:71]
	v_mfma_f32_16x16x32_f16 v[128:131], v[136:139], v[152:155], v[128:131]
	v_mfma_f32_16x16x32_f16 v[88:91], v[144:147], v[152:155], v[88:91]
	v_mfma_f32_16x16x32_f16 v[120:123], v[136:139], v[160:163], v[120:123]
	v_mfma_f32_16x16x32_f16 v[92:95], v[144:147], v[160:163], v[92:95]
	v_mfma_f32_16x16x32_f16 v[112:115], v[136:139], v[168:171], v[112:115]
	v_mfma_f32_16x16x32_f16 v[80:83], v[144:147], v[168:171], v[80:83]
	v_mfma_f32_16x16x32_f16 v[104:107], v[136:139], v[188:191], v[104:107]
	v_mfma_f32_16x16x32_f16 v[68:71], v[144:147], v[188:191], v[68:71]
	s_barrier
	s_add_i32 s15, 0, 0x14000
	s_add_i32 s17, s29, s5
	v_add_u32_e32 v2, s15, v202
	v_lshl_add_u64 v[218:219], s[38:39], 0, v[178:179]
	s_mov_b32 m0, s17
	ds_read_b128 v[192:195], v2
	ds_read_b128 v[196:199], v2 offset:1024
	ds_read_b128 v[210:213], v2 offset:2048
	ds_read_b128 v[214:217], v2 offset:3072
	global_load_lds_dwordx4 v[218:219], off
	v_lshl_add_u64 v[220:221], s[38:39], 0, v[182:183]
	s_add_i32 m0, s17, 0x2000
	s_nop 0
	global_load_lds_dwordx4 v[220:221], off
	s_waitcnt vmcnt(10)
	s_barrier
	s_waitcnt lgkmcnt(0)
	v_mfma_f32_16x16x32_f16 v[124:127], v[192:195], v[148:151], v[124:127]
	v_mfma_f32_16x16x32_f16 v[96:99], v[210:213], v[148:151], v[96:99]
	v_mfma_f32_16x16x32_f16 v[116:119], v[192:195], v[156:159], v[116:119]
	v_mfma_f32_16x16x32_f16 v[84:87], v[210:213], v[156:159], v[84:87]
	v_mfma_f32_16x16x32_f16 v[108:111], v[192:195], v[164:167], v[108:111]
	v_mfma_f32_16x16x32_f16 v[76:79], v[210:213], v[164:167], v[76:79]
	v_mfma_f32_16x16x32_f16 v[100:103], v[192:195], v[172:175], v[100:103]
	v_mfma_f32_16x16x32_f16 v[72:75], v[210:213], v[172:175], v[72:75]
	v_mfma_f32_16x16x32_f16 v[124:127], v[196:199], v[152:155], v[124:127]
	v_mfma_f32_16x16x32_f16 v[96:99], v[214:217], v[152:155], v[96:99]
	v_mfma_f32_16x16x32_f16 v[116:119], v[196:199], v[160:163], v[116:119]
	v_mfma_f32_16x16x32_f16 v[84:87], v[214:217], v[160:163], v[84:87]
	v_mfma_f32_16x16x32_f16 v[108:111], v[196:199], v[168:171], v[108:111]
	v_mfma_f32_16x16x32_f16 v[76:79], v[214:217], v[168:171], v[76:79]
	v_mfma_f32_16x16x32_f16 v[100:103], v[196:199], v[188:191], v[100:103]
	v_mfma_f32_16x16x32_f16 v[72:75], v[214:217], v[188:191], v[72:75]
	s_mov_b32 m0, s6
	v_lshl_add_u64 v[224:225], s[46:47], 0, v[176:177]
	s_barrier
	ds_read_b128 v[148:151], v208 offset:16384
	ds_read_b128 v[152:155], v208 offset:17408
	ds_read_b128 v[156:159], v208 offset:18432
	ds_read_b128 v[160:163], v208 offset:19456
	ds_read_b128 v[164:167], v208 offset:20480
	ds_read_b128 v[168:171], v208 offset:21504
	ds_read_b128 v[172:175], v208 offset:22528
	ds_read_b128 v[188:191], v208 offset:23552
	global_load_lds_dwordx4 v[224:225], off
	v_lshl_add_u64 v[226:227], s[46:47], 0, v[180:181]
	s_mov_b32 m0, s7
	s_nop 0
	global_load_lds_dwordx4 v[226:227], off
	s_waitcnt vmcnt(10)
	s_barrier
	s_waitcnt lgkmcnt(0)
	v_mfma_f32_16x16x32_f16 v[64:67], v[132:135], v[148:151], v[64:67]
	v_mfma_f32_16x16x32_f16 v[48:51], v[140:143], v[148:151], v[48:51]
	v_mfma_f32_16x16x32_f16 v[56:59], v[132:135], v[156:159], v[56:59]
	v_mfma_f32_16x16x32_f16 v[40:43], v[140:143], v[156:159], v[40:43]
	v_mfma_f32_16x16x32_f16 v[28:31], v[132:135], v[164:167], v[28:31]
	v_mfma_f32_16x16x32_f16 v[20:23], v[140:143], v[164:167], v[20:23]
	v_mfma_f32_16x16x32_f16 v[32:35], v[132:135], v[172:175], v[32:35]
	v_mfma_f32_16x16x32_f16 v[8:11], v[140:143], v[172:175], v[8:11]
	v_mfma_f32_16x16x32_f16 v[64:67], v[136:139], v[152:155], v[64:67]
	v_mfma_f32_16x16x32_f16 v[48:51], v[144:147], v[152:155], v[48:51]
	v_mfma_f32_16x16x32_f16 v[56:59], v[136:139], v[160:163], v[56:59]
	v_mfma_f32_16x16x32_f16 v[40:43], v[144:147], v[160:163], v[40:43]
	v_mfma_f32_16x16x32_f16 v[28:31], v[136:139], v[168:171], v[28:31]
	v_mfma_f32_16x16x32_f16 v[20:23], v[144:147], v[168:171], v[20:23]
	v_mfma_f32_16x16x32_f16 v[32:35], v[136:139], v[188:191], v[32:35]
	v_mfma_f32_16x16x32_f16 v[8:11], v[144:147], v[188:191], v[8:11]
	s_barrier
	s_add_u32 s30, s38, 0x80000
	s_addc_u32 s31, s39, 0
	s_add_i32 s15, s15, s5
	s_mov_b32 m0, s15
	s_nop 0
	global_load_lds_dwordx4 v178, s[30:31]
	s_add_i32 m0, s15, 0x2000
	s_nop 0
	global_load_lds_dwordx4 v182, s[30:31]
	s_waitcnt vmcnt(10)
	s_barrier
	v_mfma_f32_16x16x32_f16 v[60:63], v[192:195], v[148:151], v[60:63]
	v_mfma_f32_16x16x32_f16 v[44:47], v[210:213], v[148:151], v[44:47]
	v_mfma_f32_16x16x32_f16 v[52:55], v[192:195], v[156:159], v[52:55]
	v_mfma_f32_16x16x32_f16 v[36:39], v[210:213], v[156:159], v[36:39]
	v_mfma_f32_16x16x32_f16 v[16:19], v[192:195], v[164:167], v[16:19]
	v_mfma_f32_16x16x32_f16 v[12:15], v[210:213], v[164:167], v[12:15]
	v_mfma_f32_16x16x32_f16 v[24:27], v[192:195], v[172:175], v[24:27]
	v_mfma_f32_16x16x32_f16 v[4:7], v[210:213], v[172:175], v[4:7]
	v_mfma_f32_16x16x32_f16 v[60:63], v[196:199], v[152:155], v[60:63]
	v_mfma_f32_16x16x32_f16 v[44:47], v[214:217], v[152:155], v[44:47]
	v_mfma_f32_16x16x32_f16 v[52:55], v[196:199], v[160:163], v[52:55]
	v_mfma_f32_16x16x32_f16 v[36:39], v[214:217], v[160:163], v[36:39]
	v_mfma_f32_16x16x32_f16 v[16:19], v[196:199], v[168:171], v[16:19]
	v_mfma_f32_16x16x32_f16 v[12:15], v[214:217], v[168:171], v[12:15]
	v_mfma_f32_16x16x32_f16 v[24:27], v[196:199], v[188:191], v[24:27]
	v_mfma_f32_16x16x32_f16 v[4:7], v[214:217], v[188:191], v[4:7]
	s_add_i32 s15, 0, 0x18000
	v_add_u32_e32 v2, s15, v202
	s_barrier
	ds_read_b128 v[132:135], v2
	ds_read_b128 v[136:139], v2 offset:1024
	ds_read_b128 v[140:143], v2 offset:2048
	ds_read_b128 v[144:147], v2 offset:3072
	s_add_u32 s30, s46, 0x80000
	s_addc_u32 s31, s47, 0
	s_mov_b32 m0, s8
	ds_read_b128 v[148:151], v208 offset:32768
	ds_read_b128 v[152:155], v208 offset:33792
	ds_read_b128 v[156:159], v208 offset:34816
	ds_read_b128 v[160:163], v208 offset:35840
	ds_read_b128 v[164:167], v208 offset:36864
	ds_read_b128 v[168:171], v208 offset:37888
	ds_read_b128 v[172:175], v208 offset:38912
	ds_read_b128 v[188:191], v208 offset:39936
	global_load_lds_dwordx4 v176, s[30:31]
	s_mov_b32 m0, s9
	s_nop 0
	global_load_lds_dwordx4 v180, s[30:31]
	s_waitcnt vmcnt(10)
	s_barrier
	s_waitcnt lgkmcnt(0)
	v_mfma_f32_16x16x32_f16 v[128:131], v[132:135], v[148:151], v[128:131]
	v_mfma_f32_16x16x32_f16 v[88:91], v[140:143], v[148:151], v[88:91]
	v_mfma_f32_16x16x32_f16 v[120:123], v[132:135], v[156:159], v[120:123]
	v_mfma_f32_16x16x32_f16 v[92:95], v[140:143], v[156:159], v[92:95]
	v_mfma_f32_16x16x32_f16 v[112:115], v[132:135], v[164:167], v[112:115]
	v_mfma_f32_16x16x32_f16 v[80:83], v[140:143], v[164:167], v[80:83]
	v_mfma_f32_16x16x32_f16 v[104:107], v[132:135], v[172:175], v[104:107]
	v_mfma_f32_16x16x32_f16 v[68:71], v[140:143], v[172:175], v[68:71]
	v_mfma_f32_16x16x32_f16 v[128:131], v[136:139], v[152:155], v[128:131]
	v_mfma_f32_16x16x32_f16 v[88:91], v[144:147], v[152:155], v[88:91]
	v_mfma_f32_16x16x32_f16 v[120:123], v[136:139], v[160:163], v[120:123]
	v_mfma_f32_16x16x32_f16 v[92:95], v[144:147], v[160:163], v[92:95]
	v_mfma_f32_16x16x32_f16 v[112:115], v[136:139], v[168:171], v[112:115]
	v_mfma_f32_16x16x32_f16 v[80:83], v[144:147], v[168:171], v[80:83]
	v_mfma_f32_16x16x32_f16 v[104:107], v[136:139], v[188:191], v[104:107]
	v_mfma_f32_16x16x32_f16 v[68:71], v[144:147], v[188:191], v[68:71]
	s_barrier
	s_add_i32 s17, 0, 0x1c000
	s_add_i32 s15, s15, s5
	v_add_u32_e32 v2, s17, v202
	v_lshl_add_u64 v[218:219], v[218:219], 0, s[88:89]
	s_mov_b32 m0, s15
	ds_read_b128 v[192:195], v2
	ds_read_b128 v[196:199], v2 offset:1024
	ds_read_b128 v[210:213], v2 offset:2048
	ds_read_b128 v[214:217], v2 offset:3072
	global_load_lds_dwordx4 v[218:219], off
	v_lshl_add_u64 v[218:219], v[220:221], 0, s[88:89]
	s_add_i32 m0, s15, 0x2000
	s_nop 0
	global_load_lds_dwordx4 v[218:219], off
	s_waitcnt vmcnt(10)
	s_barrier
	s_waitcnt lgkmcnt(0)
	v_mfma_f32_16x16x32_f16 v[124:127], v[192:195], v[148:151], v[124:127]
	v_mfma_f32_16x16x32_f16 v[96:99], v[210:213], v[148:151], v[96:99]
	v_mfma_f32_16x16x32_f16 v[116:119], v[192:195], v[156:159], v[116:119]
	v_mfma_f32_16x16x32_f16 v[84:87], v[210:213], v[156:159], v[84:87]
	v_mfma_f32_16x16x32_f16 v[108:111], v[192:195], v[164:167], v[108:111]
	v_mfma_f32_16x16x32_f16 v[76:79], v[210:213], v[164:167], v[76:79]
	v_mfma_f32_16x16x32_f16 v[100:103], v[192:195], v[172:175], v[100:103]
	v_mfma_f32_16x16x32_f16 v[72:75], v[210:213], v[172:175], v[72:75]
	v_mfma_f32_16x16x32_f16 v[124:127], v[196:199], v[152:155], v[124:127]
	v_mfma_f32_16x16x32_f16 v[96:99], v[214:217], v[152:155], v[96:99]
	v_mfma_f32_16x16x32_f16 v[116:119], v[196:199], v[160:163], v[116:119]
	v_mfma_f32_16x16x32_f16 v[84:87], v[214:217], v[160:163], v[84:87]
	v_mfma_f32_16x16x32_f16 v[108:111], v[196:199], v[168:171], v[108:111]
	v_mfma_f32_16x16x32_f16 v[76:79], v[214:217], v[168:171], v[76:79]
	v_mfma_f32_16x16x32_f16 v[100:103], v[196:199], v[188:191], v[100:103]
	v_mfma_f32_16x16x32_f16 v[72:75], v[214:217], v[188:191], v[72:75]
	s_mov_b32 m0, s69
	v_lshl_add_u64 v[218:219], v[224:225], 0, s[88:89]
	s_barrier
	ds_read_b128 v[148:151], v208 offset:49152
	ds_read_b128 v[152:155], v208 offset:50176
	ds_read_b128 v[156:159], v208 offset:51200
	ds_read_b128 v[160:163], v208 offset:52224
	ds_read_b128 v[164:167], v208 offset:53248
	ds_read_b128 v[168:171], v208 offset:54272
	ds_read_b128 v[172:175], v208 offset:55296
	ds_read_b128 v[188:191], v208 offset:56320
	global_load_lds_dwordx4 v[218:219], off
	v_lshl_add_u64 v[218:219], v[226:227], 0, s[88:89]
	s_mov_b32 m0, s70
	s_nop 0
	global_load_lds_dwordx4 v[218:219], off
	s_waitcnt vmcnt(10)
	s_barrier
	s_waitcnt lgkmcnt(0)
	v_mfma_f32_16x16x32_f16 v[64:67], v[132:135], v[148:151], v[64:67]
	v_mfma_f32_16x16x32_f16 v[48:51], v[140:143], v[148:151], v[48:51]
	v_mfma_f32_16x16x32_f16 v[56:59], v[132:135], v[156:159], v[56:59]
	v_mfma_f32_16x16x32_f16 v[40:43], v[140:143], v[156:159], v[40:43]
	v_mfma_f32_16x16x32_f16 v[28:31], v[132:135], v[164:167], v[28:31]
	v_mfma_f32_16x16x32_f16 v[20:23], v[140:143], v[164:167], v[20:23]
	v_mfma_f32_16x16x32_f16 v[32:35], v[132:135], v[172:175], v[32:35]
	v_mfma_f32_16x16x32_f16 v[8:11], v[140:143], v[172:175], v[8:11]
	v_mfma_f32_16x16x32_f16 v[64:67], v[136:139], v[152:155], v[64:67]
	v_mfma_f32_16x16x32_f16 v[48:51], v[144:147], v[152:155], v[48:51]
	v_mfma_f32_16x16x32_f16 v[56:59], v[136:139], v[160:163], v[56:59]
	v_mfma_f32_16x16x32_f16 v[40:43], v[144:147], v[160:163], v[40:43]
	v_mfma_f32_16x16x32_f16 v[28:31], v[136:139], v[168:171], v[28:31]
	v_mfma_f32_16x16x32_f16 v[20:23], v[144:147], v[168:171], v[20:23]
	v_mfma_f32_16x16x32_f16 v[32:35], v[136:139], v[188:191], v[32:35]
	v_mfma_f32_16x16x32_f16 v[8:11], v[144:147], v[188:191], v[8:11]
	s_barrier
	s_add_u32 s30, s38, 0x80080
	s_addc_u32 s31, s39, 0
	s_add_i32 s15, s17, s5
	s_mov_b32 m0, s15
	s_nop 0
	global_load_lds_dwordx4 v178, s[30:31]
	s_add_i32 m0, s15, 0x2000
	s_nop 0
	global_load_lds_dwordx4 v182, s[30:31]
	s_waitcnt vmcnt(10)
	s_barrier
	v_mfma_f32_16x16x32_f16 v[60:63], v[192:195], v[148:151], v[60:63]
	v_mfma_f32_16x16x32_f16 v[44:47], v[210:213], v[148:151], v[44:47]
	v_mfma_f32_16x16x32_f16 v[52:55], v[192:195], v[156:159], v[52:55]
	v_mfma_f32_16x16x32_f16 v[36:39], v[210:213], v[156:159], v[36:39]
	v_mfma_f32_16x16x32_f16 v[16:19], v[192:195], v[164:167], v[16:19]
	v_mfma_f32_16x16x32_f16 v[12:15], v[210:213], v[164:167], v[12:15]
	v_mfma_f32_16x16x32_f16 v[24:27], v[192:195], v[172:175], v[24:27]
	v_mfma_f32_16x16x32_f16 v[4:7], v[210:213], v[172:175], v[4:7]
	v_mfma_f32_16x16x32_f16 v[60:63], v[196:199], v[152:155], v[60:63]
	v_mfma_f32_16x16x32_f16 v[44:47], v[214:217], v[152:155], v[44:47]
	v_mfma_f32_16x16x32_f16 v[52:55], v[196:199], v[160:163], v[52:55]
	v_mfma_f32_16x16x32_f16 v[36:39], v[214:217], v[160:163], v[36:39]
	v_mfma_f32_16x16x32_f16 v[16:19], v[196:199], v[168:171], v[16:19]
	v_mfma_f32_16x16x32_f16 v[12:15], v[214:217], v[168:171], v[12:15]
	v_mfma_f32_16x16x32_f16 v[24:27], v[196:199], v[188:191], v[24:27]
	v_mfma_f32_16x16x32_f16 v[4:7], v[214:217], v[188:191], v[4:7]
	s_add_i32 s14, s14, 2
	s_add_u32 s44, s44, 0x100
	s_addc_u32 s45, s45, 0
	s_add_u32 s10, s10, 0x100
	s_addc_u32 s11, s11, 0
	s_cmp_gt_u32 s14, 29
	s_barrier
	s_cbranch_scc0 .LBB0_2566
	v_mov_b32_e32 v209, v200
	v_mov_b32_e32 v2, v201
	s_mov_b64 s[38:39], 0
	v_lshlrev_b32_e32 v136, 5, v2
	v_add_u32_e32 v137, s92, v136
	v_cmp_lt_i32_e32 vcc, 14, v209
	s_and_saveexec_b64 s[10:11], vcc
	s_xor_b64 s[14:15], exec, s[10:11]
	s_cbranch_execz .LBB0_2571
	v_cmp_eq_u32_e32 vcc, 15, v209
	s_and_saveexec_b64 s[44:45], vcc
	s_mov_b64 s[38:39], exec
	ds_write_b128 v137, v[104:107] offset:128
	s_or_b64 exec, exec, s[44:45]
	s_and_b64 s[38:39], s[38:39], exec

.LBB0_3035:
	s_add_u32 s34, s26, 0x100
	s_addc_u32 s35, s27, 0
	s_add_i32 s45, 0, 0x10000
	v_add_u32_e32 v128, s45, v198
	ds_read_b128 v[108:111], v128
	ds_read_b128 v[112:115], v128 offset:1024
	ds_read_b128 v[120:123], v128 offset:2048
	ds_read_b128 v[128:131], v128 offset:3072
	s_cmpk_eq_i32 s44, 0x54
	s_cselect_b32 s39, s17, s35
	s_cselect_b32 s38, s16, s34
	s_cselect_b32 s37, s19, s15
	s_cselect_b32 s36, s18, s14
	v_lshl_add_u64 v[186:187], s[26:27], 0, v[182:183]
	s_add_i32 m0, s6, 0xc000
	ds_read_b128 v[148:151], v199
	ds_read_b128 v[152:155], v199 offset:1024
	ds_read_b128 v[156:159], v199 offset:2048
	ds_read_b128 v[160:163], v199 offset:3072
	ds_read_b128 v[164:167], v199 offset:4096
	ds_read_b128 v[168:171], v199 offset:5120
	ds_read_b128 v[172:175], v199 offset:6144
	ds_read_b128 v[176:179], v199 offset:7168
	global_load_lds_dwordx4 v[186:187], off
	v_lshl_add_u64 v[186:187], s[26:27], 0, v[184:185]
	s_add_i32 m0, s6, 0xe000
	s_nop 0
	global_load_lds_dwordx4 v[186:187], off
	s_waitcnt vmcnt(10)
	s_barrier
	s_waitcnt lgkmcnt(0)
	v_mfma_f32_16x16x32_f16 v[144:147], v[108:111], v[148:151], v[144:147]
	v_mfma_f32_16x16x32_f16 v[140:143], v[120:123], v[148:151], v[140:143]
	v_mfma_f32_16x16x32_f16 v[124:127], v[108:111], v[156:159], v[124:127]
	v_mfma_f32_16x16x32_f16 v[116:119], v[120:123], v[156:159], v[116:119]
	v_mfma_f32_16x16x32_f16 v[96:99], v[108:111], v[164:167], v[96:99]
	v_mfma_f32_16x16x32_f16 v[92:95], v[120:123], v[164:167], v[92:95]
	v_mfma_f32_16x16x32_f16 v[88:91], v[108:111], v[172:175], v[88:91]
	v_mfma_f32_16x16x32_f16 v[80:83], v[120:123], v[172:175], v[80:83]
	v_mfma_f32_16x16x32_f16 v[144:147], v[112:115], v[152:155], v[144:147]
	v_mfma_f32_16x16x32_f16 v[140:143], v[128:131], v[152:155], v[140:143]
	v_mfma_f32_16x16x32_f16 v[124:127], v[112:115], v[160:163], v[124:127]
	v_mfma_f32_16x16x32_f16 v[116:119], v[128:131], v[160:163], v[116:119]
	v_mfma_f32_16x16x32_f16 v[96:99], v[112:115], v[168:171], v[96:99]
	v_mfma_f32_16x16x32_f16 v[92:95], v[128:131], v[168:171], v[92:95]
	v_mfma_f32_16x16x32_f16 v[88:91], v[112:115], v[176:179], v[88:91]
	v_mfma_f32_16x16x32_f16 v[80:83], v[128:131], v[176:179], v[80:83]
	s_barrier
	s_add_i32 s46, 0, 0x14000
	v_add_u32_e32 v194, s46, v198
	s_add_i32 s26, s45, s5
	ds_read_b128 v[186:189], v194
	ds_read_b128 v[190:193], v194 offset:1024
	ds_read_b128 v[200:203], v194 offset:2048
	ds_read_b128 v[206:209], v194 offset:3072
	v_lshl_add_u64 v[194:195], s[36:37], 0, v[2:3]
	s_mov_b32 m0, s26
	v_lshl_add_u64 v[210:211], s[36:37], 0, v[180:181]
	global_load_lds_dwordx4 v[194:195], off
	s_add_i32 m0, s26, 0x2000
	s_nop 0
	global_load_lds_dwordx4 v[210:211], off
	s_waitcnt vmcnt(10)
	s_barrier
	s_waitcnt lgkmcnt(0)
	v_mfma_f32_16x16x32_f16 v[136:139], v[186:189], v[148:151], v[136:139]
	v_mfma_f32_16x16x32_f16 v[132:135], v[200:203], v[148:151], v[132:135]
	v_mfma_f32_16x16x32_f16 v[104:107], v[186:189], v[156:159], v[104:107]
	v_mfma_f32_16x16x32_f16 v[100:103], v[200:203], v[156:159], v[100:103]
	v_mfma_f32_16x16x32_f16 v[84:87], v[186:189], v[164:167], v[84:87]
	v_mfma_f32_16x16x32_f16 v[76:79], v[200:203], v[164:167], v[76:79]
	v_mfma_f32_16x16x32_f16 v[72:75], v[186:189], v[172:175], v[72:75]
	v_mfma_f32_16x16x32_f16 v[68:71], v[200:203], v[172:175], v[68:71]
	v_mfma_f32_16x16x32_f16 v[136:139], v[190:193], v[152:155], v[136:139]
	v_mfma_f32_16x16x32_f16 v[132:135], v[206:209], v[152:155], v[132:135]
	v_mfma_f32_16x16x32_f16 v[104:107], v[190:193], v[160:163], v[104:107]
	v_mfma_f32_16x16x32_f16 v[100:103], v[206:209], v[160:163], v[100:103]
	v_mfma_f32_16x16x32_f16 v[84:87], v[190:193], v[168:171], v[84:87]
	v_mfma_f32_16x16x32_f16 v[76:79], v[206:209], v[168:171], v[76:79]
	v_mfma_f32_16x16x32_f16 v[72:75], v[190:193], v[176:179], v[72:75]
	v_mfma_f32_16x16x32_f16 v[68:71], v[206:209], v[176:179], v[68:71]
	s_mov_b32 m0, s6
	v_lshl_add_u64 v[212:213], s[38:39], 0, v[2:3]
	s_barrier
	ds_read_b128 v[148:151], v199 offset:16384
	ds_read_b128 v[152:155], v199 offset:17408
	ds_read_b128 v[156:159], v199 offset:18432
	ds_read_b128 v[160:163], v199 offset:19456
	ds_read_b128 v[164:167], v199 offset:20480
	ds_read_b128 v[168:171], v199 offset:21504
	ds_read_b128 v[172:175], v199 offset:22528
	ds_read_b128 v[176:179], v199 offset:23552
	global_load_lds_dwordx4 v[212:213], off
	v_lshl_add_u64 v[214:215], s[38:39], 0, v[180:181]
	s_mov_b32 m0, s7
	s_nop 0
	global_load_lds_dwordx4 v[214:215], off
	s_waitcnt vmcnt(10)
	s_barrier
	s_waitcnt lgkmcnt(0)
	v_mfma_f32_16x16x32_f16 v[64:67], v[108:111], v[148:151], v[64:67]
	v_mfma_f32_16x16x32_f16 v[60:63], v[120:123], v[148:151], v[60:63]
	v_mfma_f32_16x16x32_f16 v[48:51], v[108:111], v[156:159], v[48:51]
	v_mfma_f32_16x16x32_f16 v[44:47], v[120:123], v[156:159], v[44:47]
	v_mfma_f32_16x16x32_f16 v[32:35], v[108:111], v[164:167], v[32:35]
	v_mfma_f32_16x16x32_f16 v[28:31], v[120:123], v[164:167], v[28:31]
	v_mfma_f32_16x16x32_f16 v[20:23], v[108:111], v[172:175], v[20:23]
	v_mfma_f32_16x16x32_f16 v[12:15], v[120:123], v[172:175], v[12:15]
	v_mfma_f32_16x16x32_f16 v[64:67], v[112:115], v[152:155], v[64:67]
	v_mfma_f32_16x16x32_f16 v[60:63], v[128:131], v[152:155], v[60:63]
	v_mfma_f32_16x16x32_f16 v[48:51], v[112:115], v[160:163], v[48:51]
	v_mfma_f32_16x16x32_f16 v[44:47], v[128:131], v[160:163], v[44:47]
	v_mfma_f32_16x16x32_f16 v[32:35], v[112:115], v[168:171], v[32:35]
	v_mfma_f32_16x16x32_f16 v[28:31], v[128:131], v[168:171], v[28:31]
	v_mfma_f32_16x16x32_f16 v[20:23], v[112:115], v[176:179], v[20:23]
	v_mfma_f32_16x16x32_f16 v[12:15], v[128:131], v[176:179], v[12:15]
	s_barrier
	s_add_u32 s26, s36, 0x160000
	s_addc_u32 s27, s37, 0
	s_add_i32 s45, s46, s5
	v_lshl_add_u64 v[108:109], s[26:27], 0, v[2:3]
	s_mov_b32 m0, s45
	s_nop 0
	global_load_lds_dwordx4 v[108:109], off
	s_add_i32 m0, s45, 0x2000
	s_nop 0
	global_load_lds_dwordx4 v180, s[26:27]
	s_waitcnt vmcnt(10)
	s_barrier
	v_mfma_f32_16x16x32_f16 v[56:59], v[186:189], v[148:151], v[56:59]
	v_mfma_f32_16x16x32_f16 v[52:55], v[200:203], v[148:151], v[52:55]
	v_mfma_f32_16x16x32_f16 v[40:43], v[186:189], v[156:159], v[40:43]
	v_mfma_f32_16x16x32_f16 v[36:39], v[200:203], v[156:159], v[36:39]
	v_mfma_f32_16x16x32_f16 v[24:27], v[186:189], v[164:167], v[24:27]
	v_mfma_f32_16x16x32_f16 v[16:19], v[200:203], v[164:167], v[16:19]
	v_mfma_f32_16x16x32_f16 v[8:11], v[186:189], v[172:175], v[8:11]
	v_mfma_f32_16x16x32_f16 v[4:7], v[200:203], v[172:175], v[4:7]
	v_mfma_f32_16x16x32_f16 v[56:59], v[190:193], v[152:155], v[56:59]
	v_mfma_f32_16x16x32_f16 v[52:55], v[206:209], v[152:155], v[52:55]
	v_mfma_f32_16x16x32_f16 v[40:43], v[190:193], v[160:163], v[40:43]
	v_mfma_f32_16x16x32_f16 v[36:39], v[206:209], v[160:163], v[36:39]
	v_mfma_f32_16x16x32_f16 v[24:27], v[190:193], v[168:171], v[24:27]
	v_mfma_f32_16x16x32_f16 v[16:19], v[206:209], v[168:171], v[16:19]
	v_mfma_f32_16x16x32_f16 v[8:11], v[190:193], v[176:179], v[8:11]
	v_mfma_f32_16x16x32_f16 v[4:7], v[206:209], v[176:179], v[4:7]
	s_add_i32 s45, 0, 0x18000
	v_add_u32_e32 v128, s45, v198
	s_barrier
	ds_read_b128 v[108:111], v128
	ds_read_b128 v[112:115], v128 offset:1024
	ds_read_b128 v[120:123], v128 offset:2048
	ds_read_b128 v[128:131], v128 offset:3072
	s_add_u32 s26, s38, 0x160000
	s_addc_u32 s27, s39, 0
	s_mov_b32 m0, s8
	v_lshl_add_u64 v[186:187], s[26:27], 0, v[2:3]
	ds_read_b128 v[148:151], v199 offset:32768
	ds_read_b128 v[152:155], v199 offset:33792
	ds_read_b128 v[156:159], v199 offset:34816
	ds_read_b128 v[160:163], v199 offset:35840
	ds_read_b128 v[164:167], v199 offset:36864
	ds_read_b128 v[168:171], v199 offset:37888
	ds_read_b128 v[172:175], v199 offset:38912
	ds_read_b128 v[176:179], v199 offset:39936
	global_load_lds_dwordx4 v[186:187], off
	s_mov_b32 m0, s9
	s_nop 0
	global_load_lds_dwordx4 v180, s[26:27]
	s_waitcnt vmcnt(10)
	s_barrier
	s_waitcnt lgkmcnt(0)
	v_mfma_f32_16x16x32_f16 v[144:147], v[108:111], v[148:151], v[144:147]
	v_mfma_f32_16x16x32_f16 v[140:143], v[120:123], v[148:151], v[140:143]
	v_mfma_f32_16x16x32_f16 v[124:127], v[108:111], v[156:159], v[124:127]
	v_mfma_f32_16x16x32_f16 v[116:119], v[120:123], v[156:159], v[116:119]
	v_mfma_f32_16x16x32_f16 v[96:99], v[108:111], v[164:167], v[96:99]
	v_mfma_f32_16x16x32_f16 v[92:95], v[120:123], v[164:167], v[92:95]
	v_mfma_f32_16x16x32_f16 v[88:91], v[108:111], v[172:175], v[88:91]
	v_mfma_f32_16x16x32_f16 v[80:83], v[120:123], v[172:175], v[80:83]
	v_mfma_f32_16x16x32_f16 v[144:147], v[112:115], v[152:155], v[144:147]
	v_mfma_f32_16x16x32_f16 v[140:143], v[128:131], v[152:155], v[140:143]
	v_mfma_f32_16x16x32_f16 v[124:127], v[112:115], v[160:163], v[124:127]
	v_mfma_f32_16x16x32_f16 v[116:119], v[128:131], v[160:163], v[116:119]
	v_mfma_f32_16x16x32_f16 v[96:99], v[112:115], v[168:171], v[96:99]
	v_mfma_f32_16x16x32_f16 v[92:95], v[128:131], v[168:171], v[92:95]
	v_mfma_f32_16x16x32_f16 v[88:91], v[112:115], v[176:179], v[88:91]
	v_mfma_f32_16x16x32_f16 v[80:83], v[128:131], v[176:179], v[80:83]
	s_barrier
	s_add_i32 s38, 0, 0x1c000
	s_add_i32 s26, s45, s5
	v_add_u32_e32 v206, s38, v198
	v_lshl_add_u64 v[194:195], v[194:195], 0, s[88:89]
	s_mov_b32 m0, s26
	ds_read_b128 v[186:189], v206
	ds_read_b128 v[190:193], v206 offset:1024
	ds_read_b128 v[200:203], v206 offset:2048
	ds_read_b128 v[206:209], v206 offset:3072
	global_load_lds_dwordx4 v[194:195], off
	v_lshl_add_u64 v[194:195], v[210:211], 0, s[88:89]
	s_add_i32 m0, s26, 0x2000
	s_nop 0
	global_load_lds_dwordx4 v[194:195], off
	s_waitcnt vmcnt(10)
	s_barrier
	s_waitcnt lgkmcnt(0)
	v_mfma_f32_16x16x32_f16 v[136:139], v[186:189], v[148:151], v[136:139]
	v_mfma_f32_16x16x32_f16 v[132:135], v[200:203], v[148:151], v[132:135]
	v_mfma_f32_16x16x32_f16 v[104:107], v[186:189], v[156:159], v[104:107]
	v_mfma_f32_16x16x32_f16 v[100:103], v[200:203], v[156:159], v[100:103]
	v_mfma_f32_16x16x32_f16 v[84:87], v[186:189], v[164:167], v[84:87]
	v_mfma_f32_16x16x32_f16 v[76:79], v[200:203], v[164:167], v[76:79]
	v_mfma_f32_16x16x32_f16 v[72:75], v[186:189], v[172:175], v[72:75]
	v_mfma_f32_16x16x32_f16 v[68:71], v[200:203], v[172:175], v[68:71]
	v_mfma_f32_16x16x32_f16 v[136:139], v[190:193], v[152:155], v[136:139]
	v_mfma_f32_16x16x32_f16 v[132:135], v[206:209], v[152:155], v[132:135]
	v_mfma_f32_16x16x32_f16 v[104:107], v[190:193], v[160:163], v[104:107]
	v_mfma_f32_16x16x32_f16 v[100:103], v[206:209], v[160:163], v[100:103]
	v_mfma_f32_16x16x32_f16 v[84:87], v[190:193], v[168:171], v[84:87]
	v_mfma_f32_16x16x32_f16 v[76:79], v[206:209], v[168:171], v[76:79]
	v_mfma_f32_16x16x32_f16 v[72:75], v[190:193], v[176:179], v[72:75]
	v_mfma_f32_16x16x32_f16 v[68:71], v[206:209], v[176:179], v[68:71]
	s_mov_b32 m0, s10
	v_lshl_add_u64 v[194:195], v[212:213], 0, s[88:89]
	s_barrier
	ds_read_b128 v[148:151], v199 offset:49152
	ds_read_b128 v[152:155], v199 offset:50176
	ds_read_b128 v[156:159], v199 offset:51200
	ds_read_b128 v[160:163], v199 offset:52224
	ds_read_b128 v[164:167], v199 offset:53248
	ds_read_b128 v[168:171], v199 offset:54272
	ds_read_b128 v[172:175], v199 offset:55296
	ds_read_b128 v[176:179], v199 offset:56320
	global_load_lds_dwordx4 v[194:195], off
	v_lshl_add_u64 v[194:195], v[214:215], 0, s[88:89]
	s_mov_b32 m0, s11
	s_nop 0
	global_load_lds_dwordx4 v[194:195], off
	s_waitcnt vmcnt(10)
	s_barrier
	s_waitcnt lgkmcnt(0)
	v_mfma_f32_16x16x32_f16 v[64:67], v[108:111], v[148:151], v[64:67]
	v_mfma_f32_16x16x32_f16 v[60:63], v[120:123], v[148:151], v[60:63]
	v_mfma_f32_16x16x32_f16 v[48:51], v[108:111], v[156:159], v[48:51]
	v_mfma_f32_16x16x32_f16 v[44:47], v[120:123], v[156:159], v[44:47]
	v_mfma_f32_16x16x32_f16 v[32:35], v[108:111], v[164:167], v[32:35]
	v_mfma_f32_16x16x32_f16 v[28:31], v[120:123], v[164:167], v[28:31]
	v_mfma_f32_16x16x32_f16 v[20:23], v[108:111], v[172:175], v[20:23]
	v_mfma_f32_16x16x32_f16 v[12:15], v[120:123], v[172:175], v[12:15]
	v_mfma_f32_16x16x32_f16 v[64:67], v[112:115], v[152:155], v[64:67]
	v_mfma_f32_16x16x32_f16 v[60:63], v[128:131], v[152:155], v[60:63]
	v_mfma_f32_16x16x32_f16 v[48:51], v[112:115], v[160:163], v[48:51]
	v_mfma_f32_16x16x32_f16 v[44:47], v[128:131], v[160:163], v[44:47]
	v_mfma_f32_16x16x32_f16 v[32:35], v[112:115], v[168:171], v[32:35]
	v_mfma_f32_16x16x32_f16 v[28:31], v[128:131], v[168:171], v[28:31]
	v_mfma_f32_16x16x32_f16 v[20:23], v[112:115], v[176:179], v[20:23]
	v_mfma_f32_16x16x32_f16 v[12:15], v[128:131], v[176:179], v[12:15]
	s_barrier
	s_add_u32 s26, s36, 0x160080
	s_addc_u32 s27, s37, 0
	s_add_i32 s36, s38, s5
	v_lshl_add_u64 v[108:109], s[26:27], 0, v[2:3]
	s_mov_b32 m0, s36
	s_nop 0
	global_load_lds_dwordx4 v[108:109], off
	s_add_i32 m0, s36, 0x2000
	s_nop 0
	global_load_lds_dwordx4 v180, s[26:27]
	s_waitcnt vmcnt(10)
	s_barrier
	v_mfma_f32_16x16x32_f16 v[56:59], v[186:189], v[148:151], v[56:59]
	v_mfma_f32_16x16x32_f16 v[52:55], v[200:203], v[148:151], v[52:55]
	v_mfma_f32_16x16x32_f16 v[40:43], v[186:189], v[156:159], v[40:43]
	v_mfma_f32_16x16x32_f16 v[36:39], v[200:203], v[156:159], v[36:39]
	v_mfma_f32_16x16x32_f16 v[24:27], v[186:189], v[164:167], v[24:27]
	v_mfma_f32_16x16x32_f16 v[16:19], v[200:203], v[164:167], v[16:19]
	v_mfma_f32_16x16x32_f16 v[8:11], v[186:189], v[172:175], v[8:11]
	v_mfma_f32_16x16x32_f16 v[4:7], v[200:203], v[172:175], v[4:7]
	v_mfma_f32_16x16x32_f16 v[56:59], v[190:193], v[152:155], v[56:59]
	v_mfma_f32_16x16x32_f16 v[52:55], v[206:209], v[152:155], v[52:55]
	v_mfma_f32_16x16x32_f16 v[40:43], v[190:193], v[160:163], v[40:43]
	v_mfma_f32_16x16x32_f16 v[36:39], v[206:209], v[160:163], v[36:39]
	v_mfma_f32_16x16x32_f16 v[24:27], v[190:193], v[168:171], v[24:27]
	v_mfma_f32_16x16x32_f16 v[16:19], v[206:209], v[168:171], v[16:19]
	v_mfma_f32_16x16x32_f16 v[8:11], v[190:193], v[176:179], v[8:11]
	v_mfma_f32_16x16x32_f16 v[4:7], v[206:209], v[176:179], v[4:7]
	s_add_i32 s44, s44, 2
	s_add_u32 s14, s14, 0x100
	s_addc_u32 s15, s15, 0
	s_cmpk_gt_u32 s44, 0x55
	s_mov_b64 s[26:27], s[34:35]
	s_barrier
	s_cbranch_scc0 .LBB0_3035
	s_lshl_b32 s14, s42, 8
	v_mov_b32_e32 v148, v196
	v_mov_b32_e32 v108, v197
	s_add_i32 s26, s14, s12
	s_lshl_b32 s14, s43, 8
	s_or_b32 s14, s14, s13
	v_lshl_add_u32 v108, v108, 2, s14
	s_cmp_lt_i32 s42, 64
	s_movk_i32 s14, 0x3000
	s_cselect_b32 s14, s14, 0x6000
	s_cmp_gt_i32 s42, 31
	s_cselect_b32 s14, s14, 0
	s_lshl_b32 s14, s14, 2
	v_readlane_b32 s15, v251, 41
	s_add_u32 s14, s15, s14
	v_readlane_b32 s15, v251, 42
	v_ashrrev_i32_e32 v109, 31, v108
	s_addc_u32 s15, s15, 0
	v_lshlrev_b64 v[186:187], 2, v[108:109]
	v_add_u32_e32 v148, s26, v148
	v_lshl_add_u64 v[108:109], s[14:15], 0, v[186:187]
	s_mov_b64 s[14:15], 0xa000
	v_ashrrev_i32_e32 v149, 31, v148
	v_lshl_add_u64 v[110:111], v[108:109], 0, s[14:15]
	s_mov_b32 s14, 0xa000
	v_lshlrev_b64 v[190:191], 13, v[148:149]
	s_mov_b64 s[26:27], 0x20000
	v_add_co_u32_e32 v108, vcc, s14, v108
	v_readlane_b32 s14, v250, 25
	v_lshl_add_u64 v[224:225], v[190:191], 0, s[26:27]
	s_mov_b64 s[26:27], 0x40000
	v_readlane_b32 s15, v250, 26
	v_lshl_add_u64 v[194:195], v[190:191], 0, s[26:27]
	s_mov_b64 s[26:27], 0x60000
	v_addc_co_u32_e32 v109, vcc, 0, v109, vcc
	v_lshl_add_u64 v[188:189], s[14:15], 0, v[186:187]
	v_lshl_add_u64 v[192:193], v[190:191], 0, s[26:27]
	global_load_dwordx4 v[128:131], v[108:109], off
	global_load_dwordx4 v[120:123], v[110:111], off offset:64
	global_load_dwordx4 v[112:115], v[110:111], off offset:512
	s_nop 0
	global_load_dwordx4 v[108:111], v[110:111], off offset:576
	v_lshl_add_u64 v[148:149], v[188:189], 0, v[190:191]
	v_lshl_add_u64 v[150:151], v[188:189], 0, v[224:225]
	v_lshl_add_u64 v[176:177], v[188:189], 0, v[194:195]
	v_lshl_add_u64 v[160:161], v[188:189], 0, v[192:193]
	global_load_dwordx4 v[200:203], v[150:151], off offset:576
	global_load_dwordx4 v[206:209], v[150:151], off offset:512
	global_load_dwordx4 v[210:213], v[150:151], off offset:64
	global_load_dwordx4 v[214:217], v[150:151], off
	global_load_dwordx4 v[218:221], v[148:149], off offset:576
	global_load_dwordx4 v[232:235], v[148:149], off offset:512
	global_load_dwordx4 v[236:239], v[148:149], off offset:64
	global_load_dwordx4 v[240:243], v[148:149], off
	s_nop 0
	global_load_dwordx4 v[148:151], v[160:161], off offset:576
	global_load_dwordx4 v[152:155], v[160:161], off offset:512
	global_load_dwordx4 v[156:159], v[160:161], off offset:64
	s_nop 0
	global_load_dwordx4 v[160:163], v[160:161], off
	s_nop 0
	global_load_dwordx4 v[164:167], v[176:177], off offset:576
	global_load_dwordx4 v[168:171], v[176:177], off offset:512
	global_load_dwordx4 v[172:175], v[176:177], off offset:64
	s_nop 0
	global_load_dwordx4 v[176:179], v[176:177], off
	v_lshl_add_u64 v[226:227], s[14:15], 0, v[190:191]
	v_lshl_add_u64 v[226:227], v[226:227], 0, v[186:187]
	s_mov_b64 s[26:27], 0x100000
	s_and_b64 vcc, exec, s[40:41]
	s_mov_b32 s43, s30
	s_mov_b32 s42, s31
	s_mov_b64 s[34:35], s[18:19]
	s_waitcnt vmcnt(0)
	s_nop 0
	v_pk_fma_f32 v[134:135], v[134:135], v[110:111], v[220:221]
	v_pk_fma_f32 v[132:133], v[132:133], v[108:109], v[218:219]
	global_store_dwordx4 v[226:227], v[132:135], off offset:576
	v_pk_fma_f32 v[102:103], v[102:103], v[110:111], v[202:203]
	v_pk_fma_f32 v[100:101], v[100:101], v[108:109], v[200:201]
	v_lshl_add_u64 v[132:133], s[14:15], 0, v[224:225]
	v_lshl_add_u64 v[132:133], v[132:133], 0, v[186:187]
	global_store_dwordx4 v[132:133], v[100:103], off offset:576
	v_pk_fma_f32 v[106:107], v[106:107], v[114:115], v[208:209]
	v_pk_fma_f32 v[104:105], v[104:105], v[112:113], v[206:207]
	v_lshl_add_u64 v[100:101], s[14:15], 0, v[194:195]
	v_lshl_add_u64 v[100:101], v[100:101], 0, v[186:187]
	v_pk_fma_f32 v[78:79], v[78:79], v[110:111], v[166:167]
	v_pk_fma_f32 v[76:77], v[76:77], v[108:109], v[164:165]
	global_store_dwordx4 v[132:133], v[104:107], off offset:512
	v_pk_fma_f32 v[86:87], v[86:87], v[114:115], v[170:171]
	v_pk_fma_f32 v[84:85], v[84:85], v[112:113], v[168:169]
	global_store_dwordx4 v[100:101], v[76:79], off offset:576
	v_lshl_add_u64 v[106:107], v[190:191], 0, s[26:27]
	s_mov_b64 s[26:27], 0x120000
	v_lshl_add_u64 v[76:77], s[14:15], 0, v[192:193]
	global_store_dwordx4 v[100:101], v[84:87], off offset:512
	v_pk_fma_f32 v[78:79], v[90:91], v[130:131], v[162:163]
	v_pk_fma_f32 v[72:73], v[72:73], v[112:113], v[152:153]
	v_lshl_add_u64 v[84:85], v[76:77], 0, v[186:187]
	v_pk_fma_f32 v[76:77], v[88:89], v[128:129], v[160:161]
	v_lshl_add_u64 v[152:153], v[190:191], 0, s[26:27]
	s_mov_b64 s[26:27], 0x140000
	v_pk_fma_f32 v[146:147], v[146:147], v[130:131], v[242:243]
	v_pk_fma_f32 v[144:145], v[144:145], v[128:129], v[240:241]
	v_pk_fma_f32 v[142:143], v[142:143], v[122:123], v[238:239]
	v_pk_fma_f32 v[140:141], v[140:141], v[120:121], v[236:237]
	v_pk_fma_f32 v[138:139], v[138:139], v[114:115], v[234:235]
	v_pk_fma_f32 v[136:137], v[136:137], v[112:113], v[232:233]
	v_pk_fma_f32 v[126:127], v[126:127], v[130:131], v[216:217]
	v_pk_fma_f32 v[124:125], v[124:125], v[128:129], v[214:215]
	v_pk_fma_f32 v[118:119], v[118:119], v[122:123], v[212:213]
	v_pk_fma_f32 v[116:117], v[116:117], v[120:121], v[210:211]
	v_pk_fma_f32 v[98:99], v[98:99], v[130:131], v[178:179]
	v_pk_fma_f32 v[96:97], v[96:97], v[128:129], v[176:177]
	v_pk_fma_f32 v[94:95], v[94:95], v[122:123], v[174:175]
	v_pk_fma_f32 v[92:93], v[92:93], v[120:121], v[172:173]
	global_store_dwordx4 v[84:85], v[76:79], off
	v_pk_fma_f32 v[74:75], v[74:75], v[114:115], v[154:155]
	v_pk_fma_f32 v[70:71], v[70:71], v[110:111], v[150:151]
	v_pk_fma_f32 v[78:79], v[82:83], v[122:123], v[158:159]
	v_pk_fma_f32 v[76:77], v[80:81], v[120:121], v[156:157]
	v_pk_fma_f32 v[68:69], v[68:69], v[108:109], v[148:149]
	v_lshl_add_u64 v[154:155], v[190:191], 0, s[26:27]
	s_mov_b64 s[26:27], 0x160000
	global_store_dwordx4 v[226:227], v[144:147], off
	global_store_dwordx4 v[226:227], v[140:143], off offset:64
	global_store_dwordx4 v[226:227], v[136:139], off offset:512
	global_store_dwordx4 v[132:133], v[124:127], off
	global_store_dwordx4 v[132:133], v[116:119], off offset:64
	global_store_dwordx4 v[100:101], v[96:99], off
	global_store_dwordx4 v[100:101], v[92:95], off offset:64
	global_store_dwordx4 v[84:85], v[76:79], off offset:64
	global_store_dwordx4 v[84:85], v[72:75], off offset:512
	global_store_dwordx4 v[84:85], v[68:71], off offset:576
	v_lshl_add_u64 v[100:101], v[190:191], 0, s[26:27]
	v_lshl_add_u64 v[96:97], v[188:189], 0, v[154:155]
	v_lshl_add_u64 v[68:69], v[188:189], 0, v[106:107]
	v_lshl_add_u64 v[70:71], v[188:189], 0, v[152:153]
	v_lshl_add_u64 v[80:81], v[188:189], 0, v[100:101]
	global_load_dwordx4 v[102:105], v[70:71], off offset:576
	global_load_dwordx4 v[116:119], v[70:71], off offset:512
	global_load_dwordx4 v[124:127], v[70:71], off offset:64
	global_load_dwordx4 v[132:135], v[70:71], off
	global_load_dwordx4 v[136:139], v[68:69], off offset:576
	global_load_dwordx4 v[140:143], v[68:69], off offset:512
	global_load_dwordx4 v[144:147], v[68:69], off offset:64
	global_load_dwordx4 v[148:151], v[68:69], off
	s_nop 0
	global_load_dwordx4 v[68:71], v[80:81], off offset:576
	global_load_dwordx4 v[72:75], v[80:81], off offset:512
	global_load_dwordx4 v[76:79], v[80:81], off offset:64
	s_nop 0
	global_load_dwordx4 v[80:83], v[80:81], off
	s_nop 0
	global_load_dwordx4 v[84:87], v[96:97], off offset:576
	global_load_dwordx4 v[88:91], v[96:97], off offset:512
	global_load_dwordx4 v[92:95], v[96:97], off offset:64
	s_nop 0
	global_load_dwordx4 v[96:99], v[96:97], off
	v_lshl_add_u64 v[106:107], s[14:15], 0, v[106:107]
	s_waitcnt vmcnt(0)
	v_lshl_add_u64 v[106:107], v[106:107], 0, v[186:187]
	v_pk_fma_f32 v[54:55], v[54:55], v[110:111], v[138:139]
	v_pk_fma_f32 v[52:53], v[52:53], v[108:109], v[136:137]
	global_store_dwordx4 v[106:107], v[52:55], off offset:576
	v_pk_fma_f32 v[38:39], v[38:39], v[110:111], v[104:105]
	v_pk_fma_f32 v[36:37], v[36:37], v[108:109], v[102:103]
	v_lshl_add_u64 v[52:53], s[14:15], 0, v[152:153]
	v_lshl_add_u64 v[52:53], v[52:53], 0, v[186:187]
	global_store_dwordx4 v[52:53], v[36:39], off offset:576
	v_pk_fma_f32 v[18:19], v[18:19], v[110:111], v[86:87]
	v_pk_fma_f32 v[16:17], v[16:17], v[108:109], v[84:85]
	v_lshl_add_u64 v[36:37], s[14:15], 0, v[154:155]
	v_lshl_add_u64 v[36:37], v[36:37], 0, v[186:187]
	v_pk_fma_f32 v[26:27], v[26:27], v[114:115], v[90:91]
	v_pk_fma_f32 v[24:25], v[24:25], v[112:113], v[88:89]
	global_store_dwordx4 v[36:37], v[16:19], off offset:576
	v_pk_fma_f32 v[66:67], v[66:67], v[130:131], v[150:151]
	v_pk_fma_f32 v[64:65], v[64:65], v[128:129], v[148:149]
	v_lshl_add_u64 v[16:17], s[14:15], 0, v[100:101]
	v_pk_fma_f32 v[62:63], v[62:63], v[122:123], v[146:147]
	v_pk_fma_f32 v[60:61], v[60:61], v[120:121], v[144:145]
	v_pk_fma_f32 v[58:59], v[58:59], v[114:115], v[142:143]
	v_pk_fma_f32 v[56:57], v[56:57], v[112:113], v[140:141]
	v_pk_fma_f32 v[50:51], v[50:51], v[130:131], v[134:135]
	v_pk_fma_f32 v[48:49], v[48:49], v[128:129], v[132:133]
	v_pk_fma_f32 v[46:47], v[46:47], v[122:123], v[126:127]
	v_pk_fma_f32 v[44:45], v[44:45], v[120:121], v[124:125]
	v_pk_fma_f32 v[42:43], v[42:43], v[114:115], v[118:119]
	v_pk_fma_f32 v[40:41], v[40:41], v[112:113], v[116:117]
	v_pk_fma_f32 v[34:35], v[34:35], v[130:131], v[98:99]
	v_pk_fma_f32 v[32:33], v[32:33], v[128:129], v[96:97]
	v_pk_fma_f32 v[30:31], v[30:31], v[122:123], v[94:95]
	v_pk_fma_f32 v[28:29], v[28:29], v[120:121], v[92:93]
	global_store_dwordx4 v[36:37], v[24:27], off offset:512
	v_pk_fma_f32 v[18:19], v[22:23], v[130:131], v[82:83]
	v_pk_fma_f32 v[14:15], v[14:15], v[122:123], v[78:79]
	v_lshl_add_u64 v[24:25], v[16:17], 0, v[186:187]
	v_pk_fma_f32 v[16:17], v[20:21], v[128:129], v[80:81]
	v_pk_fma_f32 v[12:13], v[12:13], v[120:121], v[76:77]
	v_pk_fma_f32 v[10:11], v[10:11], v[114:115], v[74:75]
	v_pk_fma_f32 v[8:9], v[8:9], v[112:113], v[72:73]
	v_pk_fma_f32 v[6:7], v[6:7], v[110:111], v[70:71]
	v_pk_fma_f32 v[4:5], v[4:5], v[108:109], v[68:69]
	global_store_dwordx4 v[106:107], v[64:67], off
	global_store_dwordx4 v[106:107], v[60:63], off offset:64
	global_store_dwordx4 v[106:107], v[56:59], off offset:512
	global_store_dwordx4 v[52:53], v[48:51], off
	global_store_dwordx4 v[52:53], v[44:47], off offset:64
	global_store_dwordx4 v[52:53], v[40:43], off offset:512
	global_store_dwordx4 v[36:37], v[32:35], off
	global_store_dwordx4 v[36:37], v[28:31], off offset:64
	global_store_dwordx4 v[24:25], v[16:19], off
	global_store_dwordx4 v[24:25], v[12:15], off offset:64
	global_store_dwordx4 v[24:25], v[8:11], off offset:512
	global_store_dwordx4 v[24:25], v[4:7], off offset:576
	s_mov_b64 s[26:27], s[16:17]
	s_cbranch_vccz .LBB0_3028
	s_waitcnt vmcnt(0)
	s_cmpk_gt_u32 s4, 0xff
	s_cbranch_scc1 .LBB0_3039
	s_barrier

.LBB0_3048:
	s_add_u32 s40, s36, 0x100
	s_addc_u32 s41, s37, 0
	s_add_i32 s47, 0, 0x10000
	v_add_u32_e32 v144, s47, v158
	ds_read_b128 v[132:135], v144
	ds_read_b128 v[136:139], v144 offset:1024
	ds_read_b128 v[140:143], v144 offset:2048
	ds_read_b128 v[144:147], v144 offset:3072
	s_cmp_eq_u32 s46, 4
	s_cselect_b32 s43, s19, s41
	s_cselect_b32 s42, s18, s40
	s_cselect_b32 s39, s27, s45
	s_cselect_b32 s38, s26, s44
	v_lshl_add_u64 v[154:155], s[36:37], 0, v[150:151]
	s_add_i32 m0, s6, 0xc000
	ds_read_b128 v[160:163], v159
	ds_read_b128 v[164:167], v159 offset:1024
	ds_read_b128 v[168:171], v159 offset:2048
	ds_read_b128 v[172:175], v159 offset:3072
	ds_read_b128 v[176:179], v159 offset:4096
	ds_read_b128 v[180:183], v159 offset:5120
	ds_read_b128 v[184:187], v159 offset:6144
	ds_read_b128 v[188:191], v159 offset:7168
	global_load_lds_dwordx4 v[154:155], off
	v_lshl_add_u64 v[154:155], s[36:37], 0, v[152:153]
	s_add_i32 m0, s6, 0xe000
	s_nop 0
	global_load_lds_dwordx4 v[154:155], off
	s_waitcnt vmcnt(10)
	s_barrier
	s_waitcnt lgkmcnt(0)
	v_mfma_f32_16x16x32_f16 v[128:131], v[132:135], v[160:163], v[128:131]
	v_mfma_f32_16x16x32_f16 v[124:127], v[140:143], v[160:163], v[124:127]
	v_mfma_f32_16x16x32_f16 v[112:115], v[132:135], v[168:171], v[112:115]
	v_mfma_f32_16x16x32_f16 v[108:111], v[140:143], v[168:171], v[108:111]
	v_mfma_f32_16x16x32_f16 v[96:99], v[132:135], v[176:179], v[96:99]
	v_mfma_f32_16x16x32_f16 v[92:95], v[140:143], v[176:179], v[92:95]
	v_mfma_f32_16x16x32_f16 v[80:83], v[132:135], v[184:187], v[80:83]
	v_mfma_f32_16x16x32_f16 v[76:79], v[140:143], v[184:187], v[76:79]
	v_mfma_f32_16x16x32_f16 v[128:131], v[136:139], v[164:167], v[128:131]
	v_mfma_f32_16x16x32_f16 v[124:127], v[144:147], v[164:167], v[124:127]
	v_mfma_f32_16x16x32_f16 v[112:115], v[136:139], v[172:175], v[112:115]
	v_mfma_f32_16x16x32_f16 v[108:111], v[144:147], v[172:175], v[108:111]
	v_mfma_f32_16x16x32_f16 v[96:99], v[136:139], v[180:183], v[96:99]
	v_mfma_f32_16x16x32_f16 v[92:95], v[144:147], v[180:183], v[92:95]
	v_mfma_f32_16x16x32_f16 v[80:83], v[136:139], v[188:191], v[80:83]
	v_mfma_f32_16x16x32_f16 v[76:79], v[144:147], v[188:191], v[76:79]
	s_barrier
	s_add_i32 s48, 0, 0x14000
	v_add_u32_e32 v154, s48, v158
	s_add_i32 s36, s47, s5
	ds_read_b128 v[192:195], v154
	ds_read_b128 v[196:199], v154 offset:1024
	ds_read_b128 v[200:203], v154 offset:2048
	ds_read_b128 v[206:209], v154 offset:3072
	v_lshl_add_u64 v[154:155], s[38:39], 0, v[2:3]
	s_mov_b32 m0, s36
	v_lshl_add_u64 v[210:211], s[38:39], 0, v[148:149]
	global_load_lds_dwordx4 v[154:155], off
	s_add_i32 m0, s36, 0x2000
	s_nop 0
	global_load_lds_dwordx4 v[210:211], off
	s_waitcnt vmcnt(10)
	s_barrier
	s_waitcnt lgkmcnt(0)
	v_mfma_f32_16x16x32_f16 v[120:123], v[192:195], v[160:163], v[120:123]
	v_mfma_f32_16x16x32_f16 v[116:119], v[200:203], v[160:163], v[116:119]
	v_mfma_f32_16x16x32_f16 v[104:107], v[192:195], v[168:171], v[104:107]
	v_mfma_f32_16x16x32_f16 v[100:103], v[200:203], v[168:171], v[100:103]
	v_mfma_f32_16x16x32_f16 v[88:91], v[192:195], v[176:179], v[88:91]
	v_mfma_f32_16x16x32_f16 v[84:87], v[200:203], v[176:179], v[84:87]
	v_mfma_f32_16x16x32_f16 v[72:75], v[192:195], v[184:187], v[72:75]
	v_mfma_f32_16x16x32_f16 v[68:71], v[200:203], v[184:187], v[68:71]
	v_mfma_f32_16x16x32_f16 v[120:123], v[196:199], v[164:167], v[120:123]
	v_mfma_f32_16x16x32_f16 v[116:119], v[206:209], v[164:167], v[116:119]
	v_mfma_f32_16x16x32_f16 v[104:107], v[196:199], v[172:175], v[104:107]
	v_mfma_f32_16x16x32_f16 v[100:103], v[206:209], v[172:175], v[100:103]
	v_mfma_f32_16x16x32_f16 v[88:91], v[196:199], v[180:183], v[88:91]
	v_mfma_f32_16x16x32_f16 v[84:87], v[206:209], v[180:183], v[84:87]
	v_mfma_f32_16x16x32_f16 v[72:75], v[196:199], v[188:191], v[72:75]
	v_mfma_f32_16x16x32_f16 v[68:71], v[206:209], v[188:191], v[68:71]
	s_mov_b32 m0, s6
	v_lshl_add_u64 v[212:213], s[42:43], 0, v[2:3]
	s_barrier
	ds_read_b128 v[160:163], v159 offset:16384
	ds_read_b128 v[164:167], v159 offset:17408
	ds_read_b128 v[168:171], v159 offset:18432
	ds_read_b128 v[172:175], v159 offset:19456
	ds_read_b128 v[176:179], v159 offset:20480
	ds_read_b128 v[180:183], v159 offset:21504
	ds_read_b128 v[184:187], v159 offset:22528
	ds_read_b128 v[188:191], v159 offset:23552
	global_load_lds_dwordx4 v[212:213], off
	v_lshl_add_u64 v[214:215], s[42:43], 0, v[148:149]
	s_mov_b32 m0, s7
	s_nop 0
	global_load_lds_dwordx4 v[214:215], off
	s_waitcnt vmcnt(10)
	s_barrier
	s_waitcnt lgkmcnt(0)
	v_mfma_f32_16x16x32_f16 v[64:67], v[132:135], v[160:163], v[64:67]
	v_mfma_f32_16x16x32_f16 v[60:63], v[140:143], v[160:163], v[60:63]
	v_mfma_f32_16x16x32_f16 v[56:59], v[132:135], v[168:171], v[56:59]
	v_mfma_f32_16x16x32_f16 v[44:47], v[140:143], v[168:171], v[44:47]
	v_mfma_f32_16x16x32_f16 v[40:43], v[132:135], v[176:179], v[40:43]
	v_mfma_f32_16x16x32_f16 v[28:31], v[140:143], v[176:179], v[28:31]
	v_mfma_f32_16x16x32_f16 v[24:27], v[132:135], v[184:187], v[24:27]
	v_mfma_f32_16x16x32_f16 v[12:15], v[140:143], v[184:187], v[12:15]
	v_mfma_f32_16x16x32_f16 v[64:67], v[136:139], v[164:167], v[64:67]
	v_mfma_f32_16x16x32_f16 v[60:63], v[144:147], v[164:167], v[60:63]
	v_mfma_f32_16x16x32_f16 v[56:59], v[136:139], v[172:175], v[56:59]
	v_mfma_f32_16x16x32_f16 v[44:47], v[144:147], v[172:175], v[44:47]
	v_mfma_f32_16x16x32_f16 v[40:43], v[136:139], v[180:183], v[40:43]
	v_mfma_f32_16x16x32_f16 v[28:31], v[144:147], v[180:183], v[28:31]
	v_mfma_f32_16x16x32_f16 v[24:27], v[136:139], v[188:191], v[24:27]
	v_mfma_f32_16x16x32_f16 v[12:15], v[144:147], v[188:191], v[12:15]
	s_barrier
	s_add_u32 s36, s38, 0x160000
	s_addc_u32 s37, s39, 0
	s_add_i32 s47, s48, s5
	v_lshl_add_u64 v[132:133], s[36:37], 0, v[2:3]
	s_mov_b32 m0, s47
	s_nop 0
	global_load_lds_dwordx4 v[132:133], off
	s_add_i32 m0, s47, 0x2000
	s_nop 0
	global_load_lds_dwordx4 v148, s[36:37]
	s_waitcnt vmcnt(10)
	s_barrier
	v_mfma_f32_16x16x32_f16 v[52:55], v[192:195], v[160:163], v[52:55]
	v_mfma_f32_16x16x32_f16 v[48:51], v[200:203], v[160:163], v[48:51]
	v_mfma_f32_16x16x32_f16 v[36:39], v[192:195], v[168:171], v[36:39]
	v_mfma_f32_16x16x32_f16 v[32:35], v[200:203], v[168:171], v[32:35]
	v_mfma_f32_16x16x32_f16 v[20:23], v[192:195], v[176:179], v[20:23]
	v_mfma_f32_16x16x32_f16 v[16:19], v[200:203], v[176:179], v[16:19]
	v_mfma_f32_16x16x32_f16 v[8:11], v[192:195], v[184:187], v[8:11]
	v_mfma_f32_16x16x32_f16 v[4:7], v[200:203], v[184:187], v[4:7]
	v_mfma_f32_16x16x32_f16 v[52:55], v[196:199], v[164:167], v[52:55]
	v_mfma_f32_16x16x32_f16 v[48:51], v[206:209], v[164:167], v[48:51]
	v_mfma_f32_16x16x32_f16 v[36:39], v[196:199], v[172:175], v[36:39]
	v_mfma_f32_16x16x32_f16 v[32:35], v[206:209], v[172:175], v[32:35]
	v_mfma_f32_16x16x32_f16 v[20:23], v[196:199], v[180:183], v[20:23]
	v_mfma_f32_16x16x32_f16 v[16:19], v[206:209], v[180:183], v[16:19]
	v_mfma_f32_16x16x32_f16 v[8:11], v[196:199], v[188:191], v[8:11]
	v_mfma_f32_16x16x32_f16 v[4:7], v[206:209], v[188:191], v[4:7]
	s_add_i32 s47, 0, 0x18000
	v_add_u32_e32 v144, s47, v158
	s_barrier
	ds_read_b128 v[132:135], v144
	ds_read_b128 v[136:139], v144 offset:1024
	ds_read_b128 v[140:143], v144 offset:2048
	ds_read_b128 v[144:147], v144 offset:3072
	s_add_u32 s36, s42, 0x160000
	s_addc_u32 s37, s43, 0
	s_mov_b32 m0, s8
	v_lshl_add_u64 v[192:193], s[36:37], 0, v[2:3]
	ds_read_b128 v[160:163], v159 offset:32768
	ds_read_b128 v[164:167], v159 offset:33792
	ds_read_b128 v[168:171], v159 offset:34816
	ds_read_b128 v[172:175], v159 offset:35840
	ds_read_b128 v[176:179], v159 offset:36864
	ds_read_b128 v[180:183], v159 offset:37888
	ds_read_b128 v[184:187], v159 offset:38912
	ds_read_b128 v[188:191], v159 offset:39936
	global_load_lds_dwordx4 v[192:193], off
	s_mov_b32 m0, s9
	s_nop 0
	global_load_lds_dwordx4 v148, s[36:37]
	s_waitcnt vmcnt(10)
	s_barrier
	s_waitcnt lgkmcnt(0)
	v_mfma_f32_16x16x32_f16 v[128:131], v[132:135], v[160:163], v[128:131]
	v_mfma_f32_16x16x32_f16 v[124:127], v[140:143], v[160:163], v[124:127]
	v_mfma_f32_16x16x32_f16 v[112:115], v[132:135], v[168:171], v[112:115]
	v_mfma_f32_16x16x32_f16 v[108:111], v[140:143], v[168:171], v[108:111]
	v_mfma_f32_16x16x32_f16 v[96:99], v[132:135], v[176:179], v[96:99]
	v_mfma_f32_16x16x32_f16 v[92:95], v[140:143], v[176:179], v[92:95]
	v_mfma_f32_16x16x32_f16 v[80:83], v[132:135], v[184:187], v[80:83]
	v_mfma_f32_16x16x32_f16 v[76:79], v[140:143], v[184:187], v[76:79]
	v_mfma_f32_16x16x32_f16 v[128:131], v[136:139], v[164:167], v[128:131]
	v_mfma_f32_16x16x32_f16 v[124:127], v[144:147], v[164:167], v[124:127]
	v_mfma_f32_16x16x32_f16 v[112:115], v[136:139], v[172:175], v[112:115]
	v_mfma_f32_16x16x32_f16 v[108:111], v[144:147], v[172:175], v[108:111]
	v_mfma_f32_16x16x32_f16 v[96:99], v[136:139], v[180:183], v[96:99]
	v_mfma_f32_16x16x32_f16 v[92:95], v[144:147], v[180:183], v[92:95]
	v_mfma_f32_16x16x32_f16 v[80:83], v[136:139], v[188:191], v[80:83]
	v_mfma_f32_16x16x32_f16 v[76:79], v[144:147], v[188:191], v[76:79]
	s_barrier
	s_add_i32 s42, 0, 0x1c000
	s_add_i32 s36, s47, s5
	v_add_u32_e32 v206, s42, v158
	v_lshl_add_u64 v[154:155], v[154:155], 0, s[88:89]
	s_mov_b32 m0, s36
	ds_read_b128 v[192:195], v206
	ds_read_b128 v[196:199], v206 offset:1024
	ds_read_b128 v[200:203], v206 offset:2048
	ds_read_b128 v[206:209], v206 offset:3072
	global_load_lds_dwordx4 v[154:155], off
	v_lshl_add_u64 v[154:155], v[210:211], 0, s[88:89]
	s_add_i32 m0, s36, 0x2000
	s_nop 0
	global_load_lds_dwordx4 v[154:155], off
	s_waitcnt vmcnt(10)
	s_barrier
	s_waitcnt lgkmcnt(0)
	v_mfma_f32_16x16x32_f16 v[120:123], v[192:195], v[160:163], v[120:123]
	v_mfma_f32_16x16x32_f16 v[116:119], v[200:203], v[160:163], v[116:119]
	v_mfma_f32_16x16x32_f16 v[104:107], v[192:195], v[168:171], v[104:107]
	v_mfma_f32_16x16x32_f16 v[100:103], v[200:203], v[168:171], v[100:103]
	v_mfma_f32_16x16x32_f16 v[88:91], v[192:195], v[176:179], v[88:91]
	v_mfma_f32_16x16x32_f16 v[84:87], v[200:203], v[176:179], v[84:87]
	v_mfma_f32_16x16x32_f16 v[72:75], v[192:195], v[184:187], v[72:75]
	v_mfma_f32_16x16x32_f16 v[68:71], v[200:203], v[184:187], v[68:71]
	v_mfma_f32_16x16x32_f16 v[120:123], v[196:199], v[164:167], v[120:123]
	v_mfma_f32_16x16x32_f16 v[116:119], v[206:209], v[164:167], v[116:119]
	v_mfma_f32_16x16x32_f16 v[104:107], v[196:199], v[172:175], v[104:107]
	v_mfma_f32_16x16x32_f16 v[100:103], v[206:209], v[172:175], v[100:103]
	v_mfma_f32_16x16x32_f16 v[88:91], v[196:199], v[180:183], v[88:91]
	v_mfma_f32_16x16x32_f16 v[84:87], v[206:209], v[180:183], v[84:87]
	v_mfma_f32_16x16x32_f16 v[72:75], v[196:199], v[188:191], v[72:75]
	v_mfma_f32_16x16x32_f16 v[68:71], v[206:209], v[188:191], v[68:71]
	s_mov_b32 m0, s10
	v_lshl_add_u64 v[154:155], v[212:213], 0, s[88:89]
	s_barrier
	ds_read_b128 v[160:163], v159 offset:49152
	ds_read_b128 v[164:167], v159 offset:50176
	ds_read_b128 v[168:171], v159 offset:51200
	ds_read_b128 v[172:175], v159 offset:52224
	ds_read_b128 v[176:179], v159 offset:53248
	ds_read_b128 v[180:183], v159 offset:54272
	ds_read_b128 v[184:187], v159 offset:55296
	ds_read_b128 v[188:191], v159 offset:56320
	global_load_lds_dwordx4 v[154:155], off
	v_lshl_add_u64 v[154:155], v[214:215], 0, s[88:89]
	s_mov_b32 m0, s11
	s_nop 0
	global_load_lds_dwordx4 v[154:155], off
	s_waitcnt vmcnt(10)
	s_barrier
	s_waitcnt lgkmcnt(0)
	v_mfma_f32_16x16x32_f16 v[64:67], v[132:135], v[160:163], v[64:67]
	v_mfma_f32_16x16x32_f16 v[60:63], v[140:143], v[160:163], v[60:63]
	v_mfma_f32_16x16x32_f16 v[56:59], v[132:135], v[168:171], v[56:59]
	v_mfma_f32_16x16x32_f16 v[44:47], v[140:143], v[168:171], v[44:47]
	v_mfma_f32_16x16x32_f16 v[40:43], v[132:135], v[176:179], v[40:43]
	v_mfma_f32_16x16x32_f16 v[28:31], v[140:143], v[176:179], v[28:31]
	v_mfma_f32_16x16x32_f16 v[24:27], v[132:135], v[184:187], v[24:27]
	v_mfma_f32_16x16x32_f16 v[12:15], v[140:143], v[184:187], v[12:15]
	v_mfma_f32_16x16x32_f16 v[64:67], v[136:139], v[164:167], v[64:67]
	v_mfma_f32_16x16x32_f16 v[60:63], v[144:147], v[164:167], v[60:63]
	v_mfma_f32_16x16x32_f16 v[56:59], v[136:139], v[172:175], v[56:59]
	v_mfma_f32_16x16x32_f16 v[44:47], v[144:147], v[172:175], v[44:47]
	v_mfma_f32_16x16x32_f16 v[40:43], v[136:139], v[180:183], v[40:43]
	v_mfma_f32_16x16x32_f16 v[28:31], v[144:147], v[180:183], v[28:31]
	v_mfma_f32_16x16x32_f16 v[24:27], v[136:139], v[188:191], v[24:27]
	v_mfma_f32_16x16x32_f16 v[12:15], v[144:147], v[188:191], v[12:15]
	s_barrier
	s_add_u32 s36, s38, 0x160080
	s_addc_u32 s37, s39, 0
	s_add_i32 s38, s42, s5
	v_lshl_add_u64 v[132:133], s[36:37], 0, v[2:3]
	s_mov_b32 m0, s38
	s_nop 0
	global_load_lds_dwordx4 v[132:133], off
	s_add_i32 m0, s38, 0x2000
	s_nop 0
	global_load_lds_dwordx4 v148, s[36:37]
	s_waitcnt vmcnt(10)
	s_barrier
	v_mfma_f32_16x16x32_f16 v[52:55], v[192:195], v[160:163], v[52:55]
	v_mfma_f32_16x16x32_f16 v[48:51], v[200:203], v[160:163], v[48:51]
	v_mfma_f32_16x16x32_f16 v[36:39], v[192:195], v[168:171], v[36:39]
	v_mfma_f32_16x16x32_f16 v[32:35], v[200:203], v[168:171], v[32:35]
	v_mfma_f32_16x16x32_f16 v[20:23], v[192:195], v[176:179], v[20:23]
	v_mfma_f32_16x16x32_f16 v[16:19], v[200:203], v[176:179], v[16:19]
	v_mfma_f32_16x16x32_f16 v[8:11], v[192:195], v[184:187], v[8:11]
	v_mfma_f32_16x16x32_f16 v[4:7], v[200:203], v[184:187], v[4:7]
	v_mfma_f32_16x16x32_f16 v[52:55], v[196:199], v[164:167], v[52:55]
	v_mfma_f32_16x16x32_f16 v[48:51], v[206:209], v[164:167], v[48:51]
	v_mfma_f32_16x16x32_f16 v[36:39], v[196:199], v[172:175], v[36:39]
	v_mfma_f32_16x16x32_f16 v[32:35], v[206:209], v[172:175], v[32:35]
	v_mfma_f32_16x16x32_f16 v[20:23], v[196:199], v[180:183], v[20:23]
	v_mfma_f32_16x16x32_f16 v[16:19], v[206:209], v[180:183], v[16:19]
	v_mfma_f32_16x16x32_f16 v[8:11], v[196:199], v[188:191], v[8:11]
	v_mfma_f32_16x16x32_f16 v[4:7], v[206:209], v[188:191], v[4:7]
	s_add_i32 s46, s46, 2
	s_add_u32 s44, s44, 0x100
	s_addc_u32 s45, s45, 0
	s_cmp_gt_u32 s46, 5
	s_mov_b64 s[36:37], s[40:41]
	s_barrier
	s_cbranch_scc0 .LBB0_3048
	s_lshl_b32 s36, s30, 8
	v_mov_b32_e32 v160, v156
	v_mov_b32_e32 v132, v157
	s_and_b32 s36, s36, 0xff00
	s_or_b32 s36, s36, s12
	v_lshl_add_u32 v132, v132, 2, s36
	v_ashrrev_i32_e32 v133, 31, v132
	v_lshlrev_b64 v[154:155], 2, v[132:133]
	v_lshl_add_u64 v[132:133], s[16:17], 0, v[154:155]
	global_load_dwordx4 v[144:147], v[132:133], off
	global_load_dwordx4 v[140:143], v[132:133], off offset:64
	global_load_dwordx4 v[136:139], v[132:133], off offset:512
	s_nop 0
	global_load_dwordx4 v[132:135], v[132:133], off offset:576
	s_lshl_b32 s31, s31, 8
	s_ashr_i32 s30, s30, 8
	s_add_i32 s31, s13, s31
	v_add_u32_e32 v160, s31, v160
	s_ashr_i32 s31, s30, 31
	s_lshl_b64 s[30:31], s[30:31], 22
	v_readlane_b32 s36, v250, 27
	v_readlane_b32 s37, v250, 28
	s_add_u32 s30, s36, s30
	s_addc_u32 s31, s37, s31
	v_ashrrev_i32_e32 v161, 31, v160
	v_lshl_add_u64 v[154:155], s[30:31], 0, v[154:155]
	v_lshlrev_b64 v[160:161], 13, v[160:161]
	v_lshl_add_u64 v[154:155], v[154:155], 0, v[160:161]
	s_mov_b64 s[30:31], 0x20000
	s_mov_b64 s[38:39], s[26:27]
	s_mov_b64 s[36:37], s[18:19]
	s_waitcnt vmcnt(0)
	v_pk_mul_f32 v[130:131], v[130:131], v[146:147]
	v_pk_mul_f32 v[128:129], v[128:129], v[144:145]
	v_pk_mul_f32 v[54:55], v[54:55], v[138:139]
	v_pk_mul_f32 v[118:119], v[118:119], v[134:135]
	v_pk_mul_f32 v[116:117], v[116:117], v[132:133]
	global_store_dwordx4 v[154:155], v[116:119], off offset:576
	v_pk_mul_f32 v[102:103], v[102:103], v[134:135]
	v_pk_mul_f32 v[100:101], v[100:101], v[132:133]
	v_lshl_add_u64 v[116:117], v[154:155], 0, s[30:31]
	s_mov_b32 s30, 0x20000
	v_add_co_u32_e32 v118, vcc, s30, v154
	s_mov_b64 s[30:31], 0x40000
	s_nop 0
	v_addc_co_u32_e32 v119, vcc, 0, v155, vcc
	global_store_dwordx4 v[116:117], v[100:103], off offset:576
	v_pk_mul_f32 v[86:87], v[86:87], v[134:135]
	v_pk_mul_f32 v[84:85], v[84:85], v[132:133]
	v_lshl_add_u64 v[100:101], v[154:155], 0, s[30:31]
	s_mov_b32 s30, 0x40000
	v_add_co_u32_e32 v102, vcc, s30, v154
	s_mov_b64 s[30:31], 0x60000
	s_nop 0
	v_addc_co_u32_e32 v103, vcc, 0, v155, vcc
	global_store_dwordx4 v[100:101], v[84:87], off offset:576
	v_pk_mul_f32 v[70:71], v[70:71], v[134:135]
	v_pk_mul_f32 v[68:69], v[68:69], v[132:133]
	v_lshl_add_u64 v[84:85], v[154:155], 0, s[30:31]
	s_mov_b32 s30, 0x60000
	v_add_co_u32_e32 v86, vcc, s30, v154
	s_mov_b64 s[30:31], 0x100000
	s_nop 0
	v_addc_co_u32_e32 v87, vcc, 0, v155, vcc
	global_store_dwordx4 v[84:85], v[68:71], off offset:576
	v_pk_mul_f32 v[52:53], v[52:53], v[136:137]
	v_pk_mul_f32 v[38:39], v[38:39], v[138:139]
	v_lshl_add_u64 v[68:69], v[154:155], 0, s[30:31]
	s_mov_b32 s30, 0x100000
	v_add_co_u32_e32 v70, vcc, s30, v154
	s_mov_b64 s[30:31], 0x120000
	s_nop 0
	v_addc_co_u32_e32 v71, vcc, 0, v155, vcc
	global_store_dwordx4 v[68:69], v[52:55], off offset:512
	v_pk_mul_f32 v[36:37], v[36:37], v[136:137]
	v_pk_mul_f32 v[22:23], v[22:23], v[138:139]
	v_lshl_add_u64 v[52:53], v[154:155], 0, s[30:31]
	s_mov_b32 s30, 0x120000
	v_add_co_u32_e32 v54, vcc, s30, v154
	s_mov_b64 s[30:31], 0x140000
	s_nop 0
	v_addc_co_u32_e32 v55, vcc, 0, v155, vcc
	global_store_dwordx4 v[52:53], v[36:39], off offset:512
	v_pk_mul_f32 v[20:21], v[20:21], v[136:137]
	v_pk_mul_f32 v[50:51], v[50:51], v[134:135]
	v_lshl_add_u64 v[36:37], v[154:155], 0, s[30:31]
	s_mov_b32 s30, 0x140000
	v_add_co_u32_e32 v38, vcc, s30, v154
	s_mov_b64 s[30:31], 0x160000
	s_nop 0
	v_addc_co_u32_e32 v39, vcc, 0, v155, vcc
	global_store_dwordx4 v[36:37], v[20:23], off offset:512
	v_pk_mul_f32 v[48:49], v[48:49], v[132:133]
	v_pk_mul_f32 v[34:35], v[34:35], v[134:135]
	v_lshl_add_u64 v[20:21], v[154:155], 0, s[30:31]
	s_mov_b32 s30, 0x160000
	v_add_co_u32_e32 v22, vcc, s30, v154
	v_pk_mul_f32 v[32:33], v[32:33], v[132:133]
	v_pk_mul_f32 v[18:19], v[18:19], v[134:135]
	v_pk_mul_f32 v[16:17], v[16:17], v[132:133]
	v_addc_co_u32_e32 v23, vcc, 0, v155, vcc
	v_pk_mul_f32 v[126:127], v[126:127], v[142:143]
	v_pk_mul_f32 v[124:125], v[124:125], v[140:141]
	v_pk_mul_f32 v[122:123], v[122:123], v[138:139]
	v_pk_mul_f32 v[120:121], v[120:121], v[136:137]
	v_pk_mul_f32 v[114:115], v[114:115], v[146:147]
	v_pk_mul_f32 v[112:113], v[112:113], v[144:145]
	v_pk_mul_f32 v[110:111], v[110:111], v[142:143]
	v_pk_mul_f32 v[108:109], v[108:109], v[140:141]
	v_pk_mul_f32 v[106:107], v[106:107], v[138:139]
	v_pk_mul_f32 v[104:105], v[104:105], v[136:137]
	v_pk_mul_f32 v[98:99], v[98:99], v[146:147]
	v_pk_mul_f32 v[96:97], v[96:97], v[144:145]
	v_pk_mul_f32 v[94:95], v[94:95], v[142:143]
	v_pk_mul_f32 v[92:93], v[92:93], v[140:141]
	v_pk_mul_f32 v[90:91], v[90:91], v[138:139]
	v_pk_mul_f32 v[88:89], v[88:89], v[136:137]
	v_pk_mul_f32 v[82:83], v[82:83], v[146:147]
	v_pk_mul_f32 v[80:81], v[80:81], v[144:145]
	v_pk_mul_f32 v[78:79], v[78:79], v[142:143]
	v_pk_mul_f32 v[76:77], v[76:77], v[140:141]
	v_pk_mul_f32 v[74:75], v[74:75], v[138:139]
	v_pk_mul_f32 v[72:73], v[72:73], v[136:137]
	v_pk_mul_f32 v[66:67], v[66:67], v[146:147]
	v_pk_mul_f32 v[64:65], v[64:65], v[144:145]
	v_pk_mul_f32 v[62:63], v[62:63], v[142:143]
	v_pk_mul_f32 v[60:61], v[60:61], v[140:141]
	global_store_dwordx4 v[68:69], v[48:51], off offset:576
	v_pk_mul_f32 v[46:47], v[46:47], v[142:143]
	v_pk_mul_f32 v[44:45], v[44:45], v[140:141]
	v_pk_mul_f32 v[50:51], v[58:59], v[146:147]
	v_pk_mul_f32 v[48:49], v[56:57], v[144:145]
	global_store_dwordx4 v[52:53], v[32:35], off offset:576
	v_pk_mul_f32 v[30:31], v[30:31], v[142:143]
	v_pk_mul_f32 v[28:29], v[28:29], v[140:141]
	v_pk_mul_f32 v[34:35], v[42:43], v[146:147]
	v_pk_mul_f32 v[32:33], v[40:41], v[144:145]
	global_store_dwordx4 v[36:37], v[16:19], off offset:576
	v_pk_mul_f32 v[14:15], v[14:15], v[142:143]
	v_pk_mul_f32 v[12:13], v[12:13], v[140:141]
	v_pk_mul_f32 v[18:19], v[26:27], v[146:147]
	v_pk_mul_f32 v[16:17], v[24:25], v[144:145]
	v_pk_mul_f32 v[10:11], v[10:11], v[138:139]
	v_pk_mul_f32 v[8:9], v[8:9], v[136:137]
	v_pk_mul_f32 v[6:7], v[6:7], v[134:135]
	v_pk_mul_f32 v[4:5], v[4:5], v[132:133]
	s_and_b64 vcc, exec, s[34:35]
	s_mov_b32 s30, s29
	s_mov_b32 s31, s15
	global_store_dwordx4 v[154:155], v[128:131], off
	global_store_dwordx4 v[154:155], v[124:127], off offset:64
	global_store_dwordx4 v[154:155], v[120:123], off offset:512
	global_store_dwordx4 v[118:119], v[112:115], off
	global_store_dwordx4 v[116:117], v[108:111], off offset:64
	global_store_dwordx4 v[116:117], v[104:107], off offset:512
	global_store_dwordx4 v[102:103], v[96:99], off
	global_store_dwordx4 v[100:101], v[92:95], off offset:64
	global_store_dwordx4 v[100:101], v[88:91], off offset:512
	global_store_dwordx4 v[86:87], v[80:83], off
	global_store_dwordx4 v[84:85], v[76:79], off offset:64
	global_store_dwordx4 v[84:85], v[72:75], off offset:512
	global_store_dwordx4 v[70:71], v[64:67], off
	global_store_dwordx4 v[68:69], v[60:63], off offset:64
	global_store_dwordx4 v[54:55], v[48:51], off
	global_store_dwordx4 v[52:53], v[44:47], off offset:64
	global_store_dwordx4 v[38:39], v[32:35], off
	global_store_dwordx4 v[36:37], v[28:31], off offset:64
	global_store_dwordx4 v[22:23], v[16:19], off
	global_store_dwordx4 v[20:21], v[12:15], off offset:64
	global_store_dwordx4 v[20:21], v[8:11], off offset:512
	global_store_dwordx4 v[20:21], v[4:7], off offset:576
	s_cbranch_vccz .LBB0_3045
	s_waitcnt vmcnt(0)
	s_cmpk_gt_u32 s4, 0xff
	s_cbranch_scc1 .LBB0_3052
	s_barrier
